# speedup vs baseline: 1.0080x; 1.0012x over previous
; __device__ __forceinline__ float bflo(unsigned w) { return __uint_as_float(w << 16); }
; __device__ __forceinline__ float bfhi(unsigned w) { return __uint_as_float(w & 0xffff0000u); }
; __device__ void gmlp_item(const Params& p, int layer, int b, int n, int g, char* smem) {
;     ...
;   {
;     uint4 raw[8];
; #pragma unroll
;     for (int i = 0; i < 8; ++i) {
;       int q = tid + 256 * i;
;       int st = q & 127, c0 = (q >> 7) * 8;
;       raw[i] = *reinterpret_cast<const uint4*>(P + (t0 + st) * NP + 512 + g * 128 + c0);
;     }
; #pragma unroll
;     for (int i = 0; i < 8; ++i) {
;       int q = tid + 256 * i;
;       int st = q & 127, c0 = (q >> 7) * 8;
;       unsigned w[4] = {raw[i].x, raw[i].y, raw[i].z, raw[i].w};
;       float mu = mu_s[st], rs = rs_s[st];
;       const float4* gp = reinterpret_cast<const float4*>(p.gm_gain + (size_t)layer * 512 + g * 128 + c0);
;       float4 g0 = gp[0], g1 = gp[1];
;       float gg[8] = {g0.x, g0.y, g0.z, g0.w, g1.x, g1.y, g1.z, g1.w};
; #pragma unroll
;       for (int e = 0; e < 8; ++e) {
;         float v = (e & 1) ? bfhi(w[e >> 1]) : bflo(w[e >> 1]);
;         float val = (v - mu) * rs * gg[e];
;         *reinterpret_cast<u16*>(smem + 32768 + (st >> 5) * 8192 + (c0 + e) * 64 + (st & 31) * 2) = f2bf(val);
;       }
;     }
;   }
.LBB0_158:
	s_or_b64 exec, exec, s[6:7]
	v_and_b32_e32 v6, 0x7f, v60
	s_ashr_i32 s6, s8, 31
	s_bfe_u32 s10, s79, 0x20003
	s_waitcnt lgkmcnt(0)
	v_or_b32_e32 v0, s26, v6
	s_add_u32 s11, s28, s8
	v_mul_lo_u32 v128, v0, s64
	v_ashrrev_i32_e32 v34, 4, v60
	s_addc_u32 s48, s29, s6
	v_lshl_add_u64 v[0:1], v[128:129], 1, s[4:5]
	s_lshl_b32 s6, s10, 8
	s_mov_b32 s7, s27
	v_and_b32_e32 v2, -8, v34
	v_lshl_add_u64 v[0:1], v[0:1], 0, s[6:7]
	v_ashrrev_i32_e32 v3, 31, v2
	v_lshl_add_u64 v[4:5], v[2:3], 1, v[0:1]
	s_barrier
	global_load_dwordx4 v[28:31], v[4:5], off offset:1024
	s_lshl_b32 s8, s10, 7
	s_lshl_b32 s6, s10, 9
	s_add_u32 s6, s14, s6
	s_addc_u32 s7, s15, 0
	v_lshl_add_u64 v[4:5], v[2:3], 2, s[6:7]
	global_load_dwordx4 v[62:65], v[4:5], off
	global_load_dwordx4 v[66:69], v[4:5], off offset:16
	v_add_u32_e32 v3, 0x100, v60
	v_ashrrev_i32_e32 v48, 4, v3
	v_add_u32_e32 v4, 0x200, v60
	v_lshlrev_b32_e32 v12, 1, v60
	v_and_b32_e32 v82, -8, v48
	v_add_u32_e32 v5, 0x300, v60
	v_lshlrev_b32_e32 v11, 8, v60
	v_ashrrev_i32_e32 v46, 4, v4
	v_and_b32_e32 v4, 62, v12
	v_ashrrev_i32_e32 v83, 31, v82
	v_ashrrev_i32_e32 v44, 4, v5
	v_and_or_b32 v37, v11, s65, v4
	v_lshl_add_u64 v[4:5], v[82:83], 1, v[0:1]
	global_load_dwordx4 v[24:27], v[4:5], off offset:1024
	v_lshl_add_u64 v[4:5], v[82:83], 2, s[6:7]
	global_load_dwordx4 v[70:73], v[4:5], off offset:16
	global_load_dwordx4 v[74:77], v[4:5], off
	v_lshlrev_b32_e32 v3, 2, v6
	v_or_b32_e32 v6, 0x10000, v3
	v_or_b32_e32 v3, 0x10200, v3
	ds_read_b32 v39, v6
	ds_read_b32 v41, v3
	v_add_u32_e32 v7, 0x400, v60
	v_add_u32_e32 v8, 0x500, v60
	v_add_u32_e32 v9, 0x600, v60
	v_add_u32_e32 v10, 0x700, v60
	v_ashrrev_i32_e32 v42, 4, v7
	v_ashrrev_i32_e32 v40, 4, v8
	v_ashrrev_i32_e32 v38, 4, v9
	v_ashrrev_i32_e32 v36, 4, v10
	v_and_b32_e32 v58, -8, v46
	v_and_b32_e32 v56, -8, v44
	v_and_b32_e32 v54, -8, v42
	v_and_b32_e32 v52, -8, v40
	v_and_b32_e32 v50, -8, v38
	v_and_b32_e32 v32, -8, v36
	v_ashrrev_i32_e32 v59, 31, v58
	v_ashrrev_i32_e32 v57, 31, v56
	v_ashrrev_i32_e32 v55, 31, v54
	v_ashrrev_i32_e32 v53, 31, v52
	v_ashrrev_i32_e32 v51, 31, v50
	v_ashrrev_i32_e32 v33, 31, v32
	v_lshl_add_u32 v43, v2, 6, v37
	v_lshl_add_u64 v[2:3], v[58:59], 1, v[0:1]
	v_lshl_add_u64 v[4:5], v[56:57], 1, v[0:1]
	v_lshl_add_u64 v[6:7], v[54:55], 1, v[0:1]
	v_lshl_add_u64 v[8:9], v[52:53], 1, v[0:1]
	v_lshl_add_u64 v[78:79], v[50:51], 1, v[0:1]
	v_lshl_add_u64 v[0:1], v[32:33], 1, v[0:1]
	global_load_dwordx4 v[20:23], v[2:3], off offset:1024
	global_load_dwordx4 v[16:19], v[4:5], off offset:1024
	global_load_dwordx4 v[12:15], v[6:7], off offset:1024
	s_nop 0
	global_load_dwordx4 v[8:11], v[8:9], off offset:1024
	s_nop 0
	global_load_dwordx4 v[4:7], v[78:79], off offset:1024
	s_nop 0
	global_load_dwordx4 v[0:3], v[0:1], off offset:1024
	v_and_b32_e32 v35, 15, v60
	v_lshlrev_b32_e32 v128, 4, v35
	s_waitcnt vmcnt(11)
	v_lshlrev_b32_e32 v45, 16, v28
	s_waitcnt lgkmcnt(1)
	v_sub_f32_e32 v45, v45, v39
	v_and_b32_e32 v28, 0xffff0000, v28
	s_waitcnt lgkmcnt(0)
	v_mul_f32_e32 v45, v41, v45
	v_sub_f32_e32 v28, v28, v39
	s_waitcnt vmcnt(10)
	v_mul_f32_e32 v45, v45, v62
	v_mul_f32_e32 v28, v41, v28
	v_mul_f32_e32 v28, v28, v63
	v_cvt_pk_bf16_f32 v45, 0, v45
	ds_write_b16_d16_hi v43, v45 offset:32768
	v_cvt_pk_bf16_f32 v28, 0, v28
	ds_write_b16_d16_hi v43, v28 offset:32832
	v_lshlrev_b32_e32 v28, 16, v29
	v_sub_f32_e32 v28, v28, v39
	v_mul_f32_e32 v28, v41, v28
	v_mul_f32_e32 v28, v28, v64
	v_cvt_pk_bf16_f32 v28, 0, v28
	ds_write_b16_d16_hi v43, v28 offset:32896
	v_and_b32_e32 v28, 0xffff0000, v29
	v_sub_f32_e32 v28, v28, v39
	v_mul_f32_e32 v28, v41, v28
	v_mul_f32_e32 v28, v28, v65
	v_cvt_pk_bf16_f32 v28, 0, v28
	ds_write_b16_d16_hi v43, v28 offset:32960
	v_lshlrev_b32_e32 v28, 16, v30
	v_sub_f32_e32 v28, v28, v39
	v_mul_f32_e32 v28, v41, v28
	s_waitcnt vmcnt(9)
	v_mul_f32_e32 v28, v28, v66
	v_cvt_pk_bf16_f32 v28, 0, v28
	ds_write_b16_d16_hi v43, v28 offset:33024
	v_and_b32_e32 v28, 0xffff0000, v30
	v_sub_f32_e32 v28, v28, v39
	v_mul_f32_e32 v28, v41, v28
	v_mul_f32_e32 v28, v28, v67
	v_cvt_pk_bf16_f32 v28, 0, v28
	ds_write_b16_d16_hi v43, v28 offset:33088
	v_lshlrev_b32_e32 v28, 16, v31
	v_sub_f32_e32 v30, v28, v39
	v_lshl_add_u64 v[28:29], v[58:59], 2, s[6:7]
	global_load_dwordx4 v[62:65], v[28:29], off offset:16
	global_load_dwordx4 v[78:81], v[28:29], off
	v_mul_f32_e32 v28, v41, v30
	v_mul_f32_e32 v28, v28, v68
	v_cvt_pk_bf16_f32 v28, 0, v28
	ds_write_b16_d16_hi v43, v28 offset:33152
	v_and_b32_e32 v28, 0xffff0000, v31
	v_sub_f32_e32 v28, v28, v39
	v_mul_f32_e32 v28, v41, v28
	v_mul_f32_e32 v28, v28, v69
	v_cvt_pk_bf16_f32 v28, 0, v28
	v_lshl_or_b32 v29, v34, 6, v159
	v_add_u32_e32 v29, v37, v29
	ds_write_b16_d16_hi v29, v28 offset:32768
	s_waitcnt vmcnt(10)
	v_lshlrev_b32_e32 v28, 16, v24
	v_sub_f32_e32 v28, v28, v39
	v_mul_f32_e32 v28, v41, v28
	v_and_b32_e32 v24, 0xffff0000, v24
	s_waitcnt vmcnt(8)
; __device__ __forceinline__ float bflo(unsigned w) { return __uint_as_float(w << 16); }
; __device__ __forceinline__ float bfhi(unsigned w) { return __uint_as_float(w & 0xffff0000u); }
; __device__ void gmlp_item(const Params& p, int layer, int b, int n, int g, char* smem) {
;     ...
;   {
;     uint4 raw[8];
; #pragma unroll
;     for (int i = 0; i < 8; ++i) {
;       int q = tid + 256 * i;
;       int st = q & 127, c0 = (q >> 7) * 8;
;       raw[i] = *reinterpret_cast<const uint4*>(P + (t0 + st) * NP + 512 + g * 128 + c0);
;     }
; #pragma unroll
;     for (int i = 0; i < 8; ++i) {
;       int q = tid + 256 * i;
;       int st = q & 127, c0 = (q >> 7) * 8;
;       unsigned w[4] = {raw[i].x, raw[i].y, raw[i].z, raw[i].w};
;       float mu = mu_s[st], rs = rs_s[st];
;       const float4* gp = reinterpret_cast<const float4*>(p.gm_gain + (size_t)layer * 512 + g * 128 + c0);
;       float4 g0 = gp[0], g1 = gp[1];
;       float gg[8] = {g0.x, g0.y, g0.z, g0.w, g1.x, g1.y, g1.z, g1.w};
; #pragma unroll
;       for (int e = 0; e < 8; ++e) {
;         float v = (e & 1) ? bfhi(w[e >> 1]) : bflo(w[e >> 1]);
;         float val = (v - mu) * rs * gg[e];
;         *reinterpret_cast<u16*>(smem + 32768 + (st >> 5) * 8192 + (c0 + e) * 64 + (st & 31) * 2) = f2bf(val);
;       }
;     }
;   }
	v_mul_f32_e32 v28, v28, v74
	v_sub_f32_e32 v24, v24, v39
	v_mul_f32_e32 v24, v41, v24
	v_cvt_pk_bf16_f32 v28, 0, v28
	v_lshl_add_u32 v43, v82, 6, v37
	v_mul_f32_e32 v24, v24, v75
	ds_write_b16_d16_hi v43, v28 offset:32768
	v_cvt_pk_bf16_f32 v24, 0, v24
	ds_write_b16_d16_hi v43, v24 offset:32832
	v_lshlrev_b32_e32 v24, 16, v25
	v_sub_f32_e32 v24, v24, v39
	v_mul_f32_e32 v24, v41, v24
	v_mul_f32_e32 v24, v24, v76
	v_cvt_pk_bf16_f32 v24, 0, v24
	ds_write_b16_d16_hi v43, v24 offset:32896
	v_and_b32_e32 v24, 0xffff0000, v25
	v_sub_f32_e32 v24, v24, v39
	v_mul_f32_e32 v24, v41, v24
	v_mul_f32_e32 v24, v24, v77
	v_cvt_pk_bf16_f32 v24, 0, v24
	ds_write_b16_d16_hi v43, v24 offset:32960
	v_lshlrev_b32_e32 v24, 16, v26
	v_sub_f32_e32 v24, v24, v39
	v_mul_f32_e32 v24, v41, v24
	v_mul_f32_e32 v24, v24, v70
	v_cvt_pk_bf16_f32 v24, 0, v24
	ds_write_b16_d16_hi v43, v24 offset:33024
	v_and_b32_e32 v24, 0xffff0000, v26
	v_sub_f32_e32 v24, v24, v39
	v_mul_f32_e32 v24, v41, v24
	v_mul_f32_e32 v24, v24, v71
	v_cvt_pk_bf16_f32 v24, 0, v24
	ds_write_b16_d16_hi v43, v24 offset:33088
	v_lshlrev_b32_e32 v24, 16, v27
	v_sub_f32_e32 v26, v24, v39
	v_lshl_add_u64 v[24:25], v[56:57], 2, s[6:7]
	global_load_dwordx4 v[28:31], v[24:25], off offset:16
	global_load_dwordx4 v[66:69], v[24:25], off
	v_mul_f32_e32 v24, v41, v26
	v_mul_f32_e32 v24, v24, v72
	v_cvt_pk_bf16_f32 v24, 0, v24
	ds_write_b16_d16_hi v43, v24 offset:33152
	v_and_b32_e32 v24, 0xffff0000, v27
	v_sub_f32_e32 v24, v24, v39
	v_mul_f32_e32 v24, v41, v24
	v_mul_f32_e32 v24, v24, v73
	v_cvt_pk_bf16_f32 v24, 0, v24
	v_lshl_or_b32 v25, v48, 6, v159
	v_add_u32_e32 v25, v37, v25
	ds_write_b16_d16_hi v25, v24 offset:32768
	s_waitcnt vmcnt(9)
	v_lshlrev_b32_e32 v24, 16, v20
	v_sub_f32_e32 v24, v24, v39
	v_mul_f32_e32 v24, v41, v24
	v_and_b32_e32 v20, 0xffff0000, v20
	s_waitcnt vmcnt(2)
	v_mul_f32_e32 v24, v24, v78
	v_sub_f32_e32 v20, v20, v39
	v_mul_f32_e32 v20, v41, v20
	v_cvt_pk_bf16_f32 v24, 0, v24
	v_lshl_add_u32 v43, v58, 6, v37
	v_mul_f32_e32 v20, v20, v79
	ds_write_b16_d16_hi v43, v24 offset:32768
	v_cvt_pk_bf16_f32 v20, 0, v20
	ds_write_b16_d16_hi v43, v20 offset:32832
	v_lshlrev_b32_e32 v20, 16, v21
	v_sub_f32_e32 v20, v20, v39
	v_mul_f32_e32 v20, v41, v20
	v_mul_f32_e32 v20, v20, v80
	v_cvt_pk_bf16_f32 v20, 0, v20
	ds_write_b16_d16_hi v43, v20 offset:32896
	v_and_b32_e32 v20, 0xffff0000, v21
	v_sub_f32_e32 v20, v20, v39
	v_mul_f32_e32 v20, v41, v20
	v_mul_f32_e32 v20, v20, v81
	v_cvt_pk_bf16_f32 v20, 0, v20
	ds_write_b16_d16_hi v43, v20 offset:32960
	v_lshlrev_b32_e32 v20, 16, v22
	v_sub_f32_e32 v20, v20, v39
	v_mul_f32_e32 v20, v41, v20
	v_mul_f32_e32 v20, v20, v62
	v_cvt_pk_bf16_f32 v20, 0, v20
	ds_write_b16_d16_hi v43, v20 offset:33024
	v_and_b32_e32 v20, 0xffff0000, v22
	v_sub_f32_e32 v20, v20, v39
	v_mul_f32_e32 v20, v41, v20
	v_mul_f32_e32 v20, v20, v63
	v_cvt_pk_bf16_f32 v20, 0, v20
	ds_write_b16_d16_hi v43, v20 offset:33088
	v_lshlrev_b32_e32 v20, 16, v23
	v_sub_f32_e32 v22, v20, v39
	v_lshl_add_u64 v[20:21], v[54:55], 2, s[6:7]
	global_load_dwordx4 v[24:27], v[20:21], off offset:16
	global_load_dwordx4 v[70:73], v[20:21], off
	v_mul_f32_e32 v20, v41, v22
	v_mul_f32_e32 v20, v20, v64
	v_cvt_pk_bf16_f32 v20, 0, v20
	ds_write_b16_d16_hi v43, v20 offset:33152
	v_and_b32_e32 v20, 0xffff0000, v23
	v_sub_f32_e32 v20, v20, v39
	v_mul_f32_e32 v20, v41, v20
	v_mul_f32_e32 v20, v20, v65
	v_cvt_pk_bf16_f32 v20, 0, v20
	v_lshl_or_b32 v21, v46, 6, v159
	v_add_u32_e32 v21, v37, v21
	ds_write_b16_d16_hi v21, v20 offset:32768
	v_lshlrev_b32_e32 v20, 16, v16
	v_sub_f32_e32 v20, v20, v39
	v_mul_f32_e32 v20, v41, v20
	v_and_b32_e32 v16, 0xffff0000, v16
	s_waitcnt vmcnt(2)
	v_mul_f32_e32 v20, v20, v66
	v_sub_f32_e32 v16, v16, v39
	v_mul_f32_e32 v16, v41, v16
	v_cvt_pk_bf16_f32 v20, 0, v20
	v_lshl_add_u32 v43, v56, 6, v37
	v_mul_f32_e32 v16, v16, v67
	ds_write_b16_d16_hi v43, v20 offset:32768
	v_cvt_pk_bf16_f32 v16, 0, v16
	ds_write_b16_d16_hi v43, v16 offset:32832
	v_lshlrev_b32_e32 v16, 16, v17
	v_sub_f32_e32 v16, v16, v39
	v_mul_f32_e32 v16, v41, v16
	v_mul_f32_e32 v16, v16, v68
	v_cvt_pk_bf16_f32 v16, 0, v16
	ds_write_b16_d16_hi v43, v16 offset:32896
	v_and_b32_e32 v16, 0xffff0000, v17
	v_sub_f32_e32 v16, v16, v39
	v_mul_f32_e32 v16, v41, v16
	v_mul_f32_e32 v16, v16, v69
	v_cvt_pk_bf16_f32 v16, 0, v16
	ds_write_b16_d16_hi v43, v16 offset:32960
	v_lshlrev_b32_e32 v16, 16, v18
	v_sub_f32_e32 v16, v16, v39
	v_mul_f32_e32 v16, v41, v16
	v_mul_f32_e32 v16, v16, v28
	v_cvt_pk_bf16_f32 v16, 0, v16
	ds_write_b16_d16_hi v43, v16 offset:33024
	v_and_b32_e32 v16, 0xffff0000, v18
	v_sub_f32_e32 v16, v16, v39
	v_mul_f32_e32 v16, v41, v16
	v_mul_f32_e32 v16, v16, v29
	v_cvt_pk_bf16_f32 v16, 0, v16
	ds_write_b16_d16_hi v43, v16 offset:33088
	v_lshlrev_b32_e32 v16, 16, v19
	v_sub_f32_e32 v18, v16, v39
	v_lshl_add_u64 v[16:17], v[52:53], 2, s[6:7]
	global_load_dwordx4 v[20:23], v[16:17], off offset:16
	global_load_dwordx4 v[56:59], v[16:17], off
	v_mul_f32_e32 v16, v41, v18
	v_mul_f32_e32 v16, v16, v30
	v_cvt_pk_bf16_f32 v16, 0, v16
	ds_write_b16_d16_hi v43, v16 offset:33152
	v_and_b32_e32 v16, 0xffff0000, v19
	v_sub_f32_e32 v16, v16, v39
	v_mul_f32_e32 v16, v41, v16
	v_mul_f32_e32 v16, v16, v31
	v_cvt_pk_bf16_f32 v16, 0, v16
	v_lshl_or_b32 v17, v44, 6, v159
	v_add_u32_e32 v17, v37, v17
	ds_write_b16_d16_hi v17, v16 offset:32768
	v_lshlrev_b32_e32 v16, 16, v12
	v_sub_f32_e32 v16, v16, v39
	v_mul_f32_e32 v16, v41, v16
	v_and_b32_e32 v12, 0xffff0000, v12
	s_waitcnt vmcnt(2)
; __device__ __forceinline__ float bflo(unsigned w) { return __uint_as_float(w << 16); }
; __device__ __forceinline__ float bfhi(unsigned w) { return __uint_as_float(w & 0xffff0000u); }
; __device__ void gmlp_item(const Params& p, int layer, int b, int n, int g, char* smem) {
;     ...
;   {
;     uint4 raw[8];
; #pragma unroll
;     for (int i = 0; i < 8; ++i) {
;       int q = tid + 256 * i;
;       int st = q & 127, c0 = (q >> 7) * 8;
;       raw[i] = *reinterpret_cast<const uint4*>(P + (t0 + st) * NP + 512 + g * 128 + c0);
;     }
; #pragma unroll
;     for (int i = 0; i < 8; ++i) {
;       int q = tid + 256 * i;
;       int st = q & 127, c0 = (q >> 7) * 8;
;       unsigned w[4] = {raw[i].x, raw[i].y, raw[i].z, raw[i].w};
;       float mu = mu_s[st], rs = rs_s[st];
;       const float4* gp = reinterpret_cast<const float4*>(p.gm_gain + (size_t)layer * 512 + g * 128 + c0);
;       float4 g0 = gp[0], g1 = gp[1];
;       float gg[8] = {g0.x, g0.y, g0.z, g0.w, g1.x, g1.y, g1.z, g1.w};
; #pragma unroll
;       for (int e = 0; e < 8; ++e) {
;         float v = (e & 1) ? bfhi(w[e >> 1]) : bflo(w[e >> 1]);
;         float val = (v - mu) * rs * gg[e];
;         *reinterpret_cast<u16*>(smem + 32768 + (st >> 5) * 8192 + (c0 + e) * 64 + (st & 31) * 2) = f2bf(val);
;       }
;     }
;   }
	v_mul_f32_e32 v16, v16, v70
	v_sub_f32_e32 v12, v12, v39
	v_mul_f32_e32 v12, v41, v12
	v_cvt_pk_bf16_f32 v16, 0, v16
	v_lshl_add_u32 v43, v54, 6, v37
	v_mul_f32_e32 v12, v12, v71
	ds_write_b16_d16_hi v43, v16 offset:32768
	v_cvt_pk_bf16_f32 v12, 0, v12
	ds_write_b16_d16_hi v43, v12 offset:32832
	v_lshlrev_b32_e32 v12, 16, v13
	v_sub_f32_e32 v12, v12, v39
	v_mul_f32_e32 v12, v41, v12
	v_mul_f32_e32 v12, v12, v72
	v_cvt_pk_bf16_f32 v12, 0, v12
	ds_write_b16_d16_hi v43, v12 offset:32896
	v_and_b32_e32 v12, 0xffff0000, v13
	v_sub_f32_e32 v12, v12, v39
	v_mul_f32_e32 v12, v41, v12
	v_mul_f32_e32 v12, v12, v73
	v_cvt_pk_bf16_f32 v12, 0, v12
	ds_write_b16_d16_hi v43, v12 offset:32960
	v_lshlrev_b32_e32 v12, 16, v14
	v_sub_f32_e32 v12, v12, v39
	v_mul_f32_e32 v12, v41, v12
	v_mul_f32_e32 v12, v12, v24
	v_cvt_pk_bf16_f32 v12, 0, v12
	ds_write_b16_d16_hi v43, v12 offset:33024
	v_and_b32_e32 v12, 0xffff0000, v14
	v_sub_f32_e32 v12, v12, v39
	v_mul_f32_e32 v12, v41, v12
	v_mul_f32_e32 v12, v12, v25
	v_cvt_pk_bf16_f32 v12, 0, v12
	ds_write_b16_d16_hi v43, v12 offset:33088
	v_lshlrev_b32_e32 v12, 16, v15
	v_sub_f32_e32 v14, v12, v39
	v_lshl_add_u64 v[12:13], v[50:51], 2, s[6:7]
	global_load_dwordx4 v[16:19], v[12:13], off offset:16
	global_load_dwordx4 v[28:31], v[12:13], off
	v_mul_f32_e32 v12, v41, v14
	v_mul_f32_e32 v12, v12, v26
	v_cvt_pk_bf16_f32 v12, 0, v12
	ds_write_b16_d16_hi v43, v12 offset:33152
	v_and_b32_e32 v12, 0xffff0000, v15
	v_sub_f32_e32 v12, v12, v39
	v_mul_f32_e32 v12, v41, v12
	v_mul_f32_e32 v12, v12, v27
	v_cvt_pk_bf16_f32 v12, 0, v12
	v_lshl_or_b32 v13, v42, 6, v159
	v_add_u32_e32 v13, v37, v13
	ds_write_b16_d16_hi v13, v12 offset:32768
	v_lshlrev_b32_e32 v12, 16, v8
	v_sub_f32_e32 v12, v12, v39
	v_mul_f32_e32 v12, v41, v12
	v_and_b32_e32 v8, 0xffff0000, v8
	s_waitcnt vmcnt(2)
	v_mul_f32_e32 v12, v12, v56
	v_sub_f32_e32 v8, v8, v39
	v_mul_f32_e32 v8, v41, v8
	v_cvt_pk_bf16_f32 v12, 0, v12
	v_lshl_add_u32 v43, v52, 6, v37
	v_mul_f32_e32 v8, v8, v57
	ds_write_b16_d16_hi v43, v12 offset:32768
	v_cvt_pk_bf16_f32 v8, 0, v8
	ds_write_b16_d16_hi v43, v8 offset:32832
	v_lshlrev_b32_e32 v8, 16, v9
	v_sub_f32_e32 v8, v8, v39
	v_mul_f32_e32 v8, v41, v8
	v_mul_f32_e32 v8, v8, v58
	v_cvt_pk_bf16_f32 v8, 0, v8
	ds_write_b16_d16_hi v43, v8 offset:32896
	v_and_b32_e32 v8, 0xffff0000, v9
	v_sub_f32_e32 v8, v8, v39
	v_mul_f32_e32 v8, v41, v8
	v_mul_f32_e32 v8, v8, v59
	v_cvt_pk_bf16_f32 v8, 0, v8
	ds_write_b16_d16_hi v43, v8 offset:32960
	v_lshlrev_b32_e32 v8, 16, v10
	v_sub_f32_e32 v8, v8, v39
	v_mul_f32_e32 v8, v41, v8
	v_mul_f32_e32 v8, v8, v20
	v_cvt_pk_bf16_f32 v8, 0, v8
	ds_write_b16_d16_hi v43, v8 offset:33024
	v_and_b32_e32 v8, 0xffff0000, v10
	v_sub_f32_e32 v8, v8, v39
	v_mul_f32_e32 v8, v41, v8
	v_mul_f32_e32 v8, v8, v21
	v_cvt_pk_bf16_f32 v10, 0, v8
	v_lshl_add_u64 v[8:9], v[32:33], 2, s[6:7]
	global_load_dwordx4 v[12:15], v[8:9], off offset:16
	global_load_dwordx4 v[24:27], v[8:9], off
	v_lshlrev_b32_e32 v8, 16, v11
	v_sub_f32_e32 v8, v8, v39
	v_mul_f32_e32 v8, v41, v8
	v_mul_f32_e32 v8, v8, v22
	v_cvt_pk_bf16_f32 v8, 0, v8
	ds_write_b16_d16_hi v43, v8 offset:33152
	v_and_b32_e32 v8, 0xffff0000, v11
	v_sub_f32_e32 v8, v8, v39
	v_mul_f32_e32 v8, v41, v8
	v_mul_f32_e32 v8, v8, v23
	v_cvt_pk_bf16_f32 v8, 0, v8
	v_lshl_or_b32 v9, v40, 6, v159
	v_add_u32_e32 v9, v37, v9
	ds_write_b16_d16_hi v43, v10 offset:33088
	ds_write_b16_d16_hi v9, v8 offset:32768
	v_lshlrev_b32_e32 v8, 16, v4
	v_sub_f32_e32 v8, v8, v39
	v_mul_f32_e32 v8, v41, v8
	v_and_b32_e32 v4, 0xffff0000, v4
	s_waitcnt vmcnt(2)
	v_mul_f32_e32 v8, v8, v28
	v_sub_f32_e32 v4, v4, v39
	v_mul_f32_e32 v4, v41, v4
	v_cvt_pk_bf16_f32 v8, 0, v8
	v_lshl_add_u32 v9, v50, 6, v37
	v_mul_f32_e32 v4, v4, v29
	ds_write_b16_d16_hi v9, v8 offset:32768
	v_cvt_pk_bf16_f32 v4, 0, v4
	ds_write_b16_d16_hi v9, v4 offset:32832
	v_lshlrev_b32_e32 v4, 16, v5
	v_sub_f32_e32 v4, v4, v39
	v_mul_f32_e32 v4, v41, v4
	v_mul_f32_e32 v4, v4, v30
	v_cvt_pk_bf16_f32 v4, 0, v4
	ds_write_b16_d16_hi v9, v4 offset:32896
	v_and_b32_e32 v4, 0xffff0000, v5
	v_sub_f32_e32 v4, v4, v39
	v_mul_f32_e32 v4, v41, v4
	v_mul_f32_e32 v4, v4, v31
	v_cvt_pk_bf16_f32 v4, 0, v4
	ds_write_b16_d16_hi v9, v4 offset:32960
	v_lshlrev_b32_e32 v4, 16, v6
	v_sub_f32_e32 v4, v4, v39
	v_mul_f32_e32 v4, v41, v4
	v_mul_f32_e32 v4, v4, v16
	v_cvt_pk_bf16_f32 v4, 0, v4
	ds_write_b16_d16_hi v9, v4 offset:33024
	v_and_b32_e32 v4, 0xffff0000, v6
	v_sub_f32_e32 v4, v4, v39
	v_mul_f32_e32 v4, v41, v4
	v_mul_f32_e32 v4, v4, v17
	v_cvt_pk_bf16_f32 v4, 0, v4
	ds_write_b16_d16_hi v9, v4 offset:33088
	v_lshlrev_b32_e32 v4, 16, v7
	v_sub_f32_e32 v4, v4, v39
	v_mul_f32_e32 v4, v41, v4
	v_mul_f32_e32 v4, v4, v18
	v_cvt_pk_bf16_f32 v4, 0, v4
	ds_write_b16_d16_hi v9, v4 offset:33152
	v_and_b32_e32 v4, 0xffff0000, v7
	v_sub_f32_e32 v4, v4, v39
	v_mul_f32_e32 v4, v41, v4
	v_mul_f32_e32 v4, v4, v19
	v_cvt_pk_bf16_f32 v4, 0, v4
	v_lshl_or_b32 v5, v38, 6, v159
	v_add_u32_e32 v5, v37, v5
	ds_write_b16_d16_hi v5, v4 offset:32768
	v_lshlrev_b32_e32 v4, 16, v0
	v_sub_f32_e32 v4, v4, v39
	v_mul_f32_e32 v4, v41, v4
	v_and_b32_e32 v0, 0xffff0000, v0
	s_waitcnt vmcnt(0)
; __device__ __forceinline__ float bflo(unsigned w) { return __uint_as_float(w << 16); }
; __device__ __forceinline__ float bfhi(unsigned w) { return __uint_as_float(w & 0xffff0000u); }
; __device__ void gmlp_item(const Params& p, int layer, int b, int n, int g, char* smem) {
;     ...
; #pragma unroll
;     for (int i = 0; i < 8; ++i) {
;       int q = tid + 256 * i;
;       int st = q & 127, c0 = (q >> 7) * 8;
;       unsigned w[4] = {raw[i].x, raw[i].y, raw[i].z, raw[i].w};
;       float mu = mu_s[st], rs = rs_s[st];
;       const float4* gp = reinterpret_cast<const float4*>(p.gm_gain + (size_t)layer * 512 + g * 128 + c0);
;       float4 g0 = gp[0], g1 = gp[1];
;       float gg[8] = {g0.x, g0.y, g0.z, g0.w, g1.x, g1.y, g1.z, g1.w};
; #pragma unroll
;       for (int e = 0; e < 8; ++e) {
;         float v = (e & 1) ? bfhi(w[e >> 1]) : bflo(w[e >> 1]);
;         float val = (v - mu) * rs * gg[e];
;         *reinterpret_cast<u16*>(smem + 32768 + (st >> 5) * 8192 + (c0 + e) * 64 + (st & 31) * 2) = f2bf(val);
;       }
;     }
;   }
; #pragma unroll 2
;   for (int i = 0; i < 8; ++i) {
;     int q = tid + 256 * i;
;     int t = q >> 4, cch = q & 15;
;     uint4 v = *reinterpret_cast<const uint4*>(Ws + (size_t)g * 16384 + t * 128 + cch * 8);
;     *reinterpret_cast<uint4*>(smem + (cch >> 2) * 8192 + t * 64 + (cch & 3) * 16) = v;
;   }
	v_mul_f32_e32 v4, v4, v24
	v_sub_f32_e32 v0, v0, v39
	v_mul_f32_e32 v0, v41, v0
	v_cvt_pk_bf16_f32 v4, 0, v4
	v_lshl_add_u32 v5, v32, 6, v37
	v_mul_f32_e32 v0, v0, v25
	ds_write_b16_d16_hi v5, v4 offset:32768
	v_cvt_pk_bf16_f32 v0, 0, v0
	ds_write_b16_d16_hi v5, v0 offset:32832
	v_lshlrev_b32_e32 v0, 16, v1
	v_sub_f32_e32 v0, v0, v39
	v_mul_f32_e32 v0, v41, v0
	v_mul_f32_e32 v0, v0, v26
	v_cvt_pk_bf16_f32 v0, 0, v0
	ds_write_b16_d16_hi v5, v0 offset:32896
	v_and_b32_e32 v0, 0xffff0000, v1
	v_sub_f32_e32 v0, v0, v39
	v_mul_f32_e32 v0, v41, v0
	v_mul_f32_e32 v0, v0, v27
	v_cvt_pk_bf16_f32 v0, 0, v0
	ds_write_b16_d16_hi v5, v0 offset:32960
	v_lshlrev_b32_e32 v0, 16, v2
	v_sub_f32_e32 v0, v0, v39
	v_mul_f32_e32 v0, v41, v0
	v_mul_f32_e32 v0, v0, v12
	v_cvt_pk_bf16_f32 v0, 0, v0
	ds_write_b16_d16_hi v5, v0 offset:33024
	v_and_b32_e32 v0, 0xffff0000, v2
	v_sub_f32_e32 v0, v0, v39
	v_mul_f32_e32 v0, v41, v0
	v_mul_f32_e32 v0, v0, v13
	v_cvt_pk_bf16_f32 v0, 0, v0
	ds_write_b16_d16_hi v5, v0 offset:33088
	v_lshlrev_b32_e32 v0, 16, v3
	v_sub_f32_e32 v0, v0, v39
	v_mul_f32_e32 v0, v41, v0
	v_mul_f32_e32 v0, v0, v14
	v_cvt_pk_bf16_f32 v0, 0, v0
	ds_write_b16_d16_hi v5, v0 offset:33152
	v_and_b32_e32 v0, 0xffff0000, v3
	v_sub_f32_e32 v0, v0, v39
	v_mul_f32_e32 v0, v41, v0
	v_mul_f32_e32 v0, v0, v15
	s_lshl_b32 s6, s10, 15
	v_cvt_pk_bf16_f32 v0, 0, v0
	v_lshl_or_b32 v1, v36, 6, v159
	s_add_u32 s6, s11, s6
	v_add_u32_e32 v1, v37, v1
	s_addc_u32 s7, s48, 0
	v_lshlrev_b32_e32 v3, 4, v60
	ds_write_b16_d16_hi v1, v0 offset:32768
	v_lshl_add_u64 v[0:1], s[6:7], 0, v[128:129]
	v_lshlrev_b32_e32 v2, 11, v60
	v_and_b32_e32 v3, 48, v3
	v_lshl_add_u64 v[0:1], v[0:1], 0, s[38:39]
	v_and_or_b32 v2, v2, s65, v3
	s_mov_b32 s6, 0
	v_mov_b32_e32 v120, v60
	v_ashrrev_i32_e32 v104, 4, v120
	v_add_u32_e32 v120, 0x100, v120
	v_ashrrev_i32_e32 v105, 4, v120
	v_lshlrev_b32_e32 v112, 7, v104
	v_lshlrev_b32_e32 v114, 7, v105
	v_ashrrev_i32_e32 v113, 31, v112
	v_ashrrev_i32_e32 v115, 31, v114
	v_lshl_add_u64 v[112:113], v[112:113], 1, v[0:1]
	v_lshl_add_u64 v[114:115], v[114:115], 1, v[0:1]
	global_load_dwordx4 v[72:75], v[112:113], off
	global_load_dwordx4 v[76:79], v[114:115], off
	v_lshl_add_u32 v104, v104, 6, v2
	v_lshl_add_u32 v105, v105, 6, v2
	v_add_u32_e32 v120, 0x200, v60
	v_ashrrev_i32_e32 v106, 4, v120
	v_add_u32_e32 v120, 0x100, v120
	v_ashrrev_i32_e32 v107, 4, v120
	v_lshlrev_b32_e32 v116, 7, v106
	v_lshlrev_b32_e32 v118, 7, v107
	v_ashrrev_i32_e32 v117, 31, v116
	v_ashrrev_i32_e32 v119, 31, v118
	v_lshl_add_u64 v[116:117], v[116:117], 1, v[0:1]
	v_lshl_add_u64 v[118:119], v[118:119], 1, v[0:1]
	global_load_dwordx4 v[80:83], v[116:117], off
	global_load_dwordx4 v[84:87], v[118:119], off
	v_lshl_add_u32 v106, v106, 6, v2
	v_lshl_add_u32 v107, v107, 6, v2
	v_add_u32_e32 v120, 0x400, v60
	v_ashrrev_i32_e32 v108, 4, v120
	v_add_u32_e32 v120, 0x100, v120
	v_ashrrev_i32_e32 v109, 4, v120
	v_lshlrev_b32_e32 v112, 7, v108
	v_lshlrev_b32_e32 v114, 7, v109
	v_ashrrev_i32_e32 v113, 31, v112
	v_ashrrev_i32_e32 v115, 31, v114
	v_lshl_add_u64 v[112:113], v[112:113], 1, v[0:1]
	v_lshl_add_u64 v[114:115], v[114:115], 1, v[0:1]
	global_load_dwordx4 v[88:91], v[112:113], off
	global_load_dwordx4 v[92:95], v[114:115], off
	v_lshl_add_u32 v108, v108, 6, v2
	v_lshl_add_u32 v109, v109, 6, v2
	v_add_u32_e32 v120, 0x600, v60
	v_ashrrev_i32_e32 v110, 4, v120
	v_add_u32_e32 v120, 0x100, v120
	v_ashrrev_i32_e32 v111, 4, v120
	v_lshlrev_b32_e32 v116, 7, v110
	v_lshlrev_b32_e32 v118, 7, v111
	v_ashrrev_i32_e32 v117, 31, v116
	v_ashrrev_i32_e32 v119, 31, v118
	v_lshl_add_u64 v[116:117], v[116:117], 1, v[0:1]
	v_lshl_add_u64 v[118:119], v[118:119], 1, v[0:1]
	global_load_dwordx4 v[96:99], v[116:117], off
	global_load_dwordx4 v[100:103], v[118:119], off
	v_lshl_add_u32 v110, v110, 6, v2
	v_lshl_add_u32 v111, v111, 6, v2
	s_waitcnt vmcnt(7)
	ds_write_b128 v104, v[72:75]
	s_waitcnt vmcnt(6)
	ds_write_b128 v105, v[76:79]
	s_waitcnt vmcnt(5)
	ds_write_b128 v106, v[80:83]
	s_waitcnt vmcnt(4)
	ds_write_b128 v107, v[84:87]
	s_waitcnt vmcnt(3)
	ds_write_b128 v108, v[88:91]
	s_waitcnt vmcnt(2)
	ds_write_b128 v109, v[92:95]
	s_waitcnt vmcnt(1)
	ds_write_b128 v110, v[96:99]
	s_waitcnt vmcnt(0)
	ds_write_b128 v111, v[100:103]
	s_movk_i32 s6, 0x800
	v_bfe_u32 v32, v60, 4, 2
	v_ashrrev_i32_e32 v33, 7, v60
	v_lshlrev_b32_e32 v4, 4, v32
	v_lshlrev_b32_e32 v0, 12, v33
	v_lshlrev_b32_e32 v5, 6, v35
	v_or3_b32 v37, v4, v0, v5
	s_waitcnt lgkmcnt(0)
	s_barrier
; #define MFMA16(a, b, c) __builtin_amdgcn_mfma_f32_16x16x32_bf16(a, b, c, 0, 0, 0)
; __device__ void gmlp_item(const Params& p, int layer, int b, int n, int g, char* smem) {
;     ...
;   f32x4 acc[4][4];
; #pragma unroll
;   for (int m = 0; m < 4; ++m)
; #pragma unroll
;     for (int nn = 0; nn < 4; ++nn) acc[m][nn] = f32x4{0.f, 0.f, 0.f, 0.f};
; #pragma unroll
;   for (int ks = 0; ks < 4; ++ks) {
;     bf16x8 a[4], bb[4];
; #pragma unroll
;     for (int m = 0; m < 4; ++m)
;       a[m] = *reinterpret_cast<const bf16x8*>(smem + ks * 8192 + (wr * 64 + m * 16 + fr) * 64 + fq * 16);
; #pragma unroll
;     for (int nn = 0; nn < 4; ++nn)
;       bb[nn] = *reinterpret_cast<const bf16x8*>(smem + 32768 + ks * 8192 + (wc * 64 + nn * 16 + fr) * 64 + fq * 16);
; #pragma unroll
;     for (int m = 0; m < 4; ++m)
; #pragma unroll
;       for (int nn = 0; nn < 4; ++nn) acc[m][nn] = MFMA16(a[m], bb[nn], acc[m][nn]);
;   }
;   __syncthreads();
;   {
;     float* Tf = reinterpret_cast<float*>(smem);
; #pragma unroll
;     for (int m = 0; m < 4; ++m)
; #pragma unroll
;       for (int j = 0; j < 4; ++j) {
;         int t = wr * 64 + m * 16 + fq * 4 + j;
;         float bias = p.gm_b_s[(size_t)layer * 512 + g * 128 + t];
; #pragma unroll
;         for (int nn = 0; nn < 4; ++nn) Tf[t * 132 + wc * 64 + nn * 16 + fr] = acc[m][nn][j] + bias;
;       }
	ds_read_b128 v[0:3], v37
	v_bfe_u32 v39, v60, 6, 1
	v_lshlrev_b32_e32 v6, 12, v39
	v_or3_b32 v41, v4, v6, v5
	ds_read_b128 v[4:7], v41 offset:32768
	ds_read_b128 v[8:11], v37 offset:1024
	ds_read_b128 v[12:15], v41 offset:33792
	ds_read_b128 v[24:27], v41 offset:34816
	ds_read_b128 v[28:31], v41 offset:35840
	s_waitcnt lgkmcnt(4)
	v_mfma_f32_16x16x32_bf16 v[16:19], v[0:3], v[4:7], 0
	s_ashr_i32 s7, s9, 31
	s_add_u32 s6, s28, s9
	s_addc_u32 s7, s29, s7
	s_waitcnt lgkmcnt(2)
	v_mfma_f32_16x16x32_bf16 v[20:23], v[0:3], v[12:15], 0
	v_lshlrev_b32_e32 v33, 6, v33
	s_lshl_b32 s9, s8, 2
	v_lshl_or_b32 v32, v32, 2, v33
	s_waitcnt lgkmcnt(1)
	v_mfma_f32_16x16x32_bf16 v[50:53], v[0:3], v[24:27], 0
	s_add_u32 s10, s12, s9
	s_addc_u32 s11, s13, 0
	v_ashrrev_i32_e32 v33, 31, v32
	s_waitcnt lgkmcnt(0)
	v_mfma_f32_16x16x32_bf16 v[54:57], v[0:3], v[28:31], 0
	ds_read_b128 v[0:3], v37 offset:2048
	ds_read_b128 v[74:77], v37 offset:3072
	ds_read_b128 v[98:101], v37 offset:8192
	v_lshl_add_u64 v[58:59], v[32:33], 2, s[10:11]
	v_mfma_f32_16x16x32_bf16 v[62:65], v[8:11], v[4:7], 0
	v_lshlrev_b32_e32 v33, 2, v35
	v_lshl_or_b32 v126, v39, 8, v33
	v_mad_u64_u32 v[32:33], s[10:11], v32, s67, v[126:127]
	v_mfma_f32_16x16x32_bf16 v[66:69], v[8:11], v[12:15], 0
	v_add_u32_e32 v33, 0x400, v32
	v_ashrrev_i32_e32 v49, 31, v48
	v_ashrrev_i32_e32 v47, 31, v46
	v_mfma_f32_16x16x32_bf16 v[70:73], v[8:11], v[24:27], 0
	v_ashrrev_i32_e32 v45, 31, v44
	v_ashrrev_i32_e32 v43, 31, v42
	v_ashrrev_i32_e32 v39, 31, v38
	v_mfma_f32_16x16x32_bf16 v[8:11], v[8:11], v[28:31], 0
	s_waitcnt lgkmcnt(2)
	v_mfma_f32_16x16x32_bf16 v[78:81], v[0:3], v[4:7], 0
	v_mfma_f32_16x16x32_bf16 v[82:85], v[0:3], v[12:15], 0
	v_mfma_f32_16x16x32_bf16 v[86:89], v[0:3], v[24:27], 0
	v_mfma_f32_16x16x32_bf16 v[90:93], v[0:3], v[28:31], 0
	s_waitcnt lgkmcnt(1)
	v_mfma_f32_16x16x32_bf16 v[94:97], v[74:77], v[4:7], 0
	v_mfma_f32_16x16x32_bf16 v[12:15], v[74:77], v[12:15], 0
	v_mfma_f32_16x16x32_bf16 v[24:27], v[74:77], v[24:27], 0
	v_mfma_f32_16x16x32_bf16 v[0:3], v[74:77], v[28:31], 0
	ds_read_b128 v[28:31], v41 offset:40960
	ds_read_b128 v[74:77], v37 offset:9216
	ds_read_b128 v[102:105], v41 offset:41984
	ds_read_b128 v[106:109], v41 offset:43008
	ds_read_b128 v[4:7], v41 offset:44032
	s_waitcnt lgkmcnt(4)
	v_mfma_f32_16x16x32_bf16 v[16:19], v[98:101], v[28:31], v[16:19]
	s_waitcnt lgkmcnt(2)
	v_mfma_f32_16x16x32_bf16 v[20:23], v[98:101], v[102:105], v[20:23]
	s_waitcnt lgkmcnt(1)
	v_mfma_f32_16x16x32_bf16 v[50:53], v[98:101], v[106:109], v[50:53]
	s_waitcnt lgkmcnt(0)
	v_mfma_f32_16x16x32_bf16 v[54:57], v[98:101], v[4:7], v[54:57]
	ds_read_b128 v[98:101], v37 offset:10240
	v_mfma_f32_16x16x32_bf16 v[62:65], v[74:77], v[28:31], v[62:65]
	v_mfma_f32_16x16x32_bf16 v[66:69], v[74:77], v[102:105], v[66:69]
	v_mfma_f32_16x16x32_bf16 v[70:73], v[74:77], v[106:109], v[70:73]
	v_mfma_f32_16x16x32_bf16 v[8:11], v[74:77], v[4:7], v[8:11]
	ds_read_b128 v[74:77], v37 offset:11264
	ds_read_b128 v[110:113], v37 offset:16384
	ds_read_b128 v[114:117], v37 offset:17408
	ds_read_b128 v[118:121], v37 offset:18432
	ds_read_b128 v[122:125], v37 offset:19456
	ds_read_b128 v[134:137], v41 offset:49152
	ds_read_b128 v[138:141], v41 offset:50176
	ds_read_b128 v[146:149], v41 offset:51200
	ds_read_b128 v[150:153], v41 offset:52224
	ds_read_b128 v[162:165], v37 offset:24576
	ds_read_b128 v[166:169], v37 offset:25600
	s_waitcnt lgkmcnt(11)
	v_mfma_f32_16x16x32_bf16 v[78:81], v[98:101], v[28:31], v[78:81]
	v_mfma_f32_16x16x32_bf16 v[82:85], v[98:101], v[102:105], v[82:85]
	v_mfma_f32_16x16x32_bf16 v[86:89], v[98:101], v[106:109], v[86:89]
	v_mfma_f32_16x16x32_bf16 v[90:93], v[98:101], v[4:7], v[90:93]
	ds_read_b128 v[98:101], v37 offset:26624
	ds_read_b128 v[170:173], v37 offset:27648
	ds_read_b128 v[174:177], v41 offset:57344
	ds_read_b128 v[178:181], v41 offset:58368
	s_waitcnt lgkmcnt(14)
	v_mfma_f32_16x16x32_bf16 v[28:31], v[74:77], v[28:31], v[94:97]
	s_nop 2
	ds_read_b128 v[94:97], v41 offset:59392
	ds_read_b128 v[182:185], v41 offset:60416
	s_waitcnt lgkmcnt(0)
	s_barrier
	v_mfma_f32_16x16x32_bf16 v[16:19], v[110:113], v[134:137], v[16:19]
	global_load_dwordx4 v[186:189], v[58:59], off offset:64
	global_load_dwordx4 v[190:193], v[58:59], off offset:128
	v_mfma_f32_16x16x32_bf16 v[20:23], v[110:113], v[138:141], v[20:23]
	v_ashrrev_i32_e32 v41, 31, v40
	v_mfma_f32_16x16x32_bf16 v[50:53], v[110:113], v[146:149], v[50:53]
	v_mfma_f32_16x16x32_bf16 v[54:57], v[110:113], v[150:153], v[54:57]
	global_load_dwordx4 v[110:113], v[58:59], off
	v_mfma_f32_16x16x32_bf16 v[16:19], v[162:165], v[174:177], v[16:19]
	v_mfma_f32_16x16x32_bf16 v[20:23], v[162:165], v[178:181], v[20:23]
	v_mfma_f32_16x16x32_bf16 v[50:53], v[162:165], v[94:97], v[50:53]
	s_waitcnt vmcnt(0)
; #define MFMA16(a, b, c) __builtin_amdgcn_mfma_f32_16x16x32_bf16(a, b, c, 0, 0, 0)
; __device__ void gmlp_item(const Params& p, int layer, int b, int n, int g, char* smem) {
;     ...
; #pragma unroll
;     for (int m = 0; m < 4; ++m)
; #pragma unroll
;       for (int nn = 0; nn < 4; ++nn) acc[m][nn] = MFMA16(a[m], bb[nn], acc[m][nn]);
;   }
;   __syncthreads();
;   {
;     float* Tf = reinterpret_cast<float*>(smem);
; #pragma unroll
;     for (int m = 0; m < 4; ++m)
; #pragma unroll
;       for (int j = 0; j < 4; ++j) {
;         int t = wr * 64 + m * 16 + fq * 4 + j;
;         float bias = p.gm_b_s[(size_t)layer * 512 + g * 128 + t];
; #pragma unroll
;         for (int nn = 0; nn < 4; ++nn) Tf[t * 132 + wc * 64 + nn * 16 + fr] = acc[m][nn][j] + bias;
;       }
;     __syncthreads();
;     uint4 uu[8], gt[8];
; #pragma unroll
;     for (int i = 0; i < 8; ++i) {
;       int q = tid + 256 * i, t = q >> 4, c = (q & 15) * 8;
;       uu[i] = *reinterpret_cast<const uint4*>(P + (t0 + t) * NP + g * 128 + c);
;       gt[i] = *reinterpret_cast<const uint4*>(P + (t0 + t) * NP + 1024 + g * 128 + c);
;     }
	s_nop 4
	v_add_f32_e32 v16, v16, v110
	v_mfma_f32_16x16x32_bf16 v[54:57], v[162:165], v[182:185], v[54:57]
	v_add_f32_e32 v20, v20, v110
	ds_write2_b32 v32, v16, v20 offset1:16
	v_add_f32_e32 v16, v50, v110
	v_add_f32_e32 v35, v53, v113
	v_mfma_f32_16x16x32_bf16 v[62:65], v[114:117], v[134:137], v[62:65]
	s_nop 2
	v_add_f32_e32 v20, v54, v110
	ds_write2_b32 v32, v16, v20 offset0:32 offset1:48
	v_add_f32_e32 v16, v17, v111
	v_add_f32_e32 v17, v21, v111
	ds_write2_b32 v32, v16, v17 offset0:132 offset1:148
	v_add_f32_e32 v16, v51, v111
	v_add_f32_e32 v17, v55, v111
	ds_write2_b32 v32, v16, v17 offset0:164 offset1:180
	v_add_f32_e32 v16, v18, v112
	v_add_f32_e32 v17, v22, v112
	ds_write2_b32 v33, v16, v17 offset0:8 offset1:24
	v_add_f32_e32 v16, v52, v112
	global_load_dwordx4 v[50:53], v[58:59], off offset:192
	v_mfma_f32_16x16x32_bf16 v[66:69], v[114:117], v[138:141], v[66:69]
	v_add_f32_e32 v17, v56, v112
	v_add_f32_e32 v20, v19, v113
	v_add_f32_e32 v21, v23, v113
	v_mfma_f32_16x16x32_bf16 v[70:73], v[114:117], v[146:149], v[70:73]
	ds_write2_b32 v33, v16, v17 offset0:40 offset1:56
	ds_write2_b32 v33, v20, v21 offset0:140 offset1:156
	v_add_f32_e32 v37, v57, v113
	v_mfma_f32_16x16x32_bf16 v[8:11], v[114:117], v[150:153], v[8:11]
	ds_write2_b32 v33, v35, v37 offset0:172 offset1:188
	v_add_u32_e32 v33, 0x2000, v32
	v_ashrrev_i32_e32 v35, 31, v34
	v_mfma_f32_16x16x32_bf16 v[16:19], v[166:169], v[174:177], v[62:65]
	v_ashrrev_i32_e32 v37, 31, v36
	v_lshl_add_u64 v[58:59], v[42:43], 0, s[26:27]
	v_mfma_f32_16x16x32_bf16 v[20:23], v[166:169], v[178:181], v[66:69]
	v_mfma_f32_16x16x32_bf16 v[54:57], v[166:169], v[94:97], v[70:73]
	s_nop 3
	v_add_f32_e32 v16, v16, v186
	s_nop 1
	v_add_f32_e32 v20, v20, v186
	ds_write2_b32 v33, v16, v20 offset0:64 offset1:80
	v_mfma_f32_16x16x32_bf16 v[8:11], v[166:169], v[182:185], v[8:11]
	v_add_u32_e32 v20, 0x2400, v32
	v_add_f32_e32 v16, v54, v186
	v_mfma_f32_16x16x32_bf16 v[62:65], v[118:121], v[134:137], v[78:81]
	v_mfma_f32_16x16x32_bf16 v[66:69], v[118:121], v[138:141], v[82:85]
	s_nop 3
	v_add_f32_e32 v8, v8, v186
	ds_write2_b32 v33, v16, v8 offset0:96 offset1:112
	v_add_f32_e32 v8, v17, v187
	v_add_f32_e32 v16, v21, v187
	ds_write2_b32 v33, v8, v16 offset0:196 offset1:212
	v_add_f32_e32 v8, v55, v187
	v_add_f32_e32 v9, v9, v187
	ds_write2_b32 v33, v8, v9 offset0:228 offset1:244
	v_add_f32_e32 v8, v18, v188
	v_add_f32_e32 v9, v22, v188
	v_mfma_f32_16x16x32_bf16 v[70:73], v[118:121], v[146:149], v[86:89]
	ds_write2_b32 v20, v8, v9 offset0:72 offset1:88
	v_add_f32_e32 v8, v56, v188
	v_add_f32_e32 v9, v10, v188
	v_mfma_f32_16x16x32_bf16 v[78:81], v[118:121], v[150:153], v[90:93]
	ds_write2_b32 v20, v8, v9 offset0:104 offset1:120
	v_add_f32_e32 v8, v19, v189
	v_add_f32_e32 v9, v23, v189
	v_mfma_f32_16x16x32_bf16 v[16:19], v[98:101], v[174:177], v[62:65]
	ds_write2_b32 v20, v8, v9 offset0:204 offset1:220
	v_add_f32_e32 v21, v57, v189
	v_add_f32_e32 v22, v11, v189
	v_mfma_f32_16x16x32_bf16 v[8:11], v[98:101], v[178:181], v[66:69]
	ds_write2_b32 v20, v21, v22 offset0:236 offset1:252
	s_nop 2
	v_add_f32_e32 v16, v16, v190
	v_add_u32_e32 v33, 0x4000, v32
	v_mfma_f32_16x16x32_bf16 v[20:23], v[98:101], v[94:97], v[70:73]
	v_lshl_add_u64 v[62:63], v[38:39], 0, s[26:27]
	v_add_f32_e32 v8, v8, v190
	ds_write2_b32 v33, v16, v8 offset0:128 offset1:144
	v_mfma_f32_16x16x32_bf16 v[54:57], v[98:101], v[182:185], v[78:81]
	v_add_f32_e32 v10, v10, v192
	s_nop 2
	v_add_f32_e32 v8, v20, v190
	v_mfma_f32_16x16x32_bf16 v[12:15], v[74:77], v[102:105], v[12:15]
	v_mfma_f32_16x16x32_bf16 v[24:27], v[74:77], v[106:109], v[24:27]
	s_nop 0
	v_add_f32_e32 v16, v54, v190
	ds_write2_b32 v33, v8, v16 offset0:160 offset1:176
	v_add_f32_e32 v8, v17, v191
	v_mfma_f32_16x16x32_bf16 v[0:3], v[74:77], v[4:7], v[0:3]
	v_add_f32_e32 v4, v9, v191
	v_add_u32_e32 v9, 0x4400, v32
	ds_write2_b32 v9, v8, v4 offset0:4 offset1:20
	v_mfma_f32_16x16x32_bf16 v[4:7], v[122:125], v[134:137], v[28:31]
	v_add_f32_e32 v8, v21, v191
	v_add_f32_e32 v16, v55, v191
	ds_write2_b32 v9, v8, v16 offset0:36 offset1:52
	v_mfma_f32_16x16x32_bf16 v[12:15], v[122:125], v[138:141], v[12:15]
	v_add_f32_e32 v8, v18, v192
	ds_write2_b32 v9, v8, v10 offset0:136 offset1:152
	v_add_f32_e32 v8, v22, v192
	v_mfma_f32_16x16x32_bf16 v[24:27], v[122:125], v[146:149], v[24:27]
	v_add_f32_e32 v10, v56, v192
	ds_write2_b32 v9, v8, v10 offset0:168 offset1:184
	v_add_f32_e32 v8, v19, v193
	v_mfma_f32_16x16x32_bf16 v[0:3], v[122:125], v[150:153], v[0:3]
	v_add_f32_e32 v9, v11, v193
	v_add_u32_e32 v16, 0x4800, v32
	ds_write2_b32 v16, v8, v9 offset0:12 offset1:28
	v_mfma_f32_16x16x32_bf16 v[4:7], v[170:173], v[174:177], v[4:7]
	v_add_f32_e32 v17, v23, v193
	v_add_f32_e32 v18, v57, v193
	ds_write2_b32 v16, v17, v18 offset0:44 offset1:60
	v_mfma_f32_16x16x32_bf16 v[8:11], v[170:173], v[178:181], v[12:15]
	v_add_u32_e32 v16, 0x6000, v32
	s_waitcnt vmcnt(0)
	s_nop 1
	v_add_f32_e32 v4, v4, v50
	v_lshl_add_u64 v[56:57], v[36:37], 0, s[26:27]
	v_mfma_f32_16x16x32_bf16 v[12:15], v[170:173], v[94:97], v[24:27]
	v_lshl_add_u64 v[20:21], v[44:45], 0, s[26:27]
	v_add_f32_e32 v8, v8, v50
	ds_write2_b32 v16, v4, v8 offset0:192 offset1:208
	v_mfma_f32_16x16x32_bf16 v[0:3], v[170:173], v[182:185], v[0:3]
	s_nop 3
	v_add_f32_e32 v4, v12, v50
	s_nop 2
	v_add_f32_e32 v0, v0, v50
	ds_write2_b32 v16, v4, v0 offset0:224 offset1:240
	v_add_f32_e32 v0, v5, v51
	v_add_f32_e32 v4, v9, v51
	v_add_u32_e32 v5, 0x6400, v32
	ds_write2_b32 v5, v0, v4 offset0:68 offset1:84
	v_add_f32_e32 v0, v13, v51
	v_add_f32_e32 v1, v1, v51
	ds_write2_b32 v5, v0, v1 offset0:100 offset1:116
	v_add_f32_e32 v0, v6, v52
	v_add_f32_e32 v1, v10, v52
	ds_write2_b32 v5, v0, v1 offset0:200 offset1:216
	v_add_f32_e32 v0, v14, v52
	v_add_f32_e32 v1, v2, v52
	ds_write2_b32 v5, v0, v1 offset0:232 offset1:248
	v_add_f32_e32 v0, v7, v53
	v_add_f32_e32 v1, v11, v53
	v_add_u32_e32 v2, 0x6800, v32
	ds_write2_b32 v2, v0, v1 offset0:76 offset1:92
	v_add_f32_e32 v0, v15, v53
	v_add_f32_e32 v1, v3, v53
	ds_write2_b32 v2, v0, v1 offset0:108 offset1:124
	v_lshlrev_b32_e32 v0, 3, v60
	v_lshl_add_u64 v[8:9], v[34:35], 0, s[26:27]
	v_mov_b64_e32 v[10:11], s[4:5]
	v_and_b32_e32 v24, 0x78, v0
	v_mad_u64_u32 v[0:1], s[4:5], v8, s55, v[10:11]
	v_mad_i32_i24 v1, v9, s55, v1
	s_lshl_b32 s4, s8, 1
	s_mov_b32 s5, s27
	v_lshl_add_u64 v[0:1], v[0:1], 0, s[4:5]
	v_lshlrev_b32_e32 v128, 1, v24
	v_lshl_add_u64 v[12:13], v[48:49], 0, s[26:27]
	v_lshl_add_u64 v[52:53], v[0:1], 0, v[128:129]
	v_mad_u64_u32 v[0:1], s[8:9], v12, s55, v[10:11]
	v_mad_i32_i24 v1, v13, s55, v1
	v_lshl_add_u64 v[0:1], v[0:1], 0, s[4:5]
	v_lshl_add_u64 v[32:33], v[0:1], 0, v[128:129]
	v_mad_u64_u32 v[0:1], s[8:9], v56, s55, v[10:11]
	v_mad_i32_i24 v1, v57, s55, v1
	v_lshl_add_u64 v[0:1], v[0:1], 0, s[4:5]
	v_lshl_add_u64 v[4:5], v[0:1], 0, v[128:129]
	s_waitcnt lgkmcnt(0)
	s_barrier
; __device__ __forceinline__ unsigned pack2(float a, float b) { return (unsigned)f2bf(a) | ((unsigned)f2bf(b) << 16); }
; __device__ __forceinline__ float bflo(unsigned w) { return __uint_as_float(w << 16); }
; __device__ __forceinline__ float bfhi(unsigned w) { return __uint_as_float(w & 0xffff0000u); }
; __device__ __forceinline__ float silu_f(float g) { return g / (1.f + __expf(-g)); }
; __device__ void gmlp_item(const Params& p, int layer, int b, int n, int g, char* smem) {
;     ...
;     uint4 uu[8], gt[8];
; #pragma unroll
;     for (int i = 0; i < 8; ++i) {
;       int q = tid + 256 * i, t = q >> 4, c = (q & 15) * 8;
;       uu[i] = *reinterpret_cast<const uint4*>(P + (t0 + t) * NP + g * 128 + c);
;       gt[i] = *reinterpret_cast<const uint4*>(P + (t0 + t) * NP + 1024 + g * 128 + c);
;     }
; #pragma unroll
;     for (int i = 0; i < 8; ++i) {
;       int q = tid + 256 * i, t = q >> 4, c = (q & 15) * 8;
;       float4 m0 = *reinterpret_cast<const float4*>(Tf + t * 132 + c);
;       float4 m1 = *reinterpret_cast<const float4*>(Tf + t * 132 + c + 4);
;       float mm[8] = {m0.x, m0.y, m0.z, m0.w, m1.x, m1.y, m1.z, m1.w};
;       unsigned uw[4] = {uu[i].x, uu[i].y, uu[i].z, uu[i].w};
;       unsigned gw[4] = {gt[i].x, gt[i].y, gt[i].z, gt[i].w};
;       unsigned ow[4];
; #pragma unroll
;       for (int e = 0; e < 4; ++e) {
;         float y0 = bflo(uw[e]) * mm[2 * e] * silu_f(bflo(gw[e]));
;         float y1 = bfhi(uw[e]) * mm[2 * e + 1] * silu_f(bfhi(gw[e]));
;         ow[e] = pack2(y0, y1);
;       }
;       *reinterpret_cast<uint4*>(Y + (t0 + t) * YW + g * 128 + c) = make_uint4(ow[0], ow[1], ow[2], ow[3]);
;     }
	global_load_dwordx4 v[0:3], v[4:5], off
	s_nop 0
	global_load_dwordx4 v[4:7], v[4:5], off offset:2048
	v_lshl_add_u64 v[16:17], v[46:47], 0, s[26:27]
	v_mad_u64_u32 v[14:15], s[8:9], v16, s55, v[10:11]
	v_mad_i32_i24 v15, v17, s55, v15
	v_lshl_add_u64 v[14:15], v[14:15], 0, s[4:5]
	v_lshl_add_u64 v[30:31], v[14:15], 0, v[128:129]
	v_mad_u64_u32 v[14:15], s[8:9], v20, s55, v[10:11]
	v_mad_i32_i24 v15, v21, s55, v15
	v_lshl_add_u64 v[14:15], v[14:15], 0, s[4:5]
	v_lshl_add_u64 v[26:27], v[14:15], 0, v[128:129]
	v_mad_u64_u32 v[14:15], s[8:9], v58, s55, v[10:11]
	v_mad_i32_i24 v15, v59, s55, v15
	v_lshl_add_u64 v[14:15], v[14:15], 0, s[4:5]
	v_lshl_add_u64 v[60:61], v[40:41], 0, s[26:27]
	v_lshl_add_u64 v[22:23], v[14:15], 0, v[128:129]
	v_mad_u64_u32 v[14:15], s[8:9], v60, s55, v[10:11]
	v_mad_u64_u32 v[10:11], s[8:9], v62, s55, v[10:11]
	v_mad_i32_i24 v15, v61, s55, v15
	v_mad_i32_i24 v11, v63, s55, v11
	v_lshl_add_u64 v[14:15], v[14:15], 0, s[4:5]
	v_lshl_add_u64 v[10:11], v[10:11], 0, s[4:5]
	s_add_u32 s4, s6, s4
	s_addc_u32 s5, s7, 0
	v_lshl_add_u64 v[18:19], v[14:15], 0, v[128:129]
	v_lshl_add_u64 v[14:15], v[10:11], 0, v[128:129]
	v_lshlrev_b32_e32 v10, 2, v24
	v_lshl_add_u64 v[24:25], s[4:5], 0, v[128:129]
	v_lshl_add_u64 v[64:65], v[24:25], 0, s[40:41]
	v_mad_u64_u32 v[54:55], s[4:5], v34, s67, v[10:11]
	v_mad_u64_u32 v[34:35], s[4:5], v48, s67, v[10:11]
	v_mad_u64_u32 v[48:49], s[4:5], v12, s68, v[64:65]
	v_mad_u64_u32 v[28:29], s[4:5], v46, s67, v[10:11]
	v_mad_u64_u32 v[46:47], s[4:5], v16, s68, v[64:65]
	v_mad_u64_u32 v[50:51], s[4:5], v8, s68, v[64:65]
	v_mad_i32_i24 v49, v13, s68, v49
	v_mad_i32_i24 v47, v17, s68, v47
	v_mad_u64_u32 v[24:25], s[4:5], v44, s67, v[10:11]
	v_mad_u64_u32 v[44:45], s[4:5], v20, s68, v[64:65]
	v_mad_u64_u32 v[16:17], s[4:5], v40, s67, v[10:11]
	v_mad_u64_u32 v[12:13], s[4:5], v38, s67, v[10:11]
	v_mad_i32_i24 v51, v9, s68, v51
	v_mad_i32_i24 v45, v21, s68, v45
	v_mad_u64_u32 v[20:21], s[4:5], v42, s67, v[10:11]
	v_mad_u64_u32 v[8:9], s[4:5], v36, s67, v[10:11]
	v_mad_u64_u32 v[40:41], s[4:5], v60, s68, v[64:65]
	v_mad_i32_i24 v41, v61, s68, v41
	v_mad_u64_u32 v[42:43], s[4:5], v58, s68, v[64:65]
	v_mad_u64_u32 v[36:37], s[4:5], v56, s68, v[64:65]
	v_mad_i32_i24 v43, v59, s68, v43
	v_mad_i32_i24 v37, v57, s68, v37
	v_mad_u64_u32 v[38:39], s[4:5], v62, s68, v[64:65]
	v_mad_i32_i24 v39, v63, s68, v39
	s_waitcnt vmcnt(1)
	v_lshlrev_b32_e32 v63, 16, v1
	s_waitcnt vmcnt(0)
	v_lshlrev_b32_e32 v13, 16, v5
	v_lshlrev_b32_e32 v17, 16, v4
	v_mul_f32_e32 v9, 0xbfb8aa3b, v17
	v_and_b32_e32 v21, 0xffff0000, v5
	v_mul_f32_e32 v5, 0xbfb8aa3b, v13
	v_exp_f32_e32 v60, v9
	v_exp_f32_e32 v61, v5
	ds_read_b128 v[56:59], v8
	ds_read_b128 v[8:11], v8 offset:16
	v_and_b32_e32 v25, 0xffff0000, v4
	v_mul_f32_e32 v4, 0xbfb8aa3b, v25
	v_pk_add_f32 v[60:61], v[60:61], 1.0 op_sel_hi:[1,0]
	s_waitcnt lgkmcnt(1)
	v_mov_b32_e32 v64, v56
	v_exp_f32_e32 v4, v4
	v_lshlrev_b32_e32 v62, 16, v0
	v_mov_b32_e32 v65, v58
	v_rcp_f32_e32 v61, v61
	s_nop 0
	v_mul_f32_e32 v61, v13, v61
	v_and_b32_e32 v1, 0xffff0000, v1
	v_mul_f32_e32 v5, 0xbfb8aa3b, v21
	v_exp_f32_e32 v5, v5
	v_rcp_f32_e32 v60, v60
	s_nop 0
	v_mul_f32_e32 v60, v17, v60
	v_and_b32_e32 v0, 0xffff0000, v0
	v_mov_b32_e32 v58, v57
	v_pk_add_f32 v[4:5], v[4:5], 1.0 op_sel_hi:[1,0]
	v_pk_mul_f32 v[0:1], v[58:59], v[0:1]
	v_pk_mul_f32 v[62:63], v[64:65], v[62:63]
	v_rcp_f32_e32 v5, v5
	s_nop 0
	v_mul_f32_e32 v5, v21, v5
	v_pk_mul_f32 v[60:61], v[60:61], v[62:63]
	v_rcp_f32_e32 v4, v4
	s_nop 0
	v_mul_f32_e32 v4, v25, v4
	v_pk_mul_f32 v[0:1], v[4:5], v[0:1]
	v_lshlrev_b32_e32 v13, 16, v7
	v_lshlrev_b32_e32 v17, 16, v6
	v_cvt_pk_bf16_f32 v1, v61, v1
	v_cvt_pk_bf16_f32 v0, v60, v0
	v_mul_f32_e32 v4, 0xbfb8aa3b, v17
	v_mul_f32_e32 v5, 0xbfb8aa3b, v13
	v_exp_f32_e32 v4, v4
	v_exp_f32_e32 v5, v5
	v_and_b32_e32 v25, 0xffff0000, v6
	v_mul_f32_e32 v6, 0xbfb8aa3b, v25
	v_and_b32_e32 v21, 0xffff0000, v7
	v_exp_f32_e32 v60, v6
	v_pk_add_f32 v[64:65], v[4:5], 1.0 op_sel_hi:[1,0]
	global_load_dwordx4 v[4:7], v[14:15], off
	global_load_dwordx4 v[56:59], v[14:15], off offset:2048
	s_waitcnt lgkmcnt(0)
	v_mov_b32_e32 v14, v8
	v_mov_b32_e32 v15, v10
	v_lshlrev_b32_e32 v63, 16, v3
	v_lshlrev_b32_e32 v62, 16, v2
	v_pk_mul_f32 v[14:15], v[14:15], v[62:63]
	v_rcp_f32_e32 v63, v65
	s_nop 0
	v_mul_f32_e32 v63, v13, v63
	v_mul_f32_e32 v10, 0xbfb8aa3b, v21
	v_exp_f32_e32 v61, v10
	v_rcp_f32_e32 v62, v64
	s_nop 0
	v_mul_f32_e32 v62, v17, v62
	v_mov_b32_e32 v10, v9
	v_and_b32_e32 v3, 0xffff0000, v3
	v_pk_add_f32 v[60:61], v[60:61], 1.0 op_sel_hi:[1,0]
	v_and_b32_e32 v2, 0xffff0000, v2
	v_pk_mul_f32 v[2:3], v[10:11], v[2:3]
	v_pk_mul_f32 v[14:15], v[62:63], v[14:15]
	v_rcp_f32_e32 v9, v61
	s_nop 0
	v_mul_f32_e32 v9, v21, v9
	v_rcp_f32_e32 v8, v60
	s_nop 0
	v_mul_f32_e32 v8, v25, v8
	v_pk_mul_f32 v[2:3], v[8:9], v[2:3]
	v_cvt_pk_bf16_f32 v3, v15, v3
	v_cvt_pk_bf16_f32 v2, v14, v2
	s_waitcnt vmcnt(0)
	v_lshlrev_b32_e32 v21, 16, v56
	v_mul_f32_e32 v8, 0xbfb8aa3b, v21
	v_and_b32_e32 v29, 0xffff0000, v56
	v_lshlrev_b32_e32 v17, 16, v57
	v_exp_f32_e32 v60, v8
	v_mul_f32_e32 v8, 0xbfb8aa3b, v29
	v_exp_f32_e32 v56, v8
	v_mul_f32_e32 v8, 0xbfb8aa3b, v17
	v_exp_f32_e32 v61, v8
	ds_read_b128 v[8:11], v12
	ds_read_b128 v[12:15], v12 offset:16
	v_and_b32_e32 v25, 0xffff0000, v57
	v_lshlrev_b32_e32 v63, 16, v5
	v_pk_add_f32 v[60:61], v[60:61], 1.0 op_sel_hi:[1,0]
	s_waitcnt lgkmcnt(1)
; __device__ __forceinline__ unsigned pack2(float a, float b) { return (unsigned)f2bf(a) | ((unsigned)f2bf(b) << 16); }
; __device__ __forceinline__ float bflo(unsigned w) { return __uint_as_float(w << 16); }
; __device__ __forceinline__ float bfhi(unsigned w) { return __uint_as_float(w & 0xffff0000u); }
; __device__ __forceinline__ float silu_f(float g) { return g / (1.f + __expf(-g)); }
; __device__ void gmlp_item(const Params& p, int layer, int b, int n, int g, char* smem) {
;     ...
; #pragma unroll
;     for (int i = 0; i < 8; ++i) {
;       int q = tid + 256 * i, t = q >> 4, c = (q & 15) * 8;
;       float4 m0 = *reinterpret_cast<const float4*>(Tf + t * 132 + c);
;       float4 m1 = *reinterpret_cast<const float4*>(Tf + t * 132 + c + 4);
;       float mm[8] = {m0.x, m0.y, m0.z, m0.w, m1.x, m1.y, m1.z, m1.w};
;       unsigned uw[4] = {uu[i].x, uu[i].y, uu[i].z, uu[i].w};
;       unsigned gw[4] = {gt[i].x, gt[i].y, gt[i].z, gt[i].w};
;       unsigned ow[4];
; #pragma unroll
;       for (int e = 0; e < 4; ++e) {
;         float y0 = bflo(uw[e]) * mm[2 * e] * silu_f(bflo(gw[e]));
;         float y1 = bfhi(uw[e]) * mm[2 * e + 1] * silu_f(bfhi(gw[e]));
;         ow[e] = pack2(y0, y1);
;       }
;       *reinterpret_cast<uint4*>(Y + (t0 + t) * YW + g * 128 + c) = make_uint4(ow[0], ow[1], ow[2], ow[3]);
;     }
	v_mov_b32_e32 v64, v8
	v_mov_b32_e32 v65, v10
	v_lshlrev_b32_e32 v62, 16, v4
	v_and_b32_e32 v5, 0xffff0000, v5
	v_rcp_f32_e32 v61, v61
	s_nop 0
	v_mul_f32_e32 v61, v17, v61
	v_and_b32_e32 v4, 0xffff0000, v4
	v_mul_f32_e32 v10, 0xbfb8aa3b, v25
	v_exp_f32_e32 v57, v10
	v_rcp_f32_e32 v60, v60
	s_nop 0
	v_mul_f32_e32 v60, v21, v60
	v_mov_b32_e32 v10, v9
	v_pk_mul_f32 v[4:5], v[10:11], v[4:5]
	v_pk_add_f32 v[56:57], v[56:57], 1.0 op_sel_hi:[1,0]
	v_pk_mul_f32 v[62:63], v[64:65], v[62:63]
	v_pk_mul_f32 v[60:61], v[60:61], v[62:63]
	v_lshlrev_b32_e32 v63, 16, v7
	v_lshlrev_b32_e32 v62, 16, v6
	v_rcp_f32_e32 v9, v57
	s_nop 0
	v_mul_f32_e32 v9, v25, v9
	v_rcp_f32_e32 v8, v56
	s_nop 0
	v_mul_f32_e32 v8, v29, v8
	v_pk_mul_f32 v[4:5], v[8:9], v[4:5]
	v_lshlrev_b32_e32 v17, 16, v59
	v_lshlrev_b32_e32 v21, 16, v58
	v_cvt_pk_bf16_f32 v5, v61, v5
	v_cvt_pk_bf16_f32 v4, v60, v4
	v_mul_f32_e32 v8, 0xbfb8aa3b, v21
	v_mul_f32_e32 v9, 0xbfb8aa3b, v17
	v_exp_f32_e32 v8, v8
	v_exp_f32_e32 v9, v9
	v_and_b32_e32 v29, 0xffff0000, v58
	v_mul_f32_e32 v10, 0xbfb8aa3b, v29
	v_and_b32_e32 v25, 0xffff0000, v59
	v_exp_f32_e32 v60, v10
	v_pk_add_f32 v[64:65], v[8:9], 1.0 op_sel_hi:[1,0]
	global_load_dwordx4 v[8:11], v[18:19], off
	global_load_dwordx4 v[56:59], v[18:19], off offset:2048
	s_waitcnt lgkmcnt(0)
	v_mov_b32_e32 v18, v12
	v_mov_b32_e32 v19, v14
	v_pk_mul_f32 v[18:19], v[18:19], v[62:63]
	v_rcp_f32_e32 v63, v65
	s_nop 0
	v_mul_f32_e32 v63, v17, v63
	v_and_b32_e32 v7, 0xffff0000, v7
	v_mul_f32_e32 v14, 0xbfb8aa3b, v25
	v_exp_f32_e32 v61, v14
	v_rcp_f32_e32 v62, v64
	s_nop 0
	v_mul_f32_e32 v62, v21, v62
	v_mov_b32_e32 v14, v13
	v_and_b32_e32 v6, 0xffff0000, v6
	v_pk_add_f32 v[60:61], v[60:61], 1.0 op_sel_hi:[1,0]
	v_pk_mul_f32 v[6:7], v[14:15], v[6:7]
	v_pk_mul_f32 v[18:19], v[62:63], v[18:19]
	v_rcp_f32_e32 v13, v61
	s_nop 0
	v_mul_f32_e32 v13, v25, v13
	v_rcp_f32_e32 v12, v60
	s_nop 0
	v_mul_f32_e32 v12, v29, v12
	v_pk_mul_f32 v[6:7], v[12:13], v[6:7]
	v_cvt_pk_bf16_f32 v7, v19, v7
	v_cvt_pk_bf16_f32 v6, v18, v6
	s_waitcnt vmcnt(1)
	v_lshlrev_b32_e32 v63, 16, v9
	s_waitcnt vmcnt(0)
	v_lshlrev_b32_e32 v25, 16, v56
	v_mul_f32_e32 v12, 0xbfb8aa3b, v25
	v_and_b32_e32 v35, 0xffff0000, v56
	v_lshlrev_b32_e32 v21, 16, v57
	v_exp_f32_e32 v60, v12
	v_mul_f32_e32 v12, 0xbfb8aa3b, v35
	v_exp_f32_e32 v56, v12
	v_mul_f32_e32 v12, 0xbfb8aa3b, v21
	v_exp_f32_e32 v61, v12
	v_and_b32_e32 v29, 0xffff0000, v57
	ds_read_b128 v[12:15], v16
	ds_read_b128 v[16:19], v16 offset:16
	v_lshlrev_b32_e32 v62, 16, v8
	v_pk_add_f32 v[60:61], v[60:61], 1.0 op_sel_hi:[1,0]
	v_and_b32_e32 v9, 0xffff0000, v9
	s_waitcnt lgkmcnt(1)
	v_mov_b32_e32 v64, v12
	v_mov_b32_e32 v65, v14
	v_pk_mul_f32 v[62:63], v[64:65], v[62:63]
	v_rcp_f32_e32 v61, v61
	s_nop 0
	v_mul_f32_e32 v61, v21, v61
	v_and_b32_e32 v8, 0xffff0000, v8
	v_mul_f32_e32 v14, 0xbfb8aa3b, v29
	v_exp_f32_e32 v57, v14
	v_rcp_f32_e32 v60, v60
	s_nop 0
	v_mul_f32_e32 v60, v25, v60
	v_mov_b32_e32 v14, v13
	v_pk_mul_f32 v[8:9], v[14:15], v[8:9]
	v_pk_add_f32 v[56:57], v[56:57], 1.0 op_sel_hi:[1,0]
	v_pk_mul_f32 v[60:61], v[60:61], v[62:63]
	v_lshlrev_b32_e32 v63, 16, v11
	v_lshlrev_b32_e32 v62, 16, v10
	v_and_b32_e32 v11, 0xffff0000, v11
	v_rcp_f32_e32 v13, v57
	s_nop 0
	v_mul_f32_e32 v13, v29, v13
	v_rcp_f32_e32 v12, v56
	s_nop 0
	v_mul_f32_e32 v12, v35, v12
	v_pk_mul_f32 v[8:9], v[12:13], v[8:9]
	v_lshlrev_b32_e32 v21, 16, v59
	v_lshlrev_b32_e32 v25, 16, v58
	v_cvt_pk_bf16_f32 v9, v61, v9
	v_cvt_pk_bf16_f32 v8, v60, v8
	v_mul_f32_e32 v12, 0xbfb8aa3b, v25
	v_mul_f32_e32 v13, 0xbfb8aa3b, v21
	v_exp_f32_e32 v12, v12
	v_exp_f32_e32 v13, v13
	v_and_b32_e32 v35, 0xffff0000, v58
	v_mul_f32_e32 v14, 0xbfb8aa3b, v35
	v_and_b32_e32 v29, 0xffff0000, v59
	v_exp_f32_e32 v60, v14
	v_pk_add_f32 v[64:65], v[12:13], 1.0 op_sel_hi:[1,0]
	global_load_dwordx4 v[12:15], v[22:23], off
	global_load_dwordx4 v[56:59], v[22:23], off offset:2048
	s_waitcnt lgkmcnt(0)
	v_mov_b32_e32 v22, v16
	v_mov_b32_e32 v23, v18
	v_pk_mul_f32 v[22:23], v[22:23], v[62:63]
	v_rcp_f32_e32 v63, v65
	s_nop 0
	v_mul_f32_e32 v63, v21, v63
	v_and_b32_e32 v10, 0xffff0000, v10
	v_mul_f32_e32 v18, 0xbfb8aa3b, v29
	v_exp_f32_e32 v61, v18
	v_rcp_f32_e32 v62, v64
	s_nop 0
	v_mul_f32_e32 v62, v25, v62
	v_mov_b32_e32 v18, v17
	v_pk_mul_f32 v[10:11], v[18:19], v[10:11]
	v_pk_add_f32 v[60:61], v[60:61], 1.0 op_sel_hi:[1,0]
	v_pk_mul_f32 v[22:23], v[62:63], v[22:23]
	s_waitcnt vmcnt(1)
	v_lshlrev_b32_e32 v63, 16, v13
	v_rcp_f32_e32 v17, v61
	s_nop 0
	v_mul_f32_e32 v17, v29, v17
	v_rcp_f32_e32 v16, v60
	s_nop 0
	v_mul_f32_e32 v16, v35, v16
	v_pk_mul_f32 v[10:11], v[16:17], v[10:11]
	s_waitcnt vmcnt(0)
	v_lshlrev_b32_e32 v29, 16, v56
	v_cvt_pk_bf16_f32 v11, v23, v11
	v_mul_f32_e32 v16, 0xbfb8aa3b, v29
	v_and_b32_e32 v55, 0xffff0000, v56
	v_lshlrev_b32_e32 v25, 16, v57
	v_exp_f32_e32 v60, v16
	v_mul_f32_e32 v16, 0xbfb8aa3b, v55
	v_exp_f32_e32 v56, v16
	v_mul_f32_e32 v16, 0xbfb8aa3b, v25
	v_exp_f32_e32 v61, v16
	s_nop 0
	v_pk_add_f32 v[60:61], v[60:61], 1.0 op_sel_hi:[1,0]
	v_and_b32_e32 v35, 0xffff0000, v57
	v_cvt_pk_bf16_f32 v10, v22, v10
	ds_read_b128 v[16:19], v20
	ds_read_b128 v[20:23], v20 offset:16
	v_lshlrev_b32_e32 v62, 16, v12
	v_and_b32_e32 v13, 0xffff0000, v13
	s_waitcnt lgkmcnt(1)
; __device__ __forceinline__ unsigned pack2(float a, float b) { return (unsigned)f2bf(a) | ((unsigned)f2bf(b) << 16); }
; __device__ __forceinline__ float bflo(unsigned w) { return __uint_as_float(w << 16); }
; __device__ __forceinline__ float bfhi(unsigned w) { return __uint_as_float(w & 0xffff0000u); }
; __device__ __forceinline__ float silu_f(float g) { return g / (1.f + __expf(-g)); }
; __device__ void gmlp_item(const Params& p, int layer, int b, int n, int g, char* smem) {
;     ...
; #pragma unroll
;     for (int i = 0; i < 8; ++i) {
;       int q = tid + 256 * i, t = q >> 4, c = (q & 15) * 8;
;       float4 m0 = *reinterpret_cast<const float4*>(Tf + t * 132 + c);
;       float4 m1 = *reinterpret_cast<const float4*>(Tf + t * 132 + c + 4);
;       float mm[8] = {m0.x, m0.y, m0.z, m0.w, m1.x, m1.y, m1.z, m1.w};
;       unsigned uw[4] = {uu[i].x, uu[i].y, uu[i].z, uu[i].w};
;       unsigned gw[4] = {gt[i].x, gt[i].y, gt[i].z, gt[i].w};
;       unsigned ow[4];
; #pragma unroll
;       for (int e = 0; e < 4; ++e) {
;         float y0 = bflo(uw[e]) * mm[2 * e] * silu_f(bflo(gw[e]));
;         float y1 = bfhi(uw[e]) * mm[2 * e + 1] * silu_f(bfhi(gw[e]));
;         ow[e] = pack2(y0, y1);
;       }
;       *reinterpret_cast<uint4*>(Y + (t0 + t) * YW + g * 128 + c) = make_uint4(ow[0], ow[1], ow[2], ow[3]);
;     }
	v_mov_b32_e32 v64, v16
	v_mov_b32_e32 v65, v18
	v_pk_mul_f32 v[62:63], v[64:65], v[62:63]
	v_rcp_f32_e32 v61, v61
	s_nop 0
	v_mul_f32_e32 v61, v25, v61
	v_and_b32_e32 v12, 0xffff0000, v12
	v_mul_f32_e32 v18, 0xbfb8aa3b, v35
	v_exp_f32_e32 v57, v18
	v_rcp_f32_e32 v60, v60
	s_nop 0
	v_mul_f32_e32 v60, v29, v60
	v_mov_b32_e32 v18, v17
	v_pk_mul_f32 v[12:13], v[18:19], v[12:13]
	v_pk_add_f32 v[56:57], v[56:57], 1.0 op_sel_hi:[1,0]
	v_pk_mul_f32 v[60:61], v[60:61], v[62:63]
	v_lshlrev_b32_e32 v63, 16, v15
	v_lshlrev_b32_e32 v62, 16, v14
	v_and_b32_e32 v15, 0xffff0000, v15
	v_rcp_f32_e32 v17, v57
	s_nop 0
	v_mul_f32_e32 v17, v35, v17
	v_rcp_f32_e32 v16, v56
	s_nop 0
	v_mul_f32_e32 v16, v55, v16
	v_pk_mul_f32 v[12:13], v[16:17], v[12:13]
	v_lshlrev_b32_e32 v25, 16, v59
	v_lshlrev_b32_e32 v29, 16, v58
	v_cvt_pk_bf16_f32 v13, v61, v13
	v_cvt_pk_bf16_f32 v12, v60, v12
	v_mul_f32_e32 v16, 0xbfb8aa3b, v29
	v_mul_f32_e32 v17, 0xbfb8aa3b, v25
	v_exp_f32_e32 v16, v16
	v_exp_f32_e32 v17, v17
	v_and_b32_e32 v55, 0xffff0000, v58
	v_mul_f32_e32 v18, 0xbfb8aa3b, v55
	v_and_b32_e32 v35, 0xffff0000, v59
	v_exp_f32_e32 v60, v18
	v_pk_add_f32 v[64:65], v[16:17], 1.0 op_sel_hi:[1,0]
	global_load_dwordx4 v[16:19], v[26:27], off
	global_load_dwordx4 v[56:59], v[26:27], off offset:2048
	s_waitcnt lgkmcnt(0)
	v_mov_b32_e32 v26, v20
	v_mov_b32_e32 v27, v22
	v_pk_mul_f32 v[26:27], v[26:27], v[62:63]
	v_rcp_f32_e32 v63, v65
	s_nop 0
	v_mul_f32_e32 v63, v25, v63
	v_and_b32_e32 v14, 0xffff0000, v14
	v_mul_f32_e32 v22, 0xbfb8aa3b, v35
	v_exp_f32_e32 v61, v22
	v_rcp_f32_e32 v62, v64
	s_nop 0
	v_mul_f32_e32 v62, v29, v62
	v_mov_b32_e32 v22, v21
	v_pk_mul_f32 v[14:15], v[22:23], v[14:15]
	v_pk_add_f32 v[60:61], v[60:61], 1.0 op_sel_hi:[1,0]
	v_pk_mul_f32 v[26:27], v[62:63], v[26:27]
	s_waitcnt vmcnt(1)
	v_lshlrev_b32_e32 v63, 16, v17
	v_rcp_f32_e32 v21, v61
	s_nop 0
	v_mul_f32_e32 v21, v35, v21
	v_rcp_f32_e32 v20, v60
	s_nop 0
	v_mul_f32_e32 v20, v55, v20
	v_pk_mul_f32 v[14:15], v[20:21], v[14:15]
	s_waitcnt vmcnt(0)
	v_lshlrev_b32_e32 v35, 16, v56
	v_cvt_pk_bf16_f32 v15, v27, v15
	v_mul_f32_e32 v20, 0xbfb8aa3b, v35
	v_and_b32_e32 v66, 0xffff0000, v56
	v_lshlrev_b32_e32 v29, 16, v57
	v_exp_f32_e32 v60, v20
	v_mul_f32_e32 v20, 0xbfb8aa3b, v66
	v_exp_f32_e32 v56, v20
	v_mul_f32_e32 v20, 0xbfb8aa3b, v29
	v_exp_f32_e32 v61, v20
	s_nop 0
	v_pk_add_f32 v[60:61], v[60:61], 1.0 op_sel_hi:[1,0]
	v_and_b32_e32 v55, 0xffff0000, v57
	v_cvt_pk_bf16_f32 v14, v26, v14
	ds_read_b128 v[20:23], v24
	ds_read_b128 v[24:27], v24 offset:16
	v_lshlrev_b32_e32 v62, 16, v16
	v_and_b32_e32 v17, 0xffff0000, v17
	s_waitcnt lgkmcnt(1)
	v_mov_b32_e32 v64, v20
	v_mov_b32_e32 v65, v22
	v_pk_mul_f32 v[62:63], v[64:65], v[62:63]
	v_rcp_f32_e32 v61, v61
	s_nop 0
	v_mul_f32_e32 v61, v29, v61
	v_and_b32_e32 v16, 0xffff0000, v16
	v_mul_f32_e32 v22, 0xbfb8aa3b, v55
	v_exp_f32_e32 v57, v22
	v_rcp_f32_e32 v60, v60
	s_nop 0
	v_mul_f32_e32 v60, v35, v60
	v_mov_b32_e32 v22, v21
	v_pk_mul_f32 v[16:17], v[22:23], v[16:17]
	v_pk_add_f32 v[56:57], v[56:57], 1.0 op_sel_hi:[1,0]
	v_pk_mul_f32 v[60:61], v[60:61], v[62:63]
	v_lshlrev_b32_e32 v63, 16, v19
	v_lshlrev_b32_e32 v62, 16, v18
	v_and_b32_e32 v19, 0xffff0000, v19
	v_rcp_f32_e32 v21, v57
	s_nop 0
	v_mul_f32_e32 v21, v55, v21
	v_rcp_f32_e32 v20, v56
	s_nop 0
	v_mul_f32_e32 v20, v66, v20
	v_pk_mul_f32 v[16:17], v[20:21], v[16:17]
	v_lshlrev_b32_e32 v29, 16, v59
	v_lshlrev_b32_e32 v35, 16, v58
	v_cvt_pk_bf16_f32 v17, v61, v17
	v_cvt_pk_bf16_f32 v16, v60, v16
	v_mul_f32_e32 v20, 0xbfb8aa3b, v35
	v_mul_f32_e32 v21, 0xbfb8aa3b, v29
	v_exp_f32_e32 v20, v20
	v_exp_f32_e32 v21, v21
	v_and_b32_e32 v66, 0xffff0000, v58
	v_mul_f32_e32 v22, 0xbfb8aa3b, v66
	v_and_b32_e32 v55, 0xffff0000, v59
	v_exp_f32_e32 v60, v22
	v_pk_add_f32 v[64:65], v[20:21], 1.0 op_sel_hi:[1,0]
	global_load_dwordx4 v[20:23], v[30:31], off
	global_load_dwordx4 v[56:59], v[30:31], off offset:2048
	s_waitcnt lgkmcnt(0)
	v_mov_b32_e32 v30, v24
	v_mov_b32_e32 v31, v26
	v_pk_mul_f32 v[30:31], v[30:31], v[62:63]
	v_rcp_f32_e32 v63, v65
	s_nop 0
	v_mul_f32_e32 v63, v29, v63
	v_and_b32_e32 v18, 0xffff0000, v18
	v_mul_f32_e32 v26, 0xbfb8aa3b, v55
	v_exp_f32_e32 v61, v26
	v_rcp_f32_e32 v62, v64
	s_nop 0
	v_mul_f32_e32 v62, v35, v62
	v_mov_b32_e32 v26, v25
	v_pk_mul_f32 v[18:19], v[26:27], v[18:19]
	v_pk_add_f32 v[60:61], v[60:61], 1.0 op_sel_hi:[1,0]
	v_pk_mul_f32 v[30:31], v[62:63], v[30:31]
	s_waitcnt vmcnt(1)
	v_lshlrev_b32_e32 v63, 16, v21
	v_rcp_f32_e32 v25, v61
	s_nop 0
	v_mul_f32_e32 v25, v55, v25
	v_rcp_f32_e32 v24, v60
	s_nop 0
	v_mul_f32_e32 v24, v66, v24
	v_pk_mul_f32 v[18:19], v[24:25], v[18:19]
	s_waitcnt vmcnt(0)
	v_lshlrev_b32_e32 v55, 16, v56
	v_cvt_pk_bf16_f32 v19, v31, v19
	v_mul_f32_e32 v24, 0xbfb8aa3b, v55
	v_and_b32_e32 v67, 0xffff0000, v56
	v_lshlrev_b32_e32 v35, 16, v57
	v_exp_f32_e32 v60, v24
	v_mul_f32_e32 v24, 0xbfb8aa3b, v67
	v_exp_f32_e32 v56, v24
	v_mul_f32_e32 v24, 0xbfb8aa3b, v35
	v_exp_f32_e32 v61, v24
	s_nop 0
	v_pk_add_f32 v[60:61], v[60:61], 1.0 op_sel_hi:[1,0]
	v_and_b32_e32 v66, 0xffff0000, v57
	v_cvt_pk_bf16_f32 v18, v30, v18
	ds_read_b128 v[24:27], v28
	ds_read_b128 v[28:31], v28 offset:16
	v_lshlrev_b32_e32 v62, 16, v20
	v_and_b32_e32 v21, 0xffff0000, v21
	s_waitcnt lgkmcnt(1)
; __device__ __forceinline__ unsigned pack2(float a, float b) { return (unsigned)f2bf(a) | ((unsigned)f2bf(b) << 16); }
; __device__ __forceinline__ float bflo(unsigned w) { return __uint_as_float(w << 16); }
; __device__ __forceinline__ float bfhi(unsigned w) { return __uint_as_float(w & 0xffff0000u); }
; __device__ __forceinline__ float silu_f(float g) { return g / (1.f + __expf(-g)); }
; __device__ void gmlp_item(const Params& p, int layer, int b, int n, int g, char* smem) {
;     ...
; #pragma unroll
;     for (int i = 0; i < 8; ++i) {
;       int q = tid + 256 * i, t = q >> 4, c = (q & 15) * 8;
;       float4 m0 = *reinterpret_cast<const float4*>(Tf + t * 132 + c);
;       float4 m1 = *reinterpret_cast<const float4*>(Tf + t * 132 + c + 4);
;       float mm[8] = {m0.x, m0.y, m0.z, m0.w, m1.x, m1.y, m1.z, m1.w};
;       unsigned uw[4] = {uu[i].x, uu[i].y, uu[i].z, uu[i].w};
;       unsigned gw[4] = {gt[i].x, gt[i].y, gt[i].z, gt[i].w};
;       unsigned ow[4];
; #pragma unroll
;       for (int e = 0; e < 4; ++e) {
;         float y0 = bflo(uw[e]) * mm[2 * e] * silu_f(bflo(gw[e]));
;         float y1 = bfhi(uw[e]) * mm[2 * e + 1] * silu_f(bfhi(gw[e]));
;         ow[e] = pack2(y0, y1);
;       }
;       *reinterpret_cast<uint4*>(Y + (t0 + t) * YW + g * 128 + c) = make_uint4(ow[0], ow[1], ow[2], ow[3]);
;     }
	v_mov_b32_e32 v64, v24
	v_mov_b32_e32 v65, v26
	v_pk_mul_f32 v[62:63], v[64:65], v[62:63]
	v_rcp_f32_e32 v61, v61
	s_nop 0
	v_mul_f32_e32 v61, v35, v61
	v_and_b32_e32 v20, 0xffff0000, v20
	v_mul_f32_e32 v26, 0xbfb8aa3b, v66
	v_exp_f32_e32 v57, v26
	v_rcp_f32_e32 v60, v60
	s_nop 0
	v_mul_f32_e32 v60, v55, v60
	v_mov_b32_e32 v26, v25
	v_pk_mul_f32 v[20:21], v[26:27], v[20:21]
	v_pk_add_f32 v[56:57], v[56:57], 1.0 op_sel_hi:[1,0]
	v_pk_mul_f32 v[60:61], v[60:61], v[62:63]
	v_lshlrev_b32_e32 v63, 16, v23
	v_lshlrev_b32_e32 v62, 16, v22
	v_and_b32_e32 v23, 0xffff0000, v23
	v_rcp_f32_e32 v25, v57
	s_nop 0
	v_mul_f32_e32 v25, v66, v25
	v_rcp_f32_e32 v24, v56
	s_nop 0
	v_mul_f32_e32 v24, v67, v24
	v_pk_mul_f32 v[20:21], v[24:25], v[20:21]
	v_lshlrev_b32_e32 v35, 16, v59
	v_lshlrev_b32_e32 v55, 16, v58
	v_cvt_pk_bf16_f32 v21, v61, v21
	v_cvt_pk_bf16_f32 v20, v60, v20
	v_mul_f32_e32 v24, 0xbfb8aa3b, v55
	v_mul_f32_e32 v25, 0xbfb8aa3b, v35
	v_exp_f32_e32 v24, v24
	v_exp_f32_e32 v25, v25
	v_and_b32_e32 v67, 0xffff0000, v58
	v_mul_f32_e32 v26, 0xbfb8aa3b, v67
	v_and_b32_e32 v66, 0xffff0000, v59
	v_exp_f32_e32 v60, v26
	v_pk_add_f32 v[64:65], v[24:25], 1.0 op_sel_hi:[1,0]
	global_load_dwordx4 v[24:27], v[32:33], off
	global_load_dwordx4 v[56:59], v[32:33], off offset:2048
	s_waitcnt lgkmcnt(0)
	v_mov_b32_e32 v32, v28
	v_mov_b32_e32 v33, v30
	v_pk_mul_f32 v[32:33], v[32:33], v[62:63]
	v_rcp_f32_e32 v63, v65
	s_nop 0
	v_mul_f32_e32 v63, v35, v63
	v_and_b32_e32 v22, 0xffff0000, v22
	v_mul_f32_e32 v30, 0xbfb8aa3b, v66
	v_exp_f32_e32 v61, v30
	v_rcp_f32_e32 v62, v64
	s_nop 0
	v_mul_f32_e32 v62, v55, v62
	v_mov_b32_e32 v30, v29
	v_pk_mul_f32 v[22:23], v[30:31], v[22:23]
	v_pk_add_f32 v[60:61], v[60:61], 1.0 op_sel_hi:[1,0]
	v_pk_mul_f32 v[32:33], v[62:63], v[32:33]
	s_waitcnt vmcnt(1)
	v_lshlrev_b32_e32 v63, 16, v25
	v_rcp_f32_e32 v29, v61
	s_nop 0
	v_mul_f32_e32 v29, v66, v29
	v_rcp_f32_e32 v28, v60
	s_nop 0
	v_mul_f32_e32 v28, v67, v28
	v_pk_mul_f32 v[22:23], v[28:29], v[22:23]
	s_waitcnt vmcnt(0)
	v_lshlrev_b32_e32 v66, 16, v56
	v_cvt_pk_bf16_f32 v23, v33, v23
	v_mul_f32_e32 v28, 0xbfb8aa3b, v66
	v_and_b32_e32 v68, 0xffff0000, v56
	v_lshlrev_b32_e32 v55, 16, v57
	v_exp_f32_e32 v60, v28
	v_mul_f32_e32 v28, 0xbfb8aa3b, v68
	v_exp_f32_e32 v56, v28
	v_mul_f32_e32 v28, 0xbfb8aa3b, v55
	v_exp_f32_e32 v61, v28
	s_nop 0
	v_pk_add_f32 v[60:61], v[60:61], 1.0 op_sel_hi:[1,0]
	v_and_b32_e32 v67, 0xffff0000, v57
	v_cvt_pk_bf16_f32 v22, v32, v22
	ds_read_b128 v[28:31], v34
	ds_read_b128 v[32:35], v34 offset:16
	v_lshlrev_b32_e32 v62, 16, v24
	v_and_b32_e32 v25, 0xffff0000, v25
	s_waitcnt lgkmcnt(1)
	v_mov_b32_e32 v64, v28
	v_mov_b32_e32 v65, v30
	v_pk_mul_f32 v[62:63], v[64:65], v[62:63]
	v_rcp_f32_e32 v61, v61
	s_nop 0
	v_mul_f32_e32 v61, v55, v61
	v_and_b32_e32 v24, 0xffff0000, v24
	v_mul_f32_e32 v30, 0xbfb8aa3b, v67
	v_exp_f32_e32 v57, v30
	v_rcp_f32_e32 v60, v60
	s_nop 0
	v_mul_f32_e32 v60, v66, v60
	v_mov_b32_e32 v30, v29
	v_pk_mul_f32 v[24:25], v[30:31], v[24:25]
	v_pk_add_f32 v[56:57], v[56:57], 1.0 op_sel_hi:[1,0]
	v_pk_mul_f32 v[60:61], v[60:61], v[62:63]
	v_lshlrev_b32_e32 v66, 16, v58
	v_lshlrev_b32_e32 v63, 16, v27
	v_and_b32_e32 v27, 0xffff0000, v27
	v_rcp_f32_e32 v29, v57
	s_nop 0
	v_mul_f32_e32 v29, v67, v29
	v_rcp_f32_e32 v28, v56
	s_nop 0
	v_mul_f32_e32 v28, v68, v28
	v_pk_mul_f32 v[24:25], v[28:29], v[24:25]
	v_lshlrev_b32_e32 v55, 16, v59
	v_cvt_pk_bf16_f32 v25, v61, v25
	v_cvt_pk_bf16_f32 v24, v60, v24
	v_mul_f32_e32 v28, 0xbfb8aa3b, v66
	v_mul_f32_e32 v29, 0xbfb8aa3b, v55
	v_exp_f32_e32 v28, v28
	v_exp_f32_e32 v29, v29
	v_and_b32_e32 v68, 0xffff0000, v58
	v_mul_f32_e32 v30, 0xbfb8aa3b, v68
	v_and_b32_e32 v67, 0xffff0000, v59
	v_exp_f32_e32 v60, v30
	v_pk_add_f32 v[64:65], v[28:29], 1.0 op_sel_hi:[1,0]
	global_load_dwordx4 v[28:31], v[52:53], off
	global_load_dwordx4 v[56:59], v[52:53], off offset:2048
	s_waitcnt lgkmcnt(0)
; __device__ __forceinline__ unsigned pack2(float a, float b) { return (unsigned)f2bf(a) | ((unsigned)f2bf(b) << 16); }
; __device__ __forceinline__ float bflo(unsigned w) { return __uint_as_float(w << 16); }
; __device__ __forceinline__ float bfhi(unsigned w) { return __uint_as_float(w & 0xffff0000u); }
; __device__ __forceinline__ float silu_f(float g) { return g / (1.f + __expf(-g)); }
; __device__ void gmlp_item(const Params& p, int layer, int b, int n, int g, char* smem) {
;     ...
; #pragma unroll
;     for (int i = 0; i < 8; ++i) {
;       int q = tid + 256 * i, t = q >> 4, c = (q & 15) * 8;
;       float4 m0 = *reinterpret_cast<const float4*>(Tf + t * 132 + c);
;       float4 m1 = *reinterpret_cast<const float4*>(Tf + t * 132 + c + 4);
;       float mm[8] = {m0.x, m0.y, m0.z, m0.w, m1.x, m1.y, m1.z, m1.w};
;       unsigned uw[4] = {uu[i].x, uu[i].y, uu[i].z, uu[i].w};
;       unsigned gw[4] = {gt[i].x, gt[i].y, gt[i].z, gt[i].w};
;       unsigned ow[4];
; #pragma unroll
;       for (int e = 0; e < 4; ++e) {
;         float y0 = bflo(uw[e]) * mm[2 * e] * silu_f(bflo(gw[e]));
;         float y1 = bfhi(uw[e]) * mm[2 * e + 1] * silu_f(bfhi(gw[e]));
;         ow[e] = pack2(y0, y1);
;       }
;       *reinterpret_cast<uint4*>(Y + (t0 + t) * YW + g * 128 + c) = make_uint4(ow[0], ow[1], ow[2], ow[3]);
;     }
;   }
;   __syncthreads();
	v_mov_b32_e32 v52, v32
	v_lshlrev_b32_e32 v62, 16, v26
	v_mov_b32_e32 v53, v34
	v_pk_mul_f32 v[52:53], v[52:53], v[62:63]
	v_rcp_f32_e32 v63, v65
	s_nop 0
	v_mul_f32_e32 v63, v55, v63
	v_and_b32_e32 v26, 0xffff0000, v26
	v_mul_f32_e32 v34, 0xbfb8aa3b, v67
	v_exp_f32_e32 v61, v34
	v_rcp_f32_e32 v62, v64
	s_nop 0
	v_mul_f32_e32 v62, v66, v62
	v_mov_b32_e32 v34, v33
	v_pk_mul_f32 v[26:27], v[34:35], v[26:27]
	v_pk_add_f32 v[60:61], v[60:61], 1.0 op_sel_hi:[1,0]
	v_pk_mul_f32 v[52:53], v[62:63], v[52:53]
	s_waitcnt vmcnt(1)
	v_lshlrev_b32_e32 v63, 16, v29
	v_rcp_f32_e32 v33, v61
	s_nop 0
	v_mul_f32_e32 v33, v67, v33
	v_rcp_f32_e32 v32, v60
	s_nop 0
	v_mul_f32_e32 v32, v68, v32
	v_pk_mul_f32 v[26:27], v[32:33], v[26:27]
	s_waitcnt vmcnt(0)
	v_lshlrev_b32_e32 v67, 16, v56
	v_cvt_pk_bf16_f32 v27, v53, v27
	v_mul_f32_e32 v32, 0xbfb8aa3b, v67
	v_and_b32_e32 v69, 0xffff0000, v56
	v_lshlrev_b32_e32 v66, 16, v57
	v_exp_f32_e32 v60, v32
	v_mul_f32_e32 v32, 0xbfb8aa3b, v69
	v_exp_f32_e32 v56, v32
	v_mul_f32_e32 v32, 0xbfb8aa3b, v66
	v_exp_f32_e32 v61, v32
	s_nop 0
	v_pk_add_f32 v[60:61], v[60:61], 1.0 op_sel_hi:[1,0]
	v_and_b32_e32 v68, 0xffff0000, v57
	v_cvt_pk_bf16_f32 v26, v52, v26
	ds_read_b128 v[32:35], v54
	ds_read_b128 v[52:55], v54 offset:16
	v_lshlrev_b32_e32 v62, 16, v28
	v_and_b32_e32 v29, 0xffff0000, v29
	s_waitcnt lgkmcnt(1)
	v_mov_b32_e32 v64, v32
	v_mov_b32_e32 v65, v34
	v_pk_mul_f32 v[62:63], v[64:65], v[62:63]
	v_rcp_f32_e32 v61, v61
	s_nop 0
	v_mul_f32_e32 v61, v66, v61
	v_and_b32_e32 v28, 0xffff0000, v28
	v_mul_f32_e32 v34, 0xbfb8aa3b, v68
	v_exp_f32_e32 v57, v34
	v_rcp_f32_e32 v60, v60
	s_nop 0
	v_mul_f32_e32 v60, v67, v60
	v_pk_mul_f32 v[60:61], v[60:61], v[62:63]
	v_mov_b32_e32 v34, v33
	v_pk_add_f32 v[56:57], v[56:57], 1.0 op_sel_hi:[1,0]
	v_pk_mul_f32 v[28:29], v[34:35], v[28:29]
	s_nop 0
	v_rcp_f32_e32 v33, v57
	s_nop 0
	v_mul_f32_e32 v33, v68, v33
	v_rcp_f32_e32 v32, v56
	s_nop 0
	v_mul_f32_e32 v32, v69, v32
	v_pk_mul_f32 v[28:29], v[32:33], v[28:29]
	v_cvt_pk_bf16_f32 v28, 0, v28
	v_cvt_pk_bf16_f32 v33, 0, v60
	v_and_b32_e32 v28, 0xffff0000, v28
	v_lshlrev_b32_e32 v35, 16, v59
	v_lshlrev_b32_e32 v60, 16, v58
	v_cvt_pk_bf16_f32 v29, v61, v29
	v_or_b32_sdwa v28, v28, v33 dst_sel:DWORD dst_unused:UNUSED_PAD src0_sel:DWORD src1_sel:WORD_1
	v_mul_f32_e32 v32, 0xbfb8aa3b, v60
	v_mul_f32_e32 v33, 0xbfb8aa3b, v35
	v_exp_f32_e32 v32, v32
	v_exp_f32_e32 v33, v33
	v_and_b32_e32 v62, 0xffff0000, v58
	s_waitcnt lgkmcnt(0)
	v_mov_b32_e32 v58, v52
	v_and_b32_e32 v61, 0xffff0000, v59
	v_pk_add_f32 v[32:33], v[32:33], 1.0 op_sel_hi:[1,0]
	v_lshlrev_b32_e32 v57, 16, v31
	v_lshlrev_b32_e32 v56, 16, v30
	v_mov_b32_e32 v59, v54
	v_pk_mul_f32 v[56:57], v[58:59], v[56:57]
	v_rcp_f32_e32 v33, v33
	s_nop 0
	v_mul_f32_e32 v33, v35, v33
	v_mul_f32_e32 v34, 0xbfb8aa3b, v62
	v_mul_f32_e32 v35, 0xbfb8aa3b, v61
	v_exp_f32_e32 v34, v34
	v_exp_f32_e32 v35, v35
	v_rcp_f32_e32 v32, v32
	s_nop 0
	v_mul_f32_e32 v32, v60, v32
	v_pk_mul_f32 v[32:33], v[32:33], v[56:57]
	v_mov_b32_e32 v54, v53
	v_pk_add_f32 v[34:35], v[34:35], 1.0 op_sel_hi:[1,0]
	v_and_b32_e32 v31, 0xffff0000, v31
	v_and_b32_e32 v30, 0xffff0000, v30
	v_pk_mul_f32 v[30:31], v[54:55], v[30:31]
	v_rcp_f32_e32 v35, v35
	s_nop 0
	v_mul_f32_e32 v35, v61, v35
	s_mov_b64 s[4:5], 0
	v_rcp_f32_e32 v34, v34
	s_nop 0
	v_mul_f32_e32 v34, v62, v34
	v_pk_mul_f32 v[30:31], v[34:35], v[30:31]
	v_cvt_pk_bf16_f32 v31, v33, v31
	v_cvt_pk_bf16_f32 v30, v32, v30
	global_store_dwordx4 v[50:51], v[28:31], off
	global_store_dwordx4 v[48:49], v[24:27], off
	global_store_dwordx4 v[46:47], v[20:23], off
	global_store_dwordx4 v[44:45], v[16:19], off
	global_store_dwordx4 v[42:43], v[12:15], off
	global_store_dwordx4 v[40:41], v[8:11], off
	global_store_dwordx4 v[38:39], v[4:7], off
	global_store_dwordx4 v[36:37], v[0:3], off
	s_barrier

; __device__ __forceinline__ float bf2f(u16 h) { return __uint_as_float(((unsigned)h) << 16); }
; __device__ void phase_merge(const Params& p, int layer, char* smem) {
;     ...
;           } else if (r == 47) {
; #pragma unroll
;             for (int m = 0; m < 4; ++m)
; #pragma unroll
;               for (int n = 0; n < 4; ++n)
; #pragma unroll
;                 for (int j = 0; j < 4; ++j) {
;                   mg[m][n][j] += bf2f(GL[((m * 4 + n) * 4 + j) * 256]) * acc[m][n][j];
;                   acc[m][n][j] = 0.f;
;                 }
.LBB0_270:
	s_and_b32 s14, s71, 0xffff
	s_lshl_b64 s[10:11], s[14:15], s10
	v_mul_lo_u32 v1, s72, v235
	s_add_u32 s8, s8, s10
	v_or_b32_e32 v1, v1, v239
	v_mul_lo_u32 v2, s73, v235
	s_addc_u32 s9, s9, s11
	s_lshl_b64 s[6:7], s[6:7], 1
	v_lshlrev_b32_e32 v1, 1, v1
	v_or_b32_e32 v2, v2, v239
	s_add_u32 s6, s8, s6
	v_lshlrev_b32_e32 v2, 1, v2
	global_load_dwordx4 v[76:79], v1, s[4:5]
	v_lshl_add_u32 v1, s72, 7, v1
	s_addc_u32 s7, s9, s7
	global_load_dwordx4 v[80:83], v1, s[4:5]
	v_lshl_add_u32 v1, s73, 7, v2
	global_load_dwordx4 v[88:91], v2, s[6:7]
	global_load_dwordx4 v[96:99], v1, s[6:7]
	s_mul_hi_u32 s4, s68, 0xaaaaaaab
	s_lshr_b32 s4, s4, 5
	s_mul_i32 s4, s4, 48
	s_sub_i32 s8, s68, s4
	s_cmp_gt_i32 s8, 46
	s_cbranch_scc0 .LBB0_273
	ds_read_u16 v164, v234 offset:32768
	ds_read_u16 v165, v234 offset:33280
	ds_read_u16 v166, v234 offset:33792
	ds_read_u16 v167, v234 offset:34304
	ds_read_u16 v168, v234 offset:34816
	ds_read_u16 v169, v234 offset:35328
	ds_read_u16 v170, v234 offset:35840
	ds_read_u16 v171, v234 offset:36352
	ds_read_u16 v172, v234 offset:36864
	ds_read_u16 v173, v234 offset:37376
	ds_read_u16 v174, v234 offset:37888
	ds_read_u16 v175, v234 offset:38400
	ds_read_u16 v176, v234 offset:38912
	ds_read_u16 v177, v234 offset:39424
	s_waitcnt lgkmcnt(13)
	v_lshlrev_b32_e32 v164, 16, v164
	v_fmac_f32_e32 v64, v160, v164
	ds_read_u16 v178, v234 offset:39936
	s_waitcnt lgkmcnt(13)
	v_lshlrev_b32_e32 v165, 16, v165
	v_fmac_f32_e32 v65, v161, v165
	ds_read_u16 v179, v234 offset:40448
	s_waitcnt lgkmcnt(13)
	v_lshlrev_b32_e32 v166, 16, v166
	v_fmac_f32_e32 v66, v162, v166
	ds_read_u16 v180, v234 offset:40960
	s_waitcnt lgkmcnt(13)
	v_lshlrev_b32_e32 v167, 16, v167
	v_fmac_f32_e32 v67, v163, v167
	ds_read_u16 v181, v234 offset:41472
	s_waitcnt lgkmcnt(13)
	v_lshlrev_b32_e32 v168, 16, v168
	v_fmac_f32_e32 v60, v156, v168
	ds_read_u16 v182, v234 offset:41984
	s_waitcnt lgkmcnt(13)
	v_lshlrev_b32_e32 v169, 16, v169
	v_fmac_f32_e32 v61, v157, v169
	ds_read_u16 v183, v234 offset:42496
	s_waitcnt lgkmcnt(13)
	v_lshlrev_b32_e32 v170, 16, v170
	v_fmac_f32_e32 v62, v158, v170
	ds_read_u16 v184, v234 offset:43008
	s_waitcnt lgkmcnt(13)
	v_lshlrev_b32_e32 v171, 16, v171
	v_fmac_f32_e32 v63, v159, v171
	ds_read_u16 v185, v234 offset:43520
	s_waitcnt lgkmcnt(13)
	v_lshlrev_b32_e32 v172, 16, v172
	v_fmac_f32_e32 v56, v152, v172
	ds_read_u16 v186, v234 offset:44032
	s_waitcnt lgkmcnt(13)
	v_lshlrev_b32_e32 v173, 16, v173
	v_fmac_f32_e32 v57, v153, v173
	ds_read_u16 v187, v234 offset:44544
	s_waitcnt lgkmcnt(13)
	v_lshlrev_b32_e32 v174, 16, v174
	v_fmac_f32_e32 v58, v154, v174
	ds_read_u16 v188, v234 offset:45056
	s_waitcnt lgkmcnt(13)
	v_lshlrev_b32_e32 v175, 16, v175
	v_fmac_f32_e32 v59, v155, v175
	ds_read_u16 v189, v234 offset:45568
	s_waitcnt lgkmcnt(13)
	v_lshlrev_b32_e32 v176, 16, v176
	v_fmac_f32_e32 v52, v148, v176
	ds_read_u16 v190, v234 offset:46080
	s_waitcnt lgkmcnt(13)
	v_lshlrev_b32_e32 v177, 16, v177
	v_fmac_f32_e32 v53, v149, v177
	ds_read_u16 v191, v234 offset:46592
	s_waitcnt lgkmcnt(13)
	v_lshlrev_b32_e32 v178, 16, v178
	v_fmac_f32_e32 v54, v150, v178
	ds_read_u16 v192, v234 offset:47104
	s_waitcnt lgkmcnt(13)
	v_lshlrev_b32_e32 v179, 16, v179
	v_fmac_f32_e32 v55, v151, v179
	ds_read_u16 v193, v234 offset:47616
	s_waitcnt lgkmcnt(13)
	v_lshlrev_b32_e32 v180, 16, v180
	v_fmac_f32_e32 v48, v144, v180
	ds_read_u16 v194, v234 offset:48128
	s_waitcnt lgkmcnt(13)
	v_lshlrev_b32_e32 v181, 16, v181
	v_fmac_f32_e32 v49, v145, v181
	ds_read_u16 v195, v234 offset:48640
	s_waitcnt lgkmcnt(13)
	v_lshlrev_b32_e32 v182, 16, v182
	v_fmac_f32_e32 v50, v146, v182
	ds_read_u16 v196, v234 offset:49152
	s_waitcnt lgkmcnt(13)
	v_lshlrev_b32_e32 v183, 16, v183
	v_fmac_f32_e32 v51, v147, v183
	ds_read_u16 v197, v234 offset:49664
	s_waitcnt lgkmcnt(13)
	v_lshlrev_b32_e32 v184, 16, v184
	v_fmac_f32_e32 v44, v140, v184
	ds_read_u16 v198, v234 offset:50176
	s_waitcnt lgkmcnt(13)
	v_lshlrev_b32_e32 v185, 16, v185
	v_fmac_f32_e32 v45, v141, v185
	ds_read_u16 v199, v234 offset:50688
	s_waitcnt lgkmcnt(13)
	v_lshlrev_b32_e32 v186, 16, v186
	v_fmac_f32_e32 v46, v142, v186
	ds_read_u16 v200, v234 offset:51200
	s_waitcnt lgkmcnt(13)
	v_lshlrev_b32_e32 v187, 16, v187
	v_fmac_f32_e32 v47, v143, v187
	ds_read_u16 v201, v234 offset:51712
	s_waitcnt lgkmcnt(13)
	v_lshlrev_b32_e32 v188, 16, v188
	v_fmac_f32_e32 v40, v136, v188
	ds_read_u16 v202, v234 offset:52224
	s_waitcnt lgkmcnt(13)
; __device__ __forceinline__ float bf2f(u16 h) { return __uint_as_float(((unsigned)h) << 16); }
; __device__ void phase_merge(const Params& p, int layer, char* smem) {
;     ...
;           } else if (r == 47) {
; #pragma unroll
;             for (int m = 0; m < 4; ++m)
; #pragma unroll
;               for (int n = 0; n < 4; ++n)
; #pragma unroll
;                 for (int j = 0; j < 4; ++j) {
;                   mg[m][n][j] += bf2f(GL[((m * 4 + n) * 4 + j) * 256]) * acc[m][n][j];
;                   acc[m][n][j] = 0.f;
;                 }
	v_lshlrev_b32_e32 v189, 16, v189
	v_fmac_f32_e32 v41, v137, v189
	ds_read_u16 v203, v234 offset:52736
	s_waitcnt lgkmcnt(13)
	v_lshlrev_b32_e32 v190, 16, v190
	v_fmac_f32_e32 v42, v138, v190
	ds_read_u16 v204, v234 offset:53248
	s_waitcnt lgkmcnt(13)
	v_lshlrev_b32_e32 v191, 16, v191
	v_fmac_f32_e32 v43, v139, v191
	ds_read_u16 v205, v234 offset:53760
	s_waitcnt lgkmcnt(13)
	v_lshlrev_b32_e32 v192, 16, v192
	v_fmac_f32_e32 v36, v132, v192
	ds_read_u16 v206, v234 offset:54272
	s_waitcnt lgkmcnt(13)
	v_lshlrev_b32_e32 v193, 16, v193
	v_fmac_f32_e32 v37, v133, v193
	ds_read_u16 v207, v234 offset:54784
	s_waitcnt lgkmcnt(13)
	v_lshlrev_b32_e32 v194, 16, v194
	v_fmac_f32_e32 v38, v134, v194
	ds_read_u16 v208, v234 offset:55296
	s_waitcnt lgkmcnt(13)
	v_lshlrev_b32_e32 v195, 16, v195
	v_fmac_f32_e32 v39, v135, v195
	ds_read_u16 v209, v234 offset:55808
	s_waitcnt lgkmcnt(13)
	v_lshlrev_b32_e32 v196, 16, v196
	v_fmac_f32_e32 v32, v128, v196
	ds_read_u16 v210, v234 offset:56320
	s_waitcnt lgkmcnt(13)
	v_lshlrev_b32_e32 v197, 16, v197
	v_fmac_f32_e32 v33, v129, v197
	ds_read_u16 v211, v234 offset:56832
	s_waitcnt lgkmcnt(13)
	v_lshlrev_b32_e32 v198, 16, v198
	v_fmac_f32_e32 v34, v130, v198
	ds_read_u16 v212, v234 offset:57344
	s_waitcnt lgkmcnt(13)
	v_lshlrev_b32_e32 v199, 16, v199
	v_fmac_f32_e32 v35, v131, v199
	ds_read_u16 v213, v234 offset:57856
	s_waitcnt lgkmcnt(13)
	v_lshlrev_b32_e32 v200, 16, v200
	v_fmac_f32_e32 v28, v124, v200
	ds_read_u16 v214, v234 offset:58368
	s_waitcnt lgkmcnt(13)
	v_lshlrev_b32_e32 v201, 16, v201
	v_fmac_f32_e32 v29, v125, v201
	ds_read_u16 v215, v234 offset:58880
	s_waitcnt lgkmcnt(13)
	v_lshlrev_b32_e32 v202, 16, v202
	v_fmac_f32_e32 v30, v126, v202
	ds_read_u16 v216, v234 offset:59392
	s_waitcnt lgkmcnt(13)
	v_lshlrev_b32_e32 v203, 16, v203
	v_fmac_f32_e32 v31, v127, v203
	ds_read_u16 v217, v234 offset:59904
	s_waitcnt lgkmcnt(13)
	v_lshlrev_b32_e32 v204, 16, v204
	v_fmac_f32_e32 v24, v120, v204
	ds_read_u16 v218, v234 offset:60416
	s_waitcnt lgkmcnt(13)
	v_lshlrev_b32_e32 v205, 16, v205
	v_fmac_f32_e32 v25, v121, v205
	ds_read_u16 v219, v234 offset:60928
	s_waitcnt lgkmcnt(13)
	v_lshlrev_b32_e32 v206, 16, v206
	v_fmac_f32_e32 v26, v122, v206
	ds_read_u16 v220, v234 offset:61440
	s_waitcnt lgkmcnt(13)
	v_lshlrev_b32_e32 v207, 16, v207
	v_fmac_f32_e32 v27, v123, v207
	ds_read_u16 v221, v234 offset:61952
	s_waitcnt lgkmcnt(13)
	v_lshlrev_b32_e32 v208, 16, v208
	v_fmac_f32_e32 v20, v116, v208
	ds_read_u16 v222, v234 offset:62464
	s_waitcnt lgkmcnt(13)
	v_lshlrev_b32_e32 v209, 16, v209
	v_fmac_f32_e32 v21, v117, v209
	ds_read_u16 v223, v234 offset:62976
	s_waitcnt lgkmcnt(13)
	v_lshlrev_b32_e32 v210, 16, v210
	v_fmac_f32_e32 v22, v118, v210
	ds_read_u16 v224, v234 offset:63488
	s_waitcnt lgkmcnt(13)
	v_lshlrev_b32_e32 v211, 16, v211
	v_fmac_f32_e32 v23, v119, v211
	ds_read_u16 v225, v234 offset:64000
	s_waitcnt lgkmcnt(13)
	v_lshlrev_b32_e32 v212, 16, v212
	v_fmac_f32_e32 v16, v112, v212
	ds_read_u16 v226, v234 offset:64512
	s_waitcnt lgkmcnt(13)
	v_lshlrev_b32_e32 v213, 16, v213
	v_fmac_f32_e32 v17, v113, v213
	ds_read_u16 v227, v234 offset:65024
	s_waitcnt lgkmcnt(13)
	v_lshlrev_b32_e32 v214, 16, v214
	v_fmac_f32_e32 v18, v114, v214
	s_waitcnt lgkmcnt(12)
	v_lshlrev_b32_e32 v215, 16, v215
	v_fmac_f32_e32 v19, v115, v215
	s_waitcnt lgkmcnt(11)
	v_lshlrev_b32_e32 v216, 16, v216
	v_fmac_f32_e32 v12, v108, v216
	s_waitcnt lgkmcnt(10)
	v_lshlrev_b32_e32 v217, 16, v217
	v_fmac_f32_e32 v13, v109, v217
	s_waitcnt lgkmcnt(9)
	v_lshlrev_b32_e32 v218, 16, v218
	v_fmac_f32_e32 v14, v110, v218
	s_waitcnt lgkmcnt(8)
	v_lshlrev_b32_e32 v219, 16, v219
	v_fmac_f32_e32 v15, v111, v219
	s_waitcnt lgkmcnt(7)
	v_lshlrev_b32_e32 v220, 16, v220
	v_fmac_f32_e32 v8, v100, v220
	s_waitcnt lgkmcnt(6)
	v_lshlrev_b32_e32 v221, 16, v221
	v_fmac_f32_e32 v9, v101, v221
	s_waitcnt lgkmcnt(5)
	v_lshlrev_b32_e32 v222, 16, v222
	v_fmac_f32_e32 v10, v102, v222
	s_waitcnt lgkmcnt(4)
	v_lshlrev_b32_e32 v223, 16, v223
	v_fmac_f32_e32 v11, v103, v223
	s_waitcnt lgkmcnt(3)
	v_lshlrev_b32_e32 v224, 16, v224
	v_fmac_f32_e32 v4, v104, v224
	s_waitcnt lgkmcnt(2)
	v_lshlrev_b32_e32 v225, 16, v225
	v_fmac_f32_e32 v5, v105, v225
	s_waitcnt lgkmcnt(1)
	v_lshlrev_b32_e32 v226, 16, v226
	v_fmac_f32_e32 v6, v106, v226
	s_waitcnt lgkmcnt(0)
	v_lshlrev_b32_e32 v227, 16, v227
	v_fmac_f32_e32 v7, v107, v227
	v_mov_b32_e32 v1, v0
	v_mov_b32_e32 v2, v0
	s_mov_b64 s[4:5], -1
	s_branch .LBB0_276

; __device__ __forceinline__ float bflo(unsigned w) { return __uint_as_float(w << 16); }
; __device__ __forceinline__ float bfhi(unsigned w) { return __uint_as_float(w & 0xffff0000u); }
; __device__ void gmlp_item(const Params& p, int layer, int b, int n, int g, char* smem) {
;     ...
;   {
;     uint4 raw[8];
; #pragma unroll
;     for (int i = 0; i < 8; ++i) {
;       int q = tid + 256 * i;
;       int st = q & 127, c0 = (q >> 7) * 8;
;       raw[i] = *reinterpret_cast<const uint4*>(P + (t0 + st) * NP + 512 + g * 128 + c0);
;     }
; #pragma unroll
;     for (int i = 0; i < 8; ++i) {
;       int q = tid + 256 * i;
;       int st = q & 127, c0 = (q >> 7) * 8;
;       unsigned w[4] = {raw[i].x, raw[i].y, raw[i].z, raw[i].w};
;       float mu = mu_s[st], rs = rs_s[st];
;       const float4* gp = reinterpret_cast<const float4*>(p.gm_gain + (size_t)layer * 512 + g * 128 + c0);
;       float4 g0 = gp[0], g1 = gp[1];
;       float gg[8] = {g0.x, g0.y, g0.z, g0.w, g1.x, g1.y, g1.z, g1.w};
; #pragma unroll
;       for (int e = 0; e < 8; ++e) {
;         float v = (e & 1) ? bfhi(w[e >> 1]) : bflo(w[e >> 1]);
;         float val = (v - mu) * rs * gg[e];
;         *reinterpret_cast<u16*>(smem + 32768 + (st >> 5) * 8192 + (c0 + e) * 64 + (st & 31) * 2) = f2bf(val);
;       }
;     }
;   }
.LBB0_479:
	s_or_b64 exec, exec, s[14:15]
	v_and_b32_e32 v6, 0x7f, v60
	s_ashr_i32 s14, s16, 31
	s_bfe_u32 s20, s82, 0x20003
	s_waitcnt lgkmcnt(0)
	v_or_b32_e32 v0, s36, v6
	s_add_u32 s21, s28, s16
	v_mul_lo_u32 v128, v0, s66
	v_ashrrev_i32_e32 v34, 4, v60
	s_addc_u32 s50, s29, s14
	v_lshl_add_u64 v[0:1], v[128:129], 1, s[12:13]
	s_lshl_b32 s14, s20, 8
	s_mov_b32 s15, s37
	v_and_b32_e32 v2, -8, v34
	v_lshl_add_u64 v[0:1], v[0:1], 0, s[14:15]
	v_ashrrev_i32_e32 v3, 31, v2
	v_lshl_add_u64 v[4:5], v[2:3], 1, v[0:1]
	s_barrier
	global_load_dwordx4 v[28:31], v[4:5], off offset:1024
	s_lshl_b32 s16, s20, 7
	s_lshl_b32 s14, s20, 9
	s_add_u32 s14, s26, s14
	s_addc_u32 s15, s27, 0
	v_lshl_add_u64 v[4:5], v[2:3], 2, s[14:15]
	global_load_dwordx4 v[62:65], v[4:5], off offset:2048
	global_load_dwordx4 v[66:69], v[4:5], off offset:2064
	v_add_u32_e32 v3, 0x100, v60
	v_ashrrev_i32_e32 v48, 4, v3
	v_add_u32_e32 v4, 0x200, v60
	v_lshlrev_b32_e32 v12, 1, v60
	v_and_b32_e32 v82, -8, v48
	v_add_u32_e32 v5, 0x300, v60
	v_lshlrev_b32_e32 v11, 8, v60
	v_ashrrev_i32_e32 v46, 4, v4
	v_and_b32_e32 v4, 62, v12
	v_ashrrev_i32_e32 v83, 31, v82
	v_ashrrev_i32_e32 v44, 4, v5
	v_and_or_b32 v37, v11, s67, v4
	v_lshl_add_u64 v[4:5], v[82:83], 1, v[0:1]
	global_load_dwordx4 v[24:27], v[4:5], off offset:1024
	v_lshl_add_u64 v[4:5], v[82:83], 2, s[14:15]
	global_load_dwordx4 v[70:73], v[4:5], off offset:2064
	global_load_dwordx4 v[74:77], v[4:5], off offset:2048
	v_lshlrev_b32_e32 v3, 2, v6
	v_or_b32_e32 v6, 0x10000, v3
	v_or_b32_e32 v3, 0x10200, v3
	ds_read_b32 v39, v6
	ds_read_b32 v41, v3
	v_add_u32_e32 v7, 0x400, v60
	v_add_u32_e32 v8, 0x500, v60
	v_add_u32_e32 v9, 0x600, v60
	v_add_u32_e32 v10, 0x700, v60
	v_ashrrev_i32_e32 v42, 4, v7
	v_ashrrev_i32_e32 v40, 4, v8
	v_ashrrev_i32_e32 v38, 4, v9
	v_ashrrev_i32_e32 v36, 4, v10
	v_and_b32_e32 v58, -8, v46
	v_and_b32_e32 v56, -8, v44
	v_and_b32_e32 v54, -8, v42
	v_and_b32_e32 v52, -8, v40
	v_and_b32_e32 v50, -8, v38
	v_and_b32_e32 v32, -8, v36
	v_ashrrev_i32_e32 v59, 31, v58
	v_ashrrev_i32_e32 v57, 31, v56
	v_ashrrev_i32_e32 v55, 31, v54
	v_ashrrev_i32_e32 v53, 31, v52
	v_ashrrev_i32_e32 v51, 31, v50
	v_ashrrev_i32_e32 v33, 31, v32
	v_lshl_add_u32 v43, v2, 6, v37
	v_lshl_add_u64 v[2:3], v[58:59], 1, v[0:1]
	v_lshl_add_u64 v[4:5], v[56:57], 1, v[0:1]
	v_lshl_add_u64 v[6:7], v[54:55], 1, v[0:1]
	v_lshl_add_u64 v[8:9], v[52:53], 1, v[0:1]
	v_lshl_add_u64 v[78:79], v[50:51], 1, v[0:1]
	v_lshl_add_u64 v[0:1], v[32:33], 1, v[0:1]
	global_load_dwordx4 v[20:23], v[2:3], off offset:1024
	global_load_dwordx4 v[16:19], v[4:5], off offset:1024
	global_load_dwordx4 v[12:15], v[6:7], off offset:1024
	s_nop 0
	global_load_dwordx4 v[8:11], v[8:9], off offset:1024
	s_nop 0
	global_load_dwordx4 v[4:7], v[78:79], off offset:1024
	s_nop 0
	global_load_dwordx4 v[0:3], v[0:1], off offset:1024
	v_and_b32_e32 v35, 15, v60
	v_lshlrev_b32_e32 v128, 4, v35
	s_waitcnt vmcnt(11)
	v_lshlrev_b32_e32 v45, 16, v28
	s_waitcnt lgkmcnt(1)
	v_sub_f32_e32 v45, v45, v39
	v_and_b32_e32 v28, 0xffff0000, v28
	s_waitcnt lgkmcnt(0)
	v_mul_f32_e32 v45, v41, v45
	v_sub_f32_e32 v28, v28, v39
	s_waitcnt vmcnt(10)
	v_mul_f32_e32 v45, v45, v62
	v_mul_f32_e32 v28, v41, v28
	v_mul_f32_e32 v28, v28, v63
	v_cvt_pk_bf16_f32 v45, 0, v45
	ds_write_b16_d16_hi v43, v45 offset:32768
	v_cvt_pk_bf16_f32 v28, 0, v28
	ds_write_b16_d16_hi v43, v28 offset:32832
	v_lshlrev_b32_e32 v28, 16, v29
	v_sub_f32_e32 v28, v28, v39
	v_mul_f32_e32 v28, v41, v28
	v_mul_f32_e32 v28, v28, v64
	v_cvt_pk_bf16_f32 v28, 0, v28
	ds_write_b16_d16_hi v43, v28 offset:32896
	v_and_b32_e32 v28, 0xffff0000, v29
	v_sub_f32_e32 v28, v28, v39
	v_mul_f32_e32 v28, v41, v28
	v_mul_f32_e32 v28, v28, v65
	v_cvt_pk_bf16_f32 v28, 0, v28
	ds_write_b16_d16_hi v43, v28 offset:32960
	v_lshlrev_b32_e32 v28, 16, v30
	v_sub_f32_e32 v28, v28, v39
	v_mul_f32_e32 v28, v41, v28
	s_waitcnt vmcnt(9)
	v_mul_f32_e32 v28, v28, v66
	v_cvt_pk_bf16_f32 v28, 0, v28
	ds_write_b16_d16_hi v43, v28 offset:33024
	v_and_b32_e32 v28, 0xffff0000, v30
	v_sub_f32_e32 v28, v28, v39
	v_mul_f32_e32 v28, v41, v28
	v_mul_f32_e32 v28, v28, v67
	v_cvt_pk_bf16_f32 v28, 0, v28
	ds_write_b16_d16_hi v43, v28 offset:33088
	v_lshlrev_b32_e32 v28, 16, v31
	v_sub_f32_e32 v30, v28, v39
	v_lshl_add_u64 v[28:29], v[58:59], 2, s[14:15]
	global_load_dwordx4 v[62:65], v[28:29], off offset:2064
	global_load_dwordx4 v[78:81], v[28:29], off offset:2048
	v_mul_f32_e32 v28, v41, v30
	v_mul_f32_e32 v28, v28, v68
	v_cvt_pk_bf16_f32 v28, 0, v28
	ds_write_b16_d16_hi v43, v28 offset:33152
	v_and_b32_e32 v28, 0xffff0000, v31
	v_sub_f32_e32 v28, v28, v39
	v_mul_f32_e32 v28, v41, v28
	v_mul_f32_e32 v28, v28, v69
	v_cvt_pk_bf16_f32 v28, 0, v28
	v_lshl_or_b32 v29, v34, 6, v159
	v_add_u32_e32 v29, v37, v29
	ds_write_b16_d16_hi v29, v28 offset:32768
	s_waitcnt vmcnt(10)
	v_lshlrev_b32_e32 v28, 16, v24
	v_sub_f32_e32 v28, v28, v39
	v_mul_f32_e32 v28, v41, v28
	v_and_b32_e32 v24, 0xffff0000, v24
	s_waitcnt vmcnt(8)
; __device__ __forceinline__ float bflo(unsigned w) { return __uint_as_float(w << 16); }
; __device__ __forceinline__ float bfhi(unsigned w) { return __uint_as_float(w & 0xffff0000u); }
; __device__ void gmlp_item(const Params& p, int layer, int b, int n, int g, char* smem) {
;     ...
;   {
;     uint4 raw[8];
; #pragma unroll
;     for (int i = 0; i < 8; ++i) {
;       int q = tid + 256 * i;
;       int st = q & 127, c0 = (q >> 7) * 8;
;       raw[i] = *reinterpret_cast<const uint4*>(P + (t0 + st) * NP + 512 + g * 128 + c0);
;     }
; #pragma unroll
;     for (int i = 0; i < 8; ++i) {
;       int q = tid + 256 * i;
;       int st = q & 127, c0 = (q >> 7) * 8;
;       unsigned w[4] = {raw[i].x, raw[i].y, raw[i].z, raw[i].w};
;       float mu = mu_s[st], rs = rs_s[st];
;       const float4* gp = reinterpret_cast<const float4*>(p.gm_gain + (size_t)layer * 512 + g * 128 + c0);
;       float4 g0 = gp[0], g1 = gp[1];
;       float gg[8] = {g0.x, g0.y, g0.z, g0.w, g1.x, g1.y, g1.z, g1.w};
; #pragma unroll
;       for (int e = 0; e < 8; ++e) {
;         float v = (e & 1) ? bfhi(w[e >> 1]) : bflo(w[e >> 1]);
;         float val = (v - mu) * rs * gg[e];
;         *reinterpret_cast<u16*>(smem + 32768 + (st >> 5) * 8192 + (c0 + e) * 64 + (st & 31) * 2) = f2bf(val);
;       }
;     }
;   }
	v_mul_f32_e32 v28, v28, v74
	v_sub_f32_e32 v24, v24, v39
	v_mul_f32_e32 v24, v41, v24
	v_cvt_pk_bf16_f32 v28, 0, v28
	v_lshl_add_u32 v43, v82, 6, v37
	v_mul_f32_e32 v24, v24, v75
	ds_write_b16_d16_hi v43, v28 offset:32768
	v_cvt_pk_bf16_f32 v24, 0, v24
	ds_write_b16_d16_hi v43, v24 offset:32832
	v_lshlrev_b32_e32 v24, 16, v25
	v_sub_f32_e32 v24, v24, v39
	v_mul_f32_e32 v24, v41, v24
	v_mul_f32_e32 v24, v24, v76
	v_cvt_pk_bf16_f32 v24, 0, v24
	ds_write_b16_d16_hi v43, v24 offset:32896
	v_and_b32_e32 v24, 0xffff0000, v25
	v_sub_f32_e32 v24, v24, v39
	v_mul_f32_e32 v24, v41, v24
	v_mul_f32_e32 v24, v24, v77
	v_cvt_pk_bf16_f32 v24, 0, v24
	ds_write_b16_d16_hi v43, v24 offset:32960
	v_lshlrev_b32_e32 v24, 16, v26
	v_sub_f32_e32 v24, v24, v39
	v_mul_f32_e32 v24, v41, v24
	v_mul_f32_e32 v24, v24, v70
	v_cvt_pk_bf16_f32 v24, 0, v24
	ds_write_b16_d16_hi v43, v24 offset:33024
	v_and_b32_e32 v24, 0xffff0000, v26
	v_sub_f32_e32 v24, v24, v39
	v_mul_f32_e32 v24, v41, v24
	v_mul_f32_e32 v24, v24, v71
	v_cvt_pk_bf16_f32 v24, 0, v24
	ds_write_b16_d16_hi v43, v24 offset:33088
	v_lshlrev_b32_e32 v24, 16, v27
	v_sub_f32_e32 v26, v24, v39
	v_lshl_add_u64 v[24:25], v[56:57], 2, s[14:15]
	global_load_dwordx4 v[28:31], v[24:25], off offset:2064
	global_load_dwordx4 v[66:69], v[24:25], off offset:2048
	v_mul_f32_e32 v24, v41, v26
	v_mul_f32_e32 v24, v24, v72
	v_cvt_pk_bf16_f32 v24, 0, v24
	ds_write_b16_d16_hi v43, v24 offset:33152
	v_and_b32_e32 v24, 0xffff0000, v27
	v_sub_f32_e32 v24, v24, v39
	v_mul_f32_e32 v24, v41, v24
	v_mul_f32_e32 v24, v24, v73
	v_cvt_pk_bf16_f32 v24, 0, v24
	v_lshl_or_b32 v25, v48, 6, v159
	v_add_u32_e32 v25, v37, v25
	ds_write_b16_d16_hi v25, v24 offset:32768
	s_waitcnt vmcnt(9)
	v_lshlrev_b32_e32 v24, 16, v20
	v_sub_f32_e32 v24, v24, v39
	v_mul_f32_e32 v24, v41, v24
	v_and_b32_e32 v20, 0xffff0000, v20
	s_waitcnt vmcnt(2)
	v_mul_f32_e32 v24, v24, v78
	v_sub_f32_e32 v20, v20, v39
	v_mul_f32_e32 v20, v41, v20
	v_cvt_pk_bf16_f32 v24, 0, v24
	v_lshl_add_u32 v43, v58, 6, v37
	v_mul_f32_e32 v20, v20, v79
	ds_write_b16_d16_hi v43, v24 offset:32768
	v_cvt_pk_bf16_f32 v20, 0, v20
	ds_write_b16_d16_hi v43, v20 offset:32832
	v_lshlrev_b32_e32 v20, 16, v21
	v_sub_f32_e32 v20, v20, v39
	v_mul_f32_e32 v20, v41, v20
	v_mul_f32_e32 v20, v20, v80
	v_cvt_pk_bf16_f32 v20, 0, v20
	ds_write_b16_d16_hi v43, v20 offset:32896
	v_and_b32_e32 v20, 0xffff0000, v21
	v_sub_f32_e32 v20, v20, v39
	v_mul_f32_e32 v20, v41, v20
	v_mul_f32_e32 v20, v20, v81
	v_cvt_pk_bf16_f32 v20, 0, v20
	ds_write_b16_d16_hi v43, v20 offset:32960
	v_lshlrev_b32_e32 v20, 16, v22
	v_sub_f32_e32 v20, v20, v39
	v_mul_f32_e32 v20, v41, v20
	v_mul_f32_e32 v20, v20, v62
	v_cvt_pk_bf16_f32 v20, 0, v20
	ds_write_b16_d16_hi v43, v20 offset:33024
	v_and_b32_e32 v20, 0xffff0000, v22
	v_sub_f32_e32 v20, v20, v39
	v_mul_f32_e32 v20, v41, v20
	v_mul_f32_e32 v20, v20, v63
	v_cvt_pk_bf16_f32 v20, 0, v20
	ds_write_b16_d16_hi v43, v20 offset:33088
	v_lshlrev_b32_e32 v20, 16, v23
	v_sub_f32_e32 v22, v20, v39
	v_lshl_add_u64 v[20:21], v[54:55], 2, s[14:15]
	global_load_dwordx4 v[24:27], v[20:21], off offset:2064
	global_load_dwordx4 v[70:73], v[20:21], off offset:2048
	v_mul_f32_e32 v20, v41, v22
	v_mul_f32_e32 v20, v20, v64
	v_cvt_pk_bf16_f32 v20, 0, v20
	ds_write_b16_d16_hi v43, v20 offset:33152
	v_and_b32_e32 v20, 0xffff0000, v23
	v_sub_f32_e32 v20, v20, v39
	v_mul_f32_e32 v20, v41, v20
	v_mul_f32_e32 v20, v20, v65
	v_cvt_pk_bf16_f32 v20, 0, v20
	v_lshl_or_b32 v21, v46, 6, v159
	v_add_u32_e32 v21, v37, v21
	ds_write_b16_d16_hi v21, v20 offset:32768
	v_lshlrev_b32_e32 v20, 16, v16
	v_sub_f32_e32 v20, v20, v39
	v_mul_f32_e32 v20, v41, v20
	v_and_b32_e32 v16, 0xffff0000, v16
	s_waitcnt vmcnt(2)
	v_mul_f32_e32 v20, v20, v66
	v_sub_f32_e32 v16, v16, v39
	v_mul_f32_e32 v16, v41, v16
	v_cvt_pk_bf16_f32 v20, 0, v20
	v_lshl_add_u32 v43, v56, 6, v37
	v_mul_f32_e32 v16, v16, v67
	ds_write_b16_d16_hi v43, v20 offset:32768
	v_cvt_pk_bf16_f32 v16, 0, v16
	ds_write_b16_d16_hi v43, v16 offset:32832
	v_lshlrev_b32_e32 v16, 16, v17
	v_sub_f32_e32 v16, v16, v39
	v_mul_f32_e32 v16, v41, v16
	v_mul_f32_e32 v16, v16, v68
	v_cvt_pk_bf16_f32 v16, 0, v16
	ds_write_b16_d16_hi v43, v16 offset:32896
	v_and_b32_e32 v16, 0xffff0000, v17
	v_sub_f32_e32 v16, v16, v39
	v_mul_f32_e32 v16, v41, v16
	v_mul_f32_e32 v16, v16, v69
	v_cvt_pk_bf16_f32 v16, 0, v16
	ds_write_b16_d16_hi v43, v16 offset:32960
	v_lshlrev_b32_e32 v16, 16, v18
	v_sub_f32_e32 v16, v16, v39
	v_mul_f32_e32 v16, v41, v16
	v_mul_f32_e32 v16, v16, v28
	v_cvt_pk_bf16_f32 v16, 0, v16
	ds_write_b16_d16_hi v43, v16 offset:33024
	v_and_b32_e32 v16, 0xffff0000, v18
	v_sub_f32_e32 v16, v16, v39
	v_mul_f32_e32 v16, v41, v16
	v_mul_f32_e32 v16, v16, v29
	v_cvt_pk_bf16_f32 v16, 0, v16
	ds_write_b16_d16_hi v43, v16 offset:33088
	v_lshlrev_b32_e32 v16, 16, v19
	v_sub_f32_e32 v18, v16, v39
	v_lshl_add_u64 v[16:17], v[52:53], 2, s[14:15]
	global_load_dwordx4 v[20:23], v[16:17], off offset:2064
	global_load_dwordx4 v[56:59], v[16:17], off offset:2048
	v_mul_f32_e32 v16, v41, v18
	v_mul_f32_e32 v16, v16, v30
	v_cvt_pk_bf16_f32 v16, 0, v16
	ds_write_b16_d16_hi v43, v16 offset:33152
	v_and_b32_e32 v16, 0xffff0000, v19
	v_sub_f32_e32 v16, v16, v39
	v_mul_f32_e32 v16, v41, v16
	v_mul_f32_e32 v16, v16, v31
	v_cvt_pk_bf16_f32 v16, 0, v16
	v_lshl_or_b32 v17, v44, 6, v159
	v_add_u32_e32 v17, v37, v17
	ds_write_b16_d16_hi v17, v16 offset:32768
	v_lshlrev_b32_e32 v16, 16, v12
	v_sub_f32_e32 v16, v16, v39
	v_mul_f32_e32 v16, v41, v16
	v_and_b32_e32 v12, 0xffff0000, v12
	s_waitcnt vmcnt(2)
; __device__ __forceinline__ float bflo(unsigned w) { return __uint_as_float(w << 16); }
; __device__ __forceinline__ float bfhi(unsigned w) { return __uint_as_float(w & 0xffff0000u); }
; __device__ void gmlp_item(const Params& p, int layer, int b, int n, int g, char* smem) {
;     ...
; #pragma unroll
;     for (int i = 0; i < 8; ++i) {
;       int q = tid + 256 * i;
;       int st = q & 127, c0 = (q >> 7) * 8;
;       unsigned w[4] = {raw[i].x, raw[i].y, raw[i].z, raw[i].w};
;       float mu = mu_s[st], rs = rs_s[st];
;       const float4* gp = reinterpret_cast<const float4*>(p.gm_gain + (size_t)layer * 512 + g * 128 + c0);
;       float4 g0 = gp[0], g1 = gp[1];
;       float gg[8] = {g0.x, g0.y, g0.z, g0.w, g1.x, g1.y, g1.z, g1.w};
; #pragma unroll
;       for (int e = 0; e < 8; ++e) {
;         float v = (e & 1) ? bfhi(w[e >> 1]) : bflo(w[e >> 1]);
;         float val = (v - mu) * rs * gg[e];
;         *reinterpret_cast<u16*>(smem + 32768 + (st >> 5) * 8192 + (c0 + e) * 64 + (st & 31) * 2) = f2bf(val);
;       }
;     }
	v_mul_f32_e32 v16, v16, v70
	v_sub_f32_e32 v12, v12, v39
	v_mul_f32_e32 v12, v41, v12
	v_cvt_pk_bf16_f32 v16, 0, v16
	v_lshl_add_u32 v43, v54, 6, v37
	v_mul_f32_e32 v12, v12, v71
	ds_write_b16_d16_hi v43, v16 offset:32768
	v_cvt_pk_bf16_f32 v12, 0, v12
	ds_write_b16_d16_hi v43, v12 offset:32832
	v_lshlrev_b32_e32 v12, 16, v13
	v_sub_f32_e32 v12, v12, v39
	v_mul_f32_e32 v12, v41, v12
	v_mul_f32_e32 v12, v12, v72
	v_cvt_pk_bf16_f32 v12, 0, v12
	ds_write_b16_d16_hi v43, v12 offset:32896
	v_and_b32_e32 v12, 0xffff0000, v13
	v_sub_f32_e32 v12, v12, v39
	v_mul_f32_e32 v12, v41, v12
	v_mul_f32_e32 v12, v12, v73
	v_cvt_pk_bf16_f32 v12, 0, v12
	ds_write_b16_d16_hi v43, v12 offset:32960
	v_lshlrev_b32_e32 v12, 16, v14
	v_sub_f32_e32 v12, v12, v39
	v_mul_f32_e32 v12, v41, v12
	v_mul_f32_e32 v12, v12, v24
	v_cvt_pk_bf16_f32 v12, 0, v12
	ds_write_b16_d16_hi v43, v12 offset:33024
	v_and_b32_e32 v12, 0xffff0000, v14
	v_sub_f32_e32 v12, v12, v39
	v_mul_f32_e32 v12, v41, v12
	v_mul_f32_e32 v12, v12, v25
	v_cvt_pk_bf16_f32 v12, 0, v12
	ds_write_b16_d16_hi v43, v12 offset:33088
	v_lshlrev_b32_e32 v12, 16, v15
	v_sub_f32_e32 v14, v12, v39
	v_lshl_add_u64 v[12:13], v[50:51], 2, s[14:15]
	global_load_dwordx4 v[16:19], v[12:13], off offset:2064
	global_load_dwordx4 v[28:31], v[12:13], off offset:2048
	v_mul_f32_e32 v12, v41, v14
	v_mul_f32_e32 v12, v12, v26
	v_cvt_pk_bf16_f32 v12, 0, v12
	ds_write_b16_d16_hi v43, v12 offset:33152
	v_and_b32_e32 v12, 0xffff0000, v15
	v_sub_f32_e32 v12, v12, v39
	v_mul_f32_e32 v12, v41, v12
	v_mul_f32_e32 v12, v12, v27
	v_cvt_pk_bf16_f32 v12, 0, v12
	v_lshl_or_b32 v13, v42, 6, v159
	v_add_u32_e32 v13, v37, v13
	ds_write_b16_d16_hi v13, v12 offset:32768
	v_lshlrev_b32_e32 v12, 16, v8
	v_sub_f32_e32 v12, v12, v39
	v_mul_f32_e32 v12, v41, v12
	v_and_b32_e32 v8, 0xffff0000, v8
	s_waitcnt vmcnt(2)
	v_mul_f32_e32 v12, v12, v56
	v_sub_f32_e32 v8, v8, v39
	v_mul_f32_e32 v8, v41, v8
	v_cvt_pk_bf16_f32 v12, 0, v12
	v_lshl_add_u32 v43, v52, 6, v37
	v_mul_f32_e32 v8, v8, v57
	ds_write_b16_d16_hi v43, v12 offset:32768
	v_cvt_pk_bf16_f32 v8, 0, v8
	ds_write_b16_d16_hi v43, v8 offset:32832
	v_lshlrev_b32_e32 v8, 16, v9
	v_sub_f32_e32 v8, v8, v39
	v_mul_f32_e32 v8, v41, v8
	v_mul_f32_e32 v8, v8, v58
	v_cvt_pk_bf16_f32 v8, 0, v8
	ds_write_b16_d16_hi v43, v8 offset:32896
	v_and_b32_e32 v8, 0xffff0000, v9
	v_sub_f32_e32 v8, v8, v39
	v_mul_f32_e32 v8, v41, v8
	v_mul_f32_e32 v8, v8, v59
	v_cvt_pk_bf16_f32 v8, 0, v8
	ds_write_b16_d16_hi v43, v8 offset:32960
	v_lshlrev_b32_e32 v8, 16, v10
	v_sub_f32_e32 v8, v8, v39
	v_mul_f32_e32 v8, v41, v8
	v_mul_f32_e32 v8, v8, v20
	v_cvt_pk_bf16_f32 v8, 0, v8
	ds_write_b16_d16_hi v43, v8 offset:33024
	v_and_b32_e32 v8, 0xffff0000, v10
	v_sub_f32_e32 v8, v8, v39
	v_mul_f32_e32 v8, v41, v8
	v_mul_f32_e32 v8, v8, v21
	v_cvt_pk_bf16_f32 v10, 0, v8
	v_lshl_add_u64 v[8:9], v[32:33], 2, s[14:15]
	global_load_dwordx4 v[12:15], v[8:9], off offset:2064
	global_load_dwordx4 v[24:27], v[8:9], off offset:2048
	v_lshlrev_b32_e32 v8, 16, v11
	v_sub_f32_e32 v8, v8, v39
	v_mul_f32_e32 v8, v41, v8
	v_mul_f32_e32 v8, v8, v22
	v_cvt_pk_bf16_f32 v8, 0, v8
	ds_write_b16_d16_hi v43, v8 offset:33152
	v_and_b32_e32 v8, 0xffff0000, v11
	v_sub_f32_e32 v8, v8, v39
	v_mul_f32_e32 v8, v41, v8
	v_mul_f32_e32 v8, v8, v23
	v_cvt_pk_bf16_f32 v8, 0, v8
	v_lshl_or_b32 v9, v40, 6, v159
	v_add_u32_e32 v9, v37, v9
	ds_write_b16_d16_hi v43, v10 offset:33088
	ds_write_b16_d16_hi v9, v8 offset:32768
	v_lshlrev_b32_e32 v8, 16, v4
	v_sub_f32_e32 v8, v8, v39
	v_mul_f32_e32 v8, v41, v8
	v_and_b32_e32 v4, 0xffff0000, v4
	s_waitcnt vmcnt(2)
	v_mul_f32_e32 v8, v8, v28
	v_sub_f32_e32 v4, v4, v39
	v_mul_f32_e32 v4, v41, v4
	v_cvt_pk_bf16_f32 v8, 0, v8
	v_lshl_add_u32 v9, v50, 6, v37
	v_mul_f32_e32 v4, v4, v29
	ds_write_b16_d16_hi v9, v8 offset:32768
	v_cvt_pk_bf16_f32 v4, 0, v4
	ds_write_b16_d16_hi v9, v4 offset:32832
	v_lshlrev_b32_e32 v4, 16, v5
	v_sub_f32_e32 v4, v4, v39
	v_mul_f32_e32 v4, v41, v4
	v_mul_f32_e32 v4, v4, v30
	v_cvt_pk_bf16_f32 v4, 0, v4
	ds_write_b16_d16_hi v9, v4 offset:32896
	v_and_b32_e32 v4, 0xffff0000, v5
	v_sub_f32_e32 v4, v4, v39
	v_mul_f32_e32 v4, v41, v4
	v_mul_f32_e32 v4, v4, v31
	v_cvt_pk_bf16_f32 v4, 0, v4
	ds_write_b16_d16_hi v9, v4 offset:32960
	v_lshlrev_b32_e32 v4, 16, v6
	v_sub_f32_e32 v4, v4, v39
	v_mul_f32_e32 v4, v41, v4
	v_mul_f32_e32 v4, v4, v16
	v_cvt_pk_bf16_f32 v4, 0, v4
	ds_write_b16_d16_hi v9, v4 offset:33024
	v_and_b32_e32 v4, 0xffff0000, v6
	v_sub_f32_e32 v4, v4, v39
	v_mul_f32_e32 v4, v41, v4
	v_mul_f32_e32 v4, v4, v17
	v_cvt_pk_bf16_f32 v4, 0, v4
	ds_write_b16_d16_hi v9, v4 offset:33088
	v_lshlrev_b32_e32 v4, 16, v7
	v_sub_f32_e32 v4, v4, v39
	v_mul_f32_e32 v4, v41, v4
	v_mul_f32_e32 v4, v4, v18
	v_cvt_pk_bf16_f32 v4, 0, v4
	ds_write_b16_d16_hi v9, v4 offset:33152
	v_and_b32_e32 v4, 0xffff0000, v7
	v_sub_f32_e32 v4, v4, v39
	v_mul_f32_e32 v4, v41, v4
	v_mul_f32_e32 v4, v4, v19
	v_cvt_pk_bf16_f32 v4, 0, v4
	v_lshl_or_b32 v5, v38, 6, v159
	v_add_u32_e32 v5, v37, v5
	ds_write_b16_d16_hi v5, v4 offset:32768
	v_lshlrev_b32_e32 v4, 16, v0
	v_sub_f32_e32 v4, v4, v39
	v_mul_f32_e32 v4, v41, v4
	v_and_b32_e32 v0, 0xffff0000, v0
	s_waitcnt vmcnt(0)
; __device__ __forceinline__ float bflo(unsigned w) { return __uint_as_float(w << 16); }
; __device__ __forceinline__ float bfhi(unsigned w) { return __uint_as_float(w & 0xffff0000u); }
; __device__ void gmlp_item(const Params& p, int layer, int b, int n, int g, char* smem) {
;     ...
; #pragma unroll
;       for (int e = 0; e < 8; ++e) {
;         float v = (e & 1) ? bfhi(w[e >> 1]) : bflo(w[e >> 1]);
;         float val = (v - mu) * rs * gg[e];
;         *reinterpret_cast<u16*>(smem + 32768 + (st >> 5) * 8192 + (c0 + e) * 64 + (st & 31) * 2) = f2bf(val);
;       }
;     }
;   }
; #pragma unroll 2
;   for (int i = 0; i < 8; ++i) {
;     int q = tid + 256 * i;
;     int t = q >> 4, cch = q & 15;
;     uint4 v = *reinterpret_cast<const uint4*>(Ws + (size_t)g * 16384 + t * 128 + cch * 8);
;     *reinterpret_cast<uint4*>(smem + (cch >> 2) * 8192 + t * 64 + (cch & 3) * 16) = v;
;   }
;   __syncthreads();
	v_mul_f32_e32 v4, v4, v24
	v_sub_f32_e32 v0, v0, v39
	v_mul_f32_e32 v0, v41, v0
	v_cvt_pk_bf16_f32 v4, 0, v4
	v_lshl_add_u32 v5, v32, 6, v37
	v_mul_f32_e32 v0, v0, v25
	ds_write_b16_d16_hi v5, v4 offset:32768
	v_cvt_pk_bf16_f32 v0, 0, v0
	ds_write_b16_d16_hi v5, v0 offset:32832
	v_lshlrev_b32_e32 v0, 16, v1
	v_sub_f32_e32 v0, v0, v39
	v_mul_f32_e32 v0, v41, v0
	v_mul_f32_e32 v0, v0, v26
	v_cvt_pk_bf16_f32 v0, 0, v0
	ds_write_b16_d16_hi v5, v0 offset:32896
	v_and_b32_e32 v0, 0xffff0000, v1
	v_sub_f32_e32 v0, v0, v39
	v_mul_f32_e32 v0, v41, v0
	v_mul_f32_e32 v0, v0, v27
	v_cvt_pk_bf16_f32 v0, 0, v0
	ds_write_b16_d16_hi v5, v0 offset:32960
	v_lshlrev_b32_e32 v0, 16, v2
	v_sub_f32_e32 v0, v0, v39
	v_mul_f32_e32 v0, v41, v0
	v_mul_f32_e32 v0, v0, v12
	v_cvt_pk_bf16_f32 v0, 0, v0
	ds_write_b16_d16_hi v5, v0 offset:33024
	v_and_b32_e32 v0, 0xffff0000, v2
	v_sub_f32_e32 v0, v0, v39
	v_mul_f32_e32 v0, v41, v0
	v_mul_f32_e32 v0, v0, v13
	v_cvt_pk_bf16_f32 v0, 0, v0
	ds_write_b16_d16_hi v5, v0 offset:33088
	v_lshlrev_b32_e32 v0, 16, v3
	v_sub_f32_e32 v0, v0, v39
	v_mul_f32_e32 v0, v41, v0
	v_mul_f32_e32 v0, v0, v14
	v_cvt_pk_bf16_f32 v0, 0, v0
	ds_write_b16_d16_hi v5, v0 offset:33152
	v_and_b32_e32 v0, 0xffff0000, v3
	v_sub_f32_e32 v0, v0, v39
	v_mul_f32_e32 v0, v41, v0
	v_mul_f32_e32 v0, v0, v15
	s_lshl_b32 s14, s20, 15
	v_cvt_pk_bf16_f32 v0, 0, v0
	v_lshl_or_b32 v1, v36, 6, v159
	s_add_u32 s14, s21, s14
	v_add_u32_e32 v1, v37, v1
	s_addc_u32 s15, s50, 0
	v_lshlrev_b32_e32 v3, 4, v60
	ds_write_b16_d16_hi v1, v0 offset:32768
	v_lshl_add_u64 v[0:1], s[14:15], 0, v[128:129]
	v_lshlrev_b32_e32 v2, 11, v60
	v_and_b32_e32 v3, 48, v3
	v_lshl_add_u64 v[0:1], v[0:1], 0, s[40:41]
	v_and_or_b32 v2, v2, s67, v3
	s_mov_b32 s14, 0
	v_mov_b32_e32 v120, v60
	v_ashrrev_i32_e32 v104, 4, v120
	v_add_u32_e32 v120, 0x100, v120
	v_ashrrev_i32_e32 v105, 4, v120
	v_lshlrev_b32_e32 v112, 7, v104
	v_lshlrev_b32_e32 v114, 7, v105
	v_ashrrev_i32_e32 v113, 31, v112
	v_ashrrev_i32_e32 v115, 31, v114
	v_lshl_add_u64 v[112:113], v[112:113], 1, v[0:1]
	v_lshl_add_u64 v[114:115], v[114:115], 1, v[0:1]
	global_load_dwordx4 v[72:75], v[112:113], off
	global_load_dwordx4 v[76:79], v[114:115], off
	v_lshl_add_u32 v104, v104, 6, v2
	v_lshl_add_u32 v105, v105, 6, v2
	v_add_u32_e32 v120, 0x200, v60
	v_ashrrev_i32_e32 v106, 4, v120
	v_add_u32_e32 v120, 0x100, v120
	v_ashrrev_i32_e32 v107, 4, v120
	v_lshlrev_b32_e32 v116, 7, v106
	v_lshlrev_b32_e32 v118, 7, v107
	v_ashrrev_i32_e32 v117, 31, v116
	v_ashrrev_i32_e32 v119, 31, v118
	v_lshl_add_u64 v[116:117], v[116:117], 1, v[0:1]
	v_lshl_add_u64 v[118:119], v[118:119], 1, v[0:1]
	global_load_dwordx4 v[80:83], v[116:117], off
	global_load_dwordx4 v[84:87], v[118:119], off
	v_lshl_add_u32 v106, v106, 6, v2
	v_lshl_add_u32 v107, v107, 6, v2
	v_add_u32_e32 v120, 0x400, v60
	v_ashrrev_i32_e32 v108, 4, v120
	v_add_u32_e32 v120, 0x100, v120
	v_ashrrev_i32_e32 v109, 4, v120
	v_lshlrev_b32_e32 v112, 7, v108
	v_lshlrev_b32_e32 v114, 7, v109
	v_ashrrev_i32_e32 v113, 31, v112
	v_ashrrev_i32_e32 v115, 31, v114
	v_lshl_add_u64 v[112:113], v[112:113], 1, v[0:1]
	v_lshl_add_u64 v[114:115], v[114:115], 1, v[0:1]
	global_load_dwordx4 v[88:91], v[112:113], off
	global_load_dwordx4 v[92:95], v[114:115], off
	v_lshl_add_u32 v108, v108, 6, v2
	v_lshl_add_u32 v109, v109, 6, v2
	v_add_u32_e32 v120, 0x600, v60
	v_ashrrev_i32_e32 v110, 4, v120
	v_add_u32_e32 v120, 0x100, v120
	v_ashrrev_i32_e32 v111, 4, v120
	v_lshlrev_b32_e32 v116, 7, v110
	v_lshlrev_b32_e32 v118, 7, v111
	v_ashrrev_i32_e32 v117, 31, v116
	v_ashrrev_i32_e32 v119, 31, v118
	v_lshl_add_u64 v[116:117], v[116:117], 1, v[0:1]
	v_lshl_add_u64 v[118:119], v[118:119], 1, v[0:1]
	global_load_dwordx4 v[96:99], v[116:117], off
	global_load_dwordx4 v[100:103], v[118:119], off
	v_lshl_add_u32 v110, v110, 6, v2
	v_lshl_add_u32 v111, v111, 6, v2
	s_waitcnt vmcnt(7)
	ds_write_b128 v104, v[72:75]
	s_waitcnt vmcnt(6)
	ds_write_b128 v105, v[76:79]
	s_waitcnt vmcnt(5)
	ds_write_b128 v106, v[80:83]
	s_waitcnt vmcnt(4)
	ds_write_b128 v107, v[84:87]
	s_waitcnt vmcnt(3)
	ds_write_b128 v108, v[88:91]
	s_waitcnt vmcnt(2)
	ds_write_b128 v109, v[92:95]
	s_waitcnt vmcnt(1)
	ds_write_b128 v110, v[96:99]
	s_waitcnt vmcnt(0)
	ds_write_b128 v111, v[100:103]
	s_movk_i32 s14, 0x800
	v_bfe_u32 v32, v60, 4, 2
	v_ashrrev_i32_e32 v33, 7, v60
	v_lshlrev_b32_e32 v4, 4, v32
	v_lshlrev_b32_e32 v0, 12, v33
	v_lshlrev_b32_e32 v5, 6, v35
	v_or3_b32 v37, v4, v0, v5
	s_waitcnt lgkmcnt(0)
	s_barrier
; #define MFMA16(a, b, c) __builtin_amdgcn_mfma_f32_16x16x32_bf16(a, b, c, 0, 0, 0)
; __device__ void gmlp_item(const Params& p, int layer, int b, int n, int g, char* smem) {
;     ...
;   f32x4 acc[4][4];
; #pragma unroll
;   for (int m = 0; m < 4; ++m)
; #pragma unroll
;     for (int nn = 0; nn < 4; ++nn) acc[m][nn] = f32x4{0.f, 0.f, 0.f, 0.f};
; #pragma unroll
;   for (int ks = 0; ks < 4; ++ks) {
;     bf16x8 a[4], bb[4];
; #pragma unroll
;     for (int m = 0; m < 4; ++m)
;       a[m] = *reinterpret_cast<const bf16x8*>(smem + ks * 8192 + (wr * 64 + m * 16 + fr) * 64 + fq * 16);
; #pragma unroll
;     for (int nn = 0; nn < 4; ++nn)
;       bb[nn] = *reinterpret_cast<const bf16x8*>(smem + 32768 + ks * 8192 + (wc * 64 + nn * 16 + fr) * 64 + fq * 16);
; #pragma unroll
;     for (int m = 0; m < 4; ++m)
; #pragma unroll
;       for (int nn = 0; nn < 4; ++nn) acc[m][nn] = MFMA16(a[m], bb[nn], acc[m][nn]);
;   }
;   __syncthreads();
;   {
;     float* Tf = reinterpret_cast<float*>(smem);
; #pragma unroll
;     for (int m = 0; m < 4; ++m)
; #pragma unroll
;       for (int j = 0; j < 4; ++j) {
;         int t = wr * 64 + m * 16 + fq * 4 + j;
;         float bias = p.gm_b_s[(size_t)layer * 512 + g * 128 + t];
	ds_read_b128 v[0:3], v37
	v_bfe_u32 v39, v60, 6, 1
	v_lshlrev_b32_e32 v6, 12, v39
	v_or3_b32 v41, v4, v6, v5
	ds_read_b128 v[4:7], v41 offset:32768
	ds_read_b128 v[8:11], v37 offset:1024
	ds_read_b128 v[12:15], v41 offset:33792
	ds_read_b128 v[24:27], v41 offset:34816
	ds_read_b128 v[28:31], v41 offset:35840
	s_waitcnt lgkmcnt(4)
	v_mfma_f32_16x16x32_bf16 v[16:19], v[0:3], v[4:7], 0
	s_ashr_i32 s15, s17, 31
	s_add_u32 s14, s28, s17
	s_addc_u32 s15, s29, s15
	s_waitcnt lgkmcnt(2)
	v_mfma_f32_16x16x32_bf16 v[20:23], v[0:3], v[12:15], 0
	v_lshlrev_b32_e32 v33, 6, v33
	s_lshl_b32 s17, s16, 2
	v_lshl_or_b32 v32, v32, 2, v33
	s_waitcnt lgkmcnt(1)
	v_mfma_f32_16x16x32_bf16 v[50:53], v[0:3], v[24:27], 0
	s_add_u32 s20, s24, s17
	s_addc_u32 s21, s25, 0
	v_ashrrev_i32_e32 v33, 31, v32
	s_waitcnt lgkmcnt(0)
	v_mfma_f32_16x16x32_bf16 v[54:57], v[0:3], v[28:31], 0
	ds_read_b128 v[0:3], v37 offset:2048
	ds_read_b128 v[74:77], v37 offset:3072
	ds_read_b128 v[98:101], v37 offset:8192
	v_lshl_add_u64 v[58:59], v[32:33], 2, s[20:21]
	v_mfma_f32_16x16x32_bf16 v[62:65], v[8:11], v[4:7], 0
	v_lshlrev_b32_e32 v33, 2, v35
	v_lshl_or_b32 v126, v39, 8, v33
	v_mad_u64_u32 v[32:33], s[20:21], v32, s69, v[126:127]
	v_mfma_f32_16x16x32_bf16 v[66:69], v[8:11], v[12:15], 0
	v_add_u32_e32 v33, 0x400, v32
	v_ashrrev_i32_e32 v49, 31, v48
	v_ashrrev_i32_e32 v47, 31, v46
	v_mfma_f32_16x16x32_bf16 v[70:73], v[8:11], v[24:27], 0
	v_ashrrev_i32_e32 v45, 31, v44
	v_ashrrev_i32_e32 v43, 31, v42
	v_ashrrev_i32_e32 v39, 31, v38
	v_mfma_f32_16x16x32_bf16 v[8:11], v[8:11], v[28:31], 0
	s_waitcnt lgkmcnt(2)
	v_mfma_f32_16x16x32_bf16 v[78:81], v[0:3], v[4:7], 0
	v_mfma_f32_16x16x32_bf16 v[82:85], v[0:3], v[12:15], 0
	v_mfma_f32_16x16x32_bf16 v[86:89], v[0:3], v[24:27], 0
	v_mfma_f32_16x16x32_bf16 v[90:93], v[0:3], v[28:31], 0
	s_waitcnt lgkmcnt(1)
	v_mfma_f32_16x16x32_bf16 v[94:97], v[74:77], v[4:7], 0
	v_mfma_f32_16x16x32_bf16 v[12:15], v[74:77], v[12:15], 0
	v_mfma_f32_16x16x32_bf16 v[24:27], v[74:77], v[24:27], 0
	v_mfma_f32_16x16x32_bf16 v[0:3], v[74:77], v[28:31], 0
	ds_read_b128 v[28:31], v41 offset:40960
	ds_read_b128 v[74:77], v37 offset:9216
	ds_read_b128 v[102:105], v41 offset:41984
	ds_read_b128 v[106:109], v41 offset:43008
	ds_read_b128 v[4:7], v41 offset:44032
	s_waitcnt lgkmcnt(4)
	v_mfma_f32_16x16x32_bf16 v[16:19], v[98:101], v[28:31], v[16:19]
	s_waitcnt lgkmcnt(2)
	v_mfma_f32_16x16x32_bf16 v[20:23], v[98:101], v[102:105], v[20:23]
	s_waitcnt lgkmcnt(1)
	v_mfma_f32_16x16x32_bf16 v[50:53], v[98:101], v[106:109], v[50:53]
	s_waitcnt lgkmcnt(0)
	v_mfma_f32_16x16x32_bf16 v[54:57], v[98:101], v[4:7], v[54:57]
	ds_read_b128 v[98:101], v37 offset:10240
	v_mfma_f32_16x16x32_bf16 v[62:65], v[74:77], v[28:31], v[62:65]
	v_mfma_f32_16x16x32_bf16 v[66:69], v[74:77], v[102:105], v[66:69]
	v_mfma_f32_16x16x32_bf16 v[70:73], v[74:77], v[106:109], v[70:73]
	v_mfma_f32_16x16x32_bf16 v[8:11], v[74:77], v[4:7], v[8:11]
	ds_read_b128 v[74:77], v37 offset:11264
	ds_read_b128 v[110:113], v37 offset:16384
	ds_read_b128 v[114:117], v37 offset:17408
	ds_read_b128 v[118:121], v37 offset:18432
	ds_read_b128 v[122:125], v37 offset:19456
	ds_read_b128 v[134:137], v41 offset:49152
	ds_read_b128 v[138:141], v41 offset:50176
	ds_read_b128 v[146:149], v41 offset:51200
	ds_read_b128 v[150:153], v41 offset:52224
	ds_read_b128 v[162:165], v37 offset:24576
	ds_read_b128 v[166:169], v37 offset:25600
	s_waitcnt lgkmcnt(11)
	v_mfma_f32_16x16x32_bf16 v[78:81], v[98:101], v[28:31], v[78:81]
	v_mfma_f32_16x16x32_bf16 v[82:85], v[98:101], v[102:105], v[82:85]
	v_mfma_f32_16x16x32_bf16 v[86:89], v[98:101], v[106:109], v[86:89]
	v_mfma_f32_16x16x32_bf16 v[90:93], v[98:101], v[4:7], v[90:93]
	ds_read_b128 v[98:101], v37 offset:26624
	ds_read_b128 v[170:173], v37 offset:27648
	ds_read_b128 v[174:177], v41 offset:57344
	ds_read_b128 v[178:181], v41 offset:58368
	s_waitcnt lgkmcnt(14)
	v_mfma_f32_16x16x32_bf16 v[28:31], v[74:77], v[28:31], v[94:97]
	s_nop 2
	ds_read_b128 v[94:97], v41 offset:59392
	ds_read_b128 v[182:185], v41 offset:60416
	s_waitcnt lgkmcnt(0)
	s_barrier
	v_mfma_f32_16x16x32_bf16 v[16:19], v[110:113], v[134:137], v[16:19]
	global_load_dwordx4 v[186:189], v[58:59], off offset:2112
	global_load_dwordx4 v[190:193], v[58:59], off offset:2176
	v_mfma_f32_16x16x32_bf16 v[20:23], v[110:113], v[138:141], v[20:23]
	v_ashrrev_i32_e32 v41, 31, v40
	v_mfma_f32_16x16x32_bf16 v[50:53], v[110:113], v[146:149], v[50:53]
	v_mfma_f32_16x16x32_bf16 v[54:57], v[110:113], v[150:153], v[54:57]
	global_load_dwordx4 v[110:113], v[58:59], off offset:2048
	v_mfma_f32_16x16x32_bf16 v[16:19], v[162:165], v[174:177], v[16:19]
	v_mfma_f32_16x16x32_bf16 v[20:23], v[162:165], v[178:181], v[20:23]
	v_mfma_f32_16x16x32_bf16 v[50:53], v[162:165], v[94:97], v[50:53]
	s_waitcnt vmcnt(0)
; __device__ void gmlp_item(const Params& p, int layer, int b, int n, int g, char* smem) {
;     ...
;   __syncthreads();
;   {
;     float* Tf = reinterpret_cast<float*>(smem);
; #pragma unroll
;     for (int m = 0; m < 4; ++m)
; #pragma unroll
;       for (int j = 0; j < 4; ++j) {
;         int t = wr * 64 + m * 16 + fq * 4 + j;
;         float bias = p.gm_b_s[(size_t)layer * 512 + g * 128 + t];
; #pragma unroll
;         for (int nn = 0; nn < 4; ++nn) Tf[t * 132 + wc * 64 + nn * 16 + fr] = acc[m][nn][j] + bias;
;       }
;     __syncthreads();
	s_nop 4
	v_add_f32_e32 v16, v16, v110
	v_mfma_f32_16x16x32_bf16 v[54:57], v[162:165], v[182:185], v[54:57]
	v_add_f32_e32 v20, v20, v110
	ds_write2_b32 v32, v16, v20 offset1:16
	v_add_f32_e32 v16, v50, v110
	v_add_f32_e32 v35, v53, v113
	v_mfma_f32_16x16x32_bf16 v[62:65], v[114:117], v[134:137], v[62:65]
	s_nop 2
	v_add_f32_e32 v20, v54, v110
	ds_write2_b32 v32, v16, v20 offset0:32 offset1:48
	v_add_f32_e32 v16, v17, v111
	v_add_f32_e32 v17, v21, v111
	ds_write2_b32 v32, v16, v17 offset0:132 offset1:148
	v_add_f32_e32 v16, v51, v111
	v_add_f32_e32 v17, v55, v111
	ds_write2_b32 v32, v16, v17 offset0:164 offset1:180
	v_add_f32_e32 v16, v18, v112
	v_add_f32_e32 v17, v22, v112
	ds_write2_b32 v33, v16, v17 offset0:8 offset1:24
	v_add_f32_e32 v16, v52, v112
	global_load_dwordx4 v[50:53], v[58:59], off offset:2240
	v_mfma_f32_16x16x32_bf16 v[66:69], v[114:117], v[138:141], v[66:69]
	v_add_f32_e32 v17, v56, v112
	v_add_f32_e32 v20, v19, v113
	v_add_f32_e32 v21, v23, v113
	v_mfma_f32_16x16x32_bf16 v[70:73], v[114:117], v[146:149], v[70:73]
	ds_write2_b32 v33, v16, v17 offset0:40 offset1:56
	ds_write2_b32 v33, v20, v21 offset0:140 offset1:156
	v_add_f32_e32 v37, v57, v113
	v_mfma_f32_16x16x32_bf16 v[8:11], v[114:117], v[150:153], v[8:11]
	ds_write2_b32 v33, v35, v37 offset0:172 offset1:188
	v_add_u32_e32 v33, 0x2000, v32
	v_ashrrev_i32_e32 v35, 31, v34
	v_mfma_f32_16x16x32_bf16 v[16:19], v[166:169], v[174:177], v[62:65]
	v_ashrrev_i32_e32 v37, 31, v36
	v_lshl_add_u64 v[58:59], v[42:43], 0, s[36:37]
	v_mfma_f32_16x16x32_bf16 v[20:23], v[166:169], v[178:181], v[66:69]
	v_mfma_f32_16x16x32_bf16 v[54:57], v[166:169], v[94:97], v[70:73]
	s_nop 3
	v_add_f32_e32 v16, v16, v186
	s_nop 1
	v_add_f32_e32 v20, v20, v186
	ds_write2_b32 v33, v16, v20 offset0:64 offset1:80
	v_mfma_f32_16x16x32_bf16 v[8:11], v[166:169], v[182:185], v[8:11]
	v_add_u32_e32 v20, 0x2400, v32
	v_add_f32_e32 v16, v54, v186
	v_mfma_f32_16x16x32_bf16 v[62:65], v[118:121], v[134:137], v[78:81]
	v_mfma_f32_16x16x32_bf16 v[66:69], v[118:121], v[138:141], v[82:85]
	s_nop 3
	v_add_f32_e32 v8, v8, v186
	ds_write2_b32 v33, v16, v8 offset0:96 offset1:112
	v_add_f32_e32 v8, v17, v187
	v_add_f32_e32 v16, v21, v187
	ds_write2_b32 v33, v8, v16 offset0:196 offset1:212
	v_add_f32_e32 v8, v55, v187
	v_add_f32_e32 v9, v9, v187
	ds_write2_b32 v33, v8, v9 offset0:228 offset1:244
	v_add_f32_e32 v8, v18, v188
	v_add_f32_e32 v9, v22, v188
	v_mfma_f32_16x16x32_bf16 v[70:73], v[118:121], v[146:149], v[86:89]
	ds_write2_b32 v20, v8, v9 offset0:72 offset1:88
	v_add_f32_e32 v8, v56, v188
	v_add_f32_e32 v9, v10, v188
	v_mfma_f32_16x16x32_bf16 v[78:81], v[118:121], v[150:153], v[90:93]
	ds_write2_b32 v20, v8, v9 offset0:104 offset1:120
	v_add_f32_e32 v8, v19, v189
	v_add_f32_e32 v9, v23, v189
	v_mfma_f32_16x16x32_bf16 v[16:19], v[98:101], v[174:177], v[62:65]
	ds_write2_b32 v20, v8, v9 offset0:204 offset1:220
	v_add_f32_e32 v21, v57, v189
	v_add_f32_e32 v22, v11, v189
	v_mfma_f32_16x16x32_bf16 v[8:11], v[98:101], v[178:181], v[66:69]
	ds_write2_b32 v20, v21, v22 offset0:236 offset1:252
	s_nop 2
	v_add_f32_e32 v16, v16, v190
	v_add_u32_e32 v33, 0x4000, v32
	v_mfma_f32_16x16x32_bf16 v[20:23], v[98:101], v[94:97], v[70:73]
	v_lshl_add_u64 v[62:63], v[38:39], 0, s[36:37]
	v_add_f32_e32 v8, v8, v190
	ds_write2_b32 v33, v16, v8 offset0:128 offset1:144
	v_mfma_f32_16x16x32_bf16 v[54:57], v[98:101], v[182:185], v[78:81]
	v_add_f32_e32 v10, v10, v192
	s_nop 2
	v_add_f32_e32 v8, v20, v190
	v_mfma_f32_16x16x32_bf16 v[12:15], v[74:77], v[102:105], v[12:15]
	v_mfma_f32_16x16x32_bf16 v[24:27], v[74:77], v[106:109], v[24:27]
	s_nop 0
	v_add_f32_e32 v16, v54, v190
	ds_write2_b32 v33, v8, v16 offset0:160 offset1:176
	v_add_f32_e32 v8, v17, v191
	v_mfma_f32_16x16x32_bf16 v[0:3], v[74:77], v[4:7], v[0:3]
	v_add_f32_e32 v4, v9, v191
	v_add_u32_e32 v9, 0x4400, v32
	ds_write2_b32 v9, v8, v4 offset0:4 offset1:20
	v_mfma_f32_16x16x32_bf16 v[4:7], v[122:125], v[134:137], v[28:31]
	v_add_f32_e32 v8, v21, v191
	v_add_f32_e32 v16, v55, v191
	ds_write2_b32 v9, v8, v16 offset0:36 offset1:52
	v_mfma_f32_16x16x32_bf16 v[12:15], v[122:125], v[138:141], v[12:15]
	v_add_f32_e32 v8, v18, v192
	ds_write2_b32 v9, v8, v10 offset0:136 offset1:152
	v_add_f32_e32 v8, v22, v192
	v_mfma_f32_16x16x32_bf16 v[24:27], v[122:125], v[146:149], v[24:27]
	v_add_f32_e32 v10, v56, v192
	ds_write2_b32 v9, v8, v10 offset0:168 offset1:184
	v_add_f32_e32 v8, v19, v193
	v_mfma_f32_16x16x32_bf16 v[0:3], v[122:125], v[150:153], v[0:3]
	v_add_f32_e32 v9, v11, v193
	v_add_u32_e32 v16, 0x4800, v32
	ds_write2_b32 v16, v8, v9 offset0:12 offset1:28
	v_mfma_f32_16x16x32_bf16 v[4:7], v[170:173], v[174:177], v[4:7]
	v_add_f32_e32 v17, v23, v193
	v_add_f32_e32 v18, v57, v193
	ds_write2_b32 v16, v17, v18 offset0:44 offset1:60
	v_mfma_f32_16x16x32_bf16 v[8:11], v[170:173], v[178:181], v[12:15]
	v_add_u32_e32 v16, 0x6000, v32
	s_waitcnt vmcnt(0)
	s_nop 1
	v_add_f32_e32 v4, v4, v50
	v_lshl_add_u64 v[56:57], v[36:37], 0, s[36:37]
	v_mfma_f32_16x16x32_bf16 v[12:15], v[170:173], v[94:97], v[24:27]
	v_lshl_add_u64 v[20:21], v[44:45], 0, s[36:37]
	v_add_f32_e32 v8, v8, v50
	ds_write2_b32 v16, v4, v8 offset0:192 offset1:208
	v_mfma_f32_16x16x32_bf16 v[0:3], v[170:173], v[182:185], v[0:3]
	s_nop 3
	v_add_f32_e32 v4, v12, v50
	s_nop 2
	v_add_f32_e32 v0, v0, v50
	ds_write2_b32 v16, v4, v0 offset0:224 offset1:240
	v_add_f32_e32 v0, v5, v51
	v_add_f32_e32 v4, v9, v51
	v_add_u32_e32 v5, 0x6400, v32
	ds_write2_b32 v5, v0, v4 offset0:68 offset1:84
	v_add_f32_e32 v0, v13, v51
	v_add_f32_e32 v1, v1, v51
	ds_write2_b32 v5, v0, v1 offset0:100 offset1:116
	v_add_f32_e32 v0, v6, v52
	v_add_f32_e32 v1, v10, v52
	ds_write2_b32 v5, v0, v1 offset0:200 offset1:216
	v_add_f32_e32 v0, v14, v52
	v_add_f32_e32 v1, v2, v52
	ds_write2_b32 v5, v0, v1 offset0:232 offset1:248
	v_add_f32_e32 v0, v7, v53
	v_add_f32_e32 v1, v11, v53
	v_add_u32_e32 v2, 0x6800, v32
	ds_write2_b32 v2, v0, v1 offset0:76 offset1:92
	v_add_f32_e32 v0, v15, v53
	v_add_f32_e32 v1, v3, v53
	ds_write2_b32 v2, v0, v1 offset0:108 offset1:124
	v_lshlrev_b32_e32 v0, 3, v60
	v_lshl_add_u64 v[8:9], v[34:35], 0, s[36:37]
	v_mov_b64_e32 v[10:11], s[12:13]
	v_and_b32_e32 v24, 0x78, v0
	v_mad_u64_u32 v[0:1], s[12:13], v8, s63, v[10:11]
	v_mad_i32_i24 v1, v9, s63, v1
	s_lshl_b32 s12, s16, 1
	s_mov_b32 s13, s37
	v_lshl_add_u64 v[0:1], v[0:1], 0, s[12:13]
	v_lshlrev_b32_e32 v128, 1, v24
	v_lshl_add_u64 v[12:13], v[48:49], 0, s[36:37]
	v_lshl_add_u64 v[52:53], v[0:1], 0, v[128:129]
	v_mad_u64_u32 v[0:1], s[16:17], v12, s63, v[10:11]
	v_mad_i32_i24 v1, v13, s63, v1
	v_lshl_add_u64 v[0:1], v[0:1], 0, s[12:13]
	v_lshl_add_u64 v[32:33], v[0:1], 0, v[128:129]
	v_mad_u64_u32 v[0:1], s[16:17], v56, s63, v[10:11]
	v_mad_i32_i24 v1, v57, s63, v1
	v_lshl_add_u64 v[0:1], v[0:1], 0, s[12:13]
	v_lshl_add_u64 v[4:5], v[0:1], 0, v[128:129]
	s_waitcnt lgkmcnt(0)
	s_barrier
; __device__ __forceinline__ unsigned pack2(float a, float b) { return (unsigned)f2bf(a) | ((unsigned)f2bf(b) << 16); }
; __device__ __forceinline__ float bflo(unsigned w) { return __uint_as_float(w << 16); }
; __device__ __forceinline__ float bfhi(unsigned w) { return __uint_as_float(w & 0xffff0000u); }
; __device__ __forceinline__ float silu_f(float g) { return g / (1.f + __expf(-g)); }
; __device__ void gmlp_item(const Params& p, int layer, int b, int n, int g, char* smem) {
;     ...
;     uint4 uu[8], gt[8];
; #pragma unroll
;     for (int i = 0; i < 8; ++i) {
;       int q = tid + 256 * i, t = q >> 4, c = (q & 15) * 8;
;       uu[i] = *reinterpret_cast<const uint4*>(P + (t0 + t) * NP + g * 128 + c);
;       gt[i] = *reinterpret_cast<const uint4*>(P + (t0 + t) * NP + 1024 + g * 128 + c);
;     }
; #pragma unroll
;     for (int i = 0; i < 8; ++i) {
;       int q = tid + 256 * i, t = q >> 4, c = (q & 15) * 8;
;       float4 m0 = *reinterpret_cast<const float4*>(Tf + t * 132 + c);
;       float4 m1 = *reinterpret_cast<const float4*>(Tf + t * 132 + c + 4);
;       float mm[8] = {m0.x, m0.y, m0.z, m0.w, m1.x, m1.y, m1.z, m1.w};
;       unsigned uw[4] = {uu[i].x, uu[i].y, uu[i].z, uu[i].w};
;       unsigned gw[4] = {gt[i].x, gt[i].y, gt[i].z, gt[i].w};
;       unsigned ow[4];
; #pragma unroll
;       for (int e = 0; e < 4; ++e) {
;         float y0 = bflo(uw[e]) * mm[2 * e] * silu_f(bflo(gw[e]));
;         float y1 = bfhi(uw[e]) * mm[2 * e + 1] * silu_f(bfhi(gw[e]));
;         ow[e] = pack2(y0, y1);
;       }
;       *reinterpret_cast<uint4*>(Y + (t0 + t) * YW + g * 128 + c) = make_uint4(ow[0], ow[1], ow[2], ow[3]);
	global_load_dwordx4 v[0:3], v[4:5], off
	s_nop 0
	global_load_dwordx4 v[4:7], v[4:5], off offset:2048
	v_lshl_add_u64 v[16:17], v[46:47], 0, s[36:37]
	v_mad_u64_u32 v[14:15], s[16:17], v16, s63, v[10:11]
	v_mad_i32_i24 v15, v17, s63, v15
	v_lshl_add_u64 v[14:15], v[14:15], 0, s[12:13]
	v_lshl_add_u64 v[30:31], v[14:15], 0, v[128:129]
	v_mad_u64_u32 v[14:15], s[16:17], v20, s63, v[10:11]
	v_mad_i32_i24 v15, v21, s63, v15
	v_lshl_add_u64 v[14:15], v[14:15], 0, s[12:13]
	v_lshl_add_u64 v[26:27], v[14:15], 0, v[128:129]
	v_mad_u64_u32 v[14:15], s[16:17], v58, s63, v[10:11]
	v_mad_i32_i24 v15, v59, s63, v15
	v_lshl_add_u64 v[14:15], v[14:15], 0, s[12:13]
	v_lshl_add_u64 v[60:61], v[40:41], 0, s[36:37]
	v_lshl_add_u64 v[22:23], v[14:15], 0, v[128:129]
	v_mad_u64_u32 v[14:15], s[16:17], v60, s63, v[10:11]
	v_mad_u64_u32 v[10:11], s[16:17], v62, s63, v[10:11]
	v_mad_i32_i24 v15, v61, s63, v15
	v_mad_i32_i24 v11, v63, s63, v11
	v_lshl_add_u64 v[14:15], v[14:15], 0, s[12:13]
	v_lshl_add_u64 v[10:11], v[10:11], 0, s[12:13]
	s_add_u32 s12, s14, s12
	s_addc_u32 s13, s15, 0
	v_lshl_add_u64 v[18:19], v[14:15], 0, v[128:129]
	v_lshl_add_u64 v[14:15], v[10:11], 0, v[128:129]
	v_lshlrev_b32_e32 v10, 2, v24
	v_lshl_add_u64 v[24:25], s[12:13], 0, v[128:129]
	v_lshl_add_u64 v[64:65], v[24:25], 0, s[42:43]
	v_mad_u64_u32 v[54:55], s[12:13], v34, s69, v[10:11]
	v_mad_u64_u32 v[34:35], s[12:13], v48, s69, v[10:11]
	v_mad_u64_u32 v[48:49], s[12:13], v12, s70, v[64:65]
	v_mad_u64_u32 v[28:29], s[12:13], v46, s69, v[10:11]
	v_mad_u64_u32 v[46:47], s[12:13], v16, s70, v[64:65]
	v_mad_u64_u32 v[50:51], s[12:13], v8, s70, v[64:65]
	v_mad_i32_i24 v49, v13, s70, v49
	v_mad_i32_i24 v47, v17, s70, v47
	v_mad_u64_u32 v[24:25], s[12:13], v44, s69, v[10:11]
	v_mad_u64_u32 v[44:45], s[12:13], v20, s70, v[64:65]
	v_mad_u64_u32 v[16:17], s[12:13], v40, s69, v[10:11]
	v_mad_u64_u32 v[12:13], s[12:13], v38, s69, v[10:11]
	v_mad_i32_i24 v51, v9, s70, v51
	v_mad_i32_i24 v45, v21, s70, v45
	v_mad_u64_u32 v[20:21], s[12:13], v42, s69, v[10:11]
	v_mad_u64_u32 v[8:9], s[12:13], v36, s69, v[10:11]
	v_mad_u64_u32 v[40:41], s[12:13], v60, s70, v[64:65]
	v_mad_i32_i24 v41, v61, s70, v41
	v_mad_u64_u32 v[42:43], s[12:13], v58, s70, v[64:65]
	v_mad_u64_u32 v[36:37], s[12:13], v56, s70, v[64:65]
	v_mad_i32_i24 v43, v59, s70, v43
	v_mad_i32_i24 v37, v57, s70, v37
	v_mad_u64_u32 v[38:39], s[12:13], v62, s70, v[64:65]
	v_mad_i32_i24 v39, v63, s70, v39
	s_waitcnt vmcnt(1)
	v_lshlrev_b32_e32 v63, 16, v1
	s_waitcnt vmcnt(0)
	v_lshlrev_b32_e32 v13, 16, v5
	v_lshlrev_b32_e32 v17, 16, v4
	v_mul_f32_e32 v9, 0xbfb8aa3b, v17
	v_and_b32_e32 v21, 0xffff0000, v5
	v_mul_f32_e32 v5, 0xbfb8aa3b, v13
	v_exp_f32_e32 v60, v9
	v_exp_f32_e32 v61, v5
	ds_read_b128 v[56:59], v8
	ds_read_b128 v[8:11], v8 offset:16
	v_and_b32_e32 v25, 0xffff0000, v4
	v_mul_f32_e32 v4, 0xbfb8aa3b, v25
	v_pk_add_f32 v[60:61], v[60:61], 1.0 op_sel_hi:[1,0]
	s_waitcnt lgkmcnt(1)
	v_mov_b32_e32 v64, v56
	v_exp_f32_e32 v4, v4
	v_lshlrev_b32_e32 v62, 16, v0
	v_mov_b32_e32 v65, v58
	v_rcp_f32_e32 v61, v61
	s_nop 0
	v_mul_f32_e32 v61, v13, v61
	v_and_b32_e32 v1, 0xffff0000, v1
	v_mul_f32_e32 v5, 0xbfb8aa3b, v21
	v_exp_f32_e32 v5, v5
	v_rcp_f32_e32 v60, v60
	s_nop 0
	v_mul_f32_e32 v60, v17, v60
	v_and_b32_e32 v0, 0xffff0000, v0
	v_mov_b32_e32 v58, v57
	v_pk_add_f32 v[4:5], v[4:5], 1.0 op_sel_hi:[1,0]
	v_pk_mul_f32 v[0:1], v[58:59], v[0:1]
	v_pk_mul_f32 v[62:63], v[64:65], v[62:63]
	v_rcp_f32_e32 v5, v5
	s_nop 0
	v_mul_f32_e32 v5, v21, v5
	v_pk_mul_f32 v[60:61], v[60:61], v[62:63]
	v_rcp_f32_e32 v4, v4
	s_nop 0
	v_mul_f32_e32 v4, v25, v4
	v_pk_mul_f32 v[0:1], v[4:5], v[0:1]
	v_lshlrev_b32_e32 v13, 16, v7
	v_lshlrev_b32_e32 v17, 16, v6
	v_cvt_pk_bf16_f32 v1, v61, v1
	v_cvt_pk_bf16_f32 v0, v60, v0
	v_mul_f32_e32 v4, 0xbfb8aa3b, v17
	v_mul_f32_e32 v5, 0xbfb8aa3b, v13
	v_exp_f32_e32 v4, v4
	v_exp_f32_e32 v5, v5
	v_and_b32_e32 v25, 0xffff0000, v6
	v_mul_f32_e32 v6, 0xbfb8aa3b, v25
	v_and_b32_e32 v21, 0xffff0000, v7
	v_exp_f32_e32 v60, v6
	v_pk_add_f32 v[64:65], v[4:5], 1.0 op_sel_hi:[1,0]
	global_load_dwordx4 v[4:7], v[14:15], off
	global_load_dwordx4 v[56:59], v[14:15], off offset:2048
	s_waitcnt lgkmcnt(0)
	v_mov_b32_e32 v14, v8
	v_mov_b32_e32 v15, v10
	v_lshlrev_b32_e32 v63, 16, v3
	v_lshlrev_b32_e32 v62, 16, v2
	v_pk_mul_f32 v[14:15], v[14:15], v[62:63]
	v_rcp_f32_e32 v63, v65
	s_nop 0
	v_mul_f32_e32 v63, v13, v63
	v_mul_f32_e32 v10, 0xbfb8aa3b, v21
	v_exp_f32_e32 v61, v10
	v_rcp_f32_e32 v62, v64
	s_nop 0
	v_mul_f32_e32 v62, v17, v62
	v_mov_b32_e32 v10, v9
	v_and_b32_e32 v3, 0xffff0000, v3
	v_pk_add_f32 v[60:61], v[60:61], 1.0 op_sel_hi:[1,0]
	v_and_b32_e32 v2, 0xffff0000, v2
	v_pk_mul_f32 v[2:3], v[10:11], v[2:3]
	v_pk_mul_f32 v[14:15], v[62:63], v[14:15]
	v_rcp_f32_e32 v9, v61
	s_nop 0
	v_mul_f32_e32 v9, v21, v9
	v_rcp_f32_e32 v8, v60
	s_nop 0
	v_mul_f32_e32 v8, v25, v8
	v_pk_mul_f32 v[2:3], v[8:9], v[2:3]
	v_cvt_pk_bf16_f32 v3, v15, v3
	v_cvt_pk_bf16_f32 v2, v14, v2
	s_waitcnt vmcnt(0)
	v_lshlrev_b32_e32 v21, 16, v56
	v_mul_f32_e32 v8, 0xbfb8aa3b, v21
	v_and_b32_e32 v29, 0xffff0000, v56
	v_lshlrev_b32_e32 v17, 16, v57
	v_exp_f32_e32 v60, v8
	v_mul_f32_e32 v8, 0xbfb8aa3b, v29
	v_exp_f32_e32 v56, v8
	v_mul_f32_e32 v8, 0xbfb8aa3b, v17
	v_exp_f32_e32 v61, v8
	ds_read_b128 v[8:11], v12
	ds_read_b128 v[12:15], v12 offset:16
	v_and_b32_e32 v25, 0xffff0000, v57
	v_lshlrev_b32_e32 v63, 16, v5
	v_pk_add_f32 v[60:61], v[60:61], 1.0 op_sel_hi:[1,0]
	s_waitcnt lgkmcnt(1)
; __device__ __forceinline__ unsigned pack2(float a, float b) { return (unsigned)f2bf(a) | ((unsigned)f2bf(b) << 16); }
; __device__ __forceinline__ float bflo(unsigned w) { return __uint_as_float(w << 16); }
; __device__ __forceinline__ float bfhi(unsigned w) { return __uint_as_float(w & 0xffff0000u); }
; __device__ __forceinline__ float silu_f(float g) { return g / (1.f + __expf(-g)); }
; __device__ void gmlp_item(const Params& p, int layer, int b, int n, int g, char* smem) {
;     ...
; #pragma unroll
;     for (int i = 0; i < 8; ++i) {
;       int q = tid + 256 * i, t = q >> 4, c = (q & 15) * 8;
;       float4 m0 = *reinterpret_cast<const float4*>(Tf + t * 132 + c);
;       float4 m1 = *reinterpret_cast<const float4*>(Tf + t * 132 + c + 4);
;       float mm[8] = {m0.x, m0.y, m0.z, m0.w, m1.x, m1.y, m1.z, m1.w};
;       unsigned uw[4] = {uu[i].x, uu[i].y, uu[i].z, uu[i].w};
;       unsigned gw[4] = {gt[i].x, gt[i].y, gt[i].z, gt[i].w};
;       unsigned ow[4];
; #pragma unroll
;       for (int e = 0; e < 4; ++e) {
;         float y0 = bflo(uw[e]) * mm[2 * e] * silu_f(bflo(gw[e]));
;         float y1 = bfhi(uw[e]) * mm[2 * e + 1] * silu_f(bfhi(gw[e]));
;         ow[e] = pack2(y0, y1);
;       }
;       *reinterpret_cast<uint4*>(Y + (t0 + t) * YW + g * 128 + c) = make_uint4(ow[0], ow[1], ow[2], ow[3]);
	v_mov_b32_e32 v64, v8
	v_mov_b32_e32 v65, v10
	v_lshlrev_b32_e32 v62, 16, v4
	v_and_b32_e32 v5, 0xffff0000, v5
	v_rcp_f32_e32 v61, v61
	s_nop 0
	v_mul_f32_e32 v61, v17, v61
	v_and_b32_e32 v4, 0xffff0000, v4
	v_mul_f32_e32 v10, 0xbfb8aa3b, v25
	v_exp_f32_e32 v57, v10
	v_rcp_f32_e32 v60, v60
	s_nop 0
	v_mul_f32_e32 v60, v21, v60
	v_mov_b32_e32 v10, v9
	v_pk_mul_f32 v[4:5], v[10:11], v[4:5]
	v_pk_add_f32 v[56:57], v[56:57], 1.0 op_sel_hi:[1,0]
	v_pk_mul_f32 v[62:63], v[64:65], v[62:63]
	v_pk_mul_f32 v[60:61], v[60:61], v[62:63]
	v_lshlrev_b32_e32 v63, 16, v7
	v_lshlrev_b32_e32 v62, 16, v6
	v_rcp_f32_e32 v9, v57
	s_nop 0
	v_mul_f32_e32 v9, v25, v9
	v_rcp_f32_e32 v8, v56
	s_nop 0
	v_mul_f32_e32 v8, v29, v8
	v_pk_mul_f32 v[4:5], v[8:9], v[4:5]
	v_lshlrev_b32_e32 v17, 16, v59
	v_lshlrev_b32_e32 v21, 16, v58
	v_cvt_pk_bf16_f32 v5, v61, v5
	v_cvt_pk_bf16_f32 v4, v60, v4
	v_mul_f32_e32 v8, 0xbfb8aa3b, v21
	v_mul_f32_e32 v9, 0xbfb8aa3b, v17
	v_exp_f32_e32 v8, v8
	v_exp_f32_e32 v9, v9
	v_and_b32_e32 v29, 0xffff0000, v58
	v_mul_f32_e32 v10, 0xbfb8aa3b, v29
	v_and_b32_e32 v25, 0xffff0000, v59
	v_exp_f32_e32 v60, v10
	v_pk_add_f32 v[64:65], v[8:9], 1.0 op_sel_hi:[1,0]
	global_load_dwordx4 v[8:11], v[18:19], off
	global_load_dwordx4 v[56:59], v[18:19], off offset:2048
	s_waitcnt lgkmcnt(0)
	v_mov_b32_e32 v18, v12
	v_mov_b32_e32 v19, v14
	v_pk_mul_f32 v[18:19], v[18:19], v[62:63]
	v_rcp_f32_e32 v63, v65
	s_nop 0
	v_mul_f32_e32 v63, v17, v63
	v_and_b32_e32 v7, 0xffff0000, v7
	v_mul_f32_e32 v14, 0xbfb8aa3b, v25
	v_exp_f32_e32 v61, v14
	v_rcp_f32_e32 v62, v64
	s_nop 0
	v_mul_f32_e32 v62, v21, v62
	v_mov_b32_e32 v14, v13
	v_and_b32_e32 v6, 0xffff0000, v6
	v_pk_add_f32 v[60:61], v[60:61], 1.0 op_sel_hi:[1,0]
	v_pk_mul_f32 v[6:7], v[14:15], v[6:7]
	v_pk_mul_f32 v[18:19], v[62:63], v[18:19]
	v_rcp_f32_e32 v13, v61
	s_nop 0
	v_mul_f32_e32 v13, v25, v13
	v_rcp_f32_e32 v12, v60
	s_nop 0
	v_mul_f32_e32 v12, v29, v12
	v_pk_mul_f32 v[6:7], v[12:13], v[6:7]
	v_cvt_pk_bf16_f32 v7, v19, v7
	v_cvt_pk_bf16_f32 v6, v18, v6
	s_waitcnt vmcnt(1)
	v_lshlrev_b32_e32 v63, 16, v9
	s_waitcnt vmcnt(0)
	v_lshlrev_b32_e32 v25, 16, v56
	v_mul_f32_e32 v12, 0xbfb8aa3b, v25
	v_and_b32_e32 v35, 0xffff0000, v56
	v_lshlrev_b32_e32 v21, 16, v57
	v_exp_f32_e32 v60, v12
	v_mul_f32_e32 v12, 0xbfb8aa3b, v35
	v_exp_f32_e32 v56, v12
	v_mul_f32_e32 v12, 0xbfb8aa3b, v21
	v_exp_f32_e32 v61, v12
	v_and_b32_e32 v29, 0xffff0000, v57
	ds_read_b128 v[12:15], v16
	ds_read_b128 v[16:19], v16 offset:16
	v_lshlrev_b32_e32 v62, 16, v8
	v_pk_add_f32 v[60:61], v[60:61], 1.0 op_sel_hi:[1,0]
	v_and_b32_e32 v9, 0xffff0000, v9
	s_waitcnt lgkmcnt(1)
	v_mov_b32_e32 v64, v12
	v_mov_b32_e32 v65, v14
	v_pk_mul_f32 v[62:63], v[64:65], v[62:63]
	v_rcp_f32_e32 v61, v61
	s_nop 0
	v_mul_f32_e32 v61, v21, v61
	v_and_b32_e32 v8, 0xffff0000, v8
	v_mul_f32_e32 v14, 0xbfb8aa3b, v29
	v_exp_f32_e32 v57, v14
	v_rcp_f32_e32 v60, v60
	s_nop 0
	v_mul_f32_e32 v60, v25, v60
	v_mov_b32_e32 v14, v13
	v_pk_mul_f32 v[8:9], v[14:15], v[8:9]
	v_pk_add_f32 v[56:57], v[56:57], 1.0 op_sel_hi:[1,0]
	v_pk_mul_f32 v[60:61], v[60:61], v[62:63]
	v_lshlrev_b32_e32 v63, 16, v11
	v_lshlrev_b32_e32 v62, 16, v10
	v_and_b32_e32 v11, 0xffff0000, v11
	v_rcp_f32_e32 v13, v57
	s_nop 0
	v_mul_f32_e32 v13, v29, v13
	v_rcp_f32_e32 v12, v56
	s_nop 0
	v_mul_f32_e32 v12, v35, v12
	v_pk_mul_f32 v[8:9], v[12:13], v[8:9]
	v_lshlrev_b32_e32 v21, 16, v59
	v_lshlrev_b32_e32 v25, 16, v58
	v_cvt_pk_bf16_f32 v9, v61, v9
	v_cvt_pk_bf16_f32 v8, v60, v8
	v_mul_f32_e32 v12, 0xbfb8aa3b, v25
	v_mul_f32_e32 v13, 0xbfb8aa3b, v21
	v_exp_f32_e32 v12, v12
	v_exp_f32_e32 v13, v13
	v_and_b32_e32 v35, 0xffff0000, v58
	v_mul_f32_e32 v14, 0xbfb8aa3b, v35
	v_and_b32_e32 v29, 0xffff0000, v59
	v_exp_f32_e32 v60, v14
	v_pk_add_f32 v[64:65], v[12:13], 1.0 op_sel_hi:[1,0]
	global_load_dwordx4 v[12:15], v[22:23], off
	global_load_dwordx4 v[56:59], v[22:23], off offset:2048
	s_waitcnt lgkmcnt(0)
	v_mov_b32_e32 v22, v16
	v_mov_b32_e32 v23, v18
	v_pk_mul_f32 v[22:23], v[22:23], v[62:63]
	v_rcp_f32_e32 v63, v65
	s_nop 0
	v_mul_f32_e32 v63, v21, v63
	v_and_b32_e32 v10, 0xffff0000, v10
	v_mul_f32_e32 v18, 0xbfb8aa3b, v29
	v_exp_f32_e32 v61, v18
	v_rcp_f32_e32 v62, v64
	s_nop 0
	v_mul_f32_e32 v62, v25, v62
	v_mov_b32_e32 v18, v17
	v_pk_mul_f32 v[10:11], v[18:19], v[10:11]
	v_pk_add_f32 v[60:61], v[60:61], 1.0 op_sel_hi:[1,0]
	v_pk_mul_f32 v[22:23], v[62:63], v[22:23]
	s_waitcnt vmcnt(1)
	v_lshlrev_b32_e32 v63, 16, v13
	v_rcp_f32_e32 v17, v61
	s_nop 0
	v_mul_f32_e32 v17, v29, v17
	v_rcp_f32_e32 v16, v60
	s_nop 0
	v_mul_f32_e32 v16, v35, v16
	v_pk_mul_f32 v[10:11], v[16:17], v[10:11]
	s_waitcnt vmcnt(0)
	v_lshlrev_b32_e32 v29, 16, v56
	v_cvt_pk_bf16_f32 v11, v23, v11
	v_mul_f32_e32 v16, 0xbfb8aa3b, v29
	v_and_b32_e32 v55, 0xffff0000, v56
	v_lshlrev_b32_e32 v25, 16, v57
	v_exp_f32_e32 v60, v16
	v_mul_f32_e32 v16, 0xbfb8aa3b, v55
	v_exp_f32_e32 v56, v16
	v_mul_f32_e32 v16, 0xbfb8aa3b, v25
	v_exp_f32_e32 v61, v16
	s_nop 0
	v_pk_add_f32 v[60:61], v[60:61], 1.0 op_sel_hi:[1,0]
	v_and_b32_e32 v35, 0xffff0000, v57
	v_cvt_pk_bf16_f32 v10, v22, v10
	ds_read_b128 v[16:19], v20
	ds_read_b128 v[20:23], v20 offset:16
	v_lshlrev_b32_e32 v62, 16, v12
	v_and_b32_e32 v13, 0xffff0000, v13
	s_waitcnt lgkmcnt(1)
; __device__ __forceinline__ unsigned pack2(float a, float b) { return (unsigned)f2bf(a) | ((unsigned)f2bf(b) << 16); }
; __device__ __forceinline__ float bflo(unsigned w) { return __uint_as_float(w << 16); }
; __device__ __forceinline__ float bfhi(unsigned w) { return __uint_as_float(w & 0xffff0000u); }
; __device__ __forceinline__ float silu_f(float g) { return g / (1.f + __expf(-g)); }
; __device__ void gmlp_item(const Params& p, int layer, int b, int n, int g, char* smem) {
;     ...
; #pragma unroll
;     for (int i = 0; i < 8; ++i) {
;       int q = tid + 256 * i, t = q >> 4, c = (q & 15) * 8;
;       float4 m0 = *reinterpret_cast<const float4*>(Tf + t * 132 + c);
;       float4 m1 = *reinterpret_cast<const float4*>(Tf + t * 132 + c + 4);
;       float mm[8] = {m0.x, m0.y, m0.z, m0.w, m1.x, m1.y, m1.z, m1.w};
;       unsigned uw[4] = {uu[i].x, uu[i].y, uu[i].z, uu[i].w};
;       unsigned gw[4] = {gt[i].x, gt[i].y, gt[i].z, gt[i].w};
;       unsigned ow[4];
; #pragma unroll
;       for (int e = 0; e < 4; ++e) {
;         float y0 = bflo(uw[e]) * mm[2 * e] * silu_f(bflo(gw[e]));
;         float y1 = bfhi(uw[e]) * mm[2 * e + 1] * silu_f(bfhi(gw[e]));
;         ow[e] = pack2(y0, y1);
;       }
;       *reinterpret_cast<uint4*>(Y + (t0 + t) * YW + g * 128 + c) = make_uint4(ow[0], ow[1], ow[2], ow[3]);
	v_mov_b32_e32 v64, v16
	v_mov_b32_e32 v65, v18
	v_pk_mul_f32 v[62:63], v[64:65], v[62:63]
	v_rcp_f32_e32 v61, v61
	s_nop 0
	v_mul_f32_e32 v61, v25, v61
	v_and_b32_e32 v12, 0xffff0000, v12
	v_mul_f32_e32 v18, 0xbfb8aa3b, v35
	v_exp_f32_e32 v57, v18
	v_rcp_f32_e32 v60, v60
	s_nop 0
	v_mul_f32_e32 v60, v29, v60
	v_mov_b32_e32 v18, v17
	v_pk_mul_f32 v[12:13], v[18:19], v[12:13]
	v_pk_add_f32 v[56:57], v[56:57], 1.0 op_sel_hi:[1,0]
	v_pk_mul_f32 v[60:61], v[60:61], v[62:63]
	v_lshlrev_b32_e32 v63, 16, v15
	v_lshlrev_b32_e32 v62, 16, v14
	v_and_b32_e32 v15, 0xffff0000, v15
	v_rcp_f32_e32 v17, v57
	s_nop 0
	v_mul_f32_e32 v17, v35, v17
	v_rcp_f32_e32 v16, v56
	s_nop 0
	v_mul_f32_e32 v16, v55, v16
	v_pk_mul_f32 v[12:13], v[16:17], v[12:13]
	v_lshlrev_b32_e32 v25, 16, v59
	v_lshlrev_b32_e32 v29, 16, v58
	v_cvt_pk_bf16_f32 v13, v61, v13
	v_cvt_pk_bf16_f32 v12, v60, v12
	v_mul_f32_e32 v16, 0xbfb8aa3b, v29
	v_mul_f32_e32 v17, 0xbfb8aa3b, v25
	v_exp_f32_e32 v16, v16
	v_exp_f32_e32 v17, v17
	v_and_b32_e32 v55, 0xffff0000, v58
	v_mul_f32_e32 v18, 0xbfb8aa3b, v55
	v_and_b32_e32 v35, 0xffff0000, v59
	v_exp_f32_e32 v60, v18
	v_pk_add_f32 v[64:65], v[16:17], 1.0 op_sel_hi:[1,0]
	global_load_dwordx4 v[16:19], v[26:27], off
	global_load_dwordx4 v[56:59], v[26:27], off offset:2048
	s_waitcnt lgkmcnt(0)
	v_mov_b32_e32 v26, v20
	v_mov_b32_e32 v27, v22
	v_pk_mul_f32 v[26:27], v[26:27], v[62:63]
	v_rcp_f32_e32 v63, v65
	s_nop 0
	v_mul_f32_e32 v63, v25, v63
	v_and_b32_e32 v14, 0xffff0000, v14
	v_mul_f32_e32 v22, 0xbfb8aa3b, v35
	v_exp_f32_e32 v61, v22
	v_rcp_f32_e32 v62, v64
	s_nop 0
	v_mul_f32_e32 v62, v29, v62
	v_mov_b32_e32 v22, v21
	v_pk_mul_f32 v[14:15], v[22:23], v[14:15]
	v_pk_add_f32 v[60:61], v[60:61], 1.0 op_sel_hi:[1,0]
	v_pk_mul_f32 v[26:27], v[62:63], v[26:27]
	s_waitcnt vmcnt(1)
	v_lshlrev_b32_e32 v63, 16, v17
	v_rcp_f32_e32 v21, v61
	s_nop 0
	v_mul_f32_e32 v21, v35, v21
	v_rcp_f32_e32 v20, v60
	s_nop 0
	v_mul_f32_e32 v20, v55, v20
	v_pk_mul_f32 v[14:15], v[20:21], v[14:15]
	s_waitcnt vmcnt(0)
	v_lshlrev_b32_e32 v35, 16, v56
	v_cvt_pk_bf16_f32 v15, v27, v15
	v_mul_f32_e32 v20, 0xbfb8aa3b, v35
	v_and_b32_e32 v66, 0xffff0000, v56
	v_lshlrev_b32_e32 v29, 16, v57
	v_exp_f32_e32 v60, v20
	v_mul_f32_e32 v20, 0xbfb8aa3b, v66
	v_exp_f32_e32 v56, v20
	v_mul_f32_e32 v20, 0xbfb8aa3b, v29
	v_exp_f32_e32 v61, v20
	s_nop 0
	v_pk_add_f32 v[60:61], v[60:61], 1.0 op_sel_hi:[1,0]
	v_and_b32_e32 v55, 0xffff0000, v57
	v_cvt_pk_bf16_f32 v14, v26, v14
	ds_read_b128 v[20:23], v24
	ds_read_b128 v[24:27], v24 offset:16
	v_lshlrev_b32_e32 v62, 16, v16
	v_and_b32_e32 v17, 0xffff0000, v17
	s_waitcnt lgkmcnt(1)
	v_mov_b32_e32 v64, v20
	v_mov_b32_e32 v65, v22
	v_pk_mul_f32 v[62:63], v[64:65], v[62:63]
	v_rcp_f32_e32 v61, v61
	s_nop 0
	v_mul_f32_e32 v61, v29, v61
	v_and_b32_e32 v16, 0xffff0000, v16
	v_mul_f32_e32 v22, 0xbfb8aa3b, v55
	v_exp_f32_e32 v57, v22
	v_rcp_f32_e32 v60, v60
	s_nop 0
	v_mul_f32_e32 v60, v35, v60
	v_mov_b32_e32 v22, v21
	v_pk_mul_f32 v[16:17], v[22:23], v[16:17]
	v_pk_add_f32 v[56:57], v[56:57], 1.0 op_sel_hi:[1,0]
	v_pk_mul_f32 v[60:61], v[60:61], v[62:63]
	v_lshlrev_b32_e32 v63, 16, v19
	v_lshlrev_b32_e32 v62, 16, v18
	v_and_b32_e32 v19, 0xffff0000, v19
	v_rcp_f32_e32 v21, v57
	s_nop 0
	v_mul_f32_e32 v21, v55, v21
	v_rcp_f32_e32 v20, v56
	s_nop 0
	v_mul_f32_e32 v20, v66, v20
	v_pk_mul_f32 v[16:17], v[20:21], v[16:17]
	v_lshlrev_b32_e32 v29, 16, v59
	v_lshlrev_b32_e32 v35, 16, v58
	v_cvt_pk_bf16_f32 v17, v61, v17
	v_cvt_pk_bf16_f32 v16, v60, v16
	v_mul_f32_e32 v20, 0xbfb8aa3b, v35
	v_mul_f32_e32 v21, 0xbfb8aa3b, v29
	v_exp_f32_e32 v20, v20
	v_exp_f32_e32 v21, v21
	v_and_b32_e32 v66, 0xffff0000, v58
	v_mul_f32_e32 v22, 0xbfb8aa3b, v66
	v_and_b32_e32 v55, 0xffff0000, v59
	v_exp_f32_e32 v60, v22
	v_pk_add_f32 v[64:65], v[20:21], 1.0 op_sel_hi:[1,0]
	global_load_dwordx4 v[20:23], v[30:31], off
	global_load_dwordx4 v[56:59], v[30:31], off offset:2048
	s_waitcnt lgkmcnt(0)
	v_mov_b32_e32 v30, v24
	v_mov_b32_e32 v31, v26
	v_pk_mul_f32 v[30:31], v[30:31], v[62:63]
	v_rcp_f32_e32 v63, v65
	s_nop 0
	v_mul_f32_e32 v63, v29, v63
	v_and_b32_e32 v18, 0xffff0000, v18
	v_mul_f32_e32 v26, 0xbfb8aa3b, v55
	v_exp_f32_e32 v61, v26
	v_rcp_f32_e32 v62, v64
	s_nop 0
	v_mul_f32_e32 v62, v35, v62
	v_mov_b32_e32 v26, v25
	v_pk_mul_f32 v[18:19], v[26:27], v[18:19]
	v_pk_add_f32 v[60:61], v[60:61], 1.0 op_sel_hi:[1,0]
	v_pk_mul_f32 v[30:31], v[62:63], v[30:31]
	s_waitcnt vmcnt(1)
	v_lshlrev_b32_e32 v63, 16, v21
	v_rcp_f32_e32 v25, v61
	s_nop 0
	v_mul_f32_e32 v25, v55, v25
	v_rcp_f32_e32 v24, v60
	s_nop 0
	v_mul_f32_e32 v24, v66, v24
	v_pk_mul_f32 v[18:19], v[24:25], v[18:19]
	s_waitcnt vmcnt(0)
	v_lshlrev_b32_e32 v55, 16, v56
	v_cvt_pk_bf16_f32 v19, v31, v19
	v_mul_f32_e32 v24, 0xbfb8aa3b, v55
	v_and_b32_e32 v67, 0xffff0000, v56
	v_lshlrev_b32_e32 v35, 16, v57
	v_exp_f32_e32 v60, v24
	v_mul_f32_e32 v24, 0xbfb8aa3b, v67
	v_exp_f32_e32 v56, v24
	v_mul_f32_e32 v24, 0xbfb8aa3b, v35
	v_exp_f32_e32 v61, v24
	s_nop 0
	v_pk_add_f32 v[60:61], v[60:61], 1.0 op_sel_hi:[1,0]
	v_and_b32_e32 v66, 0xffff0000, v57
	v_cvt_pk_bf16_f32 v18, v30, v18
	ds_read_b128 v[24:27], v28
	ds_read_b128 v[28:31], v28 offset:16
	v_lshlrev_b32_e32 v62, 16, v20
	v_and_b32_e32 v21, 0xffff0000, v21
	s_waitcnt lgkmcnt(1)
; __device__ __forceinline__ unsigned pack2(float a, float b) { return (unsigned)f2bf(a) | ((unsigned)f2bf(b) << 16); }
; __device__ __forceinline__ float bflo(unsigned w) { return __uint_as_float(w << 16); }
; __device__ __forceinline__ float bfhi(unsigned w) { return __uint_as_float(w & 0xffff0000u); }
; __device__ __forceinline__ float silu_f(float g) { return g / (1.f + __expf(-g)); }
; __device__ void gmlp_item(const Params& p, int layer, int b, int n, int g, char* smem) {
;     ...
; #pragma unroll
;     for (int i = 0; i < 8; ++i) {
;       int q = tid + 256 * i, t = q >> 4, c = (q & 15) * 8;
;       float4 m0 = *reinterpret_cast<const float4*>(Tf + t * 132 + c);
;       float4 m1 = *reinterpret_cast<const float4*>(Tf + t * 132 + c + 4);
;       float mm[8] = {m0.x, m0.y, m0.z, m0.w, m1.x, m1.y, m1.z, m1.w};
;       unsigned uw[4] = {uu[i].x, uu[i].y, uu[i].z, uu[i].w};
;       unsigned gw[4] = {gt[i].x, gt[i].y, gt[i].z, gt[i].w};
;       unsigned ow[4];
; #pragma unroll
;       for (int e = 0; e < 4; ++e) {
;         float y0 = bflo(uw[e]) * mm[2 * e] * silu_f(bflo(gw[e]));
;         float y1 = bfhi(uw[e]) * mm[2 * e + 1] * silu_f(bfhi(gw[e]));
;         ow[e] = pack2(y0, y1);
;       }
;       *reinterpret_cast<uint4*>(Y + (t0 + t) * YW + g * 128 + c) = make_uint4(ow[0], ow[1], ow[2], ow[3]);
	v_mov_b32_e32 v64, v24
	v_mov_b32_e32 v65, v26
	v_pk_mul_f32 v[62:63], v[64:65], v[62:63]
	v_rcp_f32_e32 v61, v61
	s_nop 0
	v_mul_f32_e32 v61, v35, v61
	v_and_b32_e32 v20, 0xffff0000, v20
	v_mul_f32_e32 v26, 0xbfb8aa3b, v66
	v_exp_f32_e32 v57, v26
	v_rcp_f32_e32 v60, v60
	s_nop 0
	v_mul_f32_e32 v60, v55, v60
	v_mov_b32_e32 v26, v25
	v_pk_mul_f32 v[20:21], v[26:27], v[20:21]
	v_pk_add_f32 v[56:57], v[56:57], 1.0 op_sel_hi:[1,0]
	v_pk_mul_f32 v[60:61], v[60:61], v[62:63]
	v_lshlrev_b32_e32 v63, 16, v23
	v_lshlrev_b32_e32 v62, 16, v22
	v_and_b32_e32 v23, 0xffff0000, v23
	v_rcp_f32_e32 v25, v57
	s_nop 0
	v_mul_f32_e32 v25, v66, v25
	v_rcp_f32_e32 v24, v56
	s_nop 0
	v_mul_f32_e32 v24, v67, v24
	v_pk_mul_f32 v[20:21], v[24:25], v[20:21]
	v_lshlrev_b32_e32 v35, 16, v59
	v_lshlrev_b32_e32 v55, 16, v58
	v_cvt_pk_bf16_f32 v21, v61, v21
	v_cvt_pk_bf16_f32 v20, v60, v20
	v_mul_f32_e32 v24, 0xbfb8aa3b, v55
	v_mul_f32_e32 v25, 0xbfb8aa3b, v35
	v_exp_f32_e32 v24, v24
	v_exp_f32_e32 v25, v25
	v_and_b32_e32 v67, 0xffff0000, v58
	v_mul_f32_e32 v26, 0xbfb8aa3b, v67
	v_and_b32_e32 v66, 0xffff0000, v59
	v_exp_f32_e32 v60, v26
	v_pk_add_f32 v[64:65], v[24:25], 1.0 op_sel_hi:[1,0]
	global_load_dwordx4 v[24:27], v[32:33], off
	global_load_dwordx4 v[56:59], v[32:33], off offset:2048
	s_waitcnt lgkmcnt(0)
	v_mov_b32_e32 v32, v28
	v_mov_b32_e32 v33, v30
	v_pk_mul_f32 v[32:33], v[32:33], v[62:63]
	v_rcp_f32_e32 v63, v65
	s_nop 0
	v_mul_f32_e32 v63, v35, v63
	v_and_b32_e32 v22, 0xffff0000, v22
	v_mul_f32_e32 v30, 0xbfb8aa3b, v66
	v_exp_f32_e32 v61, v30
	v_rcp_f32_e32 v62, v64
	s_nop 0
	v_mul_f32_e32 v62, v55, v62
	v_mov_b32_e32 v30, v29
	v_pk_mul_f32 v[22:23], v[30:31], v[22:23]
	v_pk_add_f32 v[60:61], v[60:61], 1.0 op_sel_hi:[1,0]
	v_pk_mul_f32 v[32:33], v[62:63], v[32:33]
	s_waitcnt vmcnt(1)
	v_lshlrev_b32_e32 v63, 16, v25
	v_rcp_f32_e32 v29, v61
	s_nop 0
	v_mul_f32_e32 v29, v66, v29
	v_rcp_f32_e32 v28, v60
	s_nop 0
	v_mul_f32_e32 v28, v67, v28
	v_pk_mul_f32 v[22:23], v[28:29], v[22:23]
	s_waitcnt vmcnt(0)
	v_lshlrev_b32_e32 v66, 16, v56
	v_cvt_pk_bf16_f32 v23, v33, v23
	v_mul_f32_e32 v28, 0xbfb8aa3b, v66
	v_and_b32_e32 v68, 0xffff0000, v56
	v_lshlrev_b32_e32 v55, 16, v57
	v_exp_f32_e32 v60, v28
	v_mul_f32_e32 v28, 0xbfb8aa3b, v68
	v_exp_f32_e32 v56, v28
	v_mul_f32_e32 v28, 0xbfb8aa3b, v55
	v_exp_f32_e32 v61, v28
	s_nop 0
	v_pk_add_f32 v[60:61], v[60:61], 1.0 op_sel_hi:[1,0]
	v_and_b32_e32 v67, 0xffff0000, v57
	v_cvt_pk_bf16_f32 v22, v32, v22
	ds_read_b128 v[28:31], v34
	ds_read_b128 v[32:35], v34 offset:16
	v_lshlrev_b32_e32 v62, 16, v24
	v_and_b32_e32 v25, 0xffff0000, v25
	s_waitcnt lgkmcnt(1)
	v_mov_b32_e32 v64, v28
	v_mov_b32_e32 v65, v30
	v_pk_mul_f32 v[62:63], v[64:65], v[62:63]
	v_rcp_f32_e32 v61, v61
	s_nop 0
	v_mul_f32_e32 v61, v55, v61
	v_and_b32_e32 v24, 0xffff0000, v24
	v_mul_f32_e32 v30, 0xbfb8aa3b, v67
	v_exp_f32_e32 v57, v30
	v_rcp_f32_e32 v60, v60
	s_nop 0
	v_mul_f32_e32 v60, v66, v60
	v_mov_b32_e32 v30, v29
	v_pk_mul_f32 v[24:25], v[30:31], v[24:25]
	v_pk_add_f32 v[56:57], v[56:57], 1.0 op_sel_hi:[1,0]
	v_pk_mul_f32 v[60:61], v[60:61], v[62:63]
	v_lshlrev_b32_e32 v66, 16, v58
	v_lshlrev_b32_e32 v63, 16, v27
	v_and_b32_e32 v27, 0xffff0000, v27
	v_rcp_f32_e32 v29, v57
	s_nop 0
	v_mul_f32_e32 v29, v67, v29
	v_rcp_f32_e32 v28, v56
	s_nop 0
	v_mul_f32_e32 v28, v68, v28
	v_pk_mul_f32 v[24:25], v[28:29], v[24:25]
	v_lshlrev_b32_e32 v55, 16, v59
	v_cvt_pk_bf16_f32 v25, v61, v25
	v_cvt_pk_bf16_f32 v24, v60, v24
	v_mul_f32_e32 v28, 0xbfb8aa3b, v66
	v_mul_f32_e32 v29, 0xbfb8aa3b, v55
	v_exp_f32_e32 v28, v28
	v_exp_f32_e32 v29, v29
	v_and_b32_e32 v68, 0xffff0000, v58
	v_mul_f32_e32 v30, 0xbfb8aa3b, v68
	v_and_b32_e32 v67, 0xffff0000, v59
	v_exp_f32_e32 v60, v30
	v_pk_add_f32 v[64:65], v[28:29], 1.0 op_sel_hi:[1,0]
	global_load_dwordx4 v[28:31], v[52:53], off
	global_load_dwordx4 v[56:59], v[52:53], off offset:2048
	s_waitcnt lgkmcnt(0)
; __device__ __forceinline__ unsigned pack2(float a, float b) { return (unsigned)f2bf(a) | ((unsigned)f2bf(b) << 16); }
; __device__ __forceinline__ float bflo(unsigned w) { return __uint_as_float(w << 16); }
; __device__ __forceinline__ float bfhi(unsigned w) { return __uint_as_float(w & 0xffff0000u); }
; __device__ __forceinline__ float silu_f(float g) { return g / (1.f + __expf(-g)); }
; __device__ void gmlp_item(const Params& p, int layer, int b, int n, int g, char* smem) {
;     ...
; #pragma unroll
;     for (int i = 0; i < 8; ++i) {
;       int q = tid + 256 * i, t = q >> 4, c = (q & 15) * 8;
;       float4 m0 = *reinterpret_cast<const float4*>(Tf + t * 132 + c);
;       float4 m1 = *reinterpret_cast<const float4*>(Tf + t * 132 + c + 4);
;       float mm[8] = {m0.x, m0.y, m0.z, m0.w, m1.x, m1.y, m1.z, m1.w};
;       unsigned uw[4] = {uu[i].x, uu[i].y, uu[i].z, uu[i].w};
;       unsigned gw[4] = {gt[i].x, gt[i].y, gt[i].z, gt[i].w};
;       unsigned ow[4];
; #pragma unroll
;       for (int e = 0; e < 4; ++e) {
;         float y0 = bflo(uw[e]) * mm[2 * e] * silu_f(bflo(gw[e]));
;         float y1 = bfhi(uw[e]) * mm[2 * e + 1] * silu_f(bfhi(gw[e]));
;         ow[e] = pack2(y0, y1);
;       }
;       *reinterpret_cast<uint4*>(Y + (t0 + t) * YW + g * 128 + c) = make_uint4(ow[0], ow[1], ow[2], ow[3]);
;     }
;   }
;   __syncthreads();
	v_mov_b32_e32 v52, v32
	v_lshlrev_b32_e32 v62, 16, v26
	v_mov_b32_e32 v53, v34
	v_pk_mul_f32 v[52:53], v[52:53], v[62:63]
	v_rcp_f32_e32 v63, v65
	s_nop 0
	v_mul_f32_e32 v63, v55, v63
	v_and_b32_e32 v26, 0xffff0000, v26
	v_mul_f32_e32 v34, 0xbfb8aa3b, v67
	v_exp_f32_e32 v61, v34
	v_rcp_f32_e32 v62, v64
	s_nop 0
	v_mul_f32_e32 v62, v66, v62
	v_mov_b32_e32 v34, v33
	v_pk_mul_f32 v[26:27], v[34:35], v[26:27]
	v_pk_add_f32 v[60:61], v[60:61], 1.0 op_sel_hi:[1,0]
	v_pk_mul_f32 v[52:53], v[62:63], v[52:53]
	s_waitcnt vmcnt(1)
	v_lshlrev_b32_e32 v63, 16, v29
	v_rcp_f32_e32 v33, v61
	s_nop 0
	v_mul_f32_e32 v33, v67, v33
	v_rcp_f32_e32 v32, v60
	s_nop 0
	v_mul_f32_e32 v32, v68, v32
	v_pk_mul_f32 v[26:27], v[32:33], v[26:27]
	s_waitcnt vmcnt(0)
	v_lshlrev_b32_e32 v67, 16, v56
	v_cvt_pk_bf16_f32 v27, v53, v27
	v_mul_f32_e32 v32, 0xbfb8aa3b, v67
	v_and_b32_e32 v69, 0xffff0000, v56
	v_lshlrev_b32_e32 v66, 16, v57
	v_exp_f32_e32 v60, v32
	v_mul_f32_e32 v32, 0xbfb8aa3b, v69
	v_exp_f32_e32 v56, v32
	v_mul_f32_e32 v32, 0xbfb8aa3b, v66
	v_exp_f32_e32 v61, v32
	s_nop 0
	v_pk_add_f32 v[60:61], v[60:61], 1.0 op_sel_hi:[1,0]
	v_and_b32_e32 v68, 0xffff0000, v57
	v_cvt_pk_bf16_f32 v26, v52, v26
	ds_read_b128 v[32:35], v54
	ds_read_b128 v[52:55], v54 offset:16
	v_lshlrev_b32_e32 v62, 16, v28
	v_and_b32_e32 v29, 0xffff0000, v29
	s_waitcnt lgkmcnt(1)
	v_mov_b32_e32 v64, v32
	v_mov_b32_e32 v65, v34
	v_pk_mul_f32 v[62:63], v[64:65], v[62:63]
	v_rcp_f32_e32 v61, v61
	s_nop 0
	v_mul_f32_e32 v61, v66, v61
	v_and_b32_e32 v28, 0xffff0000, v28
	v_mul_f32_e32 v34, 0xbfb8aa3b, v68
	v_exp_f32_e32 v57, v34
	v_rcp_f32_e32 v60, v60
	s_nop 0
	v_mul_f32_e32 v60, v67, v60
	v_pk_mul_f32 v[60:61], v[60:61], v[62:63]
	v_mov_b32_e32 v34, v33
	v_pk_add_f32 v[56:57], v[56:57], 1.0 op_sel_hi:[1,0]
	v_pk_mul_f32 v[28:29], v[34:35], v[28:29]
	s_nop 0
	v_rcp_f32_e32 v33, v57
	s_nop 0
	v_mul_f32_e32 v33, v68, v33
	v_rcp_f32_e32 v32, v56
	s_nop 0
	v_mul_f32_e32 v32, v69, v32
	v_pk_mul_f32 v[28:29], v[32:33], v[28:29]
	v_cvt_pk_bf16_f32 v28, 0, v28
	v_cvt_pk_bf16_f32 v33, 0, v60
	v_and_b32_e32 v28, 0xffff0000, v28
	v_lshlrev_b32_e32 v35, 16, v59
	v_lshlrev_b32_e32 v60, 16, v58
	v_cvt_pk_bf16_f32 v29, v61, v29
	v_or_b32_sdwa v28, v28, v33 dst_sel:DWORD dst_unused:UNUSED_PAD src0_sel:DWORD src1_sel:WORD_1
	v_mul_f32_e32 v32, 0xbfb8aa3b, v60
	v_mul_f32_e32 v33, 0xbfb8aa3b, v35
	v_exp_f32_e32 v32, v32
	v_exp_f32_e32 v33, v33
	v_and_b32_e32 v62, 0xffff0000, v58
	s_waitcnt lgkmcnt(0)
	v_mov_b32_e32 v58, v52
	v_and_b32_e32 v61, 0xffff0000, v59
	v_pk_add_f32 v[32:33], v[32:33], 1.0 op_sel_hi:[1,0]
	v_lshlrev_b32_e32 v57, 16, v31
	v_lshlrev_b32_e32 v56, 16, v30
	v_mov_b32_e32 v59, v54
	v_pk_mul_f32 v[56:57], v[58:59], v[56:57]
	v_rcp_f32_e32 v33, v33
	s_nop 0
	v_mul_f32_e32 v33, v35, v33
	v_mul_f32_e32 v34, 0xbfb8aa3b, v62
	v_mul_f32_e32 v35, 0xbfb8aa3b, v61
	v_exp_f32_e32 v34, v34
	v_exp_f32_e32 v35, v35
	v_rcp_f32_e32 v32, v32
	s_nop 0
	v_mul_f32_e32 v32, v60, v32
	v_pk_mul_f32 v[32:33], v[32:33], v[56:57]
	v_mov_b32_e32 v54, v53
	v_pk_add_f32 v[34:35], v[34:35], 1.0 op_sel_hi:[1,0]
	v_and_b32_e32 v31, 0xffff0000, v31
	v_and_b32_e32 v30, 0xffff0000, v30
	v_pk_mul_f32 v[30:31], v[54:55], v[30:31]
	v_rcp_f32_e32 v35, v35
	s_nop 0
	v_mul_f32_e32 v35, v61, v35
	s_mov_b64 s[12:13], 0
	v_rcp_f32_e32 v34, v34
	s_nop 0
	v_mul_f32_e32 v34, v62, v34
	v_pk_mul_f32 v[30:31], v[34:35], v[30:31]
	v_cvt_pk_bf16_f32 v31, v33, v31
	v_cvt_pk_bf16_f32 v30, v32, v30
	global_store_dwordx4 v[50:51], v[28:31], off
	global_store_dwordx4 v[48:49], v[24:27], off
	global_store_dwordx4 v[46:47], v[20:23], off
	global_store_dwordx4 v[44:45], v[16:19], off
	global_store_dwordx4 v[42:43], v[12:15], off
	global_store_dwordx4 v[40:41], v[8:11], off
	global_store_dwordx4 v[38:39], v[4:7], off
	global_store_dwordx4 v[36:37], v[0:3], off
	s_barrier

; __device__ __forceinline__ float bf2f(u16 h) { return __uint_as_float(((unsigned)h) << 16); }
; __device__ void phase_merge(const Params& p, int layer, char* smem) {
;     ...
;           } else if (r == 47) {
; #pragma unroll
;             for (int m = 0; m < 4; ++m)
; #pragma unroll
;               for (int n = 0; n < 4; ++n)
; #pragma unroll
;                 for (int j = 0; j < 4; ++j) {
;                   mg[m][n][j] += bf2f(GL[((m * 4 + n) * 4 + j) * 256]) * acc[m][n][j];
;                   acc[m][n][j] = 0.f;
;                 }
;           }
.LBB0_591:
	s_and_b32 s22, s71, 0xffff
	s_lshl_b64 s[20:21], s[22:23], s20
	v_mul_lo_u32 v1, s72, v235
	s_add_u32 s16, s16, s20
	v_or_b32_e32 v1, v1, v239
	v_mul_lo_u32 v2, s73, v235
	s_addc_u32 s17, s17, s21
	s_lshl_b64 s[14:15], s[14:15], 1
	v_lshlrev_b32_e32 v1, 1, v1
	v_or_b32_e32 v2, v2, v239
	s_add_u32 s14, s16, s14
	v_lshlrev_b32_e32 v2, 1, v2
	global_load_dwordx4 v[76:79], v1, s[12:13]
	v_lshl_add_u32 v1, s72, 7, v1
	s_addc_u32 s15, s17, s15
	global_load_dwordx4 v[80:83], v1, s[12:13]
	v_lshl_add_u32 v1, s73, 7, v2
	global_load_dwordx4 v[88:91], v2, s[14:15]
	global_load_dwordx4 v[96:99], v1, s[14:15]
	s_mul_hi_u32 s12, s67, 0xaaaaaaab
	s_lshr_b32 s12, s12, 5
	s_mul_i32 s12, s12, 48
	s_sub_i32 s16, s67, s12
	s_cmp_gt_i32 s16, 46
	s_cbranch_scc0 .LBB0_594
	ds_read_u16 v164, v234 offset:32768
	ds_read_u16 v165, v234 offset:33280
	ds_read_u16 v166, v234 offset:33792
	ds_read_u16 v167, v234 offset:34304
	ds_read_u16 v168, v234 offset:34816
	ds_read_u16 v169, v234 offset:35328
	ds_read_u16 v170, v234 offset:35840
	ds_read_u16 v171, v234 offset:36352
	ds_read_u16 v172, v234 offset:36864
	ds_read_u16 v173, v234 offset:37376
	ds_read_u16 v174, v234 offset:37888
	ds_read_u16 v175, v234 offset:38400
	ds_read_u16 v176, v234 offset:38912
	ds_read_u16 v177, v234 offset:39424
	s_waitcnt lgkmcnt(13)
	v_lshlrev_b32_e32 v164, 16, v164
	v_fmac_f32_e32 v64, v160, v164
	ds_read_u16 v178, v234 offset:39936
	s_waitcnt lgkmcnt(13)
	v_lshlrev_b32_e32 v165, 16, v165
	v_fmac_f32_e32 v65, v161, v165
	ds_read_u16 v179, v234 offset:40448
	s_waitcnt lgkmcnt(13)
	v_lshlrev_b32_e32 v166, 16, v166
	v_fmac_f32_e32 v66, v162, v166
	ds_read_u16 v180, v234 offset:40960
	s_waitcnt lgkmcnt(13)
	v_lshlrev_b32_e32 v167, 16, v167
	v_fmac_f32_e32 v67, v163, v167
	ds_read_u16 v181, v234 offset:41472
	s_waitcnt lgkmcnt(13)
	v_lshlrev_b32_e32 v168, 16, v168
	v_fmac_f32_e32 v60, v156, v168
	ds_read_u16 v182, v234 offset:41984
	s_waitcnt lgkmcnt(13)
	v_lshlrev_b32_e32 v169, 16, v169
	v_fmac_f32_e32 v61, v157, v169
	ds_read_u16 v183, v234 offset:42496
	s_waitcnt lgkmcnt(13)
	v_lshlrev_b32_e32 v170, 16, v170
	v_fmac_f32_e32 v62, v158, v170
	ds_read_u16 v184, v234 offset:43008
	s_waitcnt lgkmcnt(13)
	v_lshlrev_b32_e32 v171, 16, v171
	v_fmac_f32_e32 v63, v159, v171
	ds_read_u16 v185, v234 offset:43520
	s_waitcnt lgkmcnt(13)
	v_lshlrev_b32_e32 v172, 16, v172
	v_fmac_f32_e32 v56, v152, v172
	ds_read_u16 v186, v234 offset:44032
	s_waitcnt lgkmcnt(13)
	v_lshlrev_b32_e32 v173, 16, v173
	v_fmac_f32_e32 v57, v153, v173
	ds_read_u16 v187, v234 offset:44544
	s_waitcnt lgkmcnt(13)
	v_lshlrev_b32_e32 v174, 16, v174
	v_fmac_f32_e32 v58, v154, v174
	ds_read_u16 v188, v234 offset:45056
	s_waitcnt lgkmcnt(13)
	v_lshlrev_b32_e32 v175, 16, v175
	v_fmac_f32_e32 v59, v155, v175
	ds_read_u16 v189, v234 offset:45568
	s_waitcnt lgkmcnt(13)
	v_lshlrev_b32_e32 v176, 16, v176
	v_fmac_f32_e32 v52, v148, v176
	ds_read_u16 v190, v234 offset:46080
	s_waitcnt lgkmcnt(13)
	v_lshlrev_b32_e32 v177, 16, v177
	v_fmac_f32_e32 v53, v149, v177
	ds_read_u16 v191, v234 offset:46592
	s_waitcnt lgkmcnt(13)
	v_lshlrev_b32_e32 v178, 16, v178
	v_fmac_f32_e32 v54, v150, v178
	ds_read_u16 v192, v234 offset:47104
	s_waitcnt lgkmcnt(13)
	v_lshlrev_b32_e32 v179, 16, v179
	v_fmac_f32_e32 v55, v151, v179
	ds_read_u16 v193, v234 offset:47616
	s_waitcnt lgkmcnt(13)
	v_lshlrev_b32_e32 v180, 16, v180
	v_fmac_f32_e32 v48, v144, v180
	ds_read_u16 v194, v234 offset:48128
	s_waitcnt lgkmcnt(13)
	v_lshlrev_b32_e32 v181, 16, v181
	v_fmac_f32_e32 v49, v145, v181
	ds_read_u16 v195, v234 offset:48640
	s_waitcnt lgkmcnt(13)
	v_lshlrev_b32_e32 v182, 16, v182
	v_fmac_f32_e32 v50, v146, v182
	ds_read_u16 v196, v234 offset:49152
	s_waitcnt lgkmcnt(13)
	v_lshlrev_b32_e32 v183, 16, v183
	v_fmac_f32_e32 v51, v147, v183
	ds_read_u16 v197, v234 offset:49664
	s_waitcnt lgkmcnt(13)
	v_lshlrev_b32_e32 v184, 16, v184
	v_fmac_f32_e32 v44, v140, v184
	ds_read_u16 v198, v234 offset:50176
	s_waitcnt lgkmcnt(13)
	v_lshlrev_b32_e32 v185, 16, v185
	v_fmac_f32_e32 v45, v141, v185
	ds_read_u16 v199, v234 offset:50688
	s_waitcnt lgkmcnt(13)
	v_lshlrev_b32_e32 v186, 16, v186
	v_fmac_f32_e32 v46, v142, v186
	ds_read_u16 v200, v234 offset:51200
	s_waitcnt lgkmcnt(13)
	v_lshlrev_b32_e32 v187, 16, v187
	v_fmac_f32_e32 v47, v143, v187
	ds_read_u16 v201, v234 offset:51712
	s_waitcnt lgkmcnt(13)
	v_lshlrev_b32_e32 v188, 16, v188
	v_fmac_f32_e32 v40, v136, v188
	ds_read_u16 v202, v234 offset:52224
	s_waitcnt lgkmcnt(13)
; __device__ __forceinline__ float bf2f(u16 h) { return __uint_as_float(((unsigned)h) << 16); }
; __device__ void phase_merge(const Params& p, int layer, char* smem) {
;     ...
;           } else if (r == 47) {
; #pragma unroll
;             for (int m = 0; m < 4; ++m)
; #pragma unroll
;               for (int n = 0; n < 4; ++n)
; #pragma unroll
;                 for (int j = 0; j < 4; ++j) {
;                   mg[m][n][j] += bf2f(GL[((m * 4 + n) * 4 + j) * 256]) * acc[m][n][j];
;                   acc[m][n][j] = 0.f;
;                 }
;           }
	v_lshlrev_b32_e32 v189, 16, v189
	v_fmac_f32_e32 v41, v137, v189
	ds_read_u16 v203, v234 offset:52736
	s_waitcnt lgkmcnt(13)
	v_lshlrev_b32_e32 v190, 16, v190
	v_fmac_f32_e32 v42, v138, v190
	ds_read_u16 v204, v234 offset:53248
	s_waitcnt lgkmcnt(13)
	v_lshlrev_b32_e32 v191, 16, v191
	v_fmac_f32_e32 v43, v139, v191
	ds_read_u16 v205, v234 offset:53760
	s_waitcnt lgkmcnt(13)
	v_lshlrev_b32_e32 v192, 16, v192
	v_fmac_f32_e32 v36, v132, v192
	ds_read_u16 v206, v234 offset:54272
	s_waitcnt lgkmcnt(13)
	v_lshlrev_b32_e32 v193, 16, v193
	v_fmac_f32_e32 v37, v133, v193
	ds_read_u16 v207, v234 offset:54784
	s_waitcnt lgkmcnt(13)
	v_lshlrev_b32_e32 v194, 16, v194
	v_fmac_f32_e32 v38, v134, v194
	ds_read_u16 v208, v234 offset:55296
	s_waitcnt lgkmcnt(13)
	v_lshlrev_b32_e32 v195, 16, v195
	v_fmac_f32_e32 v39, v135, v195
	ds_read_u16 v209, v234 offset:55808
	s_waitcnt lgkmcnt(13)
	v_lshlrev_b32_e32 v196, 16, v196
	v_fmac_f32_e32 v32, v128, v196
	ds_read_u16 v210, v234 offset:56320
	s_waitcnt lgkmcnt(13)
	v_lshlrev_b32_e32 v197, 16, v197
	v_fmac_f32_e32 v33, v129, v197
	ds_read_u16 v211, v234 offset:56832
	s_waitcnt lgkmcnt(13)
	v_lshlrev_b32_e32 v198, 16, v198
	v_fmac_f32_e32 v34, v130, v198
	ds_read_u16 v212, v234 offset:57344
	s_waitcnt lgkmcnt(13)
	v_lshlrev_b32_e32 v199, 16, v199
	v_fmac_f32_e32 v35, v131, v199
	ds_read_u16 v213, v234 offset:57856
	s_waitcnt lgkmcnt(13)
	v_lshlrev_b32_e32 v200, 16, v200
	v_fmac_f32_e32 v28, v124, v200
	ds_read_u16 v214, v234 offset:58368
	s_waitcnt lgkmcnt(13)
	v_lshlrev_b32_e32 v201, 16, v201
	v_fmac_f32_e32 v29, v125, v201
	ds_read_u16 v215, v234 offset:58880
	s_waitcnt lgkmcnt(13)
	v_lshlrev_b32_e32 v202, 16, v202
	v_fmac_f32_e32 v30, v126, v202
	ds_read_u16 v216, v234 offset:59392
	s_waitcnt lgkmcnt(13)
	v_lshlrev_b32_e32 v203, 16, v203
	v_fmac_f32_e32 v31, v127, v203
	ds_read_u16 v217, v234 offset:59904
	s_waitcnt lgkmcnt(13)
	v_lshlrev_b32_e32 v204, 16, v204
	v_fmac_f32_e32 v24, v120, v204
	ds_read_u16 v218, v234 offset:60416
	s_waitcnt lgkmcnt(13)
	v_lshlrev_b32_e32 v205, 16, v205
	v_fmac_f32_e32 v25, v121, v205
	ds_read_u16 v219, v234 offset:60928
	s_waitcnt lgkmcnt(13)
	v_lshlrev_b32_e32 v206, 16, v206
	v_fmac_f32_e32 v26, v122, v206
	ds_read_u16 v220, v234 offset:61440
	s_waitcnt lgkmcnt(13)
	v_lshlrev_b32_e32 v207, 16, v207
	v_fmac_f32_e32 v27, v123, v207
	ds_read_u16 v221, v234 offset:61952
	s_waitcnt lgkmcnt(13)
	v_lshlrev_b32_e32 v208, 16, v208
	v_fmac_f32_e32 v20, v116, v208
	ds_read_u16 v222, v234 offset:62464
	s_waitcnt lgkmcnt(13)
	v_lshlrev_b32_e32 v209, 16, v209
	v_fmac_f32_e32 v21, v117, v209
	ds_read_u16 v223, v234 offset:62976
	s_waitcnt lgkmcnt(13)
	v_lshlrev_b32_e32 v210, 16, v210
	v_fmac_f32_e32 v22, v118, v210
	ds_read_u16 v224, v234 offset:63488
	s_waitcnt lgkmcnt(13)
	v_lshlrev_b32_e32 v211, 16, v211
	v_fmac_f32_e32 v23, v119, v211
	ds_read_u16 v225, v234 offset:64000
	s_waitcnt lgkmcnt(13)
	v_lshlrev_b32_e32 v212, 16, v212
	v_fmac_f32_e32 v16, v112, v212
	ds_read_u16 v226, v234 offset:64512
	s_waitcnt lgkmcnt(13)
	v_lshlrev_b32_e32 v213, 16, v213
	v_fmac_f32_e32 v17, v113, v213
	ds_read_u16 v227, v234 offset:65024
	s_waitcnt lgkmcnt(13)
	v_lshlrev_b32_e32 v214, 16, v214
	v_fmac_f32_e32 v18, v114, v214
	s_waitcnt lgkmcnt(12)
	v_lshlrev_b32_e32 v215, 16, v215
	v_fmac_f32_e32 v19, v115, v215
	s_waitcnt lgkmcnt(11)
	v_lshlrev_b32_e32 v216, 16, v216
	v_fmac_f32_e32 v12, v108, v216
	s_waitcnt lgkmcnt(10)
	v_lshlrev_b32_e32 v217, 16, v217
	v_fmac_f32_e32 v13, v109, v217
	s_waitcnt lgkmcnt(9)
	v_lshlrev_b32_e32 v218, 16, v218
	v_fmac_f32_e32 v14, v110, v218
	s_waitcnt lgkmcnt(8)
	v_lshlrev_b32_e32 v219, 16, v219
	v_fmac_f32_e32 v15, v111, v219
	s_waitcnt lgkmcnt(7)
	v_lshlrev_b32_e32 v220, 16, v220
	v_fmac_f32_e32 v8, v100, v220
	s_waitcnt lgkmcnt(6)
	v_lshlrev_b32_e32 v221, 16, v221
	v_fmac_f32_e32 v9, v101, v221
	s_waitcnt lgkmcnt(5)
	v_lshlrev_b32_e32 v222, 16, v222
	v_fmac_f32_e32 v10, v102, v222
	s_waitcnt lgkmcnt(4)
	v_lshlrev_b32_e32 v223, 16, v223
	v_fmac_f32_e32 v11, v103, v223
	s_waitcnt lgkmcnt(3)
	v_lshlrev_b32_e32 v224, 16, v224
	v_fmac_f32_e32 v4, v104, v224
	s_waitcnt lgkmcnt(2)
	v_lshlrev_b32_e32 v225, 16, v225
	v_fmac_f32_e32 v5, v105, v225
	s_waitcnt lgkmcnt(1)
	v_lshlrev_b32_e32 v226, 16, v226
	v_fmac_f32_e32 v6, v106, v226
	s_waitcnt lgkmcnt(0)
	v_lshlrev_b32_e32 v227, 16, v227
	v_fmac_f32_e32 v7, v107, v227
	v_mov_b32_e32 v1, v0
	v_mov_b32_e32 v2, v0
	s_mov_b64 s[12:13], -1
	s_branch .LBB0_597

; __device__ __forceinline__ float bflo(unsigned w) { return __uint_as_float(w << 16); }
; __device__ __forceinline__ float bfhi(unsigned w) { return __uint_as_float(w & 0xffff0000u); }
; __device__ void gmlp_item(const Params& p, int layer, int b, int n, int g, char* smem) {
;     ...
;   {
;     uint4 raw[8];
; #pragma unroll
;     for (int i = 0; i < 8; ++i) {
;       int q = tid + 256 * i;
;       int st = q & 127, c0 = (q >> 7) * 8;
;       raw[i] = *reinterpret_cast<const uint4*>(P + (t0 + st) * NP + 512 + g * 128 + c0);
;     }
; #pragma unroll
;     for (int i = 0; i < 8; ++i) {
;       int q = tid + 256 * i;
;       int st = q & 127, c0 = (q >> 7) * 8;
;       unsigned w[4] = {raw[i].x, raw[i].y, raw[i].z, raw[i].w};
;       float mu = mu_s[st], rs = rs_s[st];
;       const float4* gp = reinterpret_cast<const float4*>(p.gm_gain + (size_t)layer * 512 + g * 128 + c0);
;       float4 g0 = gp[0], g1 = gp[1];
;       float gg[8] = {g0.x, g0.y, g0.z, g0.w, g1.x, g1.y, g1.z, g1.w};
; #pragma unroll
;       for (int e = 0; e < 8; ++e) {
;         float v = (e & 1) ? bfhi(w[e >> 1]) : bflo(w[e >> 1]);
;         float val = (v - mu) * rs * gg[e];
;         *reinterpret_cast<u16*>(smem + 32768 + (st >> 5) * 8192 + (c0 + e) * 64 + (st & 31) * 2) = f2bf(val);
;       }
;     }
.LBB0_800:
	s_or_b64 exec, exec, s[14:15]
	v_and_b32_e32 v6, 0x7f, v59
	s_ashr_i32 s14, s16, 31
	s_bfe_u32 s20, s82, 0x20003
	s_waitcnt lgkmcnt(0)
	v_or_b32_e32 v0, s36, v6
	s_add_u32 s21, s28, s16
	v_mul_lo_u32 v128, v0, s66
	v_ashrrev_i32_e32 v48, 4, v59
	s_addc_u32 s48, s29, s14
	v_lshl_add_u64 v[0:1], v[128:129], 1, s[12:13]
	s_lshl_b32 s14, s20, 8
	s_mov_b32 s15, s37
	v_and_b32_e32 v2, -8, v48
	v_lshl_add_u64 v[0:1], v[0:1], 0, s[14:15]
	v_ashrrev_i32_e32 v3, 31, v2
	v_lshl_add_u64 v[4:5], v[2:3], 1, v[0:1]
	s_barrier
	global_load_dwordx4 v[28:31], v[4:5], off offset:1024
	s_lshl_b32 s16, s20, 7
	s_lshl_b32 s14, s20, 9
	s_add_u32 s14, s55, s14
	s_addc_u32 s15, s27, 0
	v_lshl_add_u64 v[4:5], v[2:3], 2, s[14:15]
	global_load_dwordx4 v[50:53], v[4:5], off
	global_load_dwordx4 v[70:73], v[4:5], off offset:16
	v_add_u32_e32 v3, 0x100, v59
	v_ashrrev_i32_e32 v68, 4, v3
	v_add_u32_e32 v4, 0x200, v59
	v_lshlrev_b32_e32 v12, 1, v59
	v_and_b32_e32 v54, -8, v68
	v_add_u32_e32 v5, 0x300, v59
	v_lshlrev_b32_e32 v11, 8, v59
	v_ashrrev_i32_e32 v66, 4, v4
	v_and_b32_e32 v4, 62, v12
	v_ashrrev_i32_e32 v55, 31, v54
	v_ashrrev_i32_e32 v64, 4, v5
	v_and_or_b32 v44, v11, s67, v4
	v_lshl_add_u64 v[4:5], v[54:55], 1, v[0:1]
	global_load_dwordx4 v[24:27], v[4:5], off offset:1024
	v_lshl_add_u64 v[4:5], v[54:55], 2, s[14:15]
	global_load_dwordx4 v[74:77], v[4:5], off offset:16
	global_load_dwordx4 v[78:81], v[4:5], off
	v_lshlrev_b32_e32 v3, 2, v6
	v_or_b32_e32 v6, 0x10000, v3
	v_or_b32_e32 v3, 0x10200, v3
	ds_read_b32 v45, v6
	ds_read_b32 v46, v3
	v_add_u32_e32 v7, 0x400, v59
	v_add_u32_e32 v8, 0x500, v59
	v_add_u32_e32 v9, 0x600, v59
	v_add_u32_e32 v10, 0x700, v59
	v_ashrrev_i32_e32 v62, 4, v7
	v_ashrrev_i32_e32 v60, 4, v8
	v_ashrrev_i32_e32 v58, 4, v9
	v_ashrrev_i32_e32 v56, 4, v10
	v_and_b32_e32 v42, -8, v66
	v_and_b32_e32 v40, -8, v64
	v_and_b32_e32 v38, -8, v62
	v_and_b32_e32 v36, -8, v60
	v_and_b32_e32 v34, -8, v58
	v_and_b32_e32 v32, -8, v56
	v_ashrrev_i32_e32 v43, 31, v42
	v_ashrrev_i32_e32 v41, 31, v40
	v_ashrrev_i32_e32 v39, 31, v38
	v_ashrrev_i32_e32 v37, 31, v36
	v_ashrrev_i32_e32 v35, 31, v34
	v_ashrrev_i32_e32 v33, 31, v32
	v_lshl_add_u32 v47, v2, 6, v44
	v_lshl_add_u64 v[2:3], v[42:43], 1, v[0:1]
	v_lshl_add_u64 v[4:5], v[40:41], 1, v[0:1]
	v_lshl_add_u64 v[6:7], v[38:39], 1, v[0:1]
	v_lshl_add_u64 v[8:9], v[36:37], 1, v[0:1]
	v_lshl_add_u64 v[82:83], v[34:35], 1, v[0:1]
	v_lshl_add_u64 v[0:1], v[32:33], 1, v[0:1]
	global_load_dwordx4 v[20:23], v[2:3], off offset:1024
	global_load_dwordx4 v[16:19], v[4:5], off offset:1024
	global_load_dwordx4 v[12:15], v[6:7], off offset:1024
	s_nop 0
	global_load_dwordx4 v[8:11], v[8:9], off offset:1024
	s_nop 0
	global_load_dwordx4 v[4:7], v[82:83], off offset:1024
	s_nop 0
	global_load_dwordx4 v[0:3], v[0:1], off offset:1024
	v_and_b32_e32 v49, 15, v59
	v_lshlrev_b32_e32 v128, 4, v49
	s_waitcnt vmcnt(11)
	v_lshlrev_b32_e32 v55, 16, v28
	v_and_b32_e32 v28, 0xffff0000, v28
	s_waitcnt lgkmcnt(1)
	v_sub_f32_e32 v55, v55, v45
	v_sub_f32_e32 v28, v28, v45
	s_waitcnt lgkmcnt(0)
	v_mul_f32_e32 v55, v46, v55
	v_mul_f32_e32 v28, v46, v28
	s_waitcnt vmcnt(10)
	v_mul_f32_e32 v50, v55, v50
	v_mul_f32_e32 v28, v28, v51
	v_cvt_pk_bf16_f32 v50, 0, v50
	ds_write_b16_d16_hi v47, v50 offset:32768
	v_cvt_pk_bf16_f32 v28, 0, v28
	ds_write_b16_d16_hi v47, v28 offset:32832
	v_lshlrev_b32_e32 v28, 16, v29
	v_sub_f32_e32 v28, v28, v45
	v_mul_f32_e32 v28, v46, v28
	v_mul_f32_e32 v28, v28, v52
	v_cvt_pk_bf16_f32 v28, 0, v28
	ds_write_b16_d16_hi v47, v28 offset:32896
	v_and_b32_e32 v28, 0xffff0000, v29
	v_sub_f32_e32 v28, v28, v45
	v_mul_f32_e32 v28, v46, v28
	v_mul_f32_e32 v28, v28, v53
	v_cvt_pk_bf16_f32 v28, 0, v28
	ds_write_b16_d16_hi v47, v28 offset:32960
	v_lshlrev_b32_e32 v28, 16, v30
	v_sub_f32_e32 v28, v28, v45
	v_mul_f32_e32 v28, v46, v28
	s_waitcnt vmcnt(9)
	v_mul_f32_e32 v28, v28, v70
	v_cvt_pk_bf16_f32 v28, 0, v28
	ds_write_b16_d16_hi v47, v28 offset:33024
	v_and_b32_e32 v28, 0xffff0000, v30
	v_sub_f32_e32 v28, v28, v45
	v_mul_f32_e32 v28, v46, v28
	v_mul_f32_e32 v28, v28, v71
	v_cvt_pk_bf16_f32 v28, 0, v28
	ds_write_b16_d16_hi v47, v28 offset:33088
	v_lshlrev_b32_e32 v28, 16, v31
	v_sub_f32_e32 v30, v28, v45
	v_lshl_add_u64 v[28:29], v[42:43], 2, s[14:15]
	global_load_dwordx4 v[50:53], v[28:29], off offset:16
	global_load_dwordx4 v[82:85], v[28:29], off
	v_mul_f32_e32 v28, v46, v30
	v_mul_f32_e32 v28, v28, v72
	v_cvt_pk_bf16_f32 v28, 0, v28
	ds_write_b16_d16_hi v47, v28 offset:33152
	v_and_b32_e32 v28, 0xffff0000, v31
	v_sub_f32_e32 v28, v28, v45
	v_mul_f32_e32 v28, v46, v28
	v_mul_f32_e32 v28, v28, v73
	v_cvt_pk_bf16_f32 v28, 0, v28
	v_lshl_or_b32 v29, v48, 6, v159
	v_add_u32_e32 v29, v44, v29
	ds_write_b16_d16_hi v29, v28 offset:32768
	s_waitcnt vmcnt(10)
	v_lshlrev_b32_e32 v28, 16, v24
	v_sub_f32_e32 v28, v28, v45
	v_mul_f32_e32 v28, v46, v28
	v_and_b32_e32 v24, 0xffff0000, v24
	s_waitcnt vmcnt(8)
; __device__ __forceinline__ float bflo(unsigned w) { return __uint_as_float(w << 16); }
; __device__ __forceinline__ float bfhi(unsigned w) { return __uint_as_float(w & 0xffff0000u); }
; __device__ void gmlp_item(const Params& p, int layer, int b, int n, int g, char* smem) {
;     ...
; #pragma unroll
;     for (int i = 0; i < 8; ++i) {
;       int q = tid + 256 * i;
;       int st = q & 127, c0 = (q >> 7) * 8;
;       unsigned w[4] = {raw[i].x, raw[i].y, raw[i].z, raw[i].w};
;       float mu = mu_s[st], rs = rs_s[st];
;       const float4* gp = reinterpret_cast<const float4*>(p.gm_gain + (size_t)layer * 512 + g * 128 + c0);
;       float4 g0 = gp[0], g1 = gp[1];
;       float gg[8] = {g0.x, g0.y, g0.z, g0.w, g1.x, g1.y, g1.z, g1.w};
; #pragma unroll
;       for (int e = 0; e < 8; ++e) {
;         float v = (e & 1) ? bfhi(w[e >> 1]) : bflo(w[e >> 1]);
;         float val = (v - mu) * rs * gg[e];
;         *reinterpret_cast<u16*>(smem + 32768 + (st >> 5) * 8192 + (c0 + e) * 64 + (st & 31) * 2) = f2bf(val);
;       }
;     }
	v_mul_f32_e32 v28, v28, v78
	v_sub_f32_e32 v24, v24, v45
	v_mul_f32_e32 v24, v46, v24
	v_cvt_pk_bf16_f32 v28, 0, v28
	v_lshl_add_u32 v43, v54, 6, v44
	v_mul_f32_e32 v24, v24, v79
	ds_write_b16_d16_hi v43, v28 offset:32768
	v_cvt_pk_bf16_f32 v24, 0, v24
	ds_write_b16_d16_hi v43, v24 offset:32832
	v_lshlrev_b32_e32 v24, 16, v25
	v_sub_f32_e32 v24, v24, v45
	v_mul_f32_e32 v24, v46, v24
	v_mul_f32_e32 v24, v24, v80
	v_cvt_pk_bf16_f32 v24, 0, v24
	ds_write_b16_d16_hi v43, v24 offset:32896
	v_and_b32_e32 v24, 0xffff0000, v25
	v_sub_f32_e32 v24, v24, v45
	v_mul_f32_e32 v24, v46, v24
	v_mul_f32_e32 v24, v24, v81
	v_cvt_pk_bf16_f32 v24, 0, v24
	ds_write_b16_d16_hi v43, v24 offset:32960
	v_lshlrev_b32_e32 v24, 16, v26
	v_sub_f32_e32 v24, v24, v45
	v_mul_f32_e32 v24, v46, v24
	v_mul_f32_e32 v24, v24, v74
	v_cvt_pk_bf16_f32 v24, 0, v24
	ds_write_b16_d16_hi v43, v24 offset:33024
	v_and_b32_e32 v24, 0xffff0000, v26
	v_sub_f32_e32 v24, v24, v45
	v_mul_f32_e32 v24, v46, v24
	v_mul_f32_e32 v24, v24, v75
	v_cvt_pk_bf16_f32 v24, 0, v24
	ds_write_b16_d16_hi v43, v24 offset:33088
	v_lshlrev_b32_e32 v24, 16, v27
	v_sub_f32_e32 v26, v24, v45
	v_lshl_add_u64 v[24:25], v[40:41], 2, s[14:15]
	global_load_dwordx4 v[28:31], v[24:25], off offset:16
	global_load_dwordx4 v[70:73], v[24:25], off
	v_mul_f32_e32 v24, v46, v26
	v_mul_f32_e32 v24, v24, v76
	v_cvt_pk_bf16_f32 v24, 0, v24
	ds_write_b16_d16_hi v43, v24 offset:33152
	v_and_b32_e32 v24, 0xffff0000, v27
	v_sub_f32_e32 v24, v24, v45
	v_mul_f32_e32 v24, v46, v24
	v_mul_f32_e32 v24, v24, v77
	v_cvt_pk_bf16_f32 v24, 0, v24
	v_lshl_or_b32 v25, v68, 6, v159
	v_add_u32_e32 v25, v44, v25
	ds_write_b16_d16_hi v25, v24 offset:32768
	s_waitcnt vmcnt(9)
	v_lshlrev_b32_e32 v24, 16, v20
	v_sub_f32_e32 v24, v24, v45
	v_mul_f32_e32 v24, v46, v24
	v_and_b32_e32 v20, 0xffff0000, v20
	s_waitcnt vmcnt(2)
	v_mul_f32_e32 v24, v24, v82
	v_sub_f32_e32 v20, v20, v45
	v_mul_f32_e32 v20, v46, v20
	v_cvt_pk_bf16_f32 v24, 0, v24
	v_lshl_add_u32 v41, v42, 6, v44
	v_mul_f32_e32 v20, v20, v83
	ds_write_b16_d16_hi v41, v24 offset:32768
	v_cvt_pk_bf16_f32 v20, 0, v20
	ds_write_b16_d16_hi v41, v20 offset:32832
	v_lshlrev_b32_e32 v20, 16, v21
	v_sub_f32_e32 v20, v20, v45
	v_mul_f32_e32 v20, v46, v20
	v_mul_f32_e32 v20, v20, v84
	v_cvt_pk_bf16_f32 v20, 0, v20
	ds_write_b16_d16_hi v41, v20 offset:32896
	v_and_b32_e32 v20, 0xffff0000, v21
	v_sub_f32_e32 v20, v20, v45
	v_mul_f32_e32 v20, v46, v20
	v_mul_f32_e32 v20, v20, v85
	v_cvt_pk_bf16_f32 v20, 0, v20
	ds_write_b16_d16_hi v41, v20 offset:32960
	v_lshlrev_b32_e32 v20, 16, v22
	v_sub_f32_e32 v20, v20, v45
	v_mul_f32_e32 v20, v46, v20
	v_mul_f32_e32 v20, v20, v50
	v_cvt_pk_bf16_f32 v20, 0, v20
	ds_write_b16_d16_hi v41, v20 offset:33024
	v_and_b32_e32 v20, 0xffff0000, v22
	v_sub_f32_e32 v20, v20, v45
	v_mul_f32_e32 v20, v46, v20
	v_mul_f32_e32 v20, v20, v51
	v_cvt_pk_bf16_f32 v20, 0, v20
	ds_write_b16_d16_hi v41, v20 offset:33088
	v_lshlrev_b32_e32 v20, 16, v23
	v_sub_f32_e32 v22, v20, v45
	v_lshl_add_u64 v[20:21], v[38:39], 2, s[14:15]
	global_load_dwordx4 v[24:27], v[20:21], off offset:16
	global_load_dwordx4 v[74:77], v[20:21], off
	v_mul_f32_e32 v20, v46, v22
	v_mul_f32_e32 v20, v20, v52
	v_cvt_pk_bf16_f32 v20, 0, v20
	ds_write_b16_d16_hi v41, v20 offset:33152
	v_and_b32_e32 v20, 0xffff0000, v23
	v_sub_f32_e32 v20, v20, v45
	v_mul_f32_e32 v20, v46, v20
	v_mul_f32_e32 v20, v20, v53
	v_cvt_pk_bf16_f32 v20, 0, v20
	v_lshl_or_b32 v21, v66, 6, v159
	v_add_u32_e32 v21, v44, v21
	ds_write_b16_d16_hi v21, v20 offset:32768
	v_lshlrev_b32_e32 v20, 16, v16
	v_sub_f32_e32 v20, v20, v45
	v_mul_f32_e32 v20, v46, v20
	v_and_b32_e32 v16, 0xffff0000, v16
	s_waitcnt vmcnt(2)
	v_mul_f32_e32 v20, v20, v70
	v_sub_f32_e32 v16, v16, v45
	v_mul_f32_e32 v16, v46, v16
	v_cvt_pk_bf16_f32 v20, 0, v20
	v_lshl_add_u32 v39, v40, 6, v44
	v_mul_f32_e32 v16, v16, v71
	ds_write_b16_d16_hi v39, v20 offset:32768
	v_cvt_pk_bf16_f32 v16, 0, v16
	ds_write_b16_d16_hi v39, v16 offset:32832
	v_lshlrev_b32_e32 v16, 16, v17
	v_sub_f32_e32 v16, v16, v45
	v_mul_f32_e32 v16, v46, v16
	v_mul_f32_e32 v16, v16, v72
	v_cvt_pk_bf16_f32 v16, 0, v16
	ds_write_b16_d16_hi v39, v16 offset:32896
	v_and_b32_e32 v16, 0xffff0000, v17
	v_sub_f32_e32 v16, v16, v45
	v_mul_f32_e32 v16, v46, v16
	v_mul_f32_e32 v16, v16, v73
	v_cvt_pk_bf16_f32 v16, 0, v16
	ds_write_b16_d16_hi v39, v16 offset:32960
	v_lshlrev_b32_e32 v16, 16, v18
	v_sub_f32_e32 v16, v16, v45
	v_mul_f32_e32 v16, v46, v16
	v_mul_f32_e32 v16, v16, v28
	v_cvt_pk_bf16_f32 v16, 0, v16
	ds_write_b16_d16_hi v39, v16 offset:33024
	v_and_b32_e32 v16, 0xffff0000, v18
	v_sub_f32_e32 v16, v16, v45
	v_mul_f32_e32 v16, v46, v16
	v_mul_f32_e32 v16, v16, v29
	v_cvt_pk_bf16_f32 v16, 0, v16
	ds_write_b16_d16_hi v39, v16 offset:33088
	v_lshlrev_b32_e32 v16, 16, v19
	v_sub_f32_e32 v18, v16, v45
	v_lshl_add_u64 v[16:17], v[36:37], 2, s[14:15]
	global_load_dwordx4 v[20:23], v[16:17], off offset:16
	global_load_dwordx4 v[40:43], v[16:17], off
	v_mul_f32_e32 v16, v46, v18
	v_mul_f32_e32 v16, v16, v30
	v_cvt_pk_bf16_f32 v16, 0, v16
	ds_write_b16_d16_hi v39, v16 offset:33152
	v_and_b32_e32 v16, 0xffff0000, v19
	v_sub_f32_e32 v16, v16, v45
	v_mul_f32_e32 v16, v46, v16
	v_mul_f32_e32 v16, v16, v31
	v_cvt_pk_bf16_f32 v16, 0, v16
	v_lshl_or_b32 v17, v64, 6, v159
	v_add_u32_e32 v17, v44, v17
	ds_write_b16_d16_hi v17, v16 offset:32768
	v_lshlrev_b32_e32 v16, 16, v12
	v_sub_f32_e32 v16, v16, v45
	v_mul_f32_e32 v16, v46, v16
	v_and_b32_e32 v12, 0xffff0000, v12
	s_waitcnt vmcnt(2)
; __device__ __forceinline__ float bflo(unsigned w) { return __uint_as_float(w << 16); }
; __device__ __forceinline__ float bfhi(unsigned w) { return __uint_as_float(w & 0xffff0000u); }
; __device__ void gmlp_item(const Params& p, int layer, int b, int n, int g, char* smem) {
;     ...
; #pragma unroll
;     for (int i = 0; i < 8; ++i) {
;       int q = tid + 256 * i;
;       int st = q & 127, c0 = (q >> 7) * 8;
;       unsigned w[4] = {raw[i].x, raw[i].y, raw[i].z, raw[i].w};
;       float mu = mu_s[st], rs = rs_s[st];
;       const float4* gp = reinterpret_cast<const float4*>(p.gm_gain + (size_t)layer * 512 + g * 128 + c0);
;       float4 g0 = gp[0], g1 = gp[1];
;       float gg[8] = {g0.x, g0.y, g0.z, g0.w, g1.x, g1.y, g1.z, g1.w};
; #pragma unroll
;       for (int e = 0; e < 8; ++e) {
;         float v = (e & 1) ? bfhi(w[e >> 1]) : bflo(w[e >> 1]);
;         float val = (v - mu) * rs * gg[e];
;         *reinterpret_cast<u16*>(smem + 32768 + (st >> 5) * 8192 + (c0 + e) * 64 + (st & 31) * 2) = f2bf(val);
;       }
;     }
	v_mul_f32_e32 v16, v16, v74
	v_sub_f32_e32 v12, v12, v45
	v_mul_f32_e32 v12, v46, v12
	v_cvt_pk_bf16_f32 v16, 0, v16
	v_lshl_add_u32 v37, v38, 6, v44
	v_mul_f32_e32 v12, v12, v75
	ds_write_b16_d16_hi v37, v16 offset:32768
	v_cvt_pk_bf16_f32 v12, 0, v12
	ds_write_b16_d16_hi v37, v12 offset:32832
	v_lshlrev_b32_e32 v12, 16, v13
	v_sub_f32_e32 v12, v12, v45
	v_mul_f32_e32 v12, v46, v12
	v_mul_f32_e32 v12, v12, v76
	v_cvt_pk_bf16_f32 v12, 0, v12
	ds_write_b16_d16_hi v37, v12 offset:32896
	v_and_b32_e32 v12, 0xffff0000, v13
	v_sub_f32_e32 v12, v12, v45
	v_mul_f32_e32 v12, v46, v12
	v_mul_f32_e32 v12, v12, v77
	v_cvt_pk_bf16_f32 v12, 0, v12
	ds_write_b16_d16_hi v37, v12 offset:32960
	v_lshlrev_b32_e32 v12, 16, v14
	v_sub_f32_e32 v12, v12, v45
	v_mul_f32_e32 v12, v46, v12
	v_mul_f32_e32 v12, v12, v24
	v_cvt_pk_bf16_f32 v12, 0, v12
	ds_write_b16_d16_hi v37, v12 offset:33024
	v_and_b32_e32 v12, 0xffff0000, v14
	v_sub_f32_e32 v12, v12, v45
	v_mul_f32_e32 v12, v46, v12
	v_mul_f32_e32 v12, v12, v25
	v_cvt_pk_bf16_f32 v12, 0, v12
	ds_write_b16_d16_hi v37, v12 offset:33088
	v_lshlrev_b32_e32 v12, 16, v15
	v_sub_f32_e32 v14, v12, v45
	v_lshl_add_u64 v[12:13], v[34:35], 2, s[14:15]
	global_load_dwordx4 v[16:19], v[12:13], off offset:16
	global_load_dwordx4 v[28:31], v[12:13], off
	v_mul_f32_e32 v12, v46, v14
	v_mul_f32_e32 v12, v12, v26
	v_cvt_pk_bf16_f32 v12, 0, v12
	ds_write_b16_d16_hi v37, v12 offset:33152
	v_and_b32_e32 v12, 0xffff0000, v15
	v_sub_f32_e32 v12, v12, v45
	v_mul_f32_e32 v12, v46, v12
	v_mul_f32_e32 v12, v12, v27
	v_cvt_pk_bf16_f32 v12, 0, v12
	v_lshl_or_b32 v13, v62, 6, v159
	v_add_u32_e32 v13, v44, v13
	ds_write_b16_d16_hi v13, v12 offset:32768
	v_lshlrev_b32_e32 v12, 16, v8
	v_sub_f32_e32 v12, v12, v45
	v_mul_f32_e32 v12, v46, v12
	v_and_b32_e32 v8, 0xffff0000, v8
	s_waitcnt vmcnt(2)
	v_mul_f32_e32 v12, v12, v40
	v_sub_f32_e32 v8, v8, v45
	v_mul_f32_e32 v8, v46, v8
	v_cvt_pk_bf16_f32 v12, 0, v12
	v_lshl_add_u32 v35, v36, 6, v44
	v_mul_f32_e32 v8, v8, v41
	ds_write_b16_d16_hi v35, v12 offset:32768
	v_cvt_pk_bf16_f32 v8, 0, v8
	ds_write_b16_d16_hi v35, v8 offset:32832
	v_lshlrev_b32_e32 v8, 16, v9
	v_sub_f32_e32 v8, v8, v45
	v_mul_f32_e32 v8, v46, v8
	v_mul_f32_e32 v8, v8, v42
	v_cvt_pk_bf16_f32 v8, 0, v8
	ds_write_b16_d16_hi v35, v8 offset:32896
	v_and_b32_e32 v8, 0xffff0000, v9
	v_sub_f32_e32 v8, v8, v45
	v_mul_f32_e32 v8, v46, v8
	v_mul_f32_e32 v8, v8, v43
	v_cvt_pk_bf16_f32 v8, 0, v8
	ds_write_b16_d16_hi v35, v8 offset:32960
	v_lshlrev_b32_e32 v8, 16, v10
	v_sub_f32_e32 v8, v8, v45
	v_mul_f32_e32 v8, v46, v8
	v_mul_f32_e32 v8, v8, v20
	v_cvt_pk_bf16_f32 v8, 0, v8
	ds_write_b16_d16_hi v35, v8 offset:33024
	v_and_b32_e32 v8, 0xffff0000, v10
	v_sub_f32_e32 v8, v8, v45
	v_mul_f32_e32 v8, v46, v8
	v_mul_f32_e32 v8, v8, v21
	v_cvt_pk_bf16_f32 v10, 0, v8
	v_lshl_add_u64 v[8:9], v[32:33], 2, s[14:15]
	global_load_dwordx4 v[12:15], v[8:9], off offset:16
	global_load_dwordx4 v[24:27], v[8:9], off
	v_lshlrev_b32_e32 v8, 16, v11
	v_sub_f32_e32 v8, v8, v45
	v_mul_f32_e32 v8, v46, v8
	v_mul_f32_e32 v8, v8, v22
	v_cvt_pk_bf16_f32 v8, 0, v8
	ds_write_b16_d16_hi v35, v8 offset:33152
	v_and_b32_e32 v8, 0xffff0000, v11
	v_sub_f32_e32 v8, v8, v45
	v_mul_f32_e32 v8, v46, v8
	v_mul_f32_e32 v8, v8, v23
	v_cvt_pk_bf16_f32 v8, 0, v8
	v_lshl_or_b32 v9, v60, 6, v159
	v_add_u32_e32 v9, v44, v9
	ds_write_b16_d16_hi v35, v10 offset:33088
	ds_write_b16_d16_hi v9, v8 offset:32768
	v_lshlrev_b32_e32 v8, 16, v4
	v_sub_f32_e32 v8, v8, v45
	v_mul_f32_e32 v8, v46, v8
	v_and_b32_e32 v4, 0xffff0000, v4
	s_waitcnt vmcnt(2)
	v_mul_f32_e32 v8, v8, v28
	v_sub_f32_e32 v4, v4, v45
	v_mul_f32_e32 v4, v46, v4
	v_cvt_pk_bf16_f32 v8, 0, v8
	v_lshl_add_u32 v9, v34, 6, v44
	v_mul_f32_e32 v4, v4, v29
	ds_write_b16_d16_hi v9, v8 offset:32768
	v_cvt_pk_bf16_f32 v4, 0, v4
	ds_write_b16_d16_hi v9, v4 offset:32832
	v_lshlrev_b32_e32 v4, 16, v5
	v_sub_f32_e32 v4, v4, v45
	v_mul_f32_e32 v4, v46, v4
	v_mul_f32_e32 v4, v4, v30
	v_cvt_pk_bf16_f32 v4, 0, v4
	ds_write_b16_d16_hi v9, v4 offset:32896
	v_and_b32_e32 v4, 0xffff0000, v5
	v_sub_f32_e32 v4, v4, v45
	v_mul_f32_e32 v4, v46, v4
	v_mul_f32_e32 v4, v4, v31
	v_cvt_pk_bf16_f32 v4, 0, v4
	ds_write_b16_d16_hi v9, v4 offset:32960
	v_lshlrev_b32_e32 v4, 16, v6
	v_sub_f32_e32 v4, v4, v45
	v_mul_f32_e32 v4, v46, v4
	v_mul_f32_e32 v4, v4, v16
	v_cvt_pk_bf16_f32 v4, 0, v4
	ds_write_b16_d16_hi v9, v4 offset:33024
	v_and_b32_e32 v4, 0xffff0000, v6
	v_sub_f32_e32 v4, v4, v45
	v_mul_f32_e32 v4, v46, v4
	v_mul_f32_e32 v4, v4, v17
	v_cvt_pk_bf16_f32 v4, 0, v4
	ds_write_b16_d16_hi v9, v4 offset:33088
	v_lshlrev_b32_e32 v4, 16, v7
	v_sub_f32_e32 v4, v4, v45
	v_mul_f32_e32 v4, v46, v4
	v_mul_f32_e32 v4, v4, v18
	v_cvt_pk_bf16_f32 v4, 0, v4
	ds_write_b16_d16_hi v9, v4 offset:33152
	v_and_b32_e32 v4, 0xffff0000, v7
	v_sub_f32_e32 v4, v4, v45
	v_mul_f32_e32 v4, v46, v4
	v_mul_f32_e32 v4, v4, v19
	v_cvt_pk_bf16_f32 v4, 0, v4
	v_lshl_or_b32 v5, v58, 6, v159
	v_add_u32_e32 v5, v44, v5
	ds_write_b16_d16_hi v5, v4 offset:32768
	v_lshlrev_b32_e32 v4, 16, v0
	v_sub_f32_e32 v4, v4, v45
	v_mul_f32_e32 v4, v46, v4
	v_and_b32_e32 v0, 0xffff0000, v0
	s_waitcnt vmcnt(0)
; __device__ __forceinline__ float bflo(unsigned w) { return __uint_as_float(w << 16); }
; __device__ __forceinline__ float bfhi(unsigned w) { return __uint_as_float(w & 0xffff0000u); }
; __device__ void gmlp_item(const Params& p, int layer, int b, int n, int g, char* smem) {
;     ...
; #pragma unroll
;     for (int i = 0; i < 8; ++i) {
;       int q = tid + 256 * i;
;       int st = q & 127, c0 = (q >> 7) * 8;
;       unsigned w[4] = {raw[i].x, raw[i].y, raw[i].z, raw[i].w};
;       float mu = mu_s[st], rs = rs_s[st];
;       const float4* gp = reinterpret_cast<const float4*>(p.gm_gain + (size_t)layer * 512 + g * 128 + c0);
;       float4 g0 = gp[0], g1 = gp[1];
;       float gg[8] = {g0.x, g0.y, g0.z, g0.w, g1.x, g1.y, g1.z, g1.w};
; #pragma unroll
;       for (int e = 0; e < 8; ++e) {
;         float v = (e & 1) ? bfhi(w[e >> 1]) : bflo(w[e >> 1]);
;         float val = (v - mu) * rs * gg[e];
;         *reinterpret_cast<u16*>(smem + 32768 + (st >> 5) * 8192 + (c0 + e) * 64 + (st & 31) * 2) = f2bf(val);
;       }
;     }
;   }
; #pragma unroll 2
;   for (int i = 0; i < 8; ++i) {
;     int q = tid + 256 * i;
;     int t = q >> 4, cch = q & 15;
;     uint4 v = *reinterpret_cast<const uint4*>(Ws + (size_t)g * 16384 + t * 128 + cch * 8);
;     *reinterpret_cast<uint4*>(smem + (cch >> 2) * 8192 + t * 64 + (cch & 3) * 16) = v;
;   }
;   __syncthreads();
	v_mul_f32_e32 v4, v4, v24
	v_sub_f32_e32 v0, v0, v45
	v_mul_f32_e32 v0, v46, v0
	v_cvt_pk_bf16_f32 v4, 0, v4
	v_lshl_add_u32 v5, v32, 6, v44
	v_mul_f32_e32 v0, v0, v25
	ds_write_b16_d16_hi v5, v4 offset:32768
	v_cvt_pk_bf16_f32 v0, 0, v0
	ds_write_b16_d16_hi v5, v0 offset:32832
	v_lshlrev_b32_e32 v0, 16, v1
	v_sub_f32_e32 v0, v0, v45
	v_mul_f32_e32 v0, v46, v0
	v_mul_f32_e32 v0, v0, v26
	v_cvt_pk_bf16_f32 v0, 0, v0
	ds_write_b16_d16_hi v5, v0 offset:32896
	v_and_b32_e32 v0, 0xffff0000, v1
	v_sub_f32_e32 v0, v0, v45
	v_mul_f32_e32 v0, v46, v0
	v_mul_f32_e32 v0, v0, v27
	v_cvt_pk_bf16_f32 v0, 0, v0
	ds_write_b16_d16_hi v5, v0 offset:32960
	v_lshlrev_b32_e32 v0, 16, v2
	v_sub_f32_e32 v0, v0, v45
	v_mul_f32_e32 v0, v46, v0
	v_mul_f32_e32 v0, v0, v12
	v_cvt_pk_bf16_f32 v0, 0, v0
	ds_write_b16_d16_hi v5, v0 offset:33024
	v_and_b32_e32 v0, 0xffff0000, v2
	v_sub_f32_e32 v0, v0, v45
	v_mul_f32_e32 v0, v46, v0
	v_mul_f32_e32 v0, v0, v13
	v_cvt_pk_bf16_f32 v0, 0, v0
	ds_write_b16_d16_hi v5, v0 offset:33088
	v_lshlrev_b32_e32 v0, 16, v3
	v_sub_f32_e32 v0, v0, v45
	v_mul_f32_e32 v0, v46, v0
	v_mul_f32_e32 v0, v0, v14
	v_cvt_pk_bf16_f32 v0, 0, v0
	ds_write_b16_d16_hi v5, v0 offset:33152
	v_and_b32_e32 v0, 0xffff0000, v3
	v_sub_f32_e32 v0, v0, v45
	v_mul_f32_e32 v0, v46, v0
	v_mul_f32_e32 v0, v0, v15
	s_lshl_b32 s14, s20, 15
	v_cvt_pk_bf16_f32 v0, 0, v0
	v_lshl_or_b32 v1, v56, 6, v159
	s_add_u32 s14, s21, s14
	v_add_u32_e32 v1, v44, v1
	s_addc_u32 s15, s48, 0
	v_lshlrev_b32_e32 v3, 4, v59
	ds_write_b16_d16_hi v1, v0 offset:32768
	v_lshl_add_u64 v[0:1], s[14:15], 0, v[128:129]
	v_lshlrev_b32_e32 v2, 11, v59
	v_and_b32_e32 v3, 48, v3
	v_lshl_add_u64 v[0:1], v[0:1], 0, s[38:39]
	v_and_or_b32 v2, v2, s67, v3
	s_mov_b32 s14, 0
	v_mov_b32_e32 v120, v59
	v_ashrrev_i32_e32 v104, 4, v120
	v_add_u32_e32 v120, 0x100, v120
	v_ashrrev_i32_e32 v105, 4, v120
	v_lshlrev_b32_e32 v112, 7, v104
	v_lshlrev_b32_e32 v114, 7, v105
	v_ashrrev_i32_e32 v113, 31, v112
	v_ashrrev_i32_e32 v115, 31, v114
	v_lshl_add_u64 v[112:113], v[112:113], 1, v[0:1]
	v_lshl_add_u64 v[114:115], v[114:115], 1, v[0:1]
	global_load_dwordx4 v[72:75], v[112:113], off
	global_load_dwordx4 v[76:79], v[114:115], off
	v_lshl_add_u32 v104, v104, 6, v2
	v_lshl_add_u32 v105, v105, 6, v2
	v_add_u32_e32 v120, 0x200, v59
	v_ashrrev_i32_e32 v106, 4, v120
	v_add_u32_e32 v120, 0x100, v120
	v_ashrrev_i32_e32 v107, 4, v120
	v_lshlrev_b32_e32 v116, 7, v106
	v_lshlrev_b32_e32 v118, 7, v107
	v_ashrrev_i32_e32 v117, 31, v116
	v_ashrrev_i32_e32 v119, 31, v118
	v_lshl_add_u64 v[116:117], v[116:117], 1, v[0:1]
	v_lshl_add_u64 v[118:119], v[118:119], 1, v[0:1]
	global_load_dwordx4 v[80:83], v[116:117], off
	global_load_dwordx4 v[84:87], v[118:119], off
	v_lshl_add_u32 v106, v106, 6, v2
	v_lshl_add_u32 v107, v107, 6, v2
	v_add_u32_e32 v120, 0x400, v59
	v_ashrrev_i32_e32 v108, 4, v120
	v_add_u32_e32 v120, 0x100, v120
	v_ashrrev_i32_e32 v109, 4, v120
	v_lshlrev_b32_e32 v112, 7, v108
	v_lshlrev_b32_e32 v114, 7, v109
	v_ashrrev_i32_e32 v113, 31, v112
	v_ashrrev_i32_e32 v115, 31, v114
	v_lshl_add_u64 v[112:113], v[112:113], 1, v[0:1]
	v_lshl_add_u64 v[114:115], v[114:115], 1, v[0:1]
	global_load_dwordx4 v[88:91], v[112:113], off
	global_load_dwordx4 v[92:95], v[114:115], off
	v_lshl_add_u32 v108, v108, 6, v2
	v_lshl_add_u32 v109, v109, 6, v2
	v_add_u32_e32 v120, 0x600, v59
	v_ashrrev_i32_e32 v110, 4, v120
	v_add_u32_e32 v120, 0x100, v120
	v_ashrrev_i32_e32 v111, 4, v120
	v_lshlrev_b32_e32 v116, 7, v110
	v_lshlrev_b32_e32 v118, 7, v111
	v_ashrrev_i32_e32 v117, 31, v116
	v_ashrrev_i32_e32 v119, 31, v118
	v_lshl_add_u64 v[116:117], v[116:117], 1, v[0:1]
	v_lshl_add_u64 v[118:119], v[118:119], 1, v[0:1]
	global_load_dwordx4 v[96:99], v[116:117], off
	global_load_dwordx4 v[100:103], v[118:119], off
	v_lshl_add_u32 v110, v110, 6, v2
	v_lshl_add_u32 v111, v111, 6, v2
	s_waitcnt vmcnt(7)
	ds_write_b128 v104, v[72:75]
	s_waitcnt vmcnt(6)
	ds_write_b128 v105, v[76:79]
	s_waitcnt vmcnt(5)
	ds_write_b128 v106, v[80:83]
	s_waitcnt vmcnt(4)
	ds_write_b128 v107, v[84:87]
	s_waitcnt vmcnt(3)
	ds_write_b128 v108, v[88:91]
	s_waitcnt vmcnt(2)
	ds_write_b128 v109, v[92:95]
	s_waitcnt vmcnt(1)
	ds_write_b128 v110, v[96:99]
	s_waitcnt vmcnt(0)
	ds_write_b128 v111, v[100:103]
	s_movk_i32 s14, 0x800
	v_bfe_u32 v54, v59, 4, 2
	v_ashrrev_i32_e32 v55, 7, v59
	v_lshlrev_b32_e32 v4, 4, v54
	v_lshlrev_b32_e32 v0, 12, v55
	v_lshlrev_b32_e32 v5, 6, v49
	v_or3_b32 v57, v4, v0, v5
	s_waitcnt lgkmcnt(0)
	s_barrier
; #define MFMA16(a, b, c) __builtin_amdgcn_mfma_f32_16x16x32_bf16(a, b, c, 0, 0, 0)
; __device__ void gmlp_item(const Params& p, int layer, int b, int n, int g, char* smem) {
;     ...
;   f32x4 acc[4][4];
; #pragma unroll
;   for (int m = 0; m < 4; ++m)
; #pragma unroll
;     for (int nn = 0; nn < 4; ++nn) acc[m][nn] = f32x4{0.f, 0.f, 0.f, 0.f};
; #pragma unroll
;   for (int ks = 0; ks < 4; ++ks) {
;     bf16x8 a[4], bb[4];
; #pragma unroll
;     for (int m = 0; m < 4; ++m)
;       a[m] = *reinterpret_cast<const bf16x8*>(smem + ks * 8192 + (wr * 64 + m * 16 + fr) * 64 + fq * 16);
; #pragma unroll
;     for (int nn = 0; nn < 4; ++nn)
;       bb[nn] = *reinterpret_cast<const bf16x8*>(smem + 32768 + ks * 8192 + (wc * 64 + nn * 16 + fr) * 64 + fq * 16);
; #pragma unroll
;     for (int m = 0; m < 4; ++m)
; #pragma unroll
;       for (int nn = 0; nn < 4; ++nn) acc[m][nn] = MFMA16(a[m], bb[nn], acc[m][nn]);
;   }
;   __syncthreads();
;   {
;     float* Tf = reinterpret_cast<float*>(smem);
; #pragma unroll
;     for (int m = 0; m < 4; ++m)
; #pragma unroll
;       for (int j = 0; j < 4; ++j) {
;         int t = wr * 64 + m * 16 + fq * 4 + j;
;         float bias = p.gm_b_s[(size_t)layer * 512 + g * 128 + t];
	ds_read_b128 v[0:3], v57
	v_bfe_u32 v61, v59, 6, 1
	v_lshlrev_b32_e32 v6, 12, v61
	v_or3_b32 v63, v4, v6, v5
	ds_read_b128 v[4:7], v63 offset:32768
	ds_read_b128 v[8:11], v57 offset:1024
	ds_read_b128 v[12:15], v63 offset:33792
	ds_read_b128 v[24:27], v63 offset:34816
	ds_read_b128 v[28:31], v63 offset:35840
	s_waitcnt lgkmcnt(4)
	v_mfma_f32_16x16x32_bf16 v[16:19], v[0:3], v[4:7], 0
	s_ashr_i32 s14, s17, 31
	s_add_u32 s17, s28, s17
	s_addc_u32 s20, s29, s14
	s_waitcnt lgkmcnt(2)
	v_mfma_f32_16x16x32_bf16 v[20:23], v[0:3], v[12:15], 0
	s_lshl_b32 s14, s16, 2
	s_add_u32 s14, s24, s14
	v_lshlrev_b32_e32 v55, 6, v55
	s_waitcnt lgkmcnt(1)
	v_mfma_f32_16x16x32_bf16 v[36:39], v[0:3], v[24:27], 0
	s_addc_u32 s15, s25, 0
	v_lshl_or_b32 v54, v54, 2, v55
	s_add_u32 s14, s14, 0x1000
	s_waitcnt lgkmcnt(0)
	v_mfma_f32_16x16x32_bf16 v[40:43], v[0:3], v[28:31], 0
	s_addc_u32 s15, s15, 0
	v_ashrrev_i32_e32 v55, 31, v54
	v_lshl_add_u64 v[126:127], v[54:55], 2, s[14:15]
	v_mfma_f32_16x16x32_bf16 v[44:47], v[8:11], v[4:7], 0
	v_or_b32_e32 v130, 32, v54
	v_ashrrev_i32_e32 v131, 31, v130
	v_lshlrev_b32_e32 v49, 2, v49
	v_mfma_f32_16x16x32_bf16 v[50:53], v[8:11], v[12:15], 0
	v_lshl_add_u64 v[130:131], v[130:131], 2, s[14:15]
	v_ashrrev_i32_e32 v69, 31, v68
	v_ashrrev_i32_e32 v67, 31, v66
	v_mfma_f32_16x16x32_bf16 v[70:73], v[8:11], v[24:27], 0
	v_ashrrev_i32_e32 v65, 31, v64
	v_mfma_f32_16x16x32_bf16 v[74:77], v[8:11], v[28:31], 0
	ds_read_b128 v[0:3], v57 offset:2048
	ds_read_b128 v[8:11], v57 offset:3072
	s_waitcnt lgkmcnt(1)
	v_mfma_f32_16x16x32_bf16 v[82:85], v[0:3], v[12:15], 0
	s_waitcnt lgkmcnt(0)
	v_mfma_f32_16x16x32_bf16 v[98:101], v[8:11], v[12:15], 0
	ds_read_b128 v[12:15], v57 offset:8192
	v_mfma_f32_16x16x32_bf16 v[78:81], v[0:3], v[4:7], 0
	v_mfma_f32_16x16x32_bf16 v[86:89], v[0:3], v[24:27], 0
	v_mfma_f32_16x16x32_bf16 v[94:97], v[8:11], v[4:7], 0
	v_mfma_f32_16x16x32_bf16 v[32:35], v[8:11], v[24:27], 0
	ds_read_b128 v[102:105], v63 offset:40960
	ds_read_b128 v[24:27], v57 offset:9216
	ds_read_b128 v[106:109], v63 offset:41984
	ds_read_b128 v[118:121], v63 offset:43008
	ds_read_b128 v[4:7], v63 offset:44032
	v_mfma_f32_16x16x32_bf16 v[90:93], v[0:3], v[28:31], 0
	s_waitcnt lgkmcnt(4)
	v_mfma_f32_16x16x32_bf16 v[110:113], v[12:15], v[102:105], v[16:19]
	s_waitcnt lgkmcnt(2)
	v_mfma_f32_16x16x32_bf16 v[114:117], v[12:15], v[106:109], v[20:23]
	s_waitcnt lgkmcnt(1)
	v_mfma_f32_16x16x32_bf16 v[122:125], v[12:15], v[118:121], v[36:39]
	s_waitcnt lgkmcnt(0)
	v_mfma_f32_16x16x32_bf16 v[134:137], v[12:15], v[4:7], v[40:43]
	ds_read_b128 v[146:149], v57 offset:10240
	ds_read_b128 v[12:15], v57 offset:11264
	v_mfma_f32_16x16x32_bf16 v[0:3], v[8:11], v[28:31], 0
	ds_read_b128 v[150:153], v57 offset:16384
	ds_read_b128 v[162:165], v57 offset:17408
	ds_read_b128 v[166:169], v57 offset:18432
	ds_read_b128 v[8:11], v57 offset:19456
	ds_read_b128 v[36:39], v63 offset:49152
	ds_read_b128 v[28:31], v63 offset:50176
	ds_read_b128 v[20:23], v63 offset:51200
	ds_read_b128 v[16:19], v63 offset:52224
	v_mfma_f32_16x16x32_bf16 v[138:141], v[24:27], v[102:105], v[44:47]
	v_mfma_f32_16x16x32_bf16 v[50:53], v[24:27], v[106:109], v[50:53]
	v_mfma_f32_16x16x32_bf16 v[70:73], v[24:27], v[118:121], v[70:73]
	v_mfma_f32_16x16x32_bf16 v[74:77], v[24:27], v[4:7], v[74:77]
	ds_read_b128 v[170:173], v57 offset:24576
	ds_read_b128 v[174:177], v57 offset:25600
	ds_read_b128 v[178:181], v57 offset:26624
	ds_read_b128 v[24:27], v57 offset:27648
	ds_read_b128 v[182:185], v63 offset:57344
	ds_read_b128 v[186:189], v63 offset:58368
	ds_read_b128 v[44:47], v63 offset:59392
	ds_read_b128 v[40:43], v63 offset:60416
	s_waitcnt lgkmcnt(0)
	v_mfma_f32_16x16x32_bf16 v[78:81], v[146:149], v[102:105], v[78:81]
	s_barrier
	global_load_dwordx4 v[190:193], v[130:131], off
	v_mfma_f32_16x16x32_bf16 v[82:85], v[146:149], v[106:109], v[82:85]
	v_ashrrev_i32_e32 v63, 31, v62
	v_mfma_f32_16x16x32_bf16 v[86:89], v[146:149], v[118:121], v[86:89]
	v_mfma_f32_16x16x32_bf16 v[90:93], v[146:149], v[4:7], v[90:93]
	global_load_dwordx4 v[146:149], v[126:127], off
	v_or_b32_e32 v126, 16, v54
	v_ashrrev_i32_e32 v127, 31, v126
	v_lshl_add_u64 v[126:127], v[126:127], 2, s[14:15]
	v_mfma_f32_16x16x32_bf16 v[110:113], v[150:153], v[36:39], v[110:113]
	v_mfma_f32_16x16x32_bf16 v[114:117], v[150:153], v[28:31], v[114:117]
	v_mfma_f32_16x16x32_bf16 v[122:125], v[150:153], v[20:23], v[122:125]
	v_mfma_f32_16x16x32_bf16 v[134:137], v[150:153], v[16:19], v[134:137]
	global_load_dwordx4 v[150:153], v[126:127], off
	v_lshl_or_b32 v126, v61, 8, v49
	v_mad_u64_u32 v[126:127], s[48:49], v54, s69, v[126:127]
	v_mfma_f32_16x16x32_bf16 v[110:113], v[170:173], v[182:185], v[110:113]
	v_add_u32_e32 v57, 0x400, v126
	v_or_b32_e32 v54, 48, v54
	v_ashrrev_i32_e32 v61, 31, v60
	v_mfma_f32_16x16x32_bf16 v[114:117], v[170:173], v[186:189], v[114:117]
	v_mfma_f32_16x16x32_bf16 v[122:125], v[170:173], v[44:47], v[122:125]
	s_waitcnt vmcnt(1)
; #define MFMA16(a, b, c) __builtin_amdgcn_mfma_f32_16x16x32_bf16(a, b, c, 0, 0, 0)
; __device__ void gmlp_item(const Params& p, int layer, int b, int n, int g, char* smem) {
;     ...
;   f32x4 acc[4][4];
; #pragma unroll
;   for (int m = 0; m < 4; ++m)
; #pragma unroll
;     for (int nn = 0; nn < 4; ++nn) acc[m][nn] = f32x4{0.f, 0.f, 0.f, 0.f};
; #pragma unroll
;   for (int ks = 0; ks < 4; ++ks) {
;     bf16x8 a[4], bb[4];
; #pragma unroll
;     for (int m = 0; m < 4; ++m)
;       a[m] = *reinterpret_cast<const bf16x8*>(smem + ks * 8192 + (wr * 64 + m * 16 + fr) * 64 + fq * 16);
; #pragma unroll
;     for (int nn = 0; nn < 4; ++nn)
;       bb[nn] = *reinterpret_cast<const bf16x8*>(smem + 32768 + ks * 8192 + (wc * 64 + nn * 16 + fr) * 64 + fq * 16);
; #pragma unroll
;     for (int m = 0; m < 4; ++m)
; #pragma unroll
;       for (int nn = 0; nn < 4; ++nn) acc[m][nn] = MFMA16(a[m], bb[nn], acc[m][nn]);
;   }
;   __syncthreads();
;   {
;     float* Tf = reinterpret_cast<float*>(smem);
; #pragma unroll
;     for (int m = 0; m < 4; ++m)
; #pragma unroll
;       for (int j = 0; j < 4; ++j) {
;         int t = wr * 64 + m * 16 + fq * 4 + j;
;         float bias = p.gm_b_s[(size_t)layer * 512 + g * 128 + t];
; #pragma unroll
;         for (int nn = 0; nn < 4; ++nn) Tf[t * 132 + wc * 64 + nn * 16 + fr] = acc[m][nn][j] + bias;
	s_nop 1
	v_add_f32_e32 v49, v110, v146
	v_mfma_f32_16x16x32_bf16 v[134:137], v[170:173], v[40:43], v[134:137]
	s_nop 1
	v_add_f32_e32 v55, v114, v146
	ds_write2_b32 v126, v49, v55 offset1:16
	v_add_f32_e32 v49, v122, v146
	v_mfma_f32_16x16x32_bf16 v[98:101], v[12:15], v[106:109], v[98:101]
	v_mfma_f32_16x16x32_bf16 v[94:97], v[12:15], v[102:105], v[94:97]
	s_nop 0
	v_add_f32_e32 v55, v134, v146
	ds_write2_b32 v126, v49, v55 offset0:32 offset1:48
	v_add_f32_e32 v49, v111, v147
	v_add_f32_e32 v55, v115, v147
	ds_write2_b32 v126, v49, v55 offset0:132 offset1:148
	v_add_f32_e32 v49, v123, v147
	v_add_f32_e32 v55, v135, v147
	ds_write2_b32 v126, v49, v55 offset0:164 offset1:180
	v_add_f32_e32 v49, v112, v148
	v_add_f32_e32 v55, v116, v148
	ds_write2_b32 v57, v49, v55 offset0:8 offset1:24
	v_add_f32_e32 v49, v124, v148
	v_add_f32_e32 v55, v136, v148
	ds_write2_b32 v57, v49, v55 offset0:40 offset1:56
	v_add_f32_e32 v49, v113, v149
	v_add_f32_e32 v55, v117, v149
	ds_write2_b32 v57, v49, v55 offset0:140 offset1:156
	v_add_f32_e32 v49, v125, v149
	v_add_f32_e32 v55, v137, v149
	ds_write2_b32 v57, v49, v55 offset0:172 offset1:188
	v_ashrrev_i32_e32 v55, 31, v54
	v_lshl_add_u64 v[54:55], v[54:55], 2, s[14:15]
	global_load_dwordx4 v[106:109], v[54:55], off
	v_mfma_f32_16x16x32_bf16 v[102:105], v[162:165], v[36:39], v[138:141]
	v_add_u32_e32 v54, 0x2000, v126
	v_ashrrev_i32_e32 v57, 31, v56
	v_mfma_f32_16x16x32_bf16 v[50:53], v[162:165], v[28:31], v[50:53]
	v_mfma_f32_16x16x32_bf16 v[70:73], v[162:165], v[20:23], v[70:73]
	v_mfma_f32_16x16x32_bf16 v[74:77], v[162:165], v[16:19], v[74:77]
	v_mfma_f32_16x16x32_bf16 v[102:105], v[174:177], v[182:185], v[102:105]
	v_mfma_f32_16x16x32_bf16 v[50:53], v[174:177], v[186:189], v[50:53]
	v_mfma_f32_16x16x32_bf16 v[70:73], v[174:177], v[44:47], v[70:73]
	s_waitcnt vmcnt(1)
	s_nop 4
	v_add_f32_e32 v49, v102, v150
	v_add_f32_e32 v50, v50, v150
	ds_write2_b32 v54, v49, v50 offset0:64 offset1:80
	v_mfma_f32_16x16x32_bf16 v[74:77], v[174:177], v[40:43], v[74:77]
	v_add_f32_e32 v55, v53, v153
	v_add_f32_e32 v49, v70, v150
	v_mfma_f32_16x16x32_bf16 v[78:81], v[166:169], v[36:39], v[78:81]
	v_mfma_f32_16x16x32_bf16 v[82:85], v[166:169], v[28:31], v[82:85]
	s_nop 3
	v_add_f32_e32 v50, v74, v150
	ds_write2_b32 v54, v49, v50 offset0:96 offset1:112
	v_add_f32_e32 v49, v103, v151
	v_add_f32_e32 v50, v51, v151
	ds_write2_b32 v54, v49, v50 offset0:196 offset1:212
	v_add_f32_e32 v49, v71, v151
	v_add_f32_e32 v50, v75, v151
	ds_write2_b32 v54, v49, v50 offset0:228 offset1:244
	v_add_f32_e32 v49, v104, v152
	v_add_f32_e32 v50, v52, v152
	v_add_u32_e32 v54, 0x2400, v126
	v_mfma_f32_16x16x32_bf16 v[86:89], v[166:169], v[20:23], v[86:89]
	ds_write2_b32 v54, v49, v50 offset0:72 offset1:88
	v_add_f32_e32 v49, v72, v152
	v_add_f32_e32 v50, v76, v152
	v_mfma_f32_16x16x32_bf16 v[90:93], v[166:169], v[16:19], v[90:93]
	ds_write2_b32 v54, v49, v50 offset0:104 offset1:120
	v_add_f32_e32 v49, v105, v153
	ds_write2_b32 v54, v49, v55 offset0:204 offset1:220
	v_mfma_f32_16x16x32_bf16 v[50:53], v[178:181], v[182:185], v[78:81]
	v_add_f32_e32 v49, v73, v153
	v_add_f32_e32 v55, v77, v153
	ds_write2_b32 v54, v49, v55 offset0:236 offset1:252
	v_mfma_f32_16x16x32_bf16 v[70:73], v[178:181], v[186:189], v[82:85]
	v_add_u32_e32 v54, 0x4000, v126
	s_nop 2
	v_add_f32_e32 v49, v50, v190
	v_mfma_f32_16x16x32_bf16 v[74:77], v[178:181], v[44:47], v[86:89]
	v_mfma_f32_16x16x32_bf16 v[78:81], v[178:181], v[40:43], v[90:93]
	s_nop 0
	v_add_f32_e32 v50, v70, v190
	ds_write2_b32 v54, v49, v50 offset0:128 offset1:144
	s_nop 3
	v_add_f32_e32 v49, v74, v190
	v_mfma_f32_16x16x32_bf16 v[32:35], v[12:15], v[118:121], v[32:35]
	v_mfma_f32_16x16x32_bf16 v[0:3], v[12:15], v[4:7], v[0:3]
	v_add_f32_e32 v50, v78, v190
	ds_write2_b32 v54, v49, v50 offset0:160 offset1:176
	v_add_f32_e32 v49, v51, v191
	v_add_f32_e32 v4, v71, v191
	v_add_u32_e32 v50, 0x4400, v126
	v_add_f32_e32 v12, v75, v191
	v_add_f32_e32 v13, v79, v191
	ds_write2_b32 v50, v49, v4 offset0:4 offset1:20
	v_mfma_f32_16x16x32_bf16 v[4:7], v[8:11], v[36:39], v[94:97]
	ds_write2_b32 v50, v12, v13 offset0:36 offset1:52
	v_ashrrev_i32_e32 v49, 31, v48
	v_lshl_add_u64 v[70:71], v[56:57], 0, s[36:37]
	v_mfma_f32_16x16x32_bf16 v[12:15], v[8:11], v[28:31], v[98:101]
	v_add_f32_e32 v28, v52, v192
	v_add_f32_e32 v29, v72, v192
	ds_write2_b32 v50, v28, v29 offset0:136 offset1:152
	v_mfma_f32_16x16x32_bf16 v[20:23], v[8:11], v[20:23], v[32:35]
	v_add_f32_e32 v28, v76, v192
	v_add_f32_e32 v29, v80, v192
	ds_write2_b32 v50, v28, v29 offset0:168 offset1:184
	v_mfma_f32_16x16x32_bf16 v[0:3], v[8:11], v[16:19], v[0:3]
	v_add_f32_e32 v8, v53, v193
	v_add_f32_e32 v9, v73, v193
	v_add_u32_e32 v16, 0x4800, v126
	v_mfma_f32_16x16x32_bf16 v[4:7], v[24:27], v[182:185], v[4:7]
	ds_write2_b32 v16, v8, v9 offset0:12 offset1:28
	v_add_f32_e32 v17, v77, v193
	v_add_f32_e32 v18, v81, v193
	v_mfma_f32_16x16x32_bf16 v[8:11], v[24:27], v[186:189], v[12:15]
	ds_write2_b32 v16, v17, v18 offset0:44 offset1:60
	s_waitcnt vmcnt(0)
; __device__ __forceinline__ unsigned pack2(float a, float b) { return (unsigned)f2bf(a) | ((unsigned)f2bf(b) << 16); }
; __device__ __forceinline__ float bflo(unsigned w) { return __uint_as_float(w << 16); }
; __device__ __forceinline__ float bfhi(unsigned w) { return __uint_as_float(w & 0xffff0000u); }
; __device__ __forceinline__ float silu_f(float g) { return g / (1.f + __expf(-g)); }
; __device__ void gmlp_item(const Params& p, int layer, int b, int n, int g, char* smem) {
;     ...
;     for (int m = 0; m < 4; ++m)
; #pragma unroll
;       for (int j = 0; j < 4; ++j) {
;         int t = wr * 64 + m * 16 + fq * 4 + j;
;         float bias = p.gm_b_s[(size_t)layer * 512 + g * 128 + t];
; #pragma unroll
;         for (int nn = 0; nn < 4; ++nn) Tf[t * 132 + wc * 64 + nn * 16 + fr] = acc[m][nn][j] + bias;
;       }
;     __syncthreads();
;     uint4 uu[8], gt[8];
; #pragma unroll
;     for (int i = 0; i < 8; ++i) {
;       int q = tid + 256 * i, t = q >> 4, c = (q & 15) * 8;
;       uu[i] = *reinterpret_cast<const uint4*>(P + (t0 + t) * NP + g * 128 + c);
;       gt[i] = *reinterpret_cast<const uint4*>(P + (t0 + t) * NP + 1024 + g * 128 + c);
;     }
; #pragma unroll
;     for (int i = 0; i < 8; ++i) {
;       int q = tid + 256 * i, t = q >> 4, c = (q & 15) * 8;
;       float4 m0 = *reinterpret_cast<const float4*>(Tf + t * 132 + c);
;       float4 m1 = *reinterpret_cast<const float4*>(Tf + t * 132 + c + 4);
;       float mm[8] = {m0.x, m0.y, m0.z, m0.w, m1.x, m1.y, m1.z, m1.w};
;       unsigned uw[4] = {uu[i].x, uu[i].y, uu[i].z, uu[i].w};
;       unsigned gw[4] = {gt[i].x, gt[i].y, gt[i].z, gt[i].w};
;       unsigned ow[4];
; #pragma unroll
;       for (int e = 0; e < 4; ++e) {
;         float y0 = bflo(uw[e]) * mm[2 * e] * silu_f(bflo(gw[e]));
;         float y1 = bfhi(uw[e]) * mm[2 * e + 1] * silu_f(bfhi(gw[e]));
;         ow[e] = pack2(y0, y1);
;       }
;       *reinterpret_cast<uint4*>(Y + (t0 + t) * YW + g * 128 + c) = make_uint4(ow[0], ow[1], ow[2], ow[3]);
	s_nop 1
	v_add_f32_e32 v4, v4, v106
	v_add_u32_e32 v16, 0x6000, v126
	v_mfma_f32_16x16x32_bf16 v[12:15], v[24:27], v[44:47], v[20:23]
	v_lshl_add_u64 v[36:37], v[62:63], 0, s[36:37]
	v_add_f32_e32 v8, v8, v106
	ds_write2_b32 v16, v4, v8 offset0:192 offset1:208
	v_mfma_f32_16x16x32_bf16 v[0:3], v[24:27], v[40:43], v[0:3]
	v_lshl_add_u64 v[20:21], v[64:65], 0, s[36:37]
	s_nop 2
	v_add_f32_e32 v4, v12, v106
	v_lshl_add_u64 v[38:39], v[60:61], 0, s[36:37]
	s_nop 1
	v_add_f32_e32 v0, v0, v106
	ds_write2_b32 v16, v4, v0 offset0:224 offset1:240
	v_add_f32_e32 v0, v5, v107
	v_add_f32_e32 v4, v9, v107
	v_add_u32_e32 v5, 0x6400, v126
	ds_write2_b32 v5, v0, v4 offset0:68 offset1:84
	v_add_f32_e32 v0, v13, v107
	v_add_f32_e32 v1, v1, v107
	ds_write2_b32 v5, v0, v1 offset0:100 offset1:116
	v_add_f32_e32 v0, v6, v108
	v_add_f32_e32 v1, v10, v108
	ds_write2_b32 v5, v0, v1 offset0:200 offset1:216
	v_add_f32_e32 v0, v14, v108
	v_add_f32_e32 v1, v2, v108
	ds_write2_b32 v5, v0, v1 offset0:232 offset1:248
	v_add_f32_e32 v0, v7, v109
	v_add_f32_e32 v1, v11, v109
	v_add_u32_e32 v2, 0x6800, v126
	ds_write2_b32 v2, v0, v1 offset0:76 offset1:92
	v_add_f32_e32 v0, v15, v109
	v_add_f32_e32 v1, v3, v109
	ds_write2_b32 v2, v0, v1 offset0:108 offset1:124
	v_lshlrev_b32_e32 v0, 3, v59
	v_lshl_add_u64 v[8:9], v[48:49], 0, s[36:37]
	v_mov_b64_e32 v[10:11], s[12:13]
	v_and_b32_e32 v24, 0x78, v0
	v_mad_u64_u32 v[0:1], s[12:13], v8, s45, v[10:11]
	v_mad_i32_i24 v1, v9, s45, v1
	s_lshl_b32 s12, s16, 1
	s_mov_b32 s13, s37
	v_lshl_add_u64 v[0:1], v[0:1], 0, s[12:13]
	v_lshlrev_b32_e32 v128, 1, v24
	v_lshl_add_u64 v[12:13], v[68:69], 0, s[36:37]
	v_lshl_add_u64 v[52:53], v[0:1], 0, v[128:129]
	v_mad_u64_u32 v[0:1], s[14:15], v12, s45, v[10:11]
	v_mad_i32_i24 v1, v13, s45, v1
	v_lshl_add_u64 v[0:1], v[0:1], 0, s[12:13]
	v_lshl_add_u64 v[32:33], v[0:1], 0, v[128:129]
	v_mad_u64_u32 v[0:1], s[14:15], v70, s45, v[10:11]
	v_mad_i32_i24 v1, v71, s45, v1
	v_lshl_add_u64 v[0:1], v[0:1], 0, s[12:13]
	v_lshl_add_u64 v[4:5], v[0:1], 0, v[128:129]
	s_waitcnt lgkmcnt(0)
	s_barrier
	global_load_dwordx4 v[0:3], v[4:5], off
	s_nop 0
	global_load_dwordx4 v[4:7], v[4:5], off offset:2048
	v_lshl_add_u64 v[16:17], v[66:67], 0, s[36:37]
	v_mad_u64_u32 v[14:15], s[14:15], v16, s45, v[10:11]
	v_mad_i32_i24 v15, v17, s45, v15
	v_lshl_add_u64 v[14:15], v[14:15], 0, s[12:13]
	v_lshl_add_u64 v[30:31], v[14:15], 0, v[128:129]
	v_mad_u64_u32 v[14:15], s[14:15], v20, s45, v[10:11]
	v_mad_i32_i24 v15, v21, s45, v15
	v_lshl_add_u64 v[14:15], v[14:15], 0, s[12:13]
	v_lshl_add_u64 v[26:27], v[14:15], 0, v[128:129]
	v_mad_u64_u32 v[14:15], s[14:15], v36, s45, v[10:11]
	v_mad_i32_i24 v15, v37, s45, v15
	v_ashrrev_i32_e32 v59, 31, v58
	v_lshl_add_u64 v[14:15], v[14:15], 0, s[12:13]
	v_lshl_add_u64 v[72:73], v[58:59], 0, s[36:37]
	v_lshl_add_u64 v[22:23], v[14:15], 0, v[128:129]
	v_mad_u64_u32 v[14:15], s[14:15], v38, s45, v[10:11]
	v_mad_u64_u32 v[10:11], s[14:15], v72, s45, v[10:11]
	v_mad_i32_i24 v15, v39, s45, v15
	v_mad_i32_i24 v11, v73, s45, v11
	v_lshl_add_u64 v[14:15], v[14:15], 0, s[12:13]
	v_lshl_add_u64 v[10:11], v[10:11], 0, s[12:13]
	s_add_u32 s12, s17, s12
	s_addc_u32 s13, s20, 0
	v_lshl_add_u64 v[18:19], v[14:15], 0, v[128:129]
	v_lshl_add_u64 v[14:15], v[10:11], 0, v[128:129]
	v_lshlrev_b32_e32 v10, 2, v24
	v_lshl_add_u64 v[24:25], s[12:13], 0, v[128:129]
	v_lshl_add_u64 v[74:75], v[24:25], 0, s[40:41]
	v_mad_u64_u32 v[54:55], s[12:13], v48, s69, v[10:11]
	v_mad_u64_u32 v[48:49], s[12:13], v12, s70, v[74:75]
	v_mad_u64_u32 v[46:47], s[12:13], v16, s70, v[74:75]
	v_mad_u64_u32 v[50:51], s[12:13], v8, s70, v[74:75]
	v_mad_i32_i24 v49, v13, s70, v49
	v_mad_i32_i24 v47, v17, s70, v47
	v_mad_u64_u32 v[44:45], s[12:13], v20, s70, v[74:75]
	v_mad_u64_u32 v[16:17], s[12:13], v60, s69, v[10:11]
	v_mad_u64_u32 v[12:13], s[12:13], v58, s69, v[10:11]
	v_mad_i32_i24 v51, v9, s70, v51
	v_mad_i32_i24 v45, v21, s70, v45
	v_mad_u64_u32 v[20:21], s[12:13], v62, s69, v[10:11]
	v_mad_u64_u32 v[8:9], s[12:13], v56, s69, v[10:11]
	v_mad_u64_u32 v[28:29], s[12:13], v66, s69, v[10:11]
	v_mad_u64_u32 v[34:35], s[12:13], v68, s69, v[10:11]
	v_mad_u64_u32 v[24:25], s[12:13], v64, s69, v[10:11]
	v_mad_u64_u32 v[42:43], s[12:13], v36, s70, v[74:75]
	v_mad_i32_i24 v43, v37, s70, v43
	v_mad_u64_u32 v[36:37], s[12:13], v70, s70, v[74:75]
	v_mad_u64_u32 v[40:41], s[12:13], v38, s70, v[74:75]
	v_mad_i32_i24 v41, v39, s70, v41
	v_mad_u64_u32 v[38:39], s[12:13], v72, s70, v[74:75]
	v_mad_i32_i24 v39, v73, s70, v39
	v_mad_i32_i24 v37, v71, s70, v37
	s_waitcnt vmcnt(1)
	v_lshlrev_b32_e32 v63, 16, v1
	s_waitcnt vmcnt(0)
	v_lshlrev_b32_e32 v13, 16, v5
	v_lshlrev_b32_e32 v17, 16, v4
	v_mul_f32_e32 v9, 0xbfb8aa3b, v17
	v_and_b32_e32 v21, 0xffff0000, v5
	v_mul_f32_e32 v5, 0xbfb8aa3b, v13
	v_exp_f32_e32 v60, v9
	v_exp_f32_e32 v61, v5
	ds_read_b128 v[56:59], v8
	ds_read_b128 v[8:11], v8 offset:16
	v_and_b32_e32 v25, 0xffff0000, v4
	v_mul_f32_e32 v4, 0xbfb8aa3b, v25
	v_pk_add_f32 v[60:61], v[60:61], 1.0 op_sel_hi:[1,0]
	s_waitcnt lgkmcnt(1)
; __device__ __forceinline__ unsigned pack2(float a, float b) { return (unsigned)f2bf(a) | ((unsigned)f2bf(b) << 16); }
; __device__ __forceinline__ float bflo(unsigned w) { return __uint_as_float(w << 16); }
; __device__ __forceinline__ float bfhi(unsigned w) { return __uint_as_float(w & 0xffff0000u); }
; __device__ __forceinline__ float silu_f(float g) { return g / (1.f + __expf(-g)); }
; __device__ void gmlp_item(const Params& p, int layer, int b, int n, int g, char* smem) {
;     ...
; #pragma unroll
;     for (int i = 0; i < 8; ++i) {
;       int q = tid + 256 * i, t = q >> 4, c = (q & 15) * 8;
;       float4 m0 = *reinterpret_cast<const float4*>(Tf + t * 132 + c);
;       float4 m1 = *reinterpret_cast<const float4*>(Tf + t * 132 + c + 4);
;       float mm[8] = {m0.x, m0.y, m0.z, m0.w, m1.x, m1.y, m1.z, m1.w};
;       unsigned uw[4] = {uu[i].x, uu[i].y, uu[i].z, uu[i].w};
;       unsigned gw[4] = {gt[i].x, gt[i].y, gt[i].z, gt[i].w};
;       unsigned ow[4];
; #pragma unroll
;       for (int e = 0; e < 4; ++e) {
;         float y0 = bflo(uw[e]) * mm[2 * e] * silu_f(bflo(gw[e]));
;         float y1 = bfhi(uw[e]) * mm[2 * e + 1] * silu_f(bfhi(gw[e]));
;         ow[e] = pack2(y0, y1);
;       }
;       *reinterpret_cast<uint4*>(Y + (t0 + t) * YW + g * 128 + c) = make_uint4(ow[0], ow[1], ow[2], ow[3]);
	v_mov_b32_e32 v64, v56
	v_exp_f32_e32 v4, v4
	v_lshlrev_b32_e32 v62, 16, v0
	v_mov_b32_e32 v65, v58
	v_rcp_f32_e32 v61, v61
	s_nop 0
	v_mul_f32_e32 v61, v13, v61
	v_and_b32_e32 v1, 0xffff0000, v1
	v_mul_f32_e32 v5, 0xbfb8aa3b, v21
	v_exp_f32_e32 v5, v5
	v_rcp_f32_e32 v60, v60
	s_nop 0
	v_mul_f32_e32 v60, v17, v60
	v_and_b32_e32 v0, 0xffff0000, v0
	v_mov_b32_e32 v58, v57
	v_pk_add_f32 v[4:5], v[4:5], 1.0 op_sel_hi:[1,0]
	v_pk_mul_f32 v[0:1], v[58:59], v[0:1]
	v_pk_mul_f32 v[62:63], v[64:65], v[62:63]
	v_rcp_f32_e32 v5, v5
	s_nop 0
	v_mul_f32_e32 v5, v21, v5
	v_pk_mul_f32 v[60:61], v[60:61], v[62:63]
	v_rcp_f32_e32 v4, v4
	s_nop 0
	v_mul_f32_e32 v4, v25, v4
	v_pk_mul_f32 v[0:1], v[4:5], v[0:1]
	v_lshlrev_b32_e32 v13, 16, v7
	v_lshlrev_b32_e32 v17, 16, v6
	v_cvt_pk_bf16_f32 v1, v61, v1
	v_cvt_pk_bf16_f32 v0, v60, v0
	v_mul_f32_e32 v4, 0xbfb8aa3b, v17
	v_mul_f32_e32 v5, 0xbfb8aa3b, v13
	v_exp_f32_e32 v4, v4
	v_exp_f32_e32 v5, v5
	v_and_b32_e32 v25, 0xffff0000, v6
	v_mul_f32_e32 v6, 0xbfb8aa3b, v25
	v_and_b32_e32 v21, 0xffff0000, v7
	v_exp_f32_e32 v60, v6
	v_pk_add_f32 v[64:65], v[4:5], 1.0 op_sel_hi:[1,0]
	global_load_dwordx4 v[4:7], v[14:15], off
	global_load_dwordx4 v[56:59], v[14:15], off offset:2048
	s_waitcnt lgkmcnt(0)
	v_mov_b32_e32 v14, v8
	v_mov_b32_e32 v15, v10
	v_lshlrev_b32_e32 v63, 16, v3
	v_lshlrev_b32_e32 v62, 16, v2
	v_pk_mul_f32 v[14:15], v[14:15], v[62:63]
	v_rcp_f32_e32 v63, v65
	s_nop 0
	v_mul_f32_e32 v63, v13, v63
	v_mul_f32_e32 v10, 0xbfb8aa3b, v21
	v_exp_f32_e32 v61, v10
	v_rcp_f32_e32 v62, v64
	s_nop 0
	v_mul_f32_e32 v62, v17, v62
	v_mov_b32_e32 v10, v9
	v_and_b32_e32 v3, 0xffff0000, v3
	v_pk_add_f32 v[60:61], v[60:61], 1.0 op_sel_hi:[1,0]
	v_and_b32_e32 v2, 0xffff0000, v2
	v_pk_mul_f32 v[2:3], v[10:11], v[2:3]
	v_pk_mul_f32 v[14:15], v[62:63], v[14:15]
	v_rcp_f32_e32 v9, v61
	s_nop 0
	v_mul_f32_e32 v9, v21, v9
	v_rcp_f32_e32 v8, v60
	s_nop 0
	v_mul_f32_e32 v8, v25, v8
	v_pk_mul_f32 v[2:3], v[8:9], v[2:3]
	v_cvt_pk_bf16_f32 v3, v15, v3
	v_cvt_pk_bf16_f32 v2, v14, v2
	s_waitcnt vmcnt(0)
	v_lshlrev_b32_e32 v21, 16, v56
	v_mul_f32_e32 v8, 0xbfb8aa3b, v21
	v_and_b32_e32 v29, 0xffff0000, v56
	v_lshlrev_b32_e32 v17, 16, v57
	v_exp_f32_e32 v60, v8
	v_mul_f32_e32 v8, 0xbfb8aa3b, v29
	v_exp_f32_e32 v56, v8
	v_mul_f32_e32 v8, 0xbfb8aa3b, v17
	v_exp_f32_e32 v61, v8
	ds_read_b128 v[8:11], v12
	ds_read_b128 v[12:15], v12 offset:16
	v_and_b32_e32 v25, 0xffff0000, v57
	v_lshlrev_b32_e32 v63, 16, v5
	v_pk_add_f32 v[60:61], v[60:61], 1.0 op_sel_hi:[1,0]
	s_waitcnt lgkmcnt(1)
	v_mov_b32_e32 v64, v8
	v_mov_b32_e32 v65, v10
	v_lshlrev_b32_e32 v62, 16, v4
	v_and_b32_e32 v5, 0xffff0000, v5
	v_rcp_f32_e32 v61, v61
	s_nop 0
	v_mul_f32_e32 v61, v17, v61
	v_and_b32_e32 v4, 0xffff0000, v4
	v_mul_f32_e32 v10, 0xbfb8aa3b, v25
	v_exp_f32_e32 v57, v10
	v_rcp_f32_e32 v60, v60
	s_nop 0
	v_mul_f32_e32 v60, v21, v60
	v_mov_b32_e32 v10, v9
	v_pk_mul_f32 v[4:5], v[10:11], v[4:5]
	v_pk_add_f32 v[56:57], v[56:57], 1.0 op_sel_hi:[1,0]
	v_pk_mul_f32 v[62:63], v[64:65], v[62:63]
	v_pk_mul_f32 v[60:61], v[60:61], v[62:63]
	v_lshlrev_b32_e32 v63, 16, v7
	v_lshlrev_b32_e32 v62, 16, v6
	v_rcp_f32_e32 v9, v57
	s_nop 0
	v_mul_f32_e32 v9, v25, v9
	v_rcp_f32_e32 v8, v56
	s_nop 0
	v_mul_f32_e32 v8, v29, v8
	v_pk_mul_f32 v[4:5], v[8:9], v[4:5]
	v_lshlrev_b32_e32 v17, 16, v59
	v_lshlrev_b32_e32 v21, 16, v58
	v_cvt_pk_bf16_f32 v5, v61, v5
	v_cvt_pk_bf16_f32 v4, v60, v4
	v_mul_f32_e32 v8, 0xbfb8aa3b, v21
	v_mul_f32_e32 v9, 0xbfb8aa3b, v17
	v_exp_f32_e32 v8, v8
	v_exp_f32_e32 v9, v9
	v_and_b32_e32 v29, 0xffff0000, v58
	v_mul_f32_e32 v10, 0xbfb8aa3b, v29
	v_and_b32_e32 v25, 0xffff0000, v59
	v_exp_f32_e32 v60, v10
	v_pk_add_f32 v[64:65], v[8:9], 1.0 op_sel_hi:[1,0]
	global_load_dwordx4 v[8:11], v[18:19], off
	global_load_dwordx4 v[56:59], v[18:19], off offset:2048
	s_waitcnt lgkmcnt(0)
	v_mov_b32_e32 v18, v12
	v_mov_b32_e32 v19, v14
	v_pk_mul_f32 v[18:19], v[18:19], v[62:63]
	v_rcp_f32_e32 v63, v65
	s_nop 0
	v_mul_f32_e32 v63, v17, v63
	v_and_b32_e32 v7, 0xffff0000, v7
	v_mul_f32_e32 v14, 0xbfb8aa3b, v25
	v_exp_f32_e32 v61, v14
	v_rcp_f32_e32 v62, v64
	s_nop 0
	v_mul_f32_e32 v62, v21, v62
	v_mov_b32_e32 v14, v13
	v_and_b32_e32 v6, 0xffff0000, v6
	v_pk_add_f32 v[60:61], v[60:61], 1.0 op_sel_hi:[1,0]
	v_pk_mul_f32 v[6:7], v[14:15], v[6:7]
	v_pk_mul_f32 v[18:19], v[62:63], v[18:19]
	v_rcp_f32_e32 v13, v61
	s_nop 0
	v_mul_f32_e32 v13, v25, v13
	v_rcp_f32_e32 v12, v60
	s_nop 0
	v_mul_f32_e32 v12, v29, v12
	v_pk_mul_f32 v[6:7], v[12:13], v[6:7]
	v_cvt_pk_bf16_f32 v7, v19, v7
	v_cvt_pk_bf16_f32 v6, v18, v6
	s_waitcnt vmcnt(1)
	v_lshlrev_b32_e32 v63, 16, v9
	s_waitcnt vmcnt(0)
	v_lshlrev_b32_e32 v25, 16, v56
	v_mul_f32_e32 v12, 0xbfb8aa3b, v25
	v_and_b32_e32 v35, 0xffff0000, v56
	v_lshlrev_b32_e32 v21, 16, v57
	v_exp_f32_e32 v60, v12
	v_mul_f32_e32 v12, 0xbfb8aa3b, v35
	v_exp_f32_e32 v56, v12
	v_mul_f32_e32 v12, 0xbfb8aa3b, v21
	v_exp_f32_e32 v61, v12
	v_and_b32_e32 v29, 0xffff0000, v57
	ds_read_b128 v[12:15], v16
	ds_read_b128 v[16:19], v16 offset:16
	v_lshlrev_b32_e32 v62, 16, v8
	v_pk_add_f32 v[60:61], v[60:61], 1.0 op_sel_hi:[1,0]
	v_and_b32_e32 v9, 0xffff0000, v9
	s_waitcnt lgkmcnt(1)
; __device__ __forceinline__ unsigned pack2(float a, float b) { return (unsigned)f2bf(a) | ((unsigned)f2bf(b) << 16); }
; __device__ __forceinline__ float bflo(unsigned w) { return __uint_as_float(w << 16); }
; __device__ __forceinline__ float bfhi(unsigned w) { return __uint_as_float(w & 0xffff0000u); }
; __device__ __forceinline__ float silu_f(float g) { return g / (1.f + __expf(-g)); }
; __device__ void gmlp_item(const Params& p, int layer, int b, int n, int g, char* smem) {
;     ...
; #pragma unroll
;     for (int i = 0; i < 8; ++i) {
;       int q = tid + 256 * i, t = q >> 4, c = (q & 15) * 8;
;       float4 m0 = *reinterpret_cast<const float4*>(Tf + t * 132 + c);
;       float4 m1 = *reinterpret_cast<const float4*>(Tf + t * 132 + c + 4);
;       float mm[8] = {m0.x, m0.y, m0.z, m0.w, m1.x, m1.y, m1.z, m1.w};
;       unsigned uw[4] = {uu[i].x, uu[i].y, uu[i].z, uu[i].w};
;       unsigned gw[4] = {gt[i].x, gt[i].y, gt[i].z, gt[i].w};
;       unsigned ow[4];
; #pragma unroll
;       for (int e = 0; e < 4; ++e) {
;         float y0 = bflo(uw[e]) * mm[2 * e] * silu_f(bflo(gw[e]));
;         float y1 = bfhi(uw[e]) * mm[2 * e + 1] * silu_f(bfhi(gw[e]));
;         ow[e] = pack2(y0, y1);
;       }
;       *reinterpret_cast<uint4*>(Y + (t0 + t) * YW + g * 128 + c) = make_uint4(ow[0], ow[1], ow[2], ow[3]);
	v_mov_b32_e32 v64, v12
	v_mov_b32_e32 v65, v14
	v_pk_mul_f32 v[62:63], v[64:65], v[62:63]
	v_rcp_f32_e32 v61, v61
	s_nop 0
	v_mul_f32_e32 v61, v21, v61
	v_and_b32_e32 v8, 0xffff0000, v8
	v_mul_f32_e32 v14, 0xbfb8aa3b, v29
	v_exp_f32_e32 v57, v14
	v_rcp_f32_e32 v60, v60
	s_nop 0
	v_mul_f32_e32 v60, v25, v60
	v_mov_b32_e32 v14, v13
	v_pk_mul_f32 v[8:9], v[14:15], v[8:9]
	v_pk_add_f32 v[56:57], v[56:57], 1.0 op_sel_hi:[1,0]
	v_pk_mul_f32 v[60:61], v[60:61], v[62:63]
	v_lshlrev_b32_e32 v63, 16, v11
	v_lshlrev_b32_e32 v62, 16, v10
	v_and_b32_e32 v11, 0xffff0000, v11
	v_rcp_f32_e32 v13, v57
	s_nop 0
	v_mul_f32_e32 v13, v29, v13
	v_rcp_f32_e32 v12, v56
	s_nop 0
	v_mul_f32_e32 v12, v35, v12
	v_pk_mul_f32 v[8:9], v[12:13], v[8:9]
	v_lshlrev_b32_e32 v21, 16, v59
	v_lshlrev_b32_e32 v25, 16, v58
	v_cvt_pk_bf16_f32 v9, v61, v9
	v_cvt_pk_bf16_f32 v8, v60, v8
	v_mul_f32_e32 v12, 0xbfb8aa3b, v25
	v_mul_f32_e32 v13, 0xbfb8aa3b, v21
	v_exp_f32_e32 v12, v12
	v_exp_f32_e32 v13, v13
	v_and_b32_e32 v35, 0xffff0000, v58
	v_mul_f32_e32 v14, 0xbfb8aa3b, v35
	v_and_b32_e32 v29, 0xffff0000, v59
	v_exp_f32_e32 v60, v14
	v_pk_add_f32 v[64:65], v[12:13], 1.0 op_sel_hi:[1,0]
	global_load_dwordx4 v[12:15], v[22:23], off
	global_load_dwordx4 v[56:59], v[22:23], off offset:2048
	s_waitcnt lgkmcnt(0)
	v_mov_b32_e32 v22, v16
	v_mov_b32_e32 v23, v18
	v_pk_mul_f32 v[22:23], v[22:23], v[62:63]
	v_rcp_f32_e32 v63, v65
	s_nop 0
	v_mul_f32_e32 v63, v21, v63
	v_and_b32_e32 v10, 0xffff0000, v10
	v_mul_f32_e32 v18, 0xbfb8aa3b, v29
	v_exp_f32_e32 v61, v18
	v_rcp_f32_e32 v62, v64
	s_nop 0
	v_mul_f32_e32 v62, v25, v62
	v_mov_b32_e32 v18, v17
	v_pk_mul_f32 v[10:11], v[18:19], v[10:11]
	v_pk_add_f32 v[60:61], v[60:61], 1.0 op_sel_hi:[1,0]
	v_pk_mul_f32 v[22:23], v[62:63], v[22:23]
	s_waitcnt vmcnt(1)
	v_lshlrev_b32_e32 v63, 16, v13
	v_rcp_f32_e32 v17, v61
	s_nop 0
	v_mul_f32_e32 v17, v29, v17
	v_rcp_f32_e32 v16, v60
	s_nop 0
	v_mul_f32_e32 v16, v35, v16
	v_pk_mul_f32 v[10:11], v[16:17], v[10:11]
	s_waitcnt vmcnt(0)
	v_lshlrev_b32_e32 v29, 16, v56
	v_cvt_pk_bf16_f32 v11, v23, v11
	v_mul_f32_e32 v16, 0xbfb8aa3b, v29
	v_and_b32_e32 v55, 0xffff0000, v56
	v_lshlrev_b32_e32 v25, 16, v57
	v_exp_f32_e32 v60, v16
	v_mul_f32_e32 v16, 0xbfb8aa3b, v55
	v_exp_f32_e32 v56, v16
	v_mul_f32_e32 v16, 0xbfb8aa3b, v25
	v_exp_f32_e32 v61, v16
	s_nop 0
	v_pk_add_f32 v[60:61], v[60:61], 1.0 op_sel_hi:[1,0]
	v_and_b32_e32 v35, 0xffff0000, v57
	v_cvt_pk_bf16_f32 v10, v22, v10
	ds_read_b128 v[16:19], v20
	ds_read_b128 v[20:23], v20 offset:16
	v_lshlrev_b32_e32 v62, 16, v12
	v_and_b32_e32 v13, 0xffff0000, v13
	s_waitcnt lgkmcnt(1)
	v_mov_b32_e32 v64, v16
	v_mov_b32_e32 v65, v18
	v_pk_mul_f32 v[62:63], v[64:65], v[62:63]
	v_rcp_f32_e32 v61, v61
	s_nop 0
	v_mul_f32_e32 v61, v25, v61
	v_and_b32_e32 v12, 0xffff0000, v12
	v_mul_f32_e32 v18, 0xbfb8aa3b, v35
	v_exp_f32_e32 v57, v18
	v_rcp_f32_e32 v60, v60
	s_nop 0
	v_mul_f32_e32 v60, v29, v60
	v_mov_b32_e32 v18, v17
	v_pk_mul_f32 v[12:13], v[18:19], v[12:13]
	v_pk_add_f32 v[56:57], v[56:57], 1.0 op_sel_hi:[1,0]
	v_pk_mul_f32 v[60:61], v[60:61], v[62:63]
	v_lshlrev_b32_e32 v63, 16, v15
	v_lshlrev_b32_e32 v62, 16, v14
	v_and_b32_e32 v15, 0xffff0000, v15
	v_rcp_f32_e32 v17, v57
	s_nop 0
	v_mul_f32_e32 v17, v35, v17
	v_rcp_f32_e32 v16, v56
	s_nop 0
	v_mul_f32_e32 v16, v55, v16
	v_pk_mul_f32 v[12:13], v[16:17], v[12:13]
	v_lshlrev_b32_e32 v25, 16, v59
	v_lshlrev_b32_e32 v29, 16, v58
	v_cvt_pk_bf16_f32 v13, v61, v13
	v_cvt_pk_bf16_f32 v12, v60, v12
	v_mul_f32_e32 v16, 0xbfb8aa3b, v29
	v_mul_f32_e32 v17, 0xbfb8aa3b, v25
	v_exp_f32_e32 v16, v16
	v_exp_f32_e32 v17, v17
	v_and_b32_e32 v55, 0xffff0000, v58
	v_mul_f32_e32 v18, 0xbfb8aa3b, v55
	v_and_b32_e32 v35, 0xffff0000, v59
	v_exp_f32_e32 v60, v18
	v_pk_add_f32 v[64:65], v[16:17], 1.0 op_sel_hi:[1,0]
	global_load_dwordx4 v[16:19], v[26:27], off
	global_load_dwordx4 v[56:59], v[26:27], off offset:2048
	s_waitcnt lgkmcnt(0)
	v_mov_b32_e32 v26, v20
	v_mov_b32_e32 v27, v22
	v_pk_mul_f32 v[26:27], v[26:27], v[62:63]
	v_rcp_f32_e32 v63, v65
	s_nop 0
	v_mul_f32_e32 v63, v25, v63
	v_and_b32_e32 v14, 0xffff0000, v14
	v_mul_f32_e32 v22, 0xbfb8aa3b, v35
	v_exp_f32_e32 v61, v22
	v_rcp_f32_e32 v62, v64
	s_nop 0
	v_mul_f32_e32 v62, v29, v62
	v_mov_b32_e32 v22, v21
	v_pk_mul_f32 v[14:15], v[22:23], v[14:15]
	v_pk_add_f32 v[60:61], v[60:61], 1.0 op_sel_hi:[1,0]
	v_pk_mul_f32 v[26:27], v[62:63], v[26:27]
	s_waitcnt vmcnt(1)
	v_lshlrev_b32_e32 v63, 16, v17
	v_rcp_f32_e32 v21, v61
	s_nop 0
	v_mul_f32_e32 v21, v35, v21
	v_rcp_f32_e32 v20, v60
	s_nop 0
	v_mul_f32_e32 v20, v55, v20
	v_pk_mul_f32 v[14:15], v[20:21], v[14:15]
	s_waitcnt vmcnt(0)
	v_lshlrev_b32_e32 v35, 16, v56
	v_cvt_pk_bf16_f32 v15, v27, v15
	v_mul_f32_e32 v20, 0xbfb8aa3b, v35
	v_and_b32_e32 v66, 0xffff0000, v56
	v_lshlrev_b32_e32 v29, 16, v57
	v_exp_f32_e32 v60, v20
	v_mul_f32_e32 v20, 0xbfb8aa3b, v66
	v_exp_f32_e32 v56, v20
	v_mul_f32_e32 v20, 0xbfb8aa3b, v29
	v_exp_f32_e32 v61, v20
	s_nop 0
	v_pk_add_f32 v[60:61], v[60:61], 1.0 op_sel_hi:[1,0]
	v_and_b32_e32 v55, 0xffff0000, v57
	v_cvt_pk_bf16_f32 v14, v26, v14
	ds_read_b128 v[20:23], v24
	ds_read_b128 v[24:27], v24 offset:16
	v_lshlrev_b32_e32 v62, 16, v16
	v_and_b32_e32 v17, 0xffff0000, v17
	s_waitcnt lgkmcnt(1)
; __device__ __forceinline__ unsigned pack2(float a, float b) { return (unsigned)f2bf(a) | ((unsigned)f2bf(b) << 16); }
; __device__ __forceinline__ float bflo(unsigned w) { return __uint_as_float(w << 16); }
; __device__ __forceinline__ float bfhi(unsigned w) { return __uint_as_float(w & 0xffff0000u); }
; __device__ __forceinline__ float silu_f(float g) { return g / (1.f + __expf(-g)); }
; __device__ void gmlp_item(const Params& p, int layer, int b, int n, int g, char* smem) {
;     ...
; #pragma unroll
;     for (int i = 0; i < 8; ++i) {
;       int q = tid + 256 * i, t = q >> 4, c = (q & 15) * 8;
;       float4 m0 = *reinterpret_cast<const float4*>(Tf + t * 132 + c);
;       float4 m1 = *reinterpret_cast<const float4*>(Tf + t * 132 + c + 4);
;       float mm[8] = {m0.x, m0.y, m0.z, m0.w, m1.x, m1.y, m1.z, m1.w};
;       unsigned uw[4] = {uu[i].x, uu[i].y, uu[i].z, uu[i].w};
;       unsigned gw[4] = {gt[i].x, gt[i].y, gt[i].z, gt[i].w};
;       unsigned ow[4];
; #pragma unroll
;       for (int e = 0; e < 4; ++e) {
;         float y0 = bflo(uw[e]) * mm[2 * e] * silu_f(bflo(gw[e]));
;         float y1 = bfhi(uw[e]) * mm[2 * e + 1] * silu_f(bfhi(gw[e]));
;         ow[e] = pack2(y0, y1);
;       }
;       *reinterpret_cast<uint4*>(Y + (t0 + t) * YW + g * 128 + c) = make_uint4(ow[0], ow[1], ow[2], ow[3]);
	v_mov_b32_e32 v64, v20
	v_mov_b32_e32 v65, v22
	v_pk_mul_f32 v[62:63], v[64:65], v[62:63]
	v_rcp_f32_e32 v61, v61
	s_nop 0
	v_mul_f32_e32 v61, v29, v61
	v_and_b32_e32 v16, 0xffff0000, v16
	v_mul_f32_e32 v22, 0xbfb8aa3b, v55
	v_exp_f32_e32 v57, v22
	v_rcp_f32_e32 v60, v60
	s_nop 0
	v_mul_f32_e32 v60, v35, v60
	v_mov_b32_e32 v22, v21
	v_pk_mul_f32 v[16:17], v[22:23], v[16:17]
	v_pk_add_f32 v[56:57], v[56:57], 1.0 op_sel_hi:[1,0]
	v_pk_mul_f32 v[60:61], v[60:61], v[62:63]
	v_lshlrev_b32_e32 v63, 16, v19
	v_lshlrev_b32_e32 v62, 16, v18
	v_and_b32_e32 v19, 0xffff0000, v19
	v_rcp_f32_e32 v21, v57
	s_nop 0
	v_mul_f32_e32 v21, v55, v21
	v_rcp_f32_e32 v20, v56
	s_nop 0
	v_mul_f32_e32 v20, v66, v20
	v_pk_mul_f32 v[16:17], v[20:21], v[16:17]
	v_lshlrev_b32_e32 v29, 16, v59
	v_lshlrev_b32_e32 v35, 16, v58
	v_cvt_pk_bf16_f32 v17, v61, v17
	v_cvt_pk_bf16_f32 v16, v60, v16
	v_mul_f32_e32 v20, 0xbfb8aa3b, v35
	v_mul_f32_e32 v21, 0xbfb8aa3b, v29
	v_exp_f32_e32 v20, v20
	v_exp_f32_e32 v21, v21
	v_and_b32_e32 v66, 0xffff0000, v58
	v_mul_f32_e32 v22, 0xbfb8aa3b, v66
	v_and_b32_e32 v55, 0xffff0000, v59
	v_exp_f32_e32 v60, v22
	v_pk_add_f32 v[64:65], v[20:21], 1.0 op_sel_hi:[1,0]
	global_load_dwordx4 v[20:23], v[30:31], off
	global_load_dwordx4 v[56:59], v[30:31], off offset:2048
	s_waitcnt lgkmcnt(0)
	v_mov_b32_e32 v30, v24
	v_mov_b32_e32 v31, v26
	v_pk_mul_f32 v[30:31], v[30:31], v[62:63]
	v_rcp_f32_e32 v63, v65
	s_nop 0
	v_mul_f32_e32 v63, v29, v63
	v_and_b32_e32 v18, 0xffff0000, v18
	v_mul_f32_e32 v26, 0xbfb8aa3b, v55
	v_exp_f32_e32 v61, v26
	v_rcp_f32_e32 v62, v64
	s_nop 0
	v_mul_f32_e32 v62, v35, v62
	v_mov_b32_e32 v26, v25
	v_pk_mul_f32 v[18:19], v[26:27], v[18:19]
	v_pk_add_f32 v[60:61], v[60:61], 1.0 op_sel_hi:[1,0]
	v_pk_mul_f32 v[30:31], v[62:63], v[30:31]
	s_waitcnt vmcnt(1)
	v_lshlrev_b32_e32 v63, 16, v21
	v_rcp_f32_e32 v25, v61
	s_nop 0
	v_mul_f32_e32 v25, v55, v25
	v_rcp_f32_e32 v24, v60
	s_nop 0
	v_mul_f32_e32 v24, v66, v24
	v_pk_mul_f32 v[18:19], v[24:25], v[18:19]
	s_waitcnt vmcnt(0)
	v_lshlrev_b32_e32 v55, 16, v56
	v_cvt_pk_bf16_f32 v19, v31, v19
	v_mul_f32_e32 v24, 0xbfb8aa3b, v55
	v_and_b32_e32 v67, 0xffff0000, v56
	v_lshlrev_b32_e32 v35, 16, v57
	v_exp_f32_e32 v60, v24
	v_mul_f32_e32 v24, 0xbfb8aa3b, v67
	v_exp_f32_e32 v56, v24
	v_mul_f32_e32 v24, 0xbfb8aa3b, v35
	v_exp_f32_e32 v61, v24
	s_nop 0
	v_pk_add_f32 v[60:61], v[60:61], 1.0 op_sel_hi:[1,0]
	v_and_b32_e32 v66, 0xffff0000, v57
	v_cvt_pk_bf16_f32 v18, v30, v18
	ds_read_b128 v[24:27], v28
	ds_read_b128 v[28:31], v28 offset:16
	v_lshlrev_b32_e32 v62, 16, v20
	v_and_b32_e32 v21, 0xffff0000, v21
	s_waitcnt lgkmcnt(1)
	v_mov_b32_e32 v64, v24
	v_mov_b32_e32 v65, v26
	v_pk_mul_f32 v[62:63], v[64:65], v[62:63]
	v_rcp_f32_e32 v61, v61
	s_nop 0
	v_mul_f32_e32 v61, v35, v61
	v_and_b32_e32 v20, 0xffff0000, v20
	v_mul_f32_e32 v26, 0xbfb8aa3b, v66
	v_exp_f32_e32 v57, v26
	v_rcp_f32_e32 v60, v60
	s_nop 0
	v_mul_f32_e32 v60, v55, v60
	v_mov_b32_e32 v26, v25
	v_pk_mul_f32 v[20:21], v[26:27], v[20:21]
	v_pk_add_f32 v[56:57], v[56:57], 1.0 op_sel_hi:[1,0]
	v_pk_mul_f32 v[60:61], v[60:61], v[62:63]
	v_lshlrev_b32_e32 v63, 16, v23
	v_lshlrev_b32_e32 v62, 16, v22
	v_and_b32_e32 v23, 0xffff0000, v23
	v_rcp_f32_e32 v25, v57
	s_nop 0
	v_mul_f32_e32 v25, v66, v25
	v_rcp_f32_e32 v24, v56
	s_nop 0
	v_mul_f32_e32 v24, v67, v24
	v_pk_mul_f32 v[20:21], v[24:25], v[20:21]
	v_lshlrev_b32_e32 v35, 16, v59
	v_lshlrev_b32_e32 v55, 16, v58
	v_cvt_pk_bf16_f32 v21, v61, v21
	v_cvt_pk_bf16_f32 v20, v60, v20
	v_mul_f32_e32 v24, 0xbfb8aa3b, v55
	v_mul_f32_e32 v25, 0xbfb8aa3b, v35
	v_exp_f32_e32 v24, v24
	v_exp_f32_e32 v25, v25
	v_and_b32_e32 v67, 0xffff0000, v58
	v_mul_f32_e32 v26, 0xbfb8aa3b, v67
	v_and_b32_e32 v66, 0xffff0000, v59
	v_exp_f32_e32 v60, v26
	v_pk_add_f32 v[64:65], v[24:25], 1.0 op_sel_hi:[1,0]
	global_load_dwordx4 v[24:27], v[32:33], off
	global_load_dwordx4 v[56:59], v[32:33], off offset:2048
	s_waitcnt lgkmcnt(0)
	v_mov_b32_e32 v32, v28
	v_mov_b32_e32 v33, v30
	v_pk_mul_f32 v[32:33], v[32:33], v[62:63]
	v_rcp_f32_e32 v63, v65
	s_nop 0
	v_mul_f32_e32 v63, v35, v63
	v_and_b32_e32 v22, 0xffff0000, v22
	v_mul_f32_e32 v30, 0xbfb8aa3b, v66
	v_exp_f32_e32 v61, v30
	v_rcp_f32_e32 v62, v64
	s_nop 0
	v_mul_f32_e32 v62, v55, v62
	v_mov_b32_e32 v30, v29
	v_pk_mul_f32 v[22:23], v[30:31], v[22:23]
	v_pk_add_f32 v[60:61], v[60:61], 1.0 op_sel_hi:[1,0]
	v_pk_mul_f32 v[32:33], v[62:63], v[32:33]
	s_waitcnt vmcnt(1)
	v_lshlrev_b32_e32 v63, 16, v25
	v_rcp_f32_e32 v29, v61
	s_nop 0
	v_mul_f32_e32 v29, v66, v29
	v_rcp_f32_e32 v28, v60
	s_nop 0
	v_mul_f32_e32 v28, v67, v28
	v_pk_mul_f32 v[22:23], v[28:29], v[22:23]
	s_waitcnt vmcnt(0)
	v_lshlrev_b32_e32 v66, 16, v56
	v_cvt_pk_bf16_f32 v23, v33, v23
	v_mul_f32_e32 v28, 0xbfb8aa3b, v66
	v_and_b32_e32 v68, 0xffff0000, v56
	v_lshlrev_b32_e32 v55, 16, v57
	v_exp_f32_e32 v60, v28
	v_mul_f32_e32 v28, 0xbfb8aa3b, v68
	v_exp_f32_e32 v56, v28
	v_mul_f32_e32 v28, 0xbfb8aa3b, v55
	v_exp_f32_e32 v61, v28
	s_nop 0
	v_pk_add_f32 v[60:61], v[60:61], 1.0 op_sel_hi:[1,0]
	v_and_b32_e32 v67, 0xffff0000, v57
	v_cvt_pk_bf16_f32 v22, v32, v22
	ds_read_b128 v[28:31], v34
	ds_read_b128 v[32:35], v34 offset:16
	v_lshlrev_b32_e32 v62, 16, v24
	v_and_b32_e32 v25, 0xffff0000, v25
	s_waitcnt lgkmcnt(1)
; __device__ __forceinline__ unsigned pack2(float a, float b) { return (unsigned)f2bf(a) | ((unsigned)f2bf(b) << 16); }
; __device__ __forceinline__ float bflo(unsigned w) { return __uint_as_float(w << 16); }
; __device__ __forceinline__ float bfhi(unsigned w) { return __uint_as_float(w & 0xffff0000u); }
; __device__ __forceinline__ float silu_f(float g) { return g / (1.f + __expf(-g)); }
; __device__ void gmlp_item(const Params& p, int layer, int b, int n, int g, char* smem) {
;     ...
; #pragma unroll
;     for (int i = 0; i < 8; ++i) {
;       int q = tid + 256 * i, t = q >> 4, c = (q & 15) * 8;
;       float4 m0 = *reinterpret_cast<const float4*>(Tf + t * 132 + c);
;       float4 m1 = *reinterpret_cast<const float4*>(Tf + t * 132 + c + 4);
;       float mm[8] = {m0.x, m0.y, m0.z, m0.w, m1.x, m1.y, m1.z, m1.w};
;       unsigned uw[4] = {uu[i].x, uu[i].y, uu[i].z, uu[i].w};
;       unsigned gw[4] = {gt[i].x, gt[i].y, gt[i].z, gt[i].w};
;       unsigned ow[4];
; #pragma unroll
;       for (int e = 0; e < 4; ++e) {
;         float y0 = bflo(uw[e]) * mm[2 * e] * silu_f(bflo(gw[e]));
;         float y1 = bfhi(uw[e]) * mm[2 * e + 1] * silu_f(bfhi(gw[e]));
;         ow[e] = pack2(y0, y1);
;       }
;       *reinterpret_cast<uint4*>(Y + (t0 + t) * YW + g * 128 + c) = make_uint4(ow[0], ow[1], ow[2], ow[3]);
;     }
;   }
;   __syncthreads();
	v_mov_b32_e32 v64, v28
	v_mov_b32_e32 v65, v30
	v_pk_mul_f32 v[62:63], v[64:65], v[62:63]
	v_rcp_f32_e32 v61, v61
	s_nop 0
	v_mul_f32_e32 v61, v55, v61
	v_and_b32_e32 v24, 0xffff0000, v24
	v_mul_f32_e32 v30, 0xbfb8aa3b, v67
	v_exp_f32_e32 v57, v30
	v_rcp_f32_e32 v60, v60
	s_nop 0
	v_mul_f32_e32 v60, v66, v60
	v_mov_b32_e32 v30, v29
	v_pk_mul_f32 v[24:25], v[30:31], v[24:25]
	v_pk_add_f32 v[56:57], v[56:57], 1.0 op_sel_hi:[1,0]
	v_pk_mul_f32 v[60:61], v[60:61], v[62:63]
	v_lshlrev_b32_e32 v66, 16, v58
	v_lshlrev_b32_e32 v63, 16, v27
	v_and_b32_e32 v27, 0xffff0000, v27
	v_rcp_f32_e32 v29, v57
	s_nop 0
	v_mul_f32_e32 v29, v67, v29
	v_rcp_f32_e32 v28, v56
	s_nop 0
	v_mul_f32_e32 v28, v68, v28
	v_pk_mul_f32 v[24:25], v[28:29], v[24:25]
	v_lshlrev_b32_e32 v55, 16, v59
	v_cvt_pk_bf16_f32 v25, v61, v25
	v_cvt_pk_bf16_f32 v24, v60, v24
	v_mul_f32_e32 v28, 0xbfb8aa3b, v66
	v_mul_f32_e32 v29, 0xbfb8aa3b, v55
	v_exp_f32_e32 v28, v28
	v_exp_f32_e32 v29, v29
	v_and_b32_e32 v68, 0xffff0000, v58
	v_mul_f32_e32 v30, 0xbfb8aa3b, v68
	v_and_b32_e32 v67, 0xffff0000, v59
	v_exp_f32_e32 v60, v30
	v_pk_add_f32 v[64:65], v[28:29], 1.0 op_sel_hi:[1,0]
	global_load_dwordx4 v[28:31], v[52:53], off
	global_load_dwordx4 v[56:59], v[52:53], off offset:2048
	s_waitcnt lgkmcnt(0)
	v_mov_b32_e32 v52, v32
	v_lshlrev_b32_e32 v62, 16, v26
	v_mov_b32_e32 v53, v34
	v_pk_mul_f32 v[52:53], v[52:53], v[62:63]
	v_rcp_f32_e32 v63, v65
	s_nop 0
	v_mul_f32_e32 v63, v55, v63
	v_and_b32_e32 v26, 0xffff0000, v26
	v_mul_f32_e32 v34, 0xbfb8aa3b, v67
	v_exp_f32_e32 v61, v34
	v_rcp_f32_e32 v62, v64
	s_nop 0
	v_mul_f32_e32 v62, v66, v62
	v_mov_b32_e32 v34, v33
	v_pk_mul_f32 v[26:27], v[34:35], v[26:27]
	v_pk_add_f32 v[60:61], v[60:61], 1.0 op_sel_hi:[1,0]
	v_pk_mul_f32 v[52:53], v[62:63], v[52:53]
	s_waitcnt vmcnt(1)
	v_lshlrev_b32_e32 v63, 16, v29
	v_rcp_f32_e32 v33, v61
	s_nop 0
	v_mul_f32_e32 v33, v67, v33
	v_rcp_f32_e32 v32, v60
	s_nop 0
	v_mul_f32_e32 v32, v68, v32
	v_pk_mul_f32 v[26:27], v[32:33], v[26:27]
	s_waitcnt vmcnt(0)
	v_lshlrev_b32_e32 v67, 16, v56
	v_cvt_pk_bf16_f32 v27, v53, v27
	v_mul_f32_e32 v32, 0xbfb8aa3b, v67
	v_and_b32_e32 v69, 0xffff0000, v56
	v_lshlrev_b32_e32 v66, 16, v57
	v_exp_f32_e32 v60, v32
	v_mul_f32_e32 v32, 0xbfb8aa3b, v69
	v_exp_f32_e32 v56, v32
	v_mul_f32_e32 v32, 0xbfb8aa3b, v66
	v_exp_f32_e32 v61, v32
	s_nop 0
	v_pk_add_f32 v[60:61], v[60:61], 1.0 op_sel_hi:[1,0]
	v_and_b32_e32 v68, 0xffff0000, v57
	v_cvt_pk_bf16_f32 v26, v52, v26
	ds_read_b128 v[32:35], v54
	ds_read_b128 v[52:55], v54 offset:16
	v_lshlrev_b32_e32 v62, 16, v28
	v_and_b32_e32 v29, 0xffff0000, v29
	s_waitcnt lgkmcnt(1)
	v_mov_b32_e32 v64, v32
	v_mov_b32_e32 v65, v34
	v_pk_mul_f32 v[62:63], v[64:65], v[62:63]
	v_rcp_f32_e32 v61, v61
	s_nop 0
	v_mul_f32_e32 v61, v66, v61
	v_and_b32_e32 v28, 0xffff0000, v28
	v_mul_f32_e32 v34, 0xbfb8aa3b, v68
	v_exp_f32_e32 v57, v34
	v_rcp_f32_e32 v60, v60
	s_nop 0
	v_mul_f32_e32 v60, v67, v60
	v_pk_mul_f32 v[60:61], v[60:61], v[62:63]
	v_mov_b32_e32 v34, v33
	v_pk_add_f32 v[56:57], v[56:57], 1.0 op_sel_hi:[1,0]
	v_pk_mul_f32 v[28:29], v[34:35], v[28:29]
	s_nop 0
	v_rcp_f32_e32 v33, v57
	s_nop 0
	v_mul_f32_e32 v33, v68, v33
	v_rcp_f32_e32 v32, v56
	s_nop 0
	v_mul_f32_e32 v32, v69, v32
	v_pk_mul_f32 v[28:29], v[32:33], v[28:29]
	v_cvt_pk_bf16_f32 v28, 0, v28
	v_cvt_pk_bf16_f32 v33, 0, v60
	v_and_b32_e32 v28, 0xffff0000, v28
	v_lshlrev_b32_e32 v35, 16, v59
	v_lshlrev_b32_e32 v60, 16, v58
	v_cvt_pk_bf16_f32 v29, v61, v29
	v_or_b32_sdwa v28, v28, v33 dst_sel:DWORD dst_unused:UNUSED_PAD src0_sel:DWORD src1_sel:WORD_1
	v_mul_f32_e32 v32, 0xbfb8aa3b, v60
	v_mul_f32_e32 v33, 0xbfb8aa3b, v35
	v_exp_f32_e32 v32, v32
	v_exp_f32_e32 v33, v33
	v_and_b32_e32 v62, 0xffff0000, v58
	s_waitcnt lgkmcnt(0)
	v_mov_b32_e32 v58, v52
	v_and_b32_e32 v61, 0xffff0000, v59
	v_pk_add_f32 v[32:33], v[32:33], 1.0 op_sel_hi:[1,0]
	v_lshlrev_b32_e32 v57, 16, v31
	v_lshlrev_b32_e32 v56, 16, v30
	v_mov_b32_e32 v59, v54
	v_pk_mul_f32 v[56:57], v[58:59], v[56:57]
	v_rcp_f32_e32 v33, v33
	s_nop 0
	v_mul_f32_e32 v33, v35, v33
	v_mul_f32_e32 v34, 0xbfb8aa3b, v62
	v_mul_f32_e32 v35, 0xbfb8aa3b, v61
	v_exp_f32_e32 v34, v34
	v_exp_f32_e32 v35, v35
	v_rcp_f32_e32 v32, v32
	s_nop 0
	v_mul_f32_e32 v32, v60, v32
	v_pk_mul_f32 v[32:33], v[32:33], v[56:57]
	v_mov_b32_e32 v54, v53
	v_pk_add_f32 v[34:35], v[34:35], 1.0 op_sel_hi:[1,0]
	v_and_b32_e32 v31, 0xffff0000, v31
	v_and_b32_e32 v30, 0xffff0000, v30
	v_pk_mul_f32 v[30:31], v[54:55], v[30:31]
	v_rcp_f32_e32 v35, v35
	s_nop 0
	v_mul_f32_e32 v35, v61, v35
	s_mov_b64 s[12:13], 0
	v_rcp_f32_e32 v34, v34
	s_nop 0
	v_mul_f32_e32 v34, v62, v34
	v_pk_mul_f32 v[30:31], v[34:35], v[30:31]
	v_cvt_pk_bf16_f32 v31, v33, v31
	v_cvt_pk_bf16_f32 v30, v32, v30
	global_store_dwordx4 v[50:51], v[28:31], off
	global_store_dwordx4 v[48:49], v[24:27], off
	global_store_dwordx4 v[46:47], v[20:23], off
	global_store_dwordx4 v[44:45], v[16:19], off
	global_store_dwordx4 v[42:43], v[12:15], off
	global_store_dwordx4 v[40:41], v[8:11], off
	global_store_dwordx4 v[38:39], v[4:7], off
	global_store_dwordx4 v[36:37], v[0:3], off
	s_barrier

; __device__ __forceinline__ float bflo(unsigned w) { return __uint_as_float(w << 16); }
; __device__ __forceinline__ float bfhi(unsigned w) { return __uint_as_float(w & 0xffff0000u); }
; __device__ void gmlp_item(const Params& p, int layer, int b, int n, int g, char* smem) {
;     ...
;   {
;     uint4 raw[8];
; #pragma unroll
;     for (int i = 0; i < 8; ++i) {
;       int q = tid + 256 * i;
;       int st = q & 127, c0 = (q >> 7) * 8;
;       raw[i] = *reinterpret_cast<const uint4*>(P + (t0 + st) * NP + 512 + g * 128 + c0);
;     }
; #pragma unroll
;     for (int i = 0; i < 8; ++i) {
;       int q = tid + 256 * i;
;       int st = q & 127, c0 = (q >> 7) * 8;
;       unsigned w[4] = {raw[i].x, raw[i].y, raw[i].z, raw[i].w};
;       float mu = mu_s[st], rs = rs_s[st];
;       const float4* gp = reinterpret_cast<const float4*>(p.gm_gain + (size_t)layer * 512 + g * 128 + c0);
;       float4 g0 = gp[0], g1 = gp[1];
;       float gg[8] = {g0.x, g0.y, g0.z, g0.w, g1.x, g1.y, g1.z, g1.w};
; #pragma unroll
;       for (int e = 0; e < 8; ++e) {
;         float v = (e & 1) ? bfhi(w[e >> 1]) : bflo(w[e >> 1]);
;         float val = (v - mu) * rs * gg[e];
;         *reinterpret_cast<u16*>(smem + 32768 + (st >> 5) * 8192 + (c0 + e) * 64 + (st & 31) * 2) = f2bf(val);
;       }
;     }
.LBB0_1121:
	s_or_b64 exec, exec, s[8:9]
	v_and_b32_e32 v6, 0x7f, v59
	s_ashr_i32 s8, s10, 31
	s_bfe_u32 s12, s75, 0x20003
	s_waitcnt lgkmcnt(0)
	v_or_b32_e32 v0, s16, v6
	s_add_u32 s13, s28, s10
	v_mul_lo_u32 v128, v0, s52
	v_ashrrev_i32_e32 v48, 4, v59
	s_addc_u32 s42, s29, s8
	v_lshl_add_u64 v[0:1], v[128:129], 1, s[6:7]
	s_lshl_b32 s8, s12, 8
	s_mov_b32 s9, s17
	v_and_b32_e32 v2, -8, v48
	v_lshl_add_u64 v[0:1], v[0:1], 0, s[8:9]
	v_ashrrev_i32_e32 v3, 31, v2
	v_lshl_add_u64 v[4:5], v[2:3], 1, v[0:1]
	s_barrier
	global_load_dwordx4 v[28:31], v[4:5], off offset:1024
	s_lshl_b32 s10, s12, 7
	s_lshl_b32 s8, s12, 9
	s_add_u32 s8, s48, s8
	s_addc_u32 s9, s23, 0
	v_lshl_add_u64 v[4:5], v[2:3], 2, s[8:9]
	global_load_dwordx4 v[50:53], v[4:5], off
	global_load_dwordx4 v[70:73], v[4:5], off offset:16
	v_add_u32_e32 v3, 0x100, v59
	v_ashrrev_i32_e32 v68, 4, v3
	v_add_u32_e32 v4, 0x200, v59
	v_lshlrev_b32_e32 v12, 1, v59
	v_and_b32_e32 v54, -8, v68
	v_add_u32_e32 v5, 0x300, v59
	v_lshlrev_b32_e32 v11, 8, v59
	v_ashrrev_i32_e32 v66, 4, v4
	v_and_b32_e32 v4, 62, v12
	v_ashrrev_i32_e32 v55, 31, v54
	v_ashrrev_i32_e32 v64, 4, v5
	v_and_or_b32 v44, v11, s53, v4
	v_lshl_add_u64 v[4:5], v[54:55], 1, v[0:1]
	global_load_dwordx4 v[24:27], v[4:5], off offset:1024
	v_lshl_add_u64 v[4:5], v[54:55], 2, s[8:9]
	global_load_dwordx4 v[74:77], v[4:5], off offset:16
	global_load_dwordx4 v[78:81], v[4:5], off
	v_lshlrev_b32_e32 v3, 2, v6
	v_or_b32_e32 v6, 0x10000, v3
	v_or_b32_e32 v3, 0x10200, v3
	ds_read_b32 v45, v6
	ds_read_b32 v46, v3
	v_add_u32_e32 v7, 0x400, v59
	v_add_u32_e32 v8, 0x500, v59
	v_add_u32_e32 v9, 0x600, v59
	v_add_u32_e32 v10, 0x700, v59
	v_ashrrev_i32_e32 v62, 4, v7
	v_ashrrev_i32_e32 v60, 4, v8
	v_ashrrev_i32_e32 v58, 4, v9
	v_ashrrev_i32_e32 v56, 4, v10
	v_and_b32_e32 v42, -8, v66
	v_and_b32_e32 v40, -8, v64
	v_and_b32_e32 v38, -8, v62
	v_and_b32_e32 v36, -8, v60
	v_and_b32_e32 v34, -8, v58
	v_and_b32_e32 v32, -8, v56
	v_ashrrev_i32_e32 v43, 31, v42
	v_ashrrev_i32_e32 v41, 31, v40
	v_ashrrev_i32_e32 v39, 31, v38
	v_ashrrev_i32_e32 v37, 31, v36
	v_ashrrev_i32_e32 v35, 31, v34
	v_ashrrev_i32_e32 v33, 31, v32
	v_lshl_add_u32 v47, v2, 6, v44
	v_lshl_add_u64 v[2:3], v[42:43], 1, v[0:1]
	v_lshl_add_u64 v[4:5], v[40:41], 1, v[0:1]
	v_lshl_add_u64 v[6:7], v[38:39], 1, v[0:1]
	v_lshl_add_u64 v[8:9], v[36:37], 1, v[0:1]
	v_lshl_add_u64 v[82:83], v[34:35], 1, v[0:1]
	v_lshl_add_u64 v[0:1], v[32:33], 1, v[0:1]
	global_load_dwordx4 v[20:23], v[2:3], off offset:1024
	global_load_dwordx4 v[16:19], v[4:5], off offset:1024
	global_load_dwordx4 v[12:15], v[6:7], off offset:1024
	s_nop 0
	global_load_dwordx4 v[8:11], v[8:9], off offset:1024
	s_nop 0
	global_load_dwordx4 v[4:7], v[82:83], off offset:1024
	s_nop 0
	global_load_dwordx4 v[0:3], v[0:1], off offset:1024
	v_and_b32_e32 v49, 15, v59
	v_lshlrev_b32_e32 v128, 4, v49
	s_waitcnt vmcnt(11)
	v_lshlrev_b32_e32 v55, 16, v28
	v_and_b32_e32 v28, 0xffff0000, v28
	s_waitcnt lgkmcnt(1)
	v_sub_f32_e32 v55, v55, v45
	v_sub_f32_e32 v28, v28, v45
	s_waitcnt lgkmcnt(0)
	v_mul_f32_e32 v55, v46, v55
	v_mul_f32_e32 v28, v46, v28
	s_waitcnt vmcnt(10)
	v_mul_f32_e32 v50, v55, v50
	v_mul_f32_e32 v28, v28, v51
	v_cvt_pk_bf16_f32 v50, 0, v50
	ds_write_b16_d16_hi v47, v50 offset:32768
	v_cvt_pk_bf16_f32 v28, 0, v28
	ds_write_b16_d16_hi v47, v28 offset:32832
	v_lshlrev_b32_e32 v28, 16, v29
	v_sub_f32_e32 v28, v28, v45
	v_mul_f32_e32 v28, v46, v28
	v_mul_f32_e32 v28, v28, v52
	v_cvt_pk_bf16_f32 v28, 0, v28
	ds_write_b16_d16_hi v47, v28 offset:32896
	v_and_b32_e32 v28, 0xffff0000, v29
	v_sub_f32_e32 v28, v28, v45
	v_mul_f32_e32 v28, v46, v28
	v_mul_f32_e32 v28, v28, v53
	v_cvt_pk_bf16_f32 v28, 0, v28
	ds_write_b16_d16_hi v47, v28 offset:32960
	v_lshlrev_b32_e32 v28, 16, v30
	v_sub_f32_e32 v28, v28, v45
	v_mul_f32_e32 v28, v46, v28
	s_waitcnt vmcnt(9)
	v_mul_f32_e32 v28, v28, v70
	v_cvt_pk_bf16_f32 v28, 0, v28
	ds_write_b16_d16_hi v47, v28 offset:33024
	v_and_b32_e32 v28, 0xffff0000, v30
	v_sub_f32_e32 v28, v28, v45
	v_mul_f32_e32 v28, v46, v28
	v_mul_f32_e32 v28, v28, v71
	v_cvt_pk_bf16_f32 v28, 0, v28
	ds_write_b16_d16_hi v47, v28 offset:33088
	v_lshlrev_b32_e32 v28, 16, v31
	v_sub_f32_e32 v30, v28, v45
	v_lshl_add_u64 v[28:29], v[42:43], 2, s[8:9]
	global_load_dwordx4 v[50:53], v[28:29], off offset:16
	global_load_dwordx4 v[82:85], v[28:29], off
	v_mul_f32_e32 v28, v46, v30
	v_mul_f32_e32 v28, v28, v72
	v_cvt_pk_bf16_f32 v28, 0, v28
	ds_write_b16_d16_hi v47, v28 offset:33152
	v_and_b32_e32 v28, 0xffff0000, v31
	v_sub_f32_e32 v28, v28, v45
	v_mul_f32_e32 v28, v46, v28
	v_mul_f32_e32 v28, v28, v73
	v_cvt_pk_bf16_f32 v28, 0, v28
	v_lshl_or_b32 v29, v48, 6, v159
	v_add_u32_e32 v29, v44, v29
	ds_write_b16_d16_hi v29, v28 offset:32768
	s_waitcnt vmcnt(10)
	v_lshlrev_b32_e32 v28, 16, v24
	v_sub_f32_e32 v28, v28, v45
	v_mul_f32_e32 v28, v46, v28
	v_and_b32_e32 v24, 0xffff0000, v24
	s_waitcnt vmcnt(8)
; __device__ __forceinline__ float bflo(unsigned w) { return __uint_as_float(w << 16); }
; __device__ __forceinline__ float bfhi(unsigned w) { return __uint_as_float(w & 0xffff0000u); }
; __device__ void gmlp_item(const Params& p, int layer, int b, int n, int g, char* smem) {
;     ...
; #pragma unroll
;     for (int i = 0; i < 8; ++i) {
;       int q = tid + 256 * i;
;       int st = q & 127, c0 = (q >> 7) * 8;
;       unsigned w[4] = {raw[i].x, raw[i].y, raw[i].z, raw[i].w};
;       float mu = mu_s[st], rs = rs_s[st];
;       const float4* gp = reinterpret_cast<const float4*>(p.gm_gain + (size_t)layer * 512 + g * 128 + c0);
;       float4 g0 = gp[0], g1 = gp[1];
;       float gg[8] = {g0.x, g0.y, g0.z, g0.w, g1.x, g1.y, g1.z, g1.w};
; #pragma unroll
;       for (int e = 0; e < 8; ++e) {
;         float v = (e & 1) ? bfhi(w[e >> 1]) : bflo(w[e >> 1]);
;         float val = (v - mu) * rs * gg[e];
;         *reinterpret_cast<u16*>(smem + 32768 + (st >> 5) * 8192 + (c0 + e) * 64 + (st & 31) * 2) = f2bf(val);
;       }
;     }
	v_mul_f32_e32 v28, v28, v78
	v_sub_f32_e32 v24, v24, v45
	v_mul_f32_e32 v24, v46, v24
	v_cvt_pk_bf16_f32 v28, 0, v28
	v_lshl_add_u32 v43, v54, 6, v44
	v_mul_f32_e32 v24, v24, v79
	ds_write_b16_d16_hi v43, v28 offset:32768
	v_cvt_pk_bf16_f32 v24, 0, v24
	ds_write_b16_d16_hi v43, v24 offset:32832
	v_lshlrev_b32_e32 v24, 16, v25
	v_sub_f32_e32 v24, v24, v45
	v_mul_f32_e32 v24, v46, v24
	v_mul_f32_e32 v24, v24, v80
	v_cvt_pk_bf16_f32 v24, 0, v24
	ds_write_b16_d16_hi v43, v24 offset:32896
	v_and_b32_e32 v24, 0xffff0000, v25
	v_sub_f32_e32 v24, v24, v45
	v_mul_f32_e32 v24, v46, v24
	v_mul_f32_e32 v24, v24, v81
	v_cvt_pk_bf16_f32 v24, 0, v24
	ds_write_b16_d16_hi v43, v24 offset:32960
	v_lshlrev_b32_e32 v24, 16, v26
	v_sub_f32_e32 v24, v24, v45
	v_mul_f32_e32 v24, v46, v24
	v_mul_f32_e32 v24, v24, v74
	v_cvt_pk_bf16_f32 v24, 0, v24
	ds_write_b16_d16_hi v43, v24 offset:33024
	v_and_b32_e32 v24, 0xffff0000, v26
	v_sub_f32_e32 v24, v24, v45
	v_mul_f32_e32 v24, v46, v24
	v_mul_f32_e32 v24, v24, v75
	v_cvt_pk_bf16_f32 v24, 0, v24
	ds_write_b16_d16_hi v43, v24 offset:33088
	v_lshlrev_b32_e32 v24, 16, v27
	v_sub_f32_e32 v26, v24, v45
	v_lshl_add_u64 v[24:25], v[40:41], 2, s[8:9]
	global_load_dwordx4 v[28:31], v[24:25], off offset:16
	global_load_dwordx4 v[70:73], v[24:25], off
	v_mul_f32_e32 v24, v46, v26
	v_mul_f32_e32 v24, v24, v76
	v_cvt_pk_bf16_f32 v24, 0, v24
	ds_write_b16_d16_hi v43, v24 offset:33152
	v_and_b32_e32 v24, 0xffff0000, v27
	v_sub_f32_e32 v24, v24, v45
	v_mul_f32_e32 v24, v46, v24
	v_mul_f32_e32 v24, v24, v77
	v_cvt_pk_bf16_f32 v24, 0, v24
	v_lshl_or_b32 v25, v68, 6, v159
	v_add_u32_e32 v25, v44, v25
	ds_write_b16_d16_hi v25, v24 offset:32768
	s_waitcnt vmcnt(9)
	v_lshlrev_b32_e32 v24, 16, v20
	v_sub_f32_e32 v24, v24, v45
	v_mul_f32_e32 v24, v46, v24
	v_and_b32_e32 v20, 0xffff0000, v20
	s_waitcnt vmcnt(2)
	v_mul_f32_e32 v24, v24, v82
	v_sub_f32_e32 v20, v20, v45
	v_mul_f32_e32 v20, v46, v20
	v_cvt_pk_bf16_f32 v24, 0, v24
	v_lshl_add_u32 v41, v42, 6, v44
	v_mul_f32_e32 v20, v20, v83
	ds_write_b16_d16_hi v41, v24 offset:32768
	v_cvt_pk_bf16_f32 v20, 0, v20
	ds_write_b16_d16_hi v41, v20 offset:32832
	v_lshlrev_b32_e32 v20, 16, v21
	v_sub_f32_e32 v20, v20, v45
	v_mul_f32_e32 v20, v46, v20
	v_mul_f32_e32 v20, v20, v84
	v_cvt_pk_bf16_f32 v20, 0, v20
	ds_write_b16_d16_hi v41, v20 offset:32896
	v_and_b32_e32 v20, 0xffff0000, v21
	v_sub_f32_e32 v20, v20, v45
	v_mul_f32_e32 v20, v46, v20
	v_mul_f32_e32 v20, v20, v85
	v_cvt_pk_bf16_f32 v20, 0, v20
	ds_write_b16_d16_hi v41, v20 offset:32960
	v_lshlrev_b32_e32 v20, 16, v22
	v_sub_f32_e32 v20, v20, v45
	v_mul_f32_e32 v20, v46, v20
	v_mul_f32_e32 v20, v20, v50
	v_cvt_pk_bf16_f32 v20, 0, v20
	ds_write_b16_d16_hi v41, v20 offset:33024
	v_and_b32_e32 v20, 0xffff0000, v22
	v_sub_f32_e32 v20, v20, v45
	v_mul_f32_e32 v20, v46, v20
	v_mul_f32_e32 v20, v20, v51
	v_cvt_pk_bf16_f32 v20, 0, v20
	ds_write_b16_d16_hi v41, v20 offset:33088
	v_lshlrev_b32_e32 v20, 16, v23
	v_sub_f32_e32 v22, v20, v45
	v_lshl_add_u64 v[20:21], v[38:39], 2, s[8:9]
	global_load_dwordx4 v[24:27], v[20:21], off offset:16
	global_load_dwordx4 v[74:77], v[20:21], off
	v_mul_f32_e32 v20, v46, v22
	v_mul_f32_e32 v20, v20, v52
	v_cvt_pk_bf16_f32 v20, 0, v20
	ds_write_b16_d16_hi v41, v20 offset:33152
	v_and_b32_e32 v20, 0xffff0000, v23
	v_sub_f32_e32 v20, v20, v45
	v_mul_f32_e32 v20, v46, v20
	v_mul_f32_e32 v20, v20, v53
	v_cvt_pk_bf16_f32 v20, 0, v20
	v_lshl_or_b32 v21, v66, 6, v159
	v_add_u32_e32 v21, v44, v21
	ds_write_b16_d16_hi v21, v20 offset:32768
	v_lshlrev_b32_e32 v20, 16, v16
	v_sub_f32_e32 v20, v20, v45
	v_mul_f32_e32 v20, v46, v20
	v_and_b32_e32 v16, 0xffff0000, v16
	s_waitcnt vmcnt(2)
	v_mul_f32_e32 v20, v20, v70
	v_sub_f32_e32 v16, v16, v45
	v_mul_f32_e32 v16, v46, v16
	v_cvt_pk_bf16_f32 v20, 0, v20
	v_lshl_add_u32 v39, v40, 6, v44
	v_mul_f32_e32 v16, v16, v71
	ds_write_b16_d16_hi v39, v20 offset:32768
	v_cvt_pk_bf16_f32 v16, 0, v16
	ds_write_b16_d16_hi v39, v16 offset:32832
	v_lshlrev_b32_e32 v16, 16, v17
	v_sub_f32_e32 v16, v16, v45
	v_mul_f32_e32 v16, v46, v16
	v_mul_f32_e32 v16, v16, v72
	v_cvt_pk_bf16_f32 v16, 0, v16
	ds_write_b16_d16_hi v39, v16 offset:32896
	v_and_b32_e32 v16, 0xffff0000, v17
	v_sub_f32_e32 v16, v16, v45
	v_mul_f32_e32 v16, v46, v16
	v_mul_f32_e32 v16, v16, v73
	v_cvt_pk_bf16_f32 v16, 0, v16
	ds_write_b16_d16_hi v39, v16 offset:32960
	v_lshlrev_b32_e32 v16, 16, v18
	v_sub_f32_e32 v16, v16, v45
	v_mul_f32_e32 v16, v46, v16
	v_mul_f32_e32 v16, v16, v28
	v_cvt_pk_bf16_f32 v16, 0, v16
	ds_write_b16_d16_hi v39, v16 offset:33024
	v_and_b32_e32 v16, 0xffff0000, v18
	v_sub_f32_e32 v16, v16, v45
	v_mul_f32_e32 v16, v46, v16
	v_mul_f32_e32 v16, v16, v29
	v_cvt_pk_bf16_f32 v16, 0, v16
	ds_write_b16_d16_hi v39, v16 offset:33088
	v_lshlrev_b32_e32 v16, 16, v19
	v_sub_f32_e32 v18, v16, v45
	v_lshl_add_u64 v[16:17], v[36:37], 2, s[8:9]
	global_load_dwordx4 v[20:23], v[16:17], off offset:16
	global_load_dwordx4 v[40:43], v[16:17], off
	v_mul_f32_e32 v16, v46, v18
	v_mul_f32_e32 v16, v16, v30
	v_cvt_pk_bf16_f32 v16, 0, v16
	ds_write_b16_d16_hi v39, v16 offset:33152
	v_and_b32_e32 v16, 0xffff0000, v19
	v_sub_f32_e32 v16, v16, v45
	v_mul_f32_e32 v16, v46, v16
	v_mul_f32_e32 v16, v16, v31
	v_cvt_pk_bf16_f32 v16, 0, v16
	v_lshl_or_b32 v17, v64, 6, v159
	v_add_u32_e32 v17, v44, v17
	ds_write_b16_d16_hi v17, v16 offset:32768
	v_lshlrev_b32_e32 v16, 16, v12
	v_sub_f32_e32 v16, v16, v45
	v_mul_f32_e32 v16, v46, v16
	v_and_b32_e32 v12, 0xffff0000, v12
	s_waitcnt vmcnt(2)
; __device__ __forceinline__ float bflo(unsigned w) { return __uint_as_float(w << 16); }
; __device__ __forceinline__ float bfhi(unsigned w) { return __uint_as_float(w & 0xffff0000u); }
; __device__ void gmlp_item(const Params& p, int layer, int b, int n, int g, char* smem) {
;     ...
; #pragma unroll
;     for (int i = 0; i < 8; ++i) {
;       int q = tid + 256 * i;
;       int st = q & 127, c0 = (q >> 7) * 8;
;       unsigned w[4] = {raw[i].x, raw[i].y, raw[i].z, raw[i].w};
;       float mu = mu_s[st], rs = rs_s[st];
;       const float4* gp = reinterpret_cast<const float4*>(p.gm_gain + (size_t)layer * 512 + g * 128 + c0);
;       float4 g0 = gp[0], g1 = gp[1];
;       float gg[8] = {g0.x, g0.y, g0.z, g0.w, g1.x, g1.y, g1.z, g1.w};
; #pragma unroll
;       for (int e = 0; e < 8; ++e) {
;         float v = (e & 1) ? bfhi(w[e >> 1]) : bflo(w[e >> 1]);
;         float val = (v - mu) * rs * gg[e];
;         *reinterpret_cast<u16*>(smem + 32768 + (st >> 5) * 8192 + (c0 + e) * 64 + (st & 31) * 2) = f2bf(val);
;       }
;     }
	v_mul_f32_e32 v16, v16, v74
	v_sub_f32_e32 v12, v12, v45
	v_mul_f32_e32 v12, v46, v12
	v_cvt_pk_bf16_f32 v16, 0, v16
	v_lshl_add_u32 v37, v38, 6, v44
	v_mul_f32_e32 v12, v12, v75
	ds_write_b16_d16_hi v37, v16 offset:32768
	v_cvt_pk_bf16_f32 v12, 0, v12
	ds_write_b16_d16_hi v37, v12 offset:32832
	v_lshlrev_b32_e32 v12, 16, v13
	v_sub_f32_e32 v12, v12, v45
	v_mul_f32_e32 v12, v46, v12
	v_mul_f32_e32 v12, v12, v76
	v_cvt_pk_bf16_f32 v12, 0, v12
	ds_write_b16_d16_hi v37, v12 offset:32896
	v_and_b32_e32 v12, 0xffff0000, v13
	v_sub_f32_e32 v12, v12, v45
	v_mul_f32_e32 v12, v46, v12
	v_mul_f32_e32 v12, v12, v77
	v_cvt_pk_bf16_f32 v12, 0, v12
	ds_write_b16_d16_hi v37, v12 offset:32960
	v_lshlrev_b32_e32 v12, 16, v14
	v_sub_f32_e32 v12, v12, v45
	v_mul_f32_e32 v12, v46, v12
	v_mul_f32_e32 v12, v12, v24
	v_cvt_pk_bf16_f32 v12, 0, v12
	ds_write_b16_d16_hi v37, v12 offset:33024
	v_and_b32_e32 v12, 0xffff0000, v14
	v_sub_f32_e32 v12, v12, v45
	v_mul_f32_e32 v12, v46, v12
	v_mul_f32_e32 v12, v12, v25
	v_cvt_pk_bf16_f32 v12, 0, v12
	ds_write_b16_d16_hi v37, v12 offset:33088
	v_lshlrev_b32_e32 v12, 16, v15
	v_sub_f32_e32 v14, v12, v45
	v_lshl_add_u64 v[12:13], v[34:35], 2, s[8:9]
	global_load_dwordx4 v[16:19], v[12:13], off offset:16
	global_load_dwordx4 v[28:31], v[12:13], off
	v_mul_f32_e32 v12, v46, v14
	v_mul_f32_e32 v12, v12, v26
	v_cvt_pk_bf16_f32 v12, 0, v12
	ds_write_b16_d16_hi v37, v12 offset:33152
	v_and_b32_e32 v12, 0xffff0000, v15
	v_sub_f32_e32 v12, v12, v45
	v_mul_f32_e32 v12, v46, v12
	v_mul_f32_e32 v12, v12, v27
	v_cvt_pk_bf16_f32 v12, 0, v12
	v_lshl_or_b32 v13, v62, 6, v159
	v_add_u32_e32 v13, v44, v13
	ds_write_b16_d16_hi v13, v12 offset:32768
	v_lshlrev_b32_e32 v12, 16, v8
	v_sub_f32_e32 v12, v12, v45
	v_mul_f32_e32 v12, v46, v12
	v_and_b32_e32 v8, 0xffff0000, v8
	s_waitcnt vmcnt(2)
	v_mul_f32_e32 v12, v12, v40
	v_sub_f32_e32 v8, v8, v45
	v_mul_f32_e32 v8, v46, v8
	v_cvt_pk_bf16_f32 v12, 0, v12
	v_lshl_add_u32 v35, v36, 6, v44
	v_mul_f32_e32 v8, v8, v41
	ds_write_b16_d16_hi v35, v12 offset:32768
	v_cvt_pk_bf16_f32 v8, 0, v8
	ds_write_b16_d16_hi v35, v8 offset:32832
	v_lshlrev_b32_e32 v8, 16, v9
	v_sub_f32_e32 v8, v8, v45
	v_mul_f32_e32 v8, v46, v8
	v_mul_f32_e32 v8, v8, v42
	v_cvt_pk_bf16_f32 v8, 0, v8
	ds_write_b16_d16_hi v35, v8 offset:32896
	v_and_b32_e32 v8, 0xffff0000, v9
	v_sub_f32_e32 v8, v8, v45
	v_mul_f32_e32 v8, v46, v8
	v_mul_f32_e32 v8, v8, v43
	v_cvt_pk_bf16_f32 v8, 0, v8
	ds_write_b16_d16_hi v35, v8 offset:32960
	v_lshlrev_b32_e32 v8, 16, v10
	v_sub_f32_e32 v8, v8, v45
	v_mul_f32_e32 v8, v46, v8
	v_mul_f32_e32 v8, v8, v20
	v_cvt_pk_bf16_f32 v8, 0, v8
	ds_write_b16_d16_hi v35, v8 offset:33024
	v_and_b32_e32 v8, 0xffff0000, v10
	v_sub_f32_e32 v8, v8, v45
	v_mul_f32_e32 v8, v46, v8
	v_mul_f32_e32 v8, v8, v21
	v_cvt_pk_bf16_f32 v10, 0, v8
	v_lshl_add_u64 v[8:9], v[32:33], 2, s[8:9]
	global_load_dwordx4 v[12:15], v[8:9], off offset:16
	global_load_dwordx4 v[24:27], v[8:9], off
	v_lshlrev_b32_e32 v8, 16, v11
	v_sub_f32_e32 v8, v8, v45
	v_mul_f32_e32 v8, v46, v8
	v_mul_f32_e32 v8, v8, v22
	v_cvt_pk_bf16_f32 v8, 0, v8
	ds_write_b16_d16_hi v35, v8 offset:33152
	v_and_b32_e32 v8, 0xffff0000, v11
	v_sub_f32_e32 v8, v8, v45
	v_mul_f32_e32 v8, v46, v8
	v_mul_f32_e32 v8, v8, v23
	v_cvt_pk_bf16_f32 v8, 0, v8
	v_lshl_or_b32 v9, v60, 6, v159
	v_add_u32_e32 v9, v44, v9
	ds_write_b16_d16_hi v35, v10 offset:33088
	ds_write_b16_d16_hi v9, v8 offset:32768
	v_lshlrev_b32_e32 v8, 16, v4
	v_sub_f32_e32 v8, v8, v45
	v_mul_f32_e32 v8, v46, v8
	v_and_b32_e32 v4, 0xffff0000, v4
	s_waitcnt vmcnt(2)
	v_mul_f32_e32 v8, v8, v28
	v_sub_f32_e32 v4, v4, v45
	v_mul_f32_e32 v4, v46, v4
	v_cvt_pk_bf16_f32 v8, 0, v8
	v_lshl_add_u32 v9, v34, 6, v44
	v_mul_f32_e32 v4, v4, v29
	ds_write_b16_d16_hi v9, v8 offset:32768
	v_cvt_pk_bf16_f32 v4, 0, v4
	ds_write_b16_d16_hi v9, v4 offset:32832
	v_lshlrev_b32_e32 v4, 16, v5
	v_sub_f32_e32 v4, v4, v45
	v_mul_f32_e32 v4, v46, v4
	v_mul_f32_e32 v4, v4, v30
	v_cvt_pk_bf16_f32 v4, 0, v4
	ds_write_b16_d16_hi v9, v4 offset:32896
	v_and_b32_e32 v4, 0xffff0000, v5
	v_sub_f32_e32 v4, v4, v45
	v_mul_f32_e32 v4, v46, v4
	v_mul_f32_e32 v4, v4, v31
	v_cvt_pk_bf16_f32 v4, 0, v4
	ds_write_b16_d16_hi v9, v4 offset:32960
	v_lshlrev_b32_e32 v4, 16, v6
	v_sub_f32_e32 v4, v4, v45
	v_mul_f32_e32 v4, v46, v4
	v_mul_f32_e32 v4, v4, v16
	v_cvt_pk_bf16_f32 v4, 0, v4
	ds_write_b16_d16_hi v9, v4 offset:33024
	v_and_b32_e32 v4, 0xffff0000, v6
	v_sub_f32_e32 v4, v4, v45
	v_mul_f32_e32 v4, v46, v4
	v_mul_f32_e32 v4, v4, v17
	v_cvt_pk_bf16_f32 v4, 0, v4
	ds_write_b16_d16_hi v9, v4 offset:33088
	v_lshlrev_b32_e32 v4, 16, v7
	v_sub_f32_e32 v4, v4, v45
	v_mul_f32_e32 v4, v46, v4
	v_mul_f32_e32 v4, v4, v18
	v_cvt_pk_bf16_f32 v4, 0, v4
	ds_write_b16_d16_hi v9, v4 offset:33152
	v_and_b32_e32 v4, 0xffff0000, v7
	v_sub_f32_e32 v4, v4, v45
	v_mul_f32_e32 v4, v46, v4
	v_mul_f32_e32 v4, v4, v19
	v_cvt_pk_bf16_f32 v4, 0, v4
	v_lshl_or_b32 v5, v58, 6, v159
	v_add_u32_e32 v5, v44, v5
	ds_write_b16_d16_hi v5, v4 offset:32768
	v_lshlrev_b32_e32 v4, 16, v0
	v_sub_f32_e32 v4, v4, v45
	v_mul_f32_e32 v4, v46, v4
	v_and_b32_e32 v0, 0xffff0000, v0
	s_waitcnt vmcnt(0)
; __device__ __forceinline__ float bflo(unsigned w) { return __uint_as_float(w << 16); }
; __device__ __forceinline__ float bfhi(unsigned w) { return __uint_as_float(w & 0xffff0000u); }
; __device__ void gmlp_item(const Params& p, int layer, int b, int n, int g, char* smem) {
;     ...
; #pragma unroll
;     for (int i = 0; i < 8; ++i) {
;       int q = tid + 256 * i;
;       int st = q & 127, c0 = (q >> 7) * 8;
;       unsigned w[4] = {raw[i].x, raw[i].y, raw[i].z, raw[i].w};
;       float mu = mu_s[st], rs = rs_s[st];
;       const float4* gp = reinterpret_cast<const float4*>(p.gm_gain + (size_t)layer * 512 + g * 128 + c0);
;       float4 g0 = gp[0], g1 = gp[1];
;       float gg[8] = {g0.x, g0.y, g0.z, g0.w, g1.x, g1.y, g1.z, g1.w};
; #pragma unroll
;       for (int e = 0; e < 8; ++e) {
;         float v = (e & 1) ? bfhi(w[e >> 1]) : bflo(w[e >> 1]);
;         float val = (v - mu) * rs * gg[e];
;         *reinterpret_cast<u16*>(smem + 32768 + (st >> 5) * 8192 + (c0 + e) * 64 + (st & 31) * 2) = f2bf(val);
;       }
;     }
;   }
; #pragma unroll 2
;   for (int i = 0; i < 8; ++i) {
;     int q = tid + 256 * i;
;     int t = q >> 4, cch = q & 15;
;     uint4 v = *reinterpret_cast<const uint4*>(Ws + (size_t)g * 16384 + t * 128 + cch * 8);
;     *reinterpret_cast<uint4*>(smem + (cch >> 2) * 8192 + t * 64 + (cch & 3) * 16) = v;
;   }
;   __syncthreads();
	v_mul_f32_e32 v4, v4, v24
	v_sub_f32_e32 v0, v0, v45
	v_mul_f32_e32 v0, v46, v0
	v_cvt_pk_bf16_f32 v4, 0, v4
	v_lshl_add_u32 v5, v32, 6, v44
	v_mul_f32_e32 v0, v0, v25
	ds_write_b16_d16_hi v5, v4 offset:32768
	v_cvt_pk_bf16_f32 v0, 0, v0
	ds_write_b16_d16_hi v5, v0 offset:32832
	v_lshlrev_b32_e32 v0, 16, v1
	v_sub_f32_e32 v0, v0, v45
	v_mul_f32_e32 v0, v46, v0
	v_mul_f32_e32 v0, v0, v26
	v_cvt_pk_bf16_f32 v0, 0, v0
	ds_write_b16_d16_hi v5, v0 offset:32896
	v_and_b32_e32 v0, 0xffff0000, v1
	v_sub_f32_e32 v0, v0, v45
	v_mul_f32_e32 v0, v46, v0
	v_mul_f32_e32 v0, v0, v27
	v_cvt_pk_bf16_f32 v0, 0, v0
	ds_write_b16_d16_hi v5, v0 offset:32960
	v_lshlrev_b32_e32 v0, 16, v2
	v_sub_f32_e32 v0, v0, v45
	v_mul_f32_e32 v0, v46, v0
	v_mul_f32_e32 v0, v0, v12
	v_cvt_pk_bf16_f32 v0, 0, v0
	ds_write_b16_d16_hi v5, v0 offset:33024
	v_and_b32_e32 v0, 0xffff0000, v2
	v_sub_f32_e32 v0, v0, v45
	v_mul_f32_e32 v0, v46, v0
	v_mul_f32_e32 v0, v0, v13
	v_cvt_pk_bf16_f32 v0, 0, v0
	ds_write_b16_d16_hi v5, v0 offset:33088
	v_lshlrev_b32_e32 v0, 16, v3
	v_sub_f32_e32 v0, v0, v45
	v_mul_f32_e32 v0, v46, v0
	v_mul_f32_e32 v0, v0, v14
	v_cvt_pk_bf16_f32 v0, 0, v0
	ds_write_b16_d16_hi v5, v0 offset:33152
	v_and_b32_e32 v0, 0xffff0000, v3
	v_sub_f32_e32 v0, v0, v45
	v_mul_f32_e32 v0, v46, v0
	v_mul_f32_e32 v0, v0, v15
	s_lshl_b32 s8, s12, 15
	v_cvt_pk_bf16_f32 v0, 0, v0
	v_lshl_or_b32 v1, v56, 6, v159
	s_add_u32 s8, s13, s8
	v_add_u32_e32 v1, v44, v1
	s_addc_u32 s9, s42, 0
	v_lshlrev_b32_e32 v3, 4, v59
	ds_write_b16_d16_hi v1, v0 offset:32768
	v_lshl_add_u64 v[0:1], s[8:9], 0, v[128:129]
	v_lshlrev_b32_e32 v2, 11, v59
	v_and_b32_e32 v3, 48, v3
	v_lshl_add_u64 v[0:1], v[0:1], 0, s[24:25]
	v_and_or_b32 v2, v2, s53, v3
	s_mov_b32 s8, 0
	v_mov_b32_e32 v120, v59
	v_ashrrev_i32_e32 v104, 4, v120
	v_add_u32_e32 v120, 0x100, v120
	v_ashrrev_i32_e32 v105, 4, v120
	v_lshlrev_b32_e32 v112, 7, v104
	v_lshlrev_b32_e32 v114, 7, v105
	v_ashrrev_i32_e32 v113, 31, v112
	v_ashrrev_i32_e32 v115, 31, v114
	v_lshl_add_u64 v[112:113], v[112:113], 1, v[0:1]
	v_lshl_add_u64 v[114:115], v[114:115], 1, v[0:1]
	global_load_dwordx4 v[72:75], v[112:113], off
	global_load_dwordx4 v[76:79], v[114:115], off
	v_lshl_add_u32 v104, v104, 6, v2
	v_lshl_add_u32 v105, v105, 6, v2
	v_add_u32_e32 v120, 0x200, v59
	v_ashrrev_i32_e32 v106, 4, v120
	v_add_u32_e32 v120, 0x100, v120
	v_ashrrev_i32_e32 v107, 4, v120
	v_lshlrev_b32_e32 v116, 7, v106
	v_lshlrev_b32_e32 v118, 7, v107
	v_ashrrev_i32_e32 v117, 31, v116
	v_ashrrev_i32_e32 v119, 31, v118
	v_lshl_add_u64 v[116:117], v[116:117], 1, v[0:1]
	v_lshl_add_u64 v[118:119], v[118:119], 1, v[0:1]
	global_load_dwordx4 v[80:83], v[116:117], off
	global_load_dwordx4 v[84:87], v[118:119], off
	v_lshl_add_u32 v106, v106, 6, v2
	v_lshl_add_u32 v107, v107, 6, v2
	v_add_u32_e32 v120, 0x400, v59
	v_ashrrev_i32_e32 v108, 4, v120
	v_add_u32_e32 v120, 0x100, v120
	v_ashrrev_i32_e32 v109, 4, v120
	v_lshlrev_b32_e32 v112, 7, v108
	v_lshlrev_b32_e32 v114, 7, v109
	v_ashrrev_i32_e32 v113, 31, v112
	v_ashrrev_i32_e32 v115, 31, v114
	v_lshl_add_u64 v[112:113], v[112:113], 1, v[0:1]
	v_lshl_add_u64 v[114:115], v[114:115], 1, v[0:1]
	global_load_dwordx4 v[88:91], v[112:113], off
	global_load_dwordx4 v[92:95], v[114:115], off
	v_lshl_add_u32 v108, v108, 6, v2
	v_lshl_add_u32 v109, v109, 6, v2
	v_add_u32_e32 v120, 0x600, v59
	v_ashrrev_i32_e32 v110, 4, v120
	v_add_u32_e32 v120, 0x100, v120
	v_ashrrev_i32_e32 v111, 4, v120
	v_lshlrev_b32_e32 v116, 7, v110
	v_lshlrev_b32_e32 v118, 7, v111
	v_ashrrev_i32_e32 v117, 31, v116
	v_ashrrev_i32_e32 v119, 31, v118
	v_lshl_add_u64 v[116:117], v[116:117], 1, v[0:1]
	v_lshl_add_u64 v[118:119], v[118:119], 1, v[0:1]
	global_load_dwordx4 v[96:99], v[116:117], off
	global_load_dwordx4 v[100:103], v[118:119], off
	v_lshl_add_u32 v110, v110, 6, v2
	v_lshl_add_u32 v111, v111, 6, v2
	s_waitcnt vmcnt(7)
	ds_write_b128 v104, v[72:75]
	s_waitcnt vmcnt(6)
	ds_write_b128 v105, v[76:79]
	s_waitcnt vmcnt(5)
	ds_write_b128 v106, v[80:83]
	s_waitcnt vmcnt(4)
	ds_write_b128 v107, v[84:87]
	s_waitcnt vmcnt(3)
	ds_write_b128 v108, v[88:91]
	s_waitcnt vmcnt(2)
	ds_write_b128 v109, v[92:95]
	s_waitcnt vmcnt(1)
	ds_write_b128 v110, v[96:99]
	s_waitcnt vmcnt(0)
	ds_write_b128 v111, v[100:103]
	s_movk_i32 s8, 0x800
	v_bfe_u32 v54, v59, 4, 2
	v_ashrrev_i32_e32 v55, 7, v59
	v_lshlrev_b32_e32 v4, 4, v54
	v_lshlrev_b32_e32 v0, 12, v55
	v_lshlrev_b32_e32 v5, 6, v49
	v_or3_b32 v57, v4, v0, v5
	s_waitcnt lgkmcnt(0)
	s_barrier
; #define MFMA16(a, b, c) __builtin_amdgcn_mfma_f32_16x16x32_bf16(a, b, c, 0, 0, 0)
; __device__ void gmlp_item(const Params& p, int layer, int b, int n, int g, char* smem) {
;     ...
;   f32x4 acc[4][4];
; #pragma unroll
;   for (int m = 0; m < 4; ++m)
; #pragma unroll
;     for (int nn = 0; nn < 4; ++nn) acc[m][nn] = f32x4{0.f, 0.f, 0.f, 0.f};
; #pragma unroll
;   for (int ks = 0; ks < 4; ++ks) {
;     bf16x8 a[4], bb[4];
; #pragma unroll
;     for (int m = 0; m < 4; ++m)
;       a[m] = *reinterpret_cast<const bf16x8*>(smem + ks * 8192 + (wr * 64 + m * 16 + fr) * 64 + fq * 16);
; #pragma unroll
;     for (int nn = 0; nn < 4; ++nn)
;       bb[nn] = *reinterpret_cast<const bf16x8*>(smem + 32768 + ks * 8192 + (wc * 64 + nn * 16 + fr) * 64 + fq * 16);
; #pragma unroll
;     for (int m = 0; m < 4; ++m)
; #pragma unroll
;       for (int nn = 0; nn < 4; ++nn) acc[m][nn] = MFMA16(a[m], bb[nn], acc[m][nn]);
;   }
;   __syncthreads();
;   {
;     float* Tf = reinterpret_cast<float*>(smem);
; #pragma unroll
;     for (int m = 0; m < 4; ++m)
; #pragma unroll
;       for (int j = 0; j < 4; ++j) {
;         int t = wr * 64 + m * 16 + fq * 4 + j;
;         float bias = p.gm_b_s[(size_t)layer * 512 + g * 128 + t];
; #pragma unroll
;         for (int nn = 0; nn < 4; ++nn) Tf[t * 132 + wc * 64 + nn * 16 + fr] = acc[m][nn][j] + bias;
	ds_read_b128 v[0:3], v57
	v_bfe_u32 v61, v59, 6, 1
	v_lshlrev_b32_e32 v6, 12, v61
	v_or3_b32 v63, v4, v6, v5
	ds_read_b128 v[4:7], v63 offset:32768
	ds_read_b128 v[8:11], v57 offset:1024
	ds_read_b128 v[12:15], v63 offset:33792
	ds_read_b128 v[24:27], v63 offset:34816
	ds_read_b128 v[28:31], v63 offset:35840
	s_waitcnt lgkmcnt(4)
	v_mfma_f32_16x16x32_bf16 v[16:19], v[0:3], v[4:7], 0
	s_ashr_i32 s8, s11, 31
	s_add_u32 s11, s28, s11
	s_addc_u32 s12, s29, s8
	s_waitcnt lgkmcnt(2)
	v_mfma_f32_16x16x32_bf16 v[20:23], v[0:3], v[12:15], 0
	s_lshl_b32 s8, s10, 2
	s_add_u32 s8, s20, s8
	v_lshlrev_b32_e32 v55, 6, v55
	s_waitcnt lgkmcnt(1)
	v_mfma_f32_16x16x32_bf16 v[36:39], v[0:3], v[24:27], 0
	s_addc_u32 s9, s21, 0
	v_lshl_or_b32 v54, v54, 2, v55
	s_add_u32 s8, s8, 0x1800
	s_waitcnt lgkmcnt(0)
	v_mfma_f32_16x16x32_bf16 v[40:43], v[0:3], v[28:31], 0
	s_addc_u32 s9, s9, 0
	v_ashrrev_i32_e32 v55, 31, v54
	v_lshl_add_u64 v[126:127], v[54:55], 2, s[8:9]
	v_mfma_f32_16x16x32_bf16 v[44:47], v[8:11], v[4:7], 0
	v_or_b32_e32 v130, 32, v54
	v_ashrrev_i32_e32 v131, 31, v130
	v_lshlrev_b32_e32 v49, 2, v49
	v_mfma_f32_16x16x32_bf16 v[50:53], v[8:11], v[12:15], 0
	v_lshl_add_u64 v[130:131], v[130:131], 2, s[8:9]
	v_ashrrev_i32_e32 v69, 31, v68
	v_ashrrev_i32_e32 v67, 31, v66
	v_mfma_f32_16x16x32_bf16 v[70:73], v[8:11], v[24:27], 0
	v_ashrrev_i32_e32 v65, 31, v64
	v_mfma_f32_16x16x32_bf16 v[74:77], v[8:11], v[28:31], 0
	ds_read_b128 v[0:3], v57 offset:2048
	ds_read_b128 v[8:11], v57 offset:3072
	s_waitcnt lgkmcnt(1)
	v_mfma_f32_16x16x32_bf16 v[82:85], v[0:3], v[12:15], 0
	s_waitcnt lgkmcnt(0)
	v_mfma_f32_16x16x32_bf16 v[98:101], v[8:11], v[12:15], 0
	ds_read_b128 v[12:15], v57 offset:8192
	v_mfma_f32_16x16x32_bf16 v[78:81], v[0:3], v[4:7], 0
	v_mfma_f32_16x16x32_bf16 v[86:89], v[0:3], v[24:27], 0
	v_mfma_f32_16x16x32_bf16 v[94:97], v[8:11], v[4:7], 0
	v_mfma_f32_16x16x32_bf16 v[32:35], v[8:11], v[24:27], 0
	ds_read_b128 v[102:105], v63 offset:40960
	ds_read_b128 v[24:27], v57 offset:9216
	ds_read_b128 v[106:109], v63 offset:41984
	ds_read_b128 v[118:121], v63 offset:43008
	ds_read_b128 v[4:7], v63 offset:44032
	v_mfma_f32_16x16x32_bf16 v[90:93], v[0:3], v[28:31], 0
	s_waitcnt lgkmcnt(4)
	v_mfma_f32_16x16x32_bf16 v[110:113], v[12:15], v[102:105], v[16:19]
	s_waitcnt lgkmcnt(2)
	v_mfma_f32_16x16x32_bf16 v[114:117], v[12:15], v[106:109], v[20:23]
	s_waitcnt lgkmcnt(1)
	v_mfma_f32_16x16x32_bf16 v[122:125], v[12:15], v[118:121], v[36:39]
	s_waitcnt lgkmcnt(0)
	v_mfma_f32_16x16x32_bf16 v[134:137], v[12:15], v[4:7], v[40:43]
	ds_read_b128 v[146:149], v57 offset:10240
	ds_read_b128 v[12:15], v57 offset:11264
	v_mfma_f32_16x16x32_bf16 v[0:3], v[8:11], v[28:31], 0
	ds_read_b128 v[150:153], v57 offset:16384
	ds_read_b128 v[162:165], v57 offset:17408
	ds_read_b128 v[166:169], v57 offset:18432
	ds_read_b128 v[8:11], v57 offset:19456
	ds_read_b128 v[36:39], v63 offset:49152
	ds_read_b128 v[28:31], v63 offset:50176
	ds_read_b128 v[20:23], v63 offset:51200
	ds_read_b128 v[16:19], v63 offset:52224
	v_mfma_f32_16x16x32_bf16 v[138:141], v[24:27], v[102:105], v[44:47]
	v_mfma_f32_16x16x32_bf16 v[50:53], v[24:27], v[106:109], v[50:53]
	v_mfma_f32_16x16x32_bf16 v[70:73], v[24:27], v[118:121], v[70:73]
	v_mfma_f32_16x16x32_bf16 v[74:77], v[24:27], v[4:7], v[74:77]
	ds_read_b128 v[170:173], v57 offset:24576
	ds_read_b128 v[174:177], v57 offset:25600
	ds_read_b128 v[178:181], v57 offset:26624
	ds_read_b128 v[24:27], v57 offset:27648
	ds_read_b128 v[182:185], v63 offset:57344
	ds_read_b128 v[186:189], v63 offset:58368
	ds_read_b128 v[44:47], v63 offset:59392
	ds_read_b128 v[40:43], v63 offset:60416
	s_waitcnt lgkmcnt(0)
	v_mfma_f32_16x16x32_bf16 v[78:81], v[146:149], v[102:105], v[78:81]
	s_barrier
	global_load_dwordx4 v[190:193], v[130:131], off
	v_mfma_f32_16x16x32_bf16 v[82:85], v[146:149], v[106:109], v[82:85]
	v_ashrrev_i32_e32 v63, 31, v62
	v_mfma_f32_16x16x32_bf16 v[86:89], v[146:149], v[118:121], v[86:89]
	v_mfma_f32_16x16x32_bf16 v[90:93], v[146:149], v[4:7], v[90:93]
	global_load_dwordx4 v[146:149], v[126:127], off
	v_or_b32_e32 v126, 16, v54
	v_ashrrev_i32_e32 v127, 31, v126
	v_lshl_add_u64 v[126:127], v[126:127], 2, s[8:9]
	v_mfma_f32_16x16x32_bf16 v[110:113], v[150:153], v[36:39], v[110:113]
	v_mfma_f32_16x16x32_bf16 v[114:117], v[150:153], v[28:31], v[114:117]
	v_mfma_f32_16x16x32_bf16 v[122:125], v[150:153], v[20:23], v[122:125]
	v_mfma_f32_16x16x32_bf16 v[134:137], v[150:153], v[16:19], v[134:137]
	global_load_dwordx4 v[150:153], v[126:127], off
	v_lshl_or_b32 v126, v61, 8, v49
	v_mad_u64_u32 v[126:127], s[42:43], v54, s55, v[126:127]
	v_mfma_f32_16x16x32_bf16 v[110:113], v[170:173], v[182:185], v[110:113]
	v_add_u32_e32 v57, 0x400, v126
	v_or_b32_e32 v54, 48, v54
	v_ashrrev_i32_e32 v61, 31, v60
	v_mfma_f32_16x16x32_bf16 v[114:117], v[170:173], v[186:189], v[114:117]
	v_mfma_f32_16x16x32_bf16 v[122:125], v[170:173], v[44:47], v[122:125]
	s_waitcnt vmcnt(1)
; #define MFMA16(a, b, c) __builtin_amdgcn_mfma_f32_16x16x32_bf16(a, b, c, 0, 0, 0)
; __device__ void gmlp_item(const Params& p, int layer, int b, int n, int g, char* smem) {
;     ...
;     for (int m = 0; m < 4; ++m)
; #pragma unroll
;       for (int nn = 0; nn < 4; ++nn) acc[m][nn] = MFMA16(a[m], bb[nn], acc[m][nn]);
;   }
;   __syncthreads();
;   {
;     float* Tf = reinterpret_cast<float*>(smem);
; #pragma unroll
;     for (int m = 0; m < 4; ++m)
; #pragma unroll
;       for (int j = 0; j < 4; ++j) {
;         int t = wr * 64 + m * 16 + fq * 4 + j;
;         float bias = p.gm_b_s[(size_t)layer * 512 + g * 128 + t];
; #pragma unroll
;         for (int nn = 0; nn < 4; ++nn) Tf[t * 132 + wc * 64 + nn * 16 + fr] = acc[m][nn][j] + bias;
	s_nop 1
	v_add_f32_e32 v49, v110, v146
	v_mfma_f32_16x16x32_bf16 v[134:137], v[170:173], v[40:43], v[134:137]
	s_nop 1
	v_add_f32_e32 v55, v114, v146
	ds_write2_b32 v126, v49, v55 offset1:16
	v_add_f32_e32 v49, v122, v146
	v_mfma_f32_16x16x32_bf16 v[98:101], v[12:15], v[106:109], v[98:101]
	v_mfma_f32_16x16x32_bf16 v[94:97], v[12:15], v[102:105], v[94:97]
	s_nop 0
	v_add_f32_e32 v55, v134, v146
	ds_write2_b32 v126, v49, v55 offset0:32 offset1:48
	v_add_f32_e32 v49, v111, v147
	v_add_f32_e32 v55, v115, v147
	ds_write2_b32 v126, v49, v55 offset0:132 offset1:148
	v_add_f32_e32 v49, v123, v147
	v_add_f32_e32 v55, v135, v147
	ds_write2_b32 v126, v49, v55 offset0:164 offset1:180
	v_add_f32_e32 v49, v112, v148
	v_add_f32_e32 v55, v116, v148
	ds_write2_b32 v57, v49, v55 offset0:8 offset1:24
	v_add_f32_e32 v49, v124, v148
	v_add_f32_e32 v55, v136, v148
	ds_write2_b32 v57, v49, v55 offset0:40 offset1:56
	v_add_f32_e32 v49, v113, v149
	v_add_f32_e32 v55, v117, v149
	ds_write2_b32 v57, v49, v55 offset0:140 offset1:156
	v_add_f32_e32 v49, v125, v149
	v_add_f32_e32 v55, v137, v149
	ds_write2_b32 v57, v49, v55 offset0:172 offset1:188
	v_ashrrev_i32_e32 v55, 31, v54
	v_lshl_add_u64 v[54:55], v[54:55], 2, s[8:9]
	global_load_dwordx4 v[106:109], v[54:55], off
	v_mfma_f32_16x16x32_bf16 v[102:105], v[162:165], v[36:39], v[138:141]
	v_add_u32_e32 v54, 0x2000, v126
	v_ashrrev_i32_e32 v57, 31, v56
	v_mfma_f32_16x16x32_bf16 v[50:53], v[162:165], v[28:31], v[50:53]
	v_mfma_f32_16x16x32_bf16 v[70:73], v[162:165], v[20:23], v[70:73]
	v_mfma_f32_16x16x32_bf16 v[74:77], v[162:165], v[16:19], v[74:77]
	v_mfma_f32_16x16x32_bf16 v[102:105], v[174:177], v[182:185], v[102:105]
	v_mfma_f32_16x16x32_bf16 v[50:53], v[174:177], v[186:189], v[50:53]
	v_mfma_f32_16x16x32_bf16 v[70:73], v[174:177], v[44:47], v[70:73]
	s_waitcnt vmcnt(1)
	s_nop 4
	v_add_f32_e32 v49, v102, v150
	v_add_f32_e32 v50, v50, v150
	ds_write2_b32 v54, v49, v50 offset0:64 offset1:80
	v_mfma_f32_16x16x32_bf16 v[74:77], v[174:177], v[40:43], v[74:77]
	v_add_f32_e32 v55, v53, v153
	v_add_f32_e32 v49, v70, v150
	v_mfma_f32_16x16x32_bf16 v[78:81], v[166:169], v[36:39], v[78:81]
	v_mfma_f32_16x16x32_bf16 v[82:85], v[166:169], v[28:31], v[82:85]
	s_nop 3
	v_add_f32_e32 v50, v74, v150
	ds_write2_b32 v54, v49, v50 offset0:96 offset1:112
	v_add_f32_e32 v49, v103, v151
	v_add_f32_e32 v50, v51, v151
	ds_write2_b32 v54, v49, v50 offset0:196 offset1:212
	v_add_f32_e32 v49, v71, v151
	v_add_f32_e32 v50, v75, v151
	ds_write2_b32 v54, v49, v50 offset0:228 offset1:244
	v_add_f32_e32 v49, v104, v152
	v_add_f32_e32 v50, v52, v152
	v_add_u32_e32 v54, 0x2400, v126
	v_mfma_f32_16x16x32_bf16 v[86:89], v[166:169], v[20:23], v[86:89]
	ds_write2_b32 v54, v49, v50 offset0:72 offset1:88
	v_add_f32_e32 v49, v72, v152
	v_add_f32_e32 v50, v76, v152
	v_mfma_f32_16x16x32_bf16 v[90:93], v[166:169], v[16:19], v[90:93]
	ds_write2_b32 v54, v49, v50 offset0:104 offset1:120
	v_add_f32_e32 v49, v105, v153
	ds_write2_b32 v54, v49, v55 offset0:204 offset1:220
	v_mfma_f32_16x16x32_bf16 v[50:53], v[178:181], v[182:185], v[78:81]
	v_add_f32_e32 v49, v73, v153
	v_add_f32_e32 v55, v77, v153
	ds_write2_b32 v54, v49, v55 offset0:236 offset1:252
	v_mfma_f32_16x16x32_bf16 v[70:73], v[178:181], v[186:189], v[82:85]
	v_add_u32_e32 v54, 0x4000, v126
	s_nop 2
	v_add_f32_e32 v49, v50, v190
	v_mfma_f32_16x16x32_bf16 v[74:77], v[178:181], v[44:47], v[86:89]
	v_mfma_f32_16x16x32_bf16 v[78:81], v[178:181], v[40:43], v[90:93]
	s_nop 0
	v_add_f32_e32 v50, v70, v190
	ds_write2_b32 v54, v49, v50 offset0:128 offset1:144
	s_nop 3
	v_add_f32_e32 v49, v74, v190
	v_mfma_f32_16x16x32_bf16 v[32:35], v[12:15], v[118:121], v[32:35]
	v_mfma_f32_16x16x32_bf16 v[0:3], v[12:15], v[4:7], v[0:3]
	v_add_f32_e32 v50, v78, v190
	ds_write2_b32 v54, v49, v50 offset0:160 offset1:176
	v_add_f32_e32 v49, v51, v191
	v_add_f32_e32 v4, v71, v191
	v_add_u32_e32 v50, 0x4400, v126
	v_add_f32_e32 v12, v75, v191
	v_add_f32_e32 v13, v79, v191
	ds_write2_b32 v50, v49, v4 offset0:4 offset1:20
	v_mfma_f32_16x16x32_bf16 v[4:7], v[8:11], v[36:39], v[94:97]
	ds_write2_b32 v50, v12, v13 offset0:36 offset1:52
	v_ashrrev_i32_e32 v49, 31, v48
	v_lshl_add_u64 v[70:71], v[56:57], 0, s[16:17]
	v_mfma_f32_16x16x32_bf16 v[12:15], v[8:11], v[28:31], v[98:101]
	v_add_f32_e32 v28, v52, v192
	v_add_f32_e32 v29, v72, v192
	ds_write2_b32 v50, v28, v29 offset0:136 offset1:152
	v_mfma_f32_16x16x32_bf16 v[20:23], v[8:11], v[20:23], v[32:35]
	v_add_f32_e32 v28, v76, v192
	v_add_f32_e32 v29, v80, v192
	ds_write2_b32 v50, v28, v29 offset0:168 offset1:184
	v_mfma_f32_16x16x32_bf16 v[0:3], v[8:11], v[16:19], v[0:3]
	v_add_f32_e32 v8, v53, v193
	v_add_f32_e32 v9, v73, v193
	v_add_u32_e32 v16, 0x4800, v126
	v_mfma_f32_16x16x32_bf16 v[4:7], v[24:27], v[182:185], v[4:7]
	ds_write2_b32 v16, v8, v9 offset0:12 offset1:28
	v_add_f32_e32 v17, v77, v193
	v_add_f32_e32 v18, v81, v193
	v_mfma_f32_16x16x32_bf16 v[8:11], v[24:27], v[186:189], v[12:15]
	ds_write2_b32 v16, v17, v18 offset0:44 offset1:60
	s_waitcnt vmcnt(0)
; __device__ __forceinline__ unsigned pack2(float a, float b) { return (unsigned)f2bf(a) | ((unsigned)f2bf(b) << 16); }
; __device__ __forceinline__ float bflo(unsigned w) { return __uint_as_float(w << 16); }
; __device__ __forceinline__ float bfhi(unsigned w) { return __uint_as_float(w & 0xffff0000u); }
; __device__ __forceinline__ float silu_f(float g) { return g / (1.f + __expf(-g)); }
; __device__ void gmlp_item(const Params& p, int layer, int b, int n, int g, char* smem) {
;     ...
;       }
;     __syncthreads();
;     uint4 uu[8], gt[8];
; #pragma unroll
;     for (int i = 0; i < 8; ++i) {
;       int q = tid + 256 * i, t = q >> 4, c = (q & 15) * 8;
;       uu[i] = *reinterpret_cast<const uint4*>(P + (t0 + t) * NP + g * 128 + c);
;       gt[i] = *reinterpret_cast<const uint4*>(P + (t0 + t) * NP + 1024 + g * 128 + c);
;     }
; #pragma unroll
;     for (int i = 0; i < 8; ++i) {
;       int q = tid + 256 * i, t = q >> 4, c = (q & 15) * 8;
;       float4 m0 = *reinterpret_cast<const float4*>(Tf + t * 132 + c);
;       float4 m1 = *reinterpret_cast<const float4*>(Tf + t * 132 + c + 4);
;       float mm[8] = {m0.x, m0.y, m0.z, m0.w, m1.x, m1.y, m1.z, m1.w};
;       unsigned uw[4] = {uu[i].x, uu[i].y, uu[i].z, uu[i].w};
;       unsigned gw[4] = {gt[i].x, gt[i].y, gt[i].z, gt[i].w};
;       unsigned ow[4];
; #pragma unroll
;       for (int e = 0; e < 4; ++e) {
;         float y0 = bflo(uw[e]) * mm[2 * e] * silu_f(bflo(gw[e]));
;         float y1 = bfhi(uw[e]) * mm[2 * e + 1] * silu_f(bfhi(gw[e]));
;         ow[e] = pack2(y0, y1);
;       }
;       *reinterpret_cast<uint4*>(Y + (t0 + t) * YW + g * 128 + c) = make_uint4(ow[0], ow[1], ow[2], ow[3]);
	s_nop 1
	v_add_f32_e32 v4, v4, v106
	v_add_u32_e32 v16, 0x6000, v126
	v_mfma_f32_16x16x32_bf16 v[12:15], v[24:27], v[44:47], v[20:23]
	v_lshl_add_u64 v[36:37], v[62:63], 0, s[16:17]
	v_add_f32_e32 v8, v8, v106
	ds_write2_b32 v16, v4, v8 offset0:192 offset1:208
	v_mfma_f32_16x16x32_bf16 v[0:3], v[24:27], v[40:43], v[0:3]
	v_lshl_add_u64 v[20:21], v[64:65], 0, s[16:17]
	s_nop 2
	v_add_f32_e32 v4, v12, v106
	v_lshl_add_u64 v[38:39], v[60:61], 0, s[16:17]
	s_nop 1
	v_add_f32_e32 v0, v0, v106
	ds_write2_b32 v16, v4, v0 offset0:224 offset1:240
	v_add_f32_e32 v0, v5, v107
	v_add_f32_e32 v4, v9, v107
	v_add_u32_e32 v5, 0x6400, v126
	ds_write2_b32 v5, v0, v4 offset0:68 offset1:84
	v_add_f32_e32 v0, v13, v107
	v_add_f32_e32 v1, v1, v107
	ds_write2_b32 v5, v0, v1 offset0:100 offset1:116
	v_add_f32_e32 v0, v6, v108
	v_add_f32_e32 v1, v10, v108
	ds_write2_b32 v5, v0, v1 offset0:200 offset1:216
	v_add_f32_e32 v0, v14, v108
	v_add_f32_e32 v1, v2, v108
	ds_write2_b32 v5, v0, v1 offset0:232 offset1:248
	v_add_f32_e32 v0, v7, v109
	v_add_f32_e32 v1, v11, v109
	v_add_u32_e32 v2, 0x6800, v126
	ds_write2_b32 v2, v0, v1 offset0:76 offset1:92
	v_add_f32_e32 v0, v15, v109
	v_add_f32_e32 v1, v3, v109
	ds_write2_b32 v2, v0, v1 offset0:108 offset1:124
	v_lshlrev_b32_e32 v0, 3, v59
	v_lshl_add_u64 v[8:9], v[48:49], 0, s[16:17]
	v_mov_b64_e32 v[10:11], s[6:7]
	v_and_b32_e32 v24, 0x78, v0
	v_mad_u64_u32 v[0:1], s[6:7], v8, s39, v[10:11]
	v_mad_i32_i24 v1, v9, s39, v1
	s_lshl_b32 s6, s10, 1
	s_mov_b32 s7, s17
	v_lshl_add_u64 v[0:1], v[0:1], 0, s[6:7]
	v_lshlrev_b32_e32 v128, 1, v24
	v_lshl_add_u64 v[12:13], v[68:69], 0, s[16:17]
	v_lshl_add_u64 v[52:53], v[0:1], 0, v[128:129]
	v_mad_u64_u32 v[0:1], s[8:9], v12, s39, v[10:11]
	v_mad_i32_i24 v1, v13, s39, v1
	v_lshl_add_u64 v[0:1], v[0:1], 0, s[6:7]
	v_lshl_add_u64 v[32:33], v[0:1], 0, v[128:129]
	v_mad_u64_u32 v[0:1], s[8:9], v70, s39, v[10:11]
	v_mad_i32_i24 v1, v71, s39, v1
	v_lshl_add_u64 v[0:1], v[0:1], 0, s[6:7]
	v_lshl_add_u64 v[4:5], v[0:1], 0, v[128:129]
	s_waitcnt lgkmcnt(0)
	s_barrier
	global_load_dwordx4 v[0:3], v[4:5], off
	s_nop 0
	global_load_dwordx4 v[4:7], v[4:5], off offset:2048
	v_lshl_add_u64 v[16:17], v[66:67], 0, s[16:17]
	v_mad_u64_u32 v[14:15], s[8:9], v16, s39, v[10:11]
	v_mad_i32_i24 v15, v17, s39, v15
	v_lshl_add_u64 v[14:15], v[14:15], 0, s[6:7]
	v_lshl_add_u64 v[30:31], v[14:15], 0, v[128:129]
	v_mad_u64_u32 v[14:15], s[8:9], v20, s39, v[10:11]
	v_mad_i32_i24 v15, v21, s39, v15
	v_lshl_add_u64 v[14:15], v[14:15], 0, s[6:7]
	v_lshl_add_u64 v[26:27], v[14:15], 0, v[128:129]
	v_mad_u64_u32 v[14:15], s[8:9], v36, s39, v[10:11]
	v_mad_i32_i24 v15, v37, s39, v15
	v_ashrrev_i32_e32 v59, 31, v58
	v_lshl_add_u64 v[14:15], v[14:15], 0, s[6:7]
	v_lshl_add_u64 v[72:73], v[58:59], 0, s[16:17]
	v_lshl_add_u64 v[22:23], v[14:15], 0, v[128:129]
	v_mad_u64_u32 v[14:15], s[8:9], v38, s39, v[10:11]
	v_mad_u64_u32 v[10:11], s[8:9], v72, s39, v[10:11]
	v_mad_i32_i24 v15, v39, s39, v15
	v_mad_i32_i24 v11, v73, s39, v11
	v_lshl_add_u64 v[14:15], v[14:15], 0, s[6:7]
	v_lshl_add_u64 v[10:11], v[10:11], 0, s[6:7]
	s_add_u32 s6, s11, s6
	s_addc_u32 s7, s12, 0
	v_lshl_add_u64 v[18:19], v[14:15], 0, v[128:129]
	v_lshl_add_u64 v[14:15], v[10:11], 0, v[128:129]
	v_lshlrev_b32_e32 v10, 2, v24
	v_lshl_add_u64 v[24:25], s[6:7], 0, v[128:129]
	v_lshl_add_u64 v[74:75], v[24:25], 0, s[26:27]
	v_mad_u64_u32 v[54:55], s[6:7], v48, s55, v[10:11]
	v_mad_u64_u32 v[48:49], s[6:7], v12, s63, v[74:75]
	v_mad_u64_u32 v[46:47], s[6:7], v16, s63, v[74:75]
	v_mad_u64_u32 v[50:51], s[6:7], v8, s63, v[74:75]
	v_mad_i32_i24 v49, v13, s63, v49
	v_mad_i32_i24 v47, v17, s63, v47
	v_mad_u64_u32 v[44:45], s[6:7], v20, s63, v[74:75]
	v_mad_u64_u32 v[16:17], s[6:7], v60, s55, v[10:11]
	v_mad_u64_u32 v[12:13], s[6:7], v58, s55, v[10:11]
	v_mad_i32_i24 v51, v9, s63, v51
	v_mad_i32_i24 v45, v21, s63, v45
	v_mad_u64_u32 v[20:21], s[6:7], v62, s55, v[10:11]
	v_mad_u64_u32 v[8:9], s[6:7], v56, s55, v[10:11]
	v_mad_u64_u32 v[28:29], s[6:7], v66, s55, v[10:11]
	v_mad_u64_u32 v[34:35], s[6:7], v68, s55, v[10:11]
	v_mad_u64_u32 v[24:25], s[6:7], v64, s55, v[10:11]
	v_mad_u64_u32 v[42:43], s[6:7], v36, s63, v[74:75]
	v_mad_i32_i24 v43, v37, s63, v43
	v_mad_u64_u32 v[36:37], s[6:7], v70, s63, v[74:75]
	v_mad_u64_u32 v[40:41], s[6:7], v38, s63, v[74:75]
	v_mad_i32_i24 v41, v39, s63, v41
	v_mad_u64_u32 v[38:39], s[6:7], v72, s63, v[74:75]
	v_mad_i32_i24 v39, v73, s63, v39
	v_mad_i32_i24 v37, v71, s63, v37
	s_waitcnt vmcnt(1)
	v_lshlrev_b32_e32 v63, 16, v1
	s_waitcnt vmcnt(0)
	v_lshlrev_b32_e32 v13, 16, v5
	v_lshlrev_b32_e32 v17, 16, v4
	v_mul_f32_e32 v9, 0xbfb8aa3b, v17
	v_and_b32_e32 v21, 0xffff0000, v5
	v_mul_f32_e32 v5, 0xbfb8aa3b, v13
	v_exp_f32_e32 v60, v9
	v_exp_f32_e32 v61, v5
	ds_read_b128 v[56:59], v8
	ds_read_b128 v[8:11], v8 offset:16
	v_and_b32_e32 v25, 0xffff0000, v4
	v_mul_f32_e32 v4, 0xbfb8aa3b, v25
	v_pk_add_f32 v[60:61], v[60:61], 1.0 op_sel_hi:[1,0]
	s_waitcnt lgkmcnt(1)
	v_mov_b32_e32 v64, v56
	v_exp_f32_e32 v4, v4
	v_lshlrev_b32_e32 v62, 16, v0
	v_mov_b32_e32 v65, v58
	v_rcp_f32_e32 v61, v61
	s_nop 0
	v_mul_f32_e32 v61, v13, v61
	v_and_b32_e32 v1, 0xffff0000, v1
	v_mul_f32_e32 v5, 0xbfb8aa3b, v21
	v_exp_f32_e32 v5, v5
	v_rcp_f32_e32 v60, v60
	s_nop 0
	v_mul_f32_e32 v60, v17, v60
	v_and_b32_e32 v0, 0xffff0000, v0
	v_mov_b32_e32 v58, v57
	v_pk_add_f32 v[4:5], v[4:5], 1.0 op_sel_hi:[1,0]
	v_pk_mul_f32 v[0:1], v[58:59], v[0:1]
	v_pk_mul_f32 v[62:63], v[64:65], v[62:63]
	v_rcp_f32_e32 v5, v5
	s_nop 0
	v_mul_f32_e32 v5, v21, v5
	v_pk_mul_f32 v[60:61], v[60:61], v[62:63]
	v_rcp_f32_e32 v4, v4
	s_nop 0
	v_mul_f32_e32 v4, v25, v4
	v_pk_mul_f32 v[0:1], v[4:5], v[0:1]
	v_lshlrev_b32_e32 v13, 16, v7
	v_lshlrev_b32_e32 v17, 16, v6
	v_cvt_pk_bf16_f32 v1, v61, v1
	v_cvt_pk_bf16_f32 v0, v60, v0
	v_mul_f32_e32 v4, 0xbfb8aa3b, v17
	v_mul_f32_e32 v5, 0xbfb8aa3b, v13
	v_exp_f32_e32 v4, v4
	v_exp_f32_e32 v5, v5
	v_and_b32_e32 v25, 0xffff0000, v6
	v_mul_f32_e32 v6, 0xbfb8aa3b, v25
	v_and_b32_e32 v21, 0xffff0000, v7
	v_exp_f32_e32 v60, v6
	v_pk_add_f32 v[64:65], v[4:5], 1.0 op_sel_hi:[1,0]
	global_load_dwordx4 v[4:7], v[14:15], off
	global_load_dwordx4 v[56:59], v[14:15], off offset:2048
	s_waitcnt lgkmcnt(0)
; __device__ __forceinline__ unsigned pack2(float a, float b) { return (unsigned)f2bf(a) | ((unsigned)f2bf(b) << 16); }
; __device__ __forceinline__ float bflo(unsigned w) { return __uint_as_float(w << 16); }
; __device__ __forceinline__ float bfhi(unsigned w) { return __uint_as_float(w & 0xffff0000u); }
; __device__ __forceinline__ float silu_f(float g) { return g / (1.f + __expf(-g)); }
; __device__ void gmlp_item(const Params& p, int layer, int b, int n, int g, char* smem) {
;     ...
; #pragma unroll
;     for (int i = 0; i < 8; ++i) {
;       int q = tid + 256 * i, t = q >> 4, c = (q & 15) * 8;
;       float4 m0 = *reinterpret_cast<const float4*>(Tf + t * 132 + c);
;       float4 m1 = *reinterpret_cast<const float4*>(Tf + t * 132 + c + 4);
;       float mm[8] = {m0.x, m0.y, m0.z, m0.w, m1.x, m1.y, m1.z, m1.w};
;       unsigned uw[4] = {uu[i].x, uu[i].y, uu[i].z, uu[i].w};
;       unsigned gw[4] = {gt[i].x, gt[i].y, gt[i].z, gt[i].w};
;       unsigned ow[4];
; #pragma unroll
;       for (int e = 0; e < 4; ++e) {
;         float y0 = bflo(uw[e]) * mm[2 * e] * silu_f(bflo(gw[e]));
;         float y1 = bfhi(uw[e]) * mm[2 * e + 1] * silu_f(bfhi(gw[e]));
;         ow[e] = pack2(y0, y1);
;       }
;       *reinterpret_cast<uint4*>(Y + (t0 + t) * YW + g * 128 + c) = make_uint4(ow[0], ow[1], ow[2], ow[3]);
	v_mov_b32_e32 v14, v8
	v_mov_b32_e32 v15, v10
	v_lshlrev_b32_e32 v63, 16, v3
	v_lshlrev_b32_e32 v62, 16, v2
	v_pk_mul_f32 v[14:15], v[14:15], v[62:63]
	v_rcp_f32_e32 v63, v65
	s_nop 0
	v_mul_f32_e32 v63, v13, v63
	v_mul_f32_e32 v10, 0xbfb8aa3b, v21
	v_exp_f32_e32 v61, v10
	v_rcp_f32_e32 v62, v64
	s_nop 0
	v_mul_f32_e32 v62, v17, v62
	v_mov_b32_e32 v10, v9
	v_and_b32_e32 v3, 0xffff0000, v3
	v_pk_add_f32 v[60:61], v[60:61], 1.0 op_sel_hi:[1,0]
	v_and_b32_e32 v2, 0xffff0000, v2
	v_pk_mul_f32 v[2:3], v[10:11], v[2:3]
	v_pk_mul_f32 v[14:15], v[62:63], v[14:15]
	v_rcp_f32_e32 v9, v61
	s_nop 0
	v_mul_f32_e32 v9, v21, v9
	v_rcp_f32_e32 v8, v60
	s_nop 0
	v_mul_f32_e32 v8, v25, v8
	v_pk_mul_f32 v[2:3], v[8:9], v[2:3]
	v_cvt_pk_bf16_f32 v3, v15, v3
	v_cvt_pk_bf16_f32 v2, v14, v2
	s_waitcnt vmcnt(0)
	v_lshlrev_b32_e32 v21, 16, v56
	v_mul_f32_e32 v8, 0xbfb8aa3b, v21
	v_and_b32_e32 v29, 0xffff0000, v56
	v_lshlrev_b32_e32 v17, 16, v57
	v_exp_f32_e32 v60, v8
	v_mul_f32_e32 v8, 0xbfb8aa3b, v29
	v_exp_f32_e32 v56, v8
	v_mul_f32_e32 v8, 0xbfb8aa3b, v17
	v_exp_f32_e32 v61, v8
	ds_read_b128 v[8:11], v12
	ds_read_b128 v[12:15], v12 offset:16
	v_and_b32_e32 v25, 0xffff0000, v57
	v_lshlrev_b32_e32 v63, 16, v5
	v_pk_add_f32 v[60:61], v[60:61], 1.0 op_sel_hi:[1,0]
	s_waitcnt lgkmcnt(1)
	v_mov_b32_e32 v64, v8
	v_mov_b32_e32 v65, v10
	v_lshlrev_b32_e32 v62, 16, v4
	v_and_b32_e32 v5, 0xffff0000, v5
	v_rcp_f32_e32 v61, v61
	s_nop 0
	v_mul_f32_e32 v61, v17, v61
	v_and_b32_e32 v4, 0xffff0000, v4
	v_mul_f32_e32 v10, 0xbfb8aa3b, v25
	v_exp_f32_e32 v57, v10
	v_rcp_f32_e32 v60, v60
	s_nop 0
	v_mul_f32_e32 v60, v21, v60
	v_mov_b32_e32 v10, v9
	v_pk_mul_f32 v[4:5], v[10:11], v[4:5]
	v_pk_add_f32 v[56:57], v[56:57], 1.0 op_sel_hi:[1,0]
	v_pk_mul_f32 v[62:63], v[64:65], v[62:63]
	v_pk_mul_f32 v[60:61], v[60:61], v[62:63]
	v_lshlrev_b32_e32 v63, 16, v7
	v_lshlrev_b32_e32 v62, 16, v6
	v_rcp_f32_e32 v9, v57
	s_nop 0
	v_mul_f32_e32 v9, v25, v9
	v_rcp_f32_e32 v8, v56
	s_nop 0
	v_mul_f32_e32 v8, v29, v8
	v_pk_mul_f32 v[4:5], v[8:9], v[4:5]
	v_lshlrev_b32_e32 v17, 16, v59
	v_lshlrev_b32_e32 v21, 16, v58
	v_cvt_pk_bf16_f32 v5, v61, v5
	v_cvt_pk_bf16_f32 v4, v60, v4
	v_mul_f32_e32 v8, 0xbfb8aa3b, v21
	v_mul_f32_e32 v9, 0xbfb8aa3b, v17
	v_exp_f32_e32 v8, v8
	v_exp_f32_e32 v9, v9
	v_and_b32_e32 v29, 0xffff0000, v58
	v_mul_f32_e32 v10, 0xbfb8aa3b, v29
	v_and_b32_e32 v25, 0xffff0000, v59
	v_exp_f32_e32 v60, v10
	v_pk_add_f32 v[64:65], v[8:9], 1.0 op_sel_hi:[1,0]
	global_load_dwordx4 v[8:11], v[18:19], off
	global_load_dwordx4 v[56:59], v[18:19], off offset:2048
	s_waitcnt lgkmcnt(0)
	v_mov_b32_e32 v18, v12
	v_mov_b32_e32 v19, v14
	v_pk_mul_f32 v[18:19], v[18:19], v[62:63]
	v_rcp_f32_e32 v63, v65
	s_nop 0
	v_mul_f32_e32 v63, v17, v63
	v_and_b32_e32 v7, 0xffff0000, v7
	v_mul_f32_e32 v14, 0xbfb8aa3b, v25
	v_exp_f32_e32 v61, v14
	v_rcp_f32_e32 v62, v64
	s_nop 0
	v_mul_f32_e32 v62, v21, v62
	v_mov_b32_e32 v14, v13
	v_and_b32_e32 v6, 0xffff0000, v6
	v_pk_add_f32 v[60:61], v[60:61], 1.0 op_sel_hi:[1,0]
	v_pk_mul_f32 v[6:7], v[14:15], v[6:7]
	v_pk_mul_f32 v[18:19], v[62:63], v[18:19]
	v_rcp_f32_e32 v13, v61
	s_nop 0
	v_mul_f32_e32 v13, v25, v13
	v_rcp_f32_e32 v12, v60
	s_nop 0
	v_mul_f32_e32 v12, v29, v12
	v_pk_mul_f32 v[6:7], v[12:13], v[6:7]
	v_cvt_pk_bf16_f32 v7, v19, v7
	v_cvt_pk_bf16_f32 v6, v18, v6
	s_waitcnt vmcnt(1)
	v_lshlrev_b32_e32 v63, 16, v9
	s_waitcnt vmcnt(0)
	v_lshlrev_b32_e32 v25, 16, v56
	v_mul_f32_e32 v12, 0xbfb8aa3b, v25
	v_and_b32_e32 v35, 0xffff0000, v56
	v_lshlrev_b32_e32 v21, 16, v57
	v_exp_f32_e32 v60, v12
	v_mul_f32_e32 v12, 0xbfb8aa3b, v35
	v_exp_f32_e32 v56, v12
	v_mul_f32_e32 v12, 0xbfb8aa3b, v21
	v_exp_f32_e32 v61, v12
	v_and_b32_e32 v29, 0xffff0000, v57
	ds_read_b128 v[12:15], v16
	ds_read_b128 v[16:19], v16 offset:16
	v_lshlrev_b32_e32 v62, 16, v8
	v_pk_add_f32 v[60:61], v[60:61], 1.0 op_sel_hi:[1,0]
	v_and_b32_e32 v9, 0xffff0000, v9
	s_waitcnt lgkmcnt(1)
	v_mov_b32_e32 v64, v12
	v_mov_b32_e32 v65, v14
	v_pk_mul_f32 v[62:63], v[64:65], v[62:63]
	v_rcp_f32_e32 v61, v61
	s_nop 0
	v_mul_f32_e32 v61, v21, v61
	v_and_b32_e32 v8, 0xffff0000, v8
	v_mul_f32_e32 v14, 0xbfb8aa3b, v29
	v_exp_f32_e32 v57, v14
	v_rcp_f32_e32 v60, v60
	s_nop 0
	v_mul_f32_e32 v60, v25, v60
	v_mov_b32_e32 v14, v13
	v_pk_mul_f32 v[8:9], v[14:15], v[8:9]
	v_pk_add_f32 v[56:57], v[56:57], 1.0 op_sel_hi:[1,0]
	v_pk_mul_f32 v[60:61], v[60:61], v[62:63]
	v_lshlrev_b32_e32 v63, 16, v11
	v_lshlrev_b32_e32 v62, 16, v10
	v_and_b32_e32 v11, 0xffff0000, v11
	v_rcp_f32_e32 v13, v57
	s_nop 0
	v_mul_f32_e32 v13, v29, v13
	v_rcp_f32_e32 v12, v56
	s_nop 0
	v_mul_f32_e32 v12, v35, v12
	v_pk_mul_f32 v[8:9], v[12:13], v[8:9]
	v_lshlrev_b32_e32 v21, 16, v59
	v_lshlrev_b32_e32 v25, 16, v58
	v_cvt_pk_bf16_f32 v9, v61, v9
	v_cvt_pk_bf16_f32 v8, v60, v8
	v_mul_f32_e32 v12, 0xbfb8aa3b, v25
	v_mul_f32_e32 v13, 0xbfb8aa3b, v21
	v_exp_f32_e32 v12, v12
	v_exp_f32_e32 v13, v13
	v_and_b32_e32 v35, 0xffff0000, v58
	v_mul_f32_e32 v14, 0xbfb8aa3b, v35
	v_and_b32_e32 v29, 0xffff0000, v59
	v_exp_f32_e32 v60, v14
	v_pk_add_f32 v[64:65], v[12:13], 1.0 op_sel_hi:[1,0]
	global_load_dwordx4 v[12:15], v[22:23], off
	global_load_dwordx4 v[56:59], v[22:23], off offset:2048
	s_waitcnt lgkmcnt(0)
	v_mov_b32_e32 v22, v16
	v_mov_b32_e32 v23, v18
	v_pk_mul_f32 v[22:23], v[22:23], v[62:63]
	v_rcp_f32_e32 v63, v65
	s_nop 0
	v_mul_f32_e32 v63, v21, v63
	v_and_b32_e32 v10, 0xffff0000, v10
	v_mul_f32_e32 v18, 0xbfb8aa3b, v29
	v_exp_f32_e32 v61, v18
	v_rcp_f32_e32 v62, v64
	s_nop 0
	v_mul_f32_e32 v62, v25, v62
	v_mov_b32_e32 v18, v17
	v_pk_mul_f32 v[10:11], v[18:19], v[10:11]
	v_pk_add_f32 v[60:61], v[60:61], 1.0 op_sel_hi:[1,0]
	v_pk_mul_f32 v[22:23], v[62:63], v[22:23]
	s_waitcnt vmcnt(1)
; __device__ __forceinline__ unsigned pack2(float a, float b) { return (unsigned)f2bf(a) | ((unsigned)f2bf(b) << 16); }
; __device__ __forceinline__ float bflo(unsigned w) { return __uint_as_float(w << 16); }
; __device__ __forceinline__ float bfhi(unsigned w) { return __uint_as_float(w & 0xffff0000u); }
; __device__ __forceinline__ float silu_f(float g) { return g / (1.f + __expf(-g)); }
; __device__ void gmlp_item(const Params& p, int layer, int b, int n, int g, char* smem) {
;     ...
; #pragma unroll
;     for (int i = 0; i < 8; ++i) {
;       int q = tid + 256 * i, t = q >> 4, c = (q & 15) * 8;
;       float4 m0 = *reinterpret_cast<const float4*>(Tf + t * 132 + c);
;       float4 m1 = *reinterpret_cast<const float4*>(Tf + t * 132 + c + 4);
;       float mm[8] = {m0.x, m0.y, m0.z, m0.w, m1.x, m1.y, m1.z, m1.w};
;       unsigned uw[4] = {uu[i].x, uu[i].y, uu[i].z, uu[i].w};
;       unsigned gw[4] = {gt[i].x, gt[i].y, gt[i].z, gt[i].w};
;       unsigned ow[4];
; #pragma unroll
;       for (int e = 0; e < 4; ++e) {
;         float y0 = bflo(uw[e]) * mm[2 * e] * silu_f(bflo(gw[e]));
;         float y1 = bfhi(uw[e]) * mm[2 * e + 1] * silu_f(bfhi(gw[e]));
;         ow[e] = pack2(y0, y1);
;       }
;       *reinterpret_cast<uint4*>(Y + (t0 + t) * YW + g * 128 + c) = make_uint4(ow[0], ow[1], ow[2], ow[3]);
	v_lshlrev_b32_e32 v63, 16, v13
	v_rcp_f32_e32 v17, v61
	s_nop 0
	v_mul_f32_e32 v17, v29, v17
	v_rcp_f32_e32 v16, v60
	s_nop 0
	v_mul_f32_e32 v16, v35, v16
	v_pk_mul_f32 v[10:11], v[16:17], v[10:11]
	s_waitcnt vmcnt(0)
	v_lshlrev_b32_e32 v29, 16, v56
	v_cvt_pk_bf16_f32 v11, v23, v11
	v_mul_f32_e32 v16, 0xbfb8aa3b, v29
	v_and_b32_e32 v55, 0xffff0000, v56
	v_lshlrev_b32_e32 v25, 16, v57
	v_exp_f32_e32 v60, v16
	v_mul_f32_e32 v16, 0xbfb8aa3b, v55
	v_exp_f32_e32 v56, v16
	v_mul_f32_e32 v16, 0xbfb8aa3b, v25
	v_exp_f32_e32 v61, v16
	s_nop 0
	v_pk_add_f32 v[60:61], v[60:61], 1.0 op_sel_hi:[1,0]
	v_and_b32_e32 v35, 0xffff0000, v57
	v_cvt_pk_bf16_f32 v10, v22, v10
	ds_read_b128 v[16:19], v20
	ds_read_b128 v[20:23], v20 offset:16
	v_lshlrev_b32_e32 v62, 16, v12
	v_and_b32_e32 v13, 0xffff0000, v13
	s_waitcnt lgkmcnt(1)
	v_mov_b32_e32 v64, v16
	v_mov_b32_e32 v65, v18
	v_pk_mul_f32 v[62:63], v[64:65], v[62:63]
	v_rcp_f32_e32 v61, v61
	s_nop 0
	v_mul_f32_e32 v61, v25, v61
	v_and_b32_e32 v12, 0xffff0000, v12
	v_mul_f32_e32 v18, 0xbfb8aa3b, v35
	v_exp_f32_e32 v57, v18
	v_rcp_f32_e32 v60, v60
	s_nop 0
	v_mul_f32_e32 v60, v29, v60
	v_mov_b32_e32 v18, v17
	v_pk_mul_f32 v[12:13], v[18:19], v[12:13]
	v_pk_add_f32 v[56:57], v[56:57], 1.0 op_sel_hi:[1,0]
	v_pk_mul_f32 v[60:61], v[60:61], v[62:63]
	v_lshlrev_b32_e32 v63, 16, v15
	v_lshlrev_b32_e32 v62, 16, v14
	v_and_b32_e32 v15, 0xffff0000, v15
	v_rcp_f32_e32 v17, v57
	s_nop 0
	v_mul_f32_e32 v17, v35, v17
	v_rcp_f32_e32 v16, v56
	s_nop 0
	v_mul_f32_e32 v16, v55, v16
	v_pk_mul_f32 v[12:13], v[16:17], v[12:13]
	v_lshlrev_b32_e32 v25, 16, v59
	v_lshlrev_b32_e32 v29, 16, v58
	v_cvt_pk_bf16_f32 v13, v61, v13
	v_cvt_pk_bf16_f32 v12, v60, v12
	v_mul_f32_e32 v16, 0xbfb8aa3b, v29
	v_mul_f32_e32 v17, 0xbfb8aa3b, v25
	v_exp_f32_e32 v16, v16
	v_exp_f32_e32 v17, v17
	v_and_b32_e32 v55, 0xffff0000, v58
	v_mul_f32_e32 v18, 0xbfb8aa3b, v55
	v_and_b32_e32 v35, 0xffff0000, v59
	v_exp_f32_e32 v60, v18
	v_pk_add_f32 v[64:65], v[16:17], 1.0 op_sel_hi:[1,0]
	global_load_dwordx4 v[16:19], v[26:27], off
	global_load_dwordx4 v[56:59], v[26:27], off offset:2048
	s_waitcnt lgkmcnt(0)
	v_mov_b32_e32 v26, v20
	v_mov_b32_e32 v27, v22
	v_pk_mul_f32 v[26:27], v[26:27], v[62:63]
	v_rcp_f32_e32 v63, v65
	s_nop 0
	v_mul_f32_e32 v63, v25, v63
	v_and_b32_e32 v14, 0xffff0000, v14
	v_mul_f32_e32 v22, 0xbfb8aa3b, v35
	v_exp_f32_e32 v61, v22
	v_rcp_f32_e32 v62, v64
	s_nop 0
	v_mul_f32_e32 v62, v29, v62
	v_mov_b32_e32 v22, v21
	v_pk_mul_f32 v[14:15], v[22:23], v[14:15]
	v_pk_add_f32 v[60:61], v[60:61], 1.0 op_sel_hi:[1,0]
	v_pk_mul_f32 v[26:27], v[62:63], v[26:27]
	s_waitcnt vmcnt(1)
	v_lshlrev_b32_e32 v63, 16, v17
	v_rcp_f32_e32 v21, v61
	s_nop 0
	v_mul_f32_e32 v21, v35, v21
	v_rcp_f32_e32 v20, v60
	s_nop 0
	v_mul_f32_e32 v20, v55, v20
	v_pk_mul_f32 v[14:15], v[20:21], v[14:15]
	s_waitcnt vmcnt(0)
	v_lshlrev_b32_e32 v35, 16, v56
	v_cvt_pk_bf16_f32 v15, v27, v15
	v_mul_f32_e32 v20, 0xbfb8aa3b, v35
	v_and_b32_e32 v66, 0xffff0000, v56
	v_lshlrev_b32_e32 v29, 16, v57
	v_exp_f32_e32 v60, v20
	v_mul_f32_e32 v20, 0xbfb8aa3b, v66
	v_exp_f32_e32 v56, v20
	v_mul_f32_e32 v20, 0xbfb8aa3b, v29
	v_exp_f32_e32 v61, v20
	s_nop 0
	v_pk_add_f32 v[60:61], v[60:61], 1.0 op_sel_hi:[1,0]
	v_and_b32_e32 v55, 0xffff0000, v57
	v_cvt_pk_bf16_f32 v14, v26, v14
	ds_read_b128 v[20:23], v24
	ds_read_b128 v[24:27], v24 offset:16
	v_lshlrev_b32_e32 v62, 16, v16
	v_and_b32_e32 v17, 0xffff0000, v17
	s_waitcnt lgkmcnt(1)
	v_mov_b32_e32 v64, v20
	v_mov_b32_e32 v65, v22
	v_pk_mul_f32 v[62:63], v[64:65], v[62:63]
	v_rcp_f32_e32 v61, v61
	s_nop 0
	v_mul_f32_e32 v61, v29, v61
	v_and_b32_e32 v16, 0xffff0000, v16
	v_mul_f32_e32 v22, 0xbfb8aa3b, v55
	v_exp_f32_e32 v57, v22
	v_rcp_f32_e32 v60, v60
	s_nop 0
	v_mul_f32_e32 v60, v35, v60
	v_mov_b32_e32 v22, v21
	v_pk_mul_f32 v[16:17], v[22:23], v[16:17]
	v_pk_add_f32 v[56:57], v[56:57], 1.0 op_sel_hi:[1,0]
	v_pk_mul_f32 v[60:61], v[60:61], v[62:63]
	v_lshlrev_b32_e32 v63, 16, v19
	v_lshlrev_b32_e32 v62, 16, v18
	v_and_b32_e32 v19, 0xffff0000, v19
	v_rcp_f32_e32 v21, v57
	s_nop 0
	v_mul_f32_e32 v21, v55, v21
	v_rcp_f32_e32 v20, v56
	s_nop 0
	v_mul_f32_e32 v20, v66, v20
	v_pk_mul_f32 v[16:17], v[20:21], v[16:17]
	v_lshlrev_b32_e32 v29, 16, v59
	v_lshlrev_b32_e32 v35, 16, v58
	v_cvt_pk_bf16_f32 v17, v61, v17
	v_cvt_pk_bf16_f32 v16, v60, v16
	v_mul_f32_e32 v20, 0xbfb8aa3b, v35
	v_mul_f32_e32 v21, 0xbfb8aa3b, v29
	v_exp_f32_e32 v20, v20
	v_exp_f32_e32 v21, v21
	v_and_b32_e32 v66, 0xffff0000, v58
	v_mul_f32_e32 v22, 0xbfb8aa3b, v66
	v_and_b32_e32 v55, 0xffff0000, v59
	v_exp_f32_e32 v60, v22
	v_pk_add_f32 v[64:65], v[20:21], 1.0 op_sel_hi:[1,0]
	global_load_dwordx4 v[20:23], v[30:31], off
	global_load_dwordx4 v[56:59], v[30:31], off offset:2048
	s_waitcnt lgkmcnt(0)
	v_mov_b32_e32 v30, v24
	v_mov_b32_e32 v31, v26
	v_pk_mul_f32 v[30:31], v[30:31], v[62:63]
	v_rcp_f32_e32 v63, v65
	s_nop 0
	v_mul_f32_e32 v63, v29, v63
	v_and_b32_e32 v18, 0xffff0000, v18
	v_mul_f32_e32 v26, 0xbfb8aa3b, v55
	v_exp_f32_e32 v61, v26
	v_rcp_f32_e32 v62, v64
	s_nop 0
	v_mul_f32_e32 v62, v35, v62
	v_mov_b32_e32 v26, v25
	v_pk_mul_f32 v[18:19], v[26:27], v[18:19]
	v_pk_add_f32 v[60:61], v[60:61], 1.0 op_sel_hi:[1,0]
	v_pk_mul_f32 v[30:31], v[62:63], v[30:31]
	s_waitcnt vmcnt(1)
	v_lshlrev_b32_e32 v63, 16, v21
	v_rcp_f32_e32 v25, v61
	s_nop 0
	v_mul_f32_e32 v25, v55, v25
	v_rcp_f32_e32 v24, v60
	s_nop 0
	v_mul_f32_e32 v24, v66, v24
	v_pk_mul_f32 v[18:19], v[24:25], v[18:19]
	s_waitcnt vmcnt(0)
; __device__ __forceinline__ unsigned pack2(float a, float b) { return (unsigned)f2bf(a) | ((unsigned)f2bf(b) << 16); }
; __device__ __forceinline__ float bflo(unsigned w) { return __uint_as_float(w << 16); }
; __device__ __forceinline__ float bfhi(unsigned w) { return __uint_as_float(w & 0xffff0000u); }
; __device__ __forceinline__ float silu_f(float g) { return g / (1.f + __expf(-g)); }
; __device__ void gmlp_item(const Params& p, int layer, int b, int n, int g, char* smem) {
;     ...
; #pragma unroll
;     for (int i = 0; i < 8; ++i) {
;       int q = tid + 256 * i, t = q >> 4, c = (q & 15) * 8;
;       float4 m0 = *reinterpret_cast<const float4*>(Tf + t * 132 + c);
;       float4 m1 = *reinterpret_cast<const float4*>(Tf + t * 132 + c + 4);
;       float mm[8] = {m0.x, m0.y, m0.z, m0.w, m1.x, m1.y, m1.z, m1.w};
;       unsigned uw[4] = {uu[i].x, uu[i].y, uu[i].z, uu[i].w};
;       unsigned gw[4] = {gt[i].x, gt[i].y, gt[i].z, gt[i].w};
;       unsigned ow[4];
; #pragma unroll
;       for (int e = 0; e < 4; ++e) {
;         float y0 = bflo(uw[e]) * mm[2 * e] * silu_f(bflo(gw[e]));
;         float y1 = bfhi(uw[e]) * mm[2 * e + 1] * silu_f(bfhi(gw[e]));
;         ow[e] = pack2(y0, y1);
;       }
;       *reinterpret_cast<uint4*>(Y + (t0 + t) * YW + g * 128 + c) = make_uint4(ow[0], ow[1], ow[2], ow[3]);
	v_lshlrev_b32_e32 v55, 16, v56
	v_cvt_pk_bf16_f32 v19, v31, v19
	v_mul_f32_e32 v24, 0xbfb8aa3b, v55
	v_and_b32_e32 v67, 0xffff0000, v56
	v_lshlrev_b32_e32 v35, 16, v57
	v_exp_f32_e32 v60, v24
	v_mul_f32_e32 v24, 0xbfb8aa3b, v67
	v_exp_f32_e32 v56, v24
	v_mul_f32_e32 v24, 0xbfb8aa3b, v35
	v_exp_f32_e32 v61, v24
	s_nop 0
	v_pk_add_f32 v[60:61], v[60:61], 1.0 op_sel_hi:[1,0]
	v_and_b32_e32 v66, 0xffff0000, v57
	v_cvt_pk_bf16_f32 v18, v30, v18
	ds_read_b128 v[24:27], v28
	ds_read_b128 v[28:31], v28 offset:16
	v_lshlrev_b32_e32 v62, 16, v20
	v_and_b32_e32 v21, 0xffff0000, v21
	s_waitcnt lgkmcnt(1)
	v_mov_b32_e32 v64, v24
	v_mov_b32_e32 v65, v26
	v_pk_mul_f32 v[62:63], v[64:65], v[62:63]
	v_rcp_f32_e32 v61, v61
	s_nop 0
	v_mul_f32_e32 v61, v35, v61
	v_and_b32_e32 v20, 0xffff0000, v20
	v_mul_f32_e32 v26, 0xbfb8aa3b, v66
	v_exp_f32_e32 v57, v26
	v_rcp_f32_e32 v60, v60
	s_nop 0
	v_mul_f32_e32 v60, v55, v60
	v_mov_b32_e32 v26, v25
	v_pk_mul_f32 v[20:21], v[26:27], v[20:21]
	v_pk_add_f32 v[56:57], v[56:57], 1.0 op_sel_hi:[1,0]
	v_pk_mul_f32 v[60:61], v[60:61], v[62:63]
	v_lshlrev_b32_e32 v63, 16, v23
	v_lshlrev_b32_e32 v62, 16, v22
	v_and_b32_e32 v23, 0xffff0000, v23
	v_rcp_f32_e32 v25, v57
	s_nop 0
	v_mul_f32_e32 v25, v66, v25
	v_rcp_f32_e32 v24, v56
	s_nop 0
	v_mul_f32_e32 v24, v67, v24
	v_pk_mul_f32 v[20:21], v[24:25], v[20:21]
	v_lshlrev_b32_e32 v35, 16, v59
	v_lshlrev_b32_e32 v55, 16, v58
	v_cvt_pk_bf16_f32 v21, v61, v21
	v_cvt_pk_bf16_f32 v20, v60, v20
	v_mul_f32_e32 v24, 0xbfb8aa3b, v55
	v_mul_f32_e32 v25, 0xbfb8aa3b, v35
	v_exp_f32_e32 v24, v24
	v_exp_f32_e32 v25, v25
	v_and_b32_e32 v67, 0xffff0000, v58
	v_mul_f32_e32 v26, 0xbfb8aa3b, v67
	v_and_b32_e32 v66, 0xffff0000, v59
	v_exp_f32_e32 v60, v26
	v_pk_add_f32 v[64:65], v[24:25], 1.0 op_sel_hi:[1,0]
	global_load_dwordx4 v[24:27], v[32:33], off
	global_load_dwordx4 v[56:59], v[32:33], off offset:2048
	s_waitcnt lgkmcnt(0)
	v_mov_b32_e32 v32, v28
	v_mov_b32_e32 v33, v30
	v_pk_mul_f32 v[32:33], v[32:33], v[62:63]
	v_rcp_f32_e32 v63, v65
	s_nop 0
	v_mul_f32_e32 v63, v35, v63
	v_and_b32_e32 v22, 0xffff0000, v22
	v_mul_f32_e32 v30, 0xbfb8aa3b, v66
	v_exp_f32_e32 v61, v30
	v_rcp_f32_e32 v62, v64
	s_nop 0
	v_mul_f32_e32 v62, v55, v62
	v_mov_b32_e32 v30, v29
	v_pk_mul_f32 v[22:23], v[30:31], v[22:23]
	v_pk_add_f32 v[60:61], v[60:61], 1.0 op_sel_hi:[1,0]
	v_pk_mul_f32 v[32:33], v[62:63], v[32:33]
	s_waitcnt vmcnt(1)
	v_lshlrev_b32_e32 v63, 16, v25
	v_rcp_f32_e32 v29, v61
	s_nop 0
	v_mul_f32_e32 v29, v66, v29
	v_rcp_f32_e32 v28, v60
	s_nop 0
	v_mul_f32_e32 v28, v67, v28
	v_pk_mul_f32 v[22:23], v[28:29], v[22:23]
	s_waitcnt vmcnt(0)
	v_lshlrev_b32_e32 v66, 16, v56
	v_cvt_pk_bf16_f32 v23, v33, v23
	v_mul_f32_e32 v28, 0xbfb8aa3b, v66
	v_and_b32_e32 v68, 0xffff0000, v56
	v_lshlrev_b32_e32 v55, 16, v57
	v_exp_f32_e32 v60, v28
	v_mul_f32_e32 v28, 0xbfb8aa3b, v68
	v_exp_f32_e32 v56, v28
	v_mul_f32_e32 v28, 0xbfb8aa3b, v55
	v_exp_f32_e32 v61, v28
	s_nop 0
	v_pk_add_f32 v[60:61], v[60:61], 1.0 op_sel_hi:[1,0]
	v_and_b32_e32 v67, 0xffff0000, v57
	v_cvt_pk_bf16_f32 v22, v32, v22
	ds_read_b128 v[28:31], v34
	ds_read_b128 v[32:35], v34 offset:16
	v_lshlrev_b32_e32 v62, 16, v24
	v_and_b32_e32 v25, 0xffff0000, v25
	s_waitcnt lgkmcnt(1)
	v_mov_b32_e32 v64, v28
	v_mov_b32_e32 v65, v30
	v_pk_mul_f32 v[62:63], v[64:65], v[62:63]
	v_rcp_f32_e32 v61, v61
	s_nop 0
	v_mul_f32_e32 v61, v55, v61
	v_and_b32_e32 v24, 0xffff0000, v24
	v_mul_f32_e32 v30, 0xbfb8aa3b, v67
	v_exp_f32_e32 v57, v30
	v_rcp_f32_e32 v60, v60
	s_nop 0
	v_mul_f32_e32 v60, v66, v60
	v_mov_b32_e32 v30, v29
	v_pk_mul_f32 v[24:25], v[30:31], v[24:25]
	v_pk_add_f32 v[56:57], v[56:57], 1.0 op_sel_hi:[1,0]
	v_pk_mul_f32 v[60:61], v[60:61], v[62:63]
	v_lshlrev_b32_e32 v66, 16, v58
	v_lshlrev_b32_e32 v63, 16, v27
	v_and_b32_e32 v27, 0xffff0000, v27
	v_rcp_f32_e32 v29, v57
	s_nop 0
	v_mul_f32_e32 v29, v67, v29
	v_rcp_f32_e32 v28, v56
	s_nop 0
	v_mul_f32_e32 v28, v68, v28
	v_pk_mul_f32 v[24:25], v[28:29], v[24:25]
	v_lshlrev_b32_e32 v55, 16, v59
	v_cvt_pk_bf16_f32 v25, v61, v25
	v_cvt_pk_bf16_f32 v24, v60, v24
	v_mul_f32_e32 v28, 0xbfb8aa3b, v66
	v_mul_f32_e32 v29, 0xbfb8aa3b, v55
	v_exp_f32_e32 v28, v28
	v_exp_f32_e32 v29, v29
	v_and_b32_e32 v68, 0xffff0000, v58
	v_mul_f32_e32 v30, 0xbfb8aa3b, v68
	v_and_b32_e32 v67, 0xffff0000, v59
	v_exp_f32_e32 v60, v30
	v_pk_add_f32 v[64:65], v[28:29], 1.0 op_sel_hi:[1,0]
	global_load_dwordx4 v[28:31], v[52:53], off
	global_load_dwordx4 v[56:59], v[52:53], off offset:2048
	s_waitcnt lgkmcnt(0)
; __device__ __forceinline__ unsigned pack2(float a, float b) { return (unsigned)f2bf(a) | ((unsigned)f2bf(b) << 16); }
; __device__ __forceinline__ float bflo(unsigned w) { return __uint_as_float(w << 16); }
; __device__ __forceinline__ float bfhi(unsigned w) { return __uint_as_float(w & 0xffff0000u); }
; __device__ __forceinline__ float silu_f(float g) { return g / (1.f + __expf(-g)); }
; __device__ void gmlp_item(const Params& p, int layer, int b, int n, int g, char* smem) {
;     ...
; #pragma unroll
;     for (int i = 0; i < 8; ++i) {
;       int q = tid + 256 * i, t = q >> 4, c = (q & 15) * 8;
;       float4 m0 = *reinterpret_cast<const float4*>(Tf + t * 132 + c);
;       float4 m1 = *reinterpret_cast<const float4*>(Tf + t * 132 + c + 4);
;       float mm[8] = {m0.x, m0.y, m0.z, m0.w, m1.x, m1.y, m1.z, m1.w};
;       unsigned uw[4] = {uu[i].x, uu[i].y, uu[i].z, uu[i].w};
;       unsigned gw[4] = {gt[i].x, gt[i].y, gt[i].z, gt[i].w};
;       unsigned ow[4];
; #pragma unroll
;       for (int e = 0; e < 4; ++e) {
;         float y0 = bflo(uw[e]) * mm[2 * e] * silu_f(bflo(gw[e]));
;         float y1 = bfhi(uw[e]) * mm[2 * e + 1] * silu_f(bfhi(gw[e]));
;         ow[e] = pack2(y0, y1);
;       }
;       *reinterpret_cast<uint4*>(Y + (t0 + t) * YW + g * 128 + c) = make_uint4(ow[0], ow[1], ow[2], ow[3]);
;     }
;   }
;   __syncthreads();
	v_mov_b32_e32 v52, v32
	v_lshlrev_b32_e32 v62, 16, v26
	v_mov_b32_e32 v53, v34
	v_pk_mul_f32 v[52:53], v[52:53], v[62:63]
	v_rcp_f32_e32 v63, v65
	s_nop 0
	v_mul_f32_e32 v63, v55, v63
	v_and_b32_e32 v26, 0xffff0000, v26
	v_mul_f32_e32 v34, 0xbfb8aa3b, v67
	v_exp_f32_e32 v61, v34
	v_rcp_f32_e32 v62, v64
	s_nop 0
	v_mul_f32_e32 v62, v66, v62
	v_mov_b32_e32 v34, v33
	v_pk_mul_f32 v[26:27], v[34:35], v[26:27]
	v_pk_add_f32 v[60:61], v[60:61], 1.0 op_sel_hi:[1,0]
	v_pk_mul_f32 v[52:53], v[62:63], v[52:53]
	s_waitcnt vmcnt(1)
	v_lshlrev_b32_e32 v63, 16, v29
	v_rcp_f32_e32 v33, v61
	s_nop 0
	v_mul_f32_e32 v33, v67, v33
	v_rcp_f32_e32 v32, v60
	s_nop 0
	v_mul_f32_e32 v32, v68, v32
	v_pk_mul_f32 v[26:27], v[32:33], v[26:27]
	s_waitcnt vmcnt(0)
	v_lshlrev_b32_e32 v67, 16, v56
	v_cvt_pk_bf16_f32 v27, v53, v27
	v_mul_f32_e32 v32, 0xbfb8aa3b, v67
	v_and_b32_e32 v69, 0xffff0000, v56
	v_lshlrev_b32_e32 v66, 16, v57
	v_exp_f32_e32 v60, v32
	v_mul_f32_e32 v32, 0xbfb8aa3b, v69
	v_exp_f32_e32 v56, v32
	v_mul_f32_e32 v32, 0xbfb8aa3b, v66
	v_exp_f32_e32 v61, v32
	s_nop 0
	v_pk_add_f32 v[60:61], v[60:61], 1.0 op_sel_hi:[1,0]
	v_and_b32_e32 v68, 0xffff0000, v57
	v_cvt_pk_bf16_f32 v26, v52, v26
	ds_read_b128 v[32:35], v54
	ds_read_b128 v[52:55], v54 offset:16
	v_lshlrev_b32_e32 v62, 16, v28
	v_and_b32_e32 v29, 0xffff0000, v29
	s_waitcnt lgkmcnt(1)
	v_mov_b32_e32 v64, v32
	v_mov_b32_e32 v65, v34
	v_pk_mul_f32 v[62:63], v[64:65], v[62:63]
	v_rcp_f32_e32 v61, v61
	s_nop 0
	v_mul_f32_e32 v61, v66, v61
	v_and_b32_e32 v28, 0xffff0000, v28
	v_mul_f32_e32 v34, 0xbfb8aa3b, v68
	v_exp_f32_e32 v57, v34
	v_rcp_f32_e32 v60, v60
	s_nop 0
	v_mul_f32_e32 v60, v67, v60
	v_pk_mul_f32 v[60:61], v[60:61], v[62:63]
	v_mov_b32_e32 v34, v33
	v_pk_add_f32 v[56:57], v[56:57], 1.0 op_sel_hi:[1,0]
	v_pk_mul_f32 v[28:29], v[34:35], v[28:29]
	s_nop 0
	v_rcp_f32_e32 v33, v57
	s_nop 0
	v_mul_f32_e32 v33, v68, v33
	v_rcp_f32_e32 v32, v56
	s_nop 0
	v_mul_f32_e32 v32, v69, v32
	v_pk_mul_f32 v[28:29], v[32:33], v[28:29]
	v_cvt_pk_bf16_f32 v28, 0, v28
	v_cvt_pk_bf16_f32 v33, 0, v60
	v_and_b32_e32 v28, 0xffff0000, v28
	v_lshlrev_b32_e32 v35, 16, v59
	v_lshlrev_b32_e32 v60, 16, v58
	v_cvt_pk_bf16_f32 v29, v61, v29
	v_or_b32_sdwa v28, v28, v33 dst_sel:DWORD dst_unused:UNUSED_PAD src0_sel:DWORD src1_sel:WORD_1
	v_mul_f32_e32 v32, 0xbfb8aa3b, v60
	v_mul_f32_e32 v33, 0xbfb8aa3b, v35
	v_exp_f32_e32 v32, v32
	v_exp_f32_e32 v33, v33
	v_and_b32_e32 v62, 0xffff0000, v58
	s_waitcnt lgkmcnt(0)
	v_mov_b32_e32 v58, v52
	v_and_b32_e32 v61, 0xffff0000, v59
	v_pk_add_f32 v[32:33], v[32:33], 1.0 op_sel_hi:[1,0]
	v_lshlrev_b32_e32 v57, 16, v31
	v_lshlrev_b32_e32 v56, 16, v30
	v_mov_b32_e32 v59, v54
	v_pk_mul_f32 v[56:57], v[58:59], v[56:57]
	v_rcp_f32_e32 v33, v33
	s_nop 0
	v_mul_f32_e32 v33, v35, v33
	v_mul_f32_e32 v34, 0xbfb8aa3b, v62
	v_mul_f32_e32 v35, 0xbfb8aa3b, v61
	v_exp_f32_e32 v34, v34
	v_exp_f32_e32 v35, v35
	v_rcp_f32_e32 v32, v32
	s_nop 0
	v_mul_f32_e32 v32, v60, v32
	v_pk_mul_f32 v[32:33], v[32:33], v[56:57]
	v_mov_b32_e32 v54, v53
	v_pk_add_f32 v[34:35], v[34:35], 1.0 op_sel_hi:[1,0]
	v_and_b32_e32 v31, 0xffff0000, v31
	v_and_b32_e32 v30, 0xffff0000, v30
	v_pk_mul_f32 v[30:31], v[54:55], v[30:31]
	v_rcp_f32_e32 v35, v35
	s_nop 0
	v_mul_f32_e32 v35, v61, v35
	s_mov_b64 s[6:7], 0
	v_rcp_f32_e32 v34, v34
	s_nop 0
	v_mul_f32_e32 v34, v62, v34
	v_pk_mul_f32 v[30:31], v[34:35], v[30:31]
	v_cvt_pk_bf16_f32 v31, v33, v31
	v_cvt_pk_bf16_f32 v30, v32, v30
	global_store_dwordx4 v[50:51], v[28:31], off
	global_store_dwordx4 v[48:49], v[24:27], off
	global_store_dwordx4 v[46:47], v[20:23], off
	global_store_dwordx4 v[44:45], v[16:19], off
	global_store_dwordx4 v[42:43], v[12:15], off
	global_store_dwordx4 v[40:41], v[8:11], off
	global_store_dwordx4 v[38:39], v[4:7], off
	global_store_dwordx4 v[36:37], v[0:3], off
	s_barrier

; __device__ __forceinline__ float bf2f(u16 h) { return __uint_as_float(((unsigned)h) << 16); }
; __device__ void phase_merge(const Params& p, int layer, char* smem) {
;     ...
;         [&](int s) {
;           int seg = s / 48, r = s - seg * 48;
;           if (r == 31) {
; #pragma unroll
;             for (int n = 0; n < 4; ++n) {
;               float bm = bmp[seg * 1024 + n * 16];
; #pragma unroll
;               for (int m = 0; m < 4; ++m)
; #pragma unroll
;                 for (int j = 0; j < 4; ++j) {
;                   GL[((m * 4 + n) * 4 + j) * 256] = f2bf(1.f / (1.f + __expf(-(acc[m][n][j] + bm))));
;                   acc[m][n][j] = 0.f;
;                 }
;             }
;           } else if (r == 47) {
; #pragma unroll
;             for (int m = 0; m < 4; ++m)
; #pragma unroll
;               for (int n = 0; n < 4; ++n)
; #pragma unroll
;                 for (int j = 0; j < 4; ++j) {
;                   mg[m][n][j] += bf2f(GL[((m * 4 + n) * 4 + j) * 256]) * acc[m][n][j];
;                   acc[m][n][j] = 0.f;
;                 }
.LBB0_1233:
	s_and_b32 s14, s64, 0xffff
	s_lshl_b64 s[12:13], s[14:15], s12
	v_mul_lo_u32 v1, s65, v235
	s_add_u32 s10, s10, s12
	v_or_b32_e32 v1, v1, v239
	v_mul_lo_u32 v2, s66, v235
	s_addc_u32 s11, s11, s13
	s_lshl_b64 s[8:9], s[8:9], 1
	v_lshlrev_b32_e32 v1, 1, v1
	v_or_b32_e32 v2, v2, v239
	s_add_u32 s8, s10, s8
	v_lshlrev_b32_e32 v2, 1, v2
	global_load_dwordx4 v[76:79], v1, s[6:7]
	v_lshl_add_u32 v1, s65, 7, v1
	s_addc_u32 s9, s11, s9
	global_load_dwordx4 v[80:83], v1, s[6:7]
	v_lshl_add_u32 v1, s66, 7, v2
	global_load_dwordx4 v[88:91], v2, s[8:9]
	global_load_dwordx4 v[96:99], v1, s[8:9]
	s_mul_hi_u32 s6, s53, 0xaaaaaaab
	s_lshr_b32 s6, s6, 5
	s_mul_i32 s6, s6, 48
	s_sub_i32 s10, s53, s6
	s_cmp_gt_i32 s10, 46
	s_cbranch_scc0 .LBB0_1236
	ds_read_u16 v164, v234 offset:32768
	ds_read_u16 v165, v234 offset:33280
	ds_read_u16 v166, v234 offset:33792
	ds_read_u16 v167, v234 offset:34304
	ds_read_u16 v168, v234 offset:34816
	ds_read_u16 v169, v234 offset:35328
	ds_read_u16 v170, v234 offset:35840
	ds_read_u16 v171, v234 offset:36352
	ds_read_u16 v172, v234 offset:36864
	ds_read_u16 v173, v234 offset:37376
	ds_read_u16 v174, v234 offset:37888
	ds_read_u16 v175, v234 offset:38400
	ds_read_u16 v176, v234 offset:38912
	ds_read_u16 v177, v234 offset:39424
	s_waitcnt lgkmcnt(13)
	v_lshlrev_b32_e32 v164, 16, v164
	v_fmac_f32_e32 v64, v160, v164
	ds_read_u16 v178, v234 offset:39936
	s_waitcnt lgkmcnt(13)
	v_lshlrev_b32_e32 v165, 16, v165
	v_fmac_f32_e32 v65, v161, v165
	ds_read_u16 v179, v234 offset:40448
	s_waitcnt lgkmcnt(13)
	v_lshlrev_b32_e32 v166, 16, v166
	v_fmac_f32_e32 v66, v162, v166
	ds_read_u16 v180, v234 offset:40960
	s_waitcnt lgkmcnt(13)
	v_lshlrev_b32_e32 v167, 16, v167
	v_fmac_f32_e32 v67, v163, v167
	ds_read_u16 v181, v234 offset:41472
	s_waitcnt lgkmcnt(13)
	v_lshlrev_b32_e32 v168, 16, v168
	v_fmac_f32_e32 v60, v156, v168
	ds_read_u16 v182, v234 offset:41984
	s_waitcnt lgkmcnt(13)
	v_lshlrev_b32_e32 v169, 16, v169
	v_fmac_f32_e32 v61, v157, v169
	ds_read_u16 v183, v234 offset:42496
	s_waitcnt lgkmcnt(13)
	v_lshlrev_b32_e32 v170, 16, v170
	v_fmac_f32_e32 v62, v158, v170
	ds_read_u16 v184, v234 offset:43008
	s_waitcnt lgkmcnt(13)
	v_lshlrev_b32_e32 v171, 16, v171
	v_fmac_f32_e32 v63, v159, v171
	ds_read_u16 v185, v234 offset:43520
	s_waitcnt lgkmcnt(13)
	v_lshlrev_b32_e32 v172, 16, v172
	v_fmac_f32_e32 v56, v152, v172
	ds_read_u16 v186, v234 offset:44032
	s_waitcnt lgkmcnt(13)
	v_lshlrev_b32_e32 v173, 16, v173
	v_fmac_f32_e32 v57, v153, v173
	ds_read_u16 v187, v234 offset:44544
	s_waitcnt lgkmcnt(13)
	v_lshlrev_b32_e32 v174, 16, v174
	v_fmac_f32_e32 v58, v154, v174
	ds_read_u16 v188, v234 offset:45056
	s_waitcnt lgkmcnt(13)
	v_lshlrev_b32_e32 v175, 16, v175
	v_fmac_f32_e32 v59, v155, v175
	ds_read_u16 v189, v234 offset:45568
	s_waitcnt lgkmcnt(13)
	v_lshlrev_b32_e32 v176, 16, v176
	v_fmac_f32_e32 v52, v148, v176
	ds_read_u16 v190, v234 offset:46080
	s_waitcnt lgkmcnt(13)
	v_lshlrev_b32_e32 v177, 16, v177
	v_fmac_f32_e32 v53, v149, v177
	ds_read_u16 v191, v234 offset:46592
	s_waitcnt lgkmcnt(13)
	v_lshlrev_b32_e32 v178, 16, v178
	v_fmac_f32_e32 v54, v150, v178
	ds_read_u16 v192, v234 offset:47104
	s_waitcnt lgkmcnt(13)
	v_lshlrev_b32_e32 v179, 16, v179
	v_fmac_f32_e32 v55, v151, v179
	ds_read_u16 v193, v234 offset:47616
	s_waitcnt lgkmcnt(13)
	v_lshlrev_b32_e32 v180, 16, v180
	v_fmac_f32_e32 v48, v144, v180
	ds_read_u16 v194, v234 offset:48128
	s_waitcnt lgkmcnt(13)
	v_lshlrev_b32_e32 v181, 16, v181
	v_fmac_f32_e32 v49, v145, v181
	ds_read_u16 v195, v234 offset:48640
	s_waitcnt lgkmcnt(13)
	v_lshlrev_b32_e32 v182, 16, v182
	v_fmac_f32_e32 v50, v146, v182
	ds_read_u16 v196, v234 offset:49152
	s_waitcnt lgkmcnt(13)
	v_lshlrev_b32_e32 v183, 16, v183
	v_fmac_f32_e32 v51, v147, v183
	ds_read_u16 v197, v234 offset:49664
	s_waitcnt lgkmcnt(13)
	v_lshlrev_b32_e32 v184, 16, v184
	v_fmac_f32_e32 v44, v140, v184
	ds_read_u16 v198, v234 offset:50176
	s_waitcnt lgkmcnt(13)
	v_lshlrev_b32_e32 v185, 16, v185
	v_fmac_f32_e32 v45, v141, v185
	ds_read_u16 v199, v234 offset:50688
	s_waitcnt lgkmcnt(13)
	v_lshlrev_b32_e32 v186, 16, v186
	v_fmac_f32_e32 v46, v142, v186
	ds_read_u16 v200, v234 offset:51200
	s_waitcnt lgkmcnt(13)
	v_lshlrev_b32_e32 v187, 16, v187
	v_fmac_f32_e32 v47, v143, v187
	ds_read_u16 v201, v234 offset:51712
	s_waitcnt lgkmcnt(13)
	v_lshlrev_b32_e32 v188, 16, v188
	v_fmac_f32_e32 v40, v136, v188
	ds_read_u16 v202, v234 offset:52224
	s_waitcnt lgkmcnt(13)
; __device__ __forceinline__ float bf2f(u16 h) { return __uint_as_float(((unsigned)h) << 16); }
; __device__ void phase_merge(const Params& p, int layer, char* smem) {
;     ...
;           } else if (r == 47) {
; #pragma unroll
;             for (int m = 0; m < 4; ++m)
; #pragma unroll
;               for (int n = 0; n < 4; ++n)
; #pragma unroll
;                 for (int j = 0; j < 4; ++j) {
;                   mg[m][n][j] += bf2f(GL[((m * 4 + n) * 4 + j) * 256]) * acc[m][n][j];
;                   acc[m][n][j] = 0.f;
;                 }
	v_lshlrev_b32_e32 v189, 16, v189
	v_fmac_f32_e32 v41, v137, v189
	ds_read_u16 v203, v234 offset:52736
	s_waitcnt lgkmcnt(13)
	v_lshlrev_b32_e32 v190, 16, v190
	v_fmac_f32_e32 v42, v138, v190
	ds_read_u16 v204, v234 offset:53248
	s_waitcnt lgkmcnt(13)
	v_lshlrev_b32_e32 v191, 16, v191
	v_fmac_f32_e32 v43, v139, v191
	ds_read_u16 v205, v234 offset:53760
	s_waitcnt lgkmcnt(13)
	v_lshlrev_b32_e32 v192, 16, v192
	v_fmac_f32_e32 v36, v132, v192
	ds_read_u16 v206, v234 offset:54272
	s_waitcnt lgkmcnt(13)
	v_lshlrev_b32_e32 v193, 16, v193
	v_fmac_f32_e32 v37, v133, v193
	ds_read_u16 v207, v234 offset:54784
	s_waitcnt lgkmcnt(13)
	v_lshlrev_b32_e32 v194, 16, v194
	v_fmac_f32_e32 v38, v134, v194
	ds_read_u16 v208, v234 offset:55296
	s_waitcnt lgkmcnt(13)
	v_lshlrev_b32_e32 v195, 16, v195
	v_fmac_f32_e32 v39, v135, v195
	ds_read_u16 v209, v234 offset:55808
	s_waitcnt lgkmcnt(13)
	v_lshlrev_b32_e32 v196, 16, v196
	v_fmac_f32_e32 v32, v128, v196
	ds_read_u16 v210, v234 offset:56320
	s_waitcnt lgkmcnt(13)
	v_lshlrev_b32_e32 v197, 16, v197
	v_fmac_f32_e32 v33, v129, v197
	ds_read_u16 v211, v234 offset:56832
	s_waitcnt lgkmcnt(13)
	v_lshlrev_b32_e32 v198, 16, v198
	v_fmac_f32_e32 v34, v130, v198
	ds_read_u16 v212, v234 offset:57344
	s_waitcnt lgkmcnt(13)
	v_lshlrev_b32_e32 v199, 16, v199
	v_fmac_f32_e32 v35, v131, v199
	ds_read_u16 v213, v234 offset:57856
	s_waitcnt lgkmcnt(13)
	v_lshlrev_b32_e32 v200, 16, v200
	v_fmac_f32_e32 v28, v124, v200
	ds_read_u16 v214, v234 offset:58368
	s_waitcnt lgkmcnt(13)
	v_lshlrev_b32_e32 v201, 16, v201
	v_fmac_f32_e32 v29, v125, v201
	ds_read_u16 v215, v234 offset:58880
	s_waitcnt lgkmcnt(13)
	v_lshlrev_b32_e32 v202, 16, v202
	v_fmac_f32_e32 v30, v126, v202
	ds_read_u16 v216, v234 offset:59392
	s_waitcnt lgkmcnt(13)
	v_lshlrev_b32_e32 v203, 16, v203
	v_fmac_f32_e32 v31, v127, v203
	ds_read_u16 v217, v234 offset:59904
	s_waitcnt lgkmcnt(13)
	v_lshlrev_b32_e32 v204, 16, v204
	v_fmac_f32_e32 v24, v120, v204
	ds_read_u16 v218, v234 offset:60416
	s_waitcnt lgkmcnt(13)
	v_lshlrev_b32_e32 v205, 16, v205
	v_fmac_f32_e32 v25, v121, v205
	ds_read_u16 v219, v234 offset:60928
	s_waitcnt lgkmcnt(13)
	v_lshlrev_b32_e32 v206, 16, v206
	v_fmac_f32_e32 v26, v122, v206
	ds_read_u16 v220, v234 offset:61440
	s_waitcnt lgkmcnt(13)
	v_lshlrev_b32_e32 v207, 16, v207
	v_fmac_f32_e32 v27, v123, v207
	ds_read_u16 v221, v234 offset:61952
	s_waitcnt lgkmcnt(13)
	v_lshlrev_b32_e32 v208, 16, v208
	v_fmac_f32_e32 v20, v116, v208
	ds_read_u16 v222, v234 offset:62464
	s_waitcnt lgkmcnt(13)
	v_lshlrev_b32_e32 v209, 16, v209
	v_fmac_f32_e32 v21, v117, v209
	ds_read_u16 v223, v234 offset:62976
	s_waitcnt lgkmcnt(13)
	v_lshlrev_b32_e32 v210, 16, v210
	v_fmac_f32_e32 v22, v118, v210
	ds_read_u16 v224, v234 offset:63488
	s_waitcnt lgkmcnt(13)
	v_lshlrev_b32_e32 v211, 16, v211
	v_fmac_f32_e32 v23, v119, v211
	ds_read_u16 v225, v234 offset:64000
	s_waitcnt lgkmcnt(13)
	v_lshlrev_b32_e32 v212, 16, v212
	v_fmac_f32_e32 v16, v112, v212
	ds_read_u16 v226, v234 offset:64512
	s_waitcnt lgkmcnt(13)
	v_lshlrev_b32_e32 v213, 16, v213
	v_fmac_f32_e32 v17, v113, v213
	ds_read_u16 v227, v234 offset:65024
	s_waitcnt lgkmcnt(13)
	v_lshlrev_b32_e32 v214, 16, v214
	v_fmac_f32_e32 v18, v114, v214
	s_waitcnt lgkmcnt(12)
	v_lshlrev_b32_e32 v215, 16, v215
	v_fmac_f32_e32 v19, v115, v215
	s_waitcnt lgkmcnt(11)
	v_lshlrev_b32_e32 v216, 16, v216
	v_fmac_f32_e32 v12, v108, v216
	s_waitcnt lgkmcnt(10)
	v_lshlrev_b32_e32 v217, 16, v217
	v_fmac_f32_e32 v13, v109, v217
	s_waitcnt lgkmcnt(9)
	v_lshlrev_b32_e32 v218, 16, v218
	v_fmac_f32_e32 v14, v110, v218
	s_waitcnt lgkmcnt(8)
	v_lshlrev_b32_e32 v219, 16, v219
	v_fmac_f32_e32 v15, v111, v219
	s_waitcnt lgkmcnt(7)
	v_lshlrev_b32_e32 v220, 16, v220
	v_fmac_f32_e32 v8, v100, v220
	s_waitcnt lgkmcnt(6)
	v_lshlrev_b32_e32 v221, 16, v221
	v_fmac_f32_e32 v9, v101, v221
	s_waitcnt lgkmcnt(5)
	v_lshlrev_b32_e32 v222, 16, v222
	v_fmac_f32_e32 v10, v102, v222
	s_waitcnt lgkmcnt(4)
	v_lshlrev_b32_e32 v223, 16, v223
	v_fmac_f32_e32 v11, v103, v223
	s_waitcnt lgkmcnt(3)
	v_lshlrev_b32_e32 v224, 16, v224
	v_fmac_f32_e32 v4, v104, v224
	s_waitcnt lgkmcnt(2)
	v_lshlrev_b32_e32 v225, 16, v225
	v_fmac_f32_e32 v5, v105, v225
	s_waitcnt lgkmcnt(1)
	v_lshlrev_b32_e32 v226, 16, v226
	v_fmac_f32_e32 v6, v106, v226
	s_waitcnt lgkmcnt(0)
	v_lshlrev_b32_e32 v227, 16, v227
	v_fmac_f32_e32 v7, v107, v227
	v_mov_b32_e32 v1, v0
	v_mov_b32_e32 v2, v0
	s_mov_b64 s[6:7], -1
	s_branch .LBB0_1239
